# single-value bf16 roundings feeding 16-bit stores (368 sites) use v_cvt_pk_bf16_f32 instead of the 2-instruction bit trick
# speedup vs baseline: 1.0280x; 1.0023x over previous
.LBB0_48:
	s_and_b64 vcc, exec, s[18:19]
	s_cbranch_vccz .LBB0_28
	v_add_u32_e32 v28, s11, v0
	s_ashr_i32 s11, s31, 1
	s_andn2_b32 s11, s11, 63
	v_add_u32_e32 v29, s11, v10
	s_lshr_b32 s11, s31, 1
	s_and_b32 s11, s11, 32
	v_or3_b32 v29, v29, s11, v11
	v_cndmask_b32_e64 v28, v28, v29, s[16:17]
	v_add_u32_e32 v29, s10, v1
	v_ashrrev_i32_e32 v30, 31, v29
	v_mul_lo_u32 v32, s14, v30
	v_mul_lo_u32 v33, s15, v29
	v_mad_u64_u32 v[30:31], s[16:17], s14, v29, 0
	v_add3_u32 v31, v31, v32, v33
	v_ashrrev_i32_e32 v29, 31, v28
	s_lshl_b64 s[44:45], s[14:15], 4
	s_waitcnt lgkmcnt(1)
	v_lshl_add_u64 v[30:31], v[30:31], 2, v[8:9]
	v_lshlrev_b64 v[28:29], 2, v[28:29]
	v_lshl_add_u64 v[30:31], v[30:31], 0, v[28:29]
	global_load_dword v46, v[30:31], off
	v_lshl_add_u64 v[32:33], v[30:31], 0, s[44:45]
	global_load_dword v47, v[32:33], off
	v_lshl_add_u64 v[30:31], v[32:33], 0, s[44:45]
	global_load_dword v48, v[30:31], off
	v_lshl_add_u64 v[32:33], v[30:31], 0, s[44:45]
	global_load_dword v49, v[32:33], off
	v_lshl_add_u64 v[30:31], v[32:33], 0, s[44:45]
	global_load_dword v50, v[30:31], off
	v_lshl_add_u64 v[32:33], v[30:31], 0, s[44:45]
	global_load_dword v51, v[32:33], off
	v_lshl_add_u64 v[30:31], v[32:33], 0, s[44:45]
	global_load_dword v52, v[30:31], off
	v_lshl_add_u64 v[32:33], v[30:31], 0, s[44:45]
	global_load_dword v53, v[32:33], off
	v_lshl_add_u64 v[30:31], v[32:33], 0, s[44:45]
	global_load_dword v28, v[30:31], off
	v_lshl_add_u64 v[32:33], v[30:31], 0, s[44:45]
	global_load_dword v29, v[32:33], off
	v_lshl_add_u64 v[30:31], v[32:33], 0, s[44:45]
	global_load_dword v44, v[30:31], off
	v_lshl_add_u64 v[32:33], v[30:31], 0, s[44:45]
	global_load_dword v45, v[32:33], off
	v_lshl_add_u64 v[30:31], v[32:33], 0, s[44:45]
	global_load_dword v54, v[30:31], off
	v_lshl_add_u64 v[32:33], v[30:31], 0, s[44:45]
	global_load_dword v55, v[32:33], off
	v_lshl_add_u64 v[30:31], v[32:33], 0, s[44:45]
	global_load_dword v56, v[30:31], off
	v_lshl_add_u64 v[32:33], v[30:31], 0, s[44:45]
	global_load_dword v57, v[32:33], off
	s_waitcnt vmcnt(15)
	ds_write_b32 v4, v46
	s_waitcnt vmcnt(14)
	ds_write_b32 v4, v47 offset:1040
	s_waitcnt vmcnt(13)
	ds_write_b32 v4, v48 offset:2080
	s_waitcnt vmcnt(12)
	ds_write_b32 v4, v49 offset:3120
	s_waitcnt vmcnt(11)
	ds_write_b32 v4, v50 offset:4160
	s_waitcnt vmcnt(10)
	ds_write_b32 v4, v51 offset:5200
	s_waitcnt vmcnt(9)
	ds_write_b32 v4, v52 offset:6240
	s_waitcnt vmcnt(8)
	ds_write_b32 v4, v53 offset:7280
	s_waitcnt vmcnt(7)
	ds_write_b32 v4, v28 offset:8320
	s_waitcnt vmcnt(6)
	ds_write_b32 v4, v29 offset:9360
	s_waitcnt vmcnt(5)
	ds_write_b32 v4, v44 offset:10400
	s_waitcnt vmcnt(4)
	ds_write_b32 v4, v45 offset:11440
	s_waitcnt vmcnt(3)
	ds_write_b32 v4, v54 offset:12480
	s_waitcnt vmcnt(2)
	ds_write_b32 v4, v55 offset:13520
	s_waitcnt vmcnt(1)
	ds_write_b32 v4, v56 offset:14560
	s_waitcnt vmcnt(0)
	ds_write_b32 v4, v57 offset:15600
	s_waitcnt lgkmcnt(0)
	s_barrier
	ds_read2_b32 v[30:31], v27 offset1:4
	ds_read2_b32 v[32:33], v27 offset0:8 offset1:12
	ds_read2_b32 v[34:35], v27 offset0:16 offset1:20
	ds_read2_b32 v[36:37], v27 offset0:24 offset1:28
	ds_read2_b32 v[38:39], v27 offset0:32 offset1:36
	ds_read2_b32 v[40:41], v27 offset0:40 offset1:44
	ds_read2_b32 v[42:43], v27 offset0:48 offset1:52
	ds_read2_b32 v[44:45], v27 offset0:56 offset1:60
	s_ashr_i32 s11, s10, 31
	s_lshl_b64 s[10:11], s[10:11], 1
	v_lshl_add_u64 v[6:7], v[6:7], 0, s[10:11]
	v_lshl_add_u64 v[6:7], v[6:7], 0, v[2:3]
	v_add_u32_e32 v46, s31, v1
	v_ashrrev_i32_e32 v47, 31, v46
	v_mul_lo_u32 v48, s8, v47
	v_mul_lo_u32 v49, s9, v46
	v_mad_u64_u32 v[46:47], s[10:11], s8, v46, 0
	v_add3_u32 v47, v47, v48, v49
	s_lshl_b64 s[46:47], s[8:9], 3
	v_lshl_add_u64 v[46:47], v[46:47], 1, v[6:7]
	s_waitcnt lgkmcnt(7)
	v_cvt_pk_bf16_f32 v50, v30, v30
	global_store_short v[46:47], v50, off
	v_lshl_add_u64 v[48:49], v[46:47], 0, s[46:47]
	v_cvt_pk_bf16_f32 v51, v31, v31
	global_store_short v[48:49], v51, off
	v_lshl_add_u64 v[46:47], v[48:49], 0, s[46:47]
	s_waitcnt lgkmcnt(6)
	v_cvt_pk_bf16_f32 v50, v32, v32
	global_store_short v[46:47], v50, off
	v_lshl_add_u64 v[48:49], v[46:47], 0, s[46:47]
	v_cvt_pk_bf16_f32 v51, v33, v33
	global_store_short v[48:49], v51, off
	v_lshl_add_u64 v[46:47], v[48:49], 0, s[46:47]
	s_waitcnt lgkmcnt(5)
	v_cvt_pk_bf16_f32 v50, v34, v34
	global_store_short v[46:47], v50, off
	v_lshl_add_u64 v[48:49], v[46:47], 0, s[46:47]
	v_cvt_pk_bf16_f32 v51, v35, v35
	global_store_short v[48:49], v51, off
	v_lshl_add_u64 v[46:47], v[48:49], 0, s[46:47]
	s_waitcnt lgkmcnt(4)
	v_cvt_pk_bf16_f32 v50, v36, v36
	global_store_short v[46:47], v50, off
	v_lshl_add_u64 v[48:49], v[46:47], 0, s[46:47]
	v_cvt_pk_bf16_f32 v51, v37, v37
	global_store_short v[48:49], v51, off
	v_lshl_add_u64 v[46:47], v[48:49], 0, s[46:47]
	s_waitcnt lgkmcnt(3)
	v_cvt_pk_bf16_f32 v50, v38, v38
	global_store_short v[46:47], v50, off
	v_lshl_add_u64 v[48:49], v[46:47], 0, s[46:47]
	v_cvt_pk_bf16_f32 v51, v39, v39
	global_store_short v[48:49], v51, off
	v_lshl_add_u64 v[46:47], v[48:49], 0, s[46:47]
	s_waitcnt lgkmcnt(2)
	v_cvt_pk_bf16_f32 v50, v40, v40
	global_store_short v[46:47], v50, off
	v_lshl_add_u64 v[48:49], v[46:47], 0, s[46:47]
	v_cvt_pk_bf16_f32 v51, v41, v41
	global_store_short v[48:49], v51, off
	v_lshl_add_u64 v[46:47], v[48:49], 0, s[46:47]
	s_waitcnt lgkmcnt(1)
	v_cvt_pk_bf16_f32 v50, v42, v42
	global_store_short v[46:47], v50, off
	v_lshl_add_u64 v[48:49], v[46:47], 0, s[46:47]
	v_cvt_pk_bf16_f32 v51, v43, v43
	global_store_short v[48:49], v51, off
	v_lshl_add_u64 v[46:47], v[48:49], 0, s[46:47]
	s_waitcnt lgkmcnt(0)
	v_cvt_pk_bf16_f32 v50, v44, v44
	global_store_short v[46:47], v50, off
	v_lshl_add_u64 v[48:49], v[46:47], 0, s[46:47]
	v_cvt_pk_bf16_f32 v51, v45, v45
	global_store_short v[48:49], v51, off
	s_barrier
	s_branch .LBB0_28

.LBB0_74:
	s_or_b64 exec, exec, s[0:1]
	s_waitcnt vmcnt(0) lgkmcnt(0)
	v_add_u32_e32 v9, s10, v9
	v_cvt_pk_bf16_f32 v13, v13, v13
	v_cmp_lt_i32_e64 s[0:1], s13, v9
	flat_store_short v[10:11], v13
	s_or_b64 s[8:9], s[0:1], s[8:9]
	v_lshl_add_u64 v[10:11], v[10:11], 0, s[6:7]
	s_andn2_b64 exec, exec, s[8:9]
	s_cbranch_execz .LBB0_79

.LBB0_87:
	flat_load_dword v4, v[0:1]
	v_add_u32_e32 v10, s10, v10
	v_cmp_lt_i32_e32 vcc, s14, v10
	v_lshl_add_u64 v[0:1], v[0:1], 0, s[8:9]
	s_or_b64 s[12:13], vcc, s[12:13]
	s_waitcnt vmcnt(0) lgkmcnt(0)
	v_cvt_pk_bf16_f32 v4, v4, v4
	flat_store_short v[2:3], v4
	v_lshl_add_u64 v[2:3], v[2:3], 0, s[6:7]
	s_andn2_b64 exec, exec, s[12:13]
	s_cbranch_execnz .LBB0_87

.LBB0_102:
	v_ashrrev_i32_e32 v4, 8, v8
	v_mul_lo_u32 v5, v3, v4
	v_and_b32_e32 v6, 0x7f8, v5
	v_lshlrev_b32_e32 v6, 2, v6
	ds_read2st64_b32 v[6:7], v6 offset1:32
	v_add_u32_e32 v8, s10, v8
	v_lshl_or_b32 v4, v4, 9, v2
	v_cmp_lt_i32_e32 vcc, s6, v8
	v_ashrrev_i32_e32 v5, 31, v4
	s_waitcnt lgkmcnt(0)
	v_mul_f32_e32 v6, 0x403504f3, v6
	v_mul_f32_e32 v7, 0x403504f3, v7
	v_add_u32_e32 v3, s4, v3
	s_or_b64 s[2:3], vcc, s[2:3]
	v_lshl_add_u64 v[4:5], v[4:5], 1, v[0:1]
	v_cvt_pk_bf16_f32 v6, v6, v6
	v_cvt_pk_bf16_f32 v7, v7, v7
	flat_store_short v[4:5], v6
	flat_store_short v[4:5], v7 offset:512
	s_andn2_b64 exec, exec, s[2:3]
	s_cbranch_execnz .LBB0_102

.LBB0_159:
	v_add_u32_e32 v124, s0, v90
	ds_read2_b32 v[92:93], v91 offset1:4
	ds_read2_b32 v[94:95], v91 offset0:8 offset1:12
	ds_read2_b32 v[96:97], v91 offset0:16 offset1:20
	ds_read2_b32 v[98:99], v91 offset0:24 offset1:28
	ds_read2_b32 v[100:101], v91 offset0:32 offset1:36
	ds_read2_b32 v[102:103], v91 offset0:40 offset1:44
	ds_read2_b32 v[104:105], v91 offset0:48 offset1:52
	ds_read2_b32 v[106:107], v91 offset0:56 offset1:60
	ds_read2_b32 v[108:109], v91 offset0:65 offset1:69
	ds_read2_b32 v[110:111], v91 offset0:73 offset1:77
	ds_read2_b32 v[112:113], v91 offset0:81 offset1:85
	ds_read2_b32 v[114:115], v91 offset0:89 offset1:93
	ds_read2_b32 v[116:117], v91 offset0:97 offset1:101
	ds_read2_b32 v[118:119], v91 offset0:105 offset1:109
	ds_read2_b32 v[120:121], v91 offset0:113 offset1:117
	ds_read2_b32 v[122:123], v91 offset0:121 offset1:125
	ds_read2_b32 v[124:125], v124 offset1:1
	s_add_i32 s0, s0, 8
	v_add_u32_e32 v91, 0x208, v91
	s_cmpk_eq_i32 s0, 0x100
	s_waitcnt lgkmcnt(0)
	v_pk_fma_f32 v[82:83], v[124:125], v[92:93], v[82:83] op_sel_hi:[0,1,1]
	v_pk_fma_f32 v[76:77], v[124:125], v[94:95], v[76:77] op_sel_hi:[0,1,1]
	v_pk_fma_f32 v[70:71], v[124:125], v[96:97], v[70:71] op_sel_hi:[0,1,1]
	v_pk_fma_f32 v[62:63], v[124:125], v[98:99], v[62:63] op_sel_hi:[0,1,1]
	v_pk_fma_f32 v[56:57], v[124:125], v[100:101], v[56:57] op_sel_hi:[0,1,1]
	v_pk_fma_f32 v[48:49], v[124:125], v[102:103], v[48:49] op_sel_hi:[0,1,1]
	v_pk_fma_f32 v[42:43], v[124:125], v[104:105], v[42:43] op_sel_hi:[0,1,1]
	v_pk_fma_f32 v[40:41], v[124:125], v[106:107], v[40:41] op_sel_hi:[0,1,1]
	v_pk_fma_f32 v[82:83], v[124:125], v[108:109], v[82:83] op_sel:[1,0,0]
	v_pk_fma_f32 v[76:77], v[124:125], v[110:111], v[76:77] op_sel:[1,0,0]
	v_pk_fma_f32 v[70:71], v[124:125], v[112:113], v[70:71] op_sel:[1,0,0]
	v_pk_fma_f32 v[62:63], v[124:125], v[114:115], v[62:63] op_sel:[1,0,0]
	v_pk_fma_f32 v[56:57], v[124:125], v[116:117], v[56:57] op_sel:[1,0,0]
	v_pk_fma_f32 v[48:49], v[124:125], v[118:119], v[48:49] op_sel:[1,0,0]
	v_pk_fma_f32 v[42:43], v[124:125], v[120:121], v[42:43] op_sel:[1,0,0]
	v_pk_fma_f32 v[40:41], v[124:125], v[122:123], v[40:41] op_sel:[1,0,0]
	s_cbranch_scc0 .LBB0_159
	s_add_i32 s19, s19, 1
	s_cmp_eq_u32 s19, 4
	s_cbranch_scc0 .LBB0_158
	s_lshl_b64 s[4:5], s[4:5], 9
	s_lshl_b32 s0, s18, 8
	s_or_b32 s4, s4, s0
	s_or_b64 s[4:5], s[4:5], s[6:7]
	s_lshl_b32 s0, s17, 1
	v_cvt_pk_bf16_f32 v50, v82, v82
	v_lshl_add_u64 v[46:47], s[4:5], 0, v[2:3]
	v_lshl_add_u64 v[44:45], v[6:7], 0, s[0:1]
	v_lshlrev_b64 v[46:47], 11, v[46:47]
	v_lshl_add_u64 v[46:47], v[44:45], 0, v[46:47]
	global_store_short v[46:47], v50, off
	v_cvt_pk_bf16_f32 v50, v83, v83
	v_lshl_add_u64 v[46:47], s[4:5], 0, v[10:11]
	v_lshlrev_b64 v[46:47], 11, v[46:47]
	v_lshl_add_u64 v[46:47], v[44:45], 0, v[46:47]
	global_store_short v[46:47], v50, off
	v_cvt_pk_bf16_f32 v50, v76, v76
	v_lshl_add_u64 v[46:47], s[4:5], 0, v[12:13]
	v_lshlrev_b64 v[46:47], 11, v[46:47]
	v_lshl_add_u64 v[46:47], v[44:45], 0, v[46:47]
	global_store_short v[46:47], v50, off
	v_cvt_pk_bf16_f32 v50, v77, v77
	v_lshl_add_u64 v[46:47], s[4:5], 0, v[14:15]
	v_lshlrev_b64 v[46:47], 11, v[46:47]
	v_lshl_add_u64 v[46:47], v[44:45], 0, v[46:47]
	global_store_short v[46:47], v50, off
	v_cvt_pk_bf16_f32 v50, v70, v70
	v_lshl_add_u64 v[46:47], s[4:5], 0, v[16:17]
	v_lshlrev_b64 v[46:47], 11, v[46:47]
	v_lshl_add_u64 v[46:47], v[44:45], 0, v[46:47]
	global_store_short v[46:47], v50, off
	v_cvt_pk_bf16_f32 v50, v71, v71
	v_lshl_add_u64 v[46:47], s[4:5], 0, v[18:19]
	v_lshlrev_b64 v[46:47], 11, v[46:47]
	v_lshl_add_u64 v[46:47], v[44:45], 0, v[46:47]
	global_store_short v[46:47], v50, off
	v_cvt_pk_bf16_f32 v50, v62, v62
	v_lshl_add_u64 v[46:47], s[4:5], 0, v[20:21]
	v_lshlrev_b64 v[46:47], 11, v[46:47]
	v_lshl_add_u64 v[46:47], v[44:45], 0, v[46:47]
	global_store_short v[46:47], v50, off
	v_cvt_pk_bf16_f32 v50, v63, v63
	v_lshl_add_u64 v[46:47], s[4:5], 0, v[22:23]
	v_lshlrev_b64 v[46:47], 11, v[46:47]
	v_lshl_add_u64 v[46:47], v[44:45], 0, v[46:47]
	global_store_short v[46:47], v50, off
	v_cvt_pk_bf16_f32 v50, v56, v56
	v_lshl_add_u64 v[46:47], s[4:5], 0, v[24:25]
	v_lshlrev_b64 v[46:47], 11, v[46:47]
	v_lshl_add_u64 v[46:47], v[44:45], 0, v[46:47]
	global_store_short v[46:47], v50, off
	v_cvt_pk_bf16_f32 v50, v57, v57
	v_lshl_add_u64 v[46:47], s[4:5], 0, v[26:27]
	v_lshlrev_b64 v[46:47], 11, v[46:47]
	v_lshl_add_u64 v[46:47], v[44:45], 0, v[46:47]
	global_store_short v[46:47], v50, off
	v_cvt_pk_bf16_f32 v48, v48, v48
	v_lshl_add_u64 v[46:47], s[4:5], 0, v[28:29]
	v_lshlrev_b64 v[46:47], 11, v[46:47]
	v_lshl_add_u64 v[46:47], v[44:45], 0, v[46:47]
	global_store_short v[46:47], v48, off
	v_cvt_pk_bf16_f32 v48, v49, v49
	v_lshl_add_u64 v[46:47], s[4:5], 0, v[30:31]
	v_lshlrev_b64 v[46:47], 11, v[46:47]
	v_lshl_add_u64 v[46:47], v[44:45], 0, v[46:47]
	global_store_short v[46:47], v48, off
	v_cvt_pk_bf16_f32 v42, v42, v42
	v_lshl_add_u64 v[46:47], s[4:5], 0, v[32:33]
	v_lshlrev_b64 v[46:47], 11, v[46:47]
	v_lshl_add_u64 v[46:47], v[44:45], 0, v[46:47]
	global_store_short v[46:47], v42, off
	v_bfe_u32 v42, v43, 16, 1
	v_add3_u32 v46, v43, v42, s16
	v_lshl_add_u64 v[42:43], s[4:5], 0, v[34:35]
	v_lshlrev_b64 v[42:43], 11, v[42:43]
	v_lshl_add_u64 v[42:43], v[44:45], 0, v[42:43]
	global_store_short_d16_hi v[42:43], v46, off
	v_cvt_pk_bf16_f32 v40, v40, v40
	v_lshl_add_u64 v[42:43], s[4:5], 0, v[36:37]
	v_lshlrev_b64 v[42:43], 11, v[42:43]
	v_lshl_add_u64 v[42:43], v[44:45], 0, v[42:43]
	global_store_short v[42:43], v40, off
	v_cvt_pk_bf16_f32 v42, v41, v41
	v_lshl_add_u64 v[40:41], s[4:5], 0, v[38:39]
	v_lshlrev_b64 v[40:41], 11, v[40:41]
	s_add_i32 s14, s14, s82
	v_lshl_add_u64 v[40:41], v[44:45], 0, v[40:41]
	s_cmpk_gt_i32 s14, 0xff
	global_store_short v[40:41], v42, off
	s_cbranch_scc0 .LBB0_157

.LBB0_250:
	s_andn2_b64 vcc, exec, s[10:11]
	s_cbranch_vccnz .LBB0_226
	s_ashr_i32 s1, s17, 1
	s_andn2_b32 s1, s1, 63
	v_add_u32_e32 v9, s1, v12
	s_lshr_b32 s1, s17, 1
	s_and_b32 s1, s1, 32
	v_add_u32_e32 v8, s16, v0
	v_or3_b32 v9, v9, s1, v13
	v_cndmask_b32_e64 v8, v8, v9, s[6:7]
	v_add_u32_e32 v9, s2, v1
	v_ashrrev_i32_e32 v10, 31, v9
	v_mul_lo_u32 v77, s4, v10
	v_mul_lo_u32 v78, s5, v9
	v_mad_u64_u32 v[10:11], s[6:7], s4, v9, 0
	v_add3_u32 v11, v11, v77, v78
	v_ashrrev_i32_e32 v9, 31, v8
	s_lshl_b64 s[44:45], s[4:5], 4
	v_lshl_add_u64 v[10:11], v[10:11], 2, v[6:7]
	v_lshlrev_b64 v[8:9], 2, v[8:9]
	v_lshl_add_u64 v[10:11], v[10:11], 0, v[8:9]
	global_load_dword v110, v[10:11], off
	v_lshl_add_u64 v[6:7], v[10:11], 0, s[44:45]
	global_load_dword v111, v[6:7], off
	v_lshl_add_u64 v[10:11], v[6:7], 0, s[44:45]
	global_load_dword v112, v[10:11], off
	v_lshl_add_u64 v[6:7], v[10:11], 0, s[44:45]
	global_load_dword v113, v[6:7], off
	v_lshl_add_u64 v[10:11], v[6:7], 0, s[44:45]
	global_load_dword v114, v[10:11], off
	v_lshl_add_u64 v[6:7], v[10:11], 0, s[44:45]
	global_load_dword v115, v[6:7], off
	v_lshl_add_u64 v[10:11], v[6:7], 0, s[44:45]
	global_load_dword v116, v[10:11], off
	v_lshl_add_u64 v[6:7], v[10:11], 0, s[44:45]
	global_load_dword v117, v[6:7], off
	v_lshl_add_u64 v[10:11], v[6:7], 0, s[44:45]
	global_load_dword v118, v[10:11], off
	v_lshl_add_u64 v[6:7], v[10:11], 0, s[44:45]
	global_load_dword v119, v[6:7], off
	v_lshl_add_u64 v[10:11], v[6:7], 0, s[44:45]
	global_load_dword v120, v[10:11], off
	v_lshl_add_u64 v[6:7], v[10:11], 0, s[44:45]
	global_load_dword v121, v[6:7], off
	v_lshl_add_u64 v[10:11], v[6:7], 0, s[44:45]
	global_load_dword v122, v[10:11], off
	v_lshl_add_u64 v[6:7], v[10:11], 0, s[44:45]
	global_load_dword v123, v[6:7], off
	v_lshl_add_u64 v[10:11], v[6:7], 0, s[44:45]
	global_load_dword v124, v[10:11], off
	v_lshl_add_u64 v[6:7], v[10:11], 0, s[44:45]
	global_load_dword v125, v[6:7], off
	s_ashr_i32 s3, s2, 31
	s_lshl_b64 s[2:3], s[2:3], 1
	v_lshl_add_u64 v[4:5], v[4:5], 0, s[2:3]
	v_lshl_add_u64 v[4:5], v[4:5], 0, v[228:229]
	v_mul_lo_u32 v76, s0, v76
	s_waitcnt vmcnt(0)
	ds_write_b32 v2, v110
	ds_write_b32 v2, v111 offset:1040
	ds_write_b32 v2, v112 offset:2080
	ds_write_b32 v2, v113 offset:3120
	ds_write_b32 v2, v114 offset:4160
	ds_write_b32 v2, v115 offset:5200
	ds_write_b32 v2, v116 offset:6240
	ds_write_b32 v2, v117 offset:7280
	ds_write_b32 v2, v118 offset:8320
	ds_write_b32 v2, v119 offset:9360
	ds_write_b32 v2, v120 offset:10400
	ds_write_b32 v2, v121 offset:11440
	ds_write_b32 v2, v122 offset:12480
	ds_write_b32 v2, v123 offset:13520
	ds_write_b32 v2, v124 offset:14560
	ds_write_b32 v2, v125 offset:15600
	s_waitcnt lgkmcnt(0)
	s_barrier
	ds_read2_b32 v[30:31], v3 offset1:4
	ds_read2_b32 v[32:33], v3 offset0:8 offset1:12
	ds_read2_b32 v[34:35], v3 offset0:16 offset1:20
	ds_read2_b32 v[36:37], v3 offset0:24 offset1:28
	ds_read2_b32 v[38:39], v3 offset0:32 offset1:36
	ds_read2_b32 v[40:41], v3 offset0:40 offset1:44
	ds_read2_b32 v[42:43], v3 offset0:48 offset1:52
	ds_read2_b32 v[44:45], v3 offset0:56 offset1:60
	v_mad_u64_u32 v[10:11], s[2:3], s0, v70, 0
	v_add3_u32 v11, v11, v76, v75
	s_lshl_b32 s46, s0, 3
	s_mov_b32 s47, 0
	v_lshl_add_u64 v[10:11], v[10:11], 1, v[4:5]
	s_waitcnt lgkmcnt(7)
	v_cvt_pk_bf16_f32 v8, v30, v30
	global_store_short v[10:11], v8, off
	v_lshl_add_u64 v[6:7], v[10:11], 0, s[46:47]
	v_cvt_pk_bf16_f32 v9, v31, v31
	global_store_short v[6:7], v9, off
	v_lshl_add_u64 v[10:11], v[6:7], 0, s[46:47]
	s_waitcnt lgkmcnt(6)
	v_cvt_pk_bf16_f32 v8, v32, v32
	global_store_short v[10:11], v8, off
	v_lshl_add_u64 v[6:7], v[10:11], 0, s[46:47]
	v_cvt_pk_bf16_f32 v9, v33, v33
	global_store_short v[6:7], v9, off
	v_lshl_add_u64 v[10:11], v[6:7], 0, s[46:47]
	s_waitcnt lgkmcnt(5)
	v_cvt_pk_bf16_f32 v8, v34, v34
	global_store_short v[10:11], v8, off
	v_lshl_add_u64 v[6:7], v[10:11], 0, s[46:47]
	v_cvt_pk_bf16_f32 v9, v35, v35
	global_store_short v[6:7], v9, off
	v_lshl_add_u64 v[10:11], v[6:7], 0, s[46:47]
	s_waitcnt lgkmcnt(4)
	v_cvt_pk_bf16_f32 v8, v36, v36
	global_store_short v[10:11], v8, off
	v_lshl_add_u64 v[6:7], v[10:11], 0, s[46:47]
	v_cvt_pk_bf16_f32 v9, v37, v37
	global_store_short v[6:7], v9, off
	v_lshl_add_u64 v[10:11], v[6:7], 0, s[46:47]
	s_waitcnt lgkmcnt(3)
	v_cvt_pk_bf16_f32 v8, v38, v38
	global_store_short v[10:11], v8, off
	v_lshl_add_u64 v[6:7], v[10:11], 0, s[46:47]
	v_cvt_pk_bf16_f32 v9, v39, v39
	global_store_short v[6:7], v9, off
	v_lshl_add_u64 v[10:11], v[6:7], 0, s[46:47]
	s_waitcnt lgkmcnt(2)
	v_cvt_pk_bf16_f32 v8, v40, v40
	global_store_short v[10:11], v8, off
	v_lshl_add_u64 v[6:7], v[10:11], 0, s[46:47]
	v_cvt_pk_bf16_f32 v9, v41, v41
	global_store_short v[6:7], v9, off
	v_lshl_add_u64 v[10:11], v[6:7], 0, s[46:47]
	s_waitcnt lgkmcnt(1)
	v_cvt_pk_bf16_f32 v8, v42, v42
	global_store_short v[10:11], v8, off
	v_lshl_add_u64 v[6:7], v[10:11], 0, s[46:47]
	v_cvt_pk_bf16_f32 v9, v43, v43
	global_store_short v[6:7], v9, off
	v_lshl_add_u64 v[10:11], v[6:7], 0, s[46:47]
	s_waitcnt lgkmcnt(0)
	v_cvt_pk_bf16_f32 v8, v44, v44
	global_store_short v[10:11], v8, off
	v_lshl_add_u64 v[6:7], v[10:11], 0, s[46:47]
	v_cvt_pk_bf16_f32 v9, v45, v45
	global_store_short v[6:7], v9, off
	s_barrier
	s_branch .LBB0_226

.LBB0_1142:
	s_or_b64 exec, exec, s[0:1]
	s_waitcnt lgkmcnt(0)
	s_barrier
	ds_read_b64 v[2:3], v229 offset:63760
	v_readlane_b32 s0, v255, 27
	v_lshlrev_b64 v[18:19], 1, v[34:35]
	v_lshlrev_b32_e32 v52, 2, v0
	v_add_u32_e32 v4, s0, v34
	s_waitcnt lgkmcnt(0)
	v_lshl_add_u64 v[16:17], v[2:3], 0, s[58:59]
	ds_read_b64 v[2:3], v229 offset:63696
	v_ashrrev_i32_e32 v5, 31, v4
	v_or_b32_e32 v0, s7, v0
	v_lshlrev_b32_e32 v228, 11, v0
	v_lshl_add_u64 v[0:1], v[16:17], 0, v[228:229]
	s_waitcnt lgkmcnt(0)
	v_lshl_add_u64 v[4:5], v[4:5], 2, v[2:3]
	global_load_dword v41, v[4:5], off
	v_add_u32_e32 v4, s0, v32
	v_ashrrev_i32_e32 v5, 31, v4
	v_lshl_add_u64 v[2:3], v[4:5], 2, v[2:3]
	global_load_dword v34, v[2:3], off
	v_lshlrev_b64 v[20:21], 1, v[32:33]
	v_lshl_add_u64 v[26:27], v[0:1], 0, v[18:19]
	v_lshl_add_u64 v[32:33], v[0:1], 0, v[20:21]
	ds_read_b128 v[4:7], v52 offset:51712
	ds_read_b128 v[0:3], v52 offset:51744
	ds_read_b128 v[8:11], v52 offset:51840
	ds_read_b128 v[12:15], v52 offset:51968
	ds_read_b128 v[22:25], v52 offset:52096
	v_readlane_b32 s1, v255, 28
	s_add_i32 s6, s6, 1
	s_waitcnt lgkmcnt(2)
	v_pk_add_f32 v[4:5], v[4:5], v[8:9]
	v_pk_add_f32 v[6:7], v[6:7], v[10:11]
	s_waitcnt lgkmcnt(1)
	v_pk_add_f32 v[4:5], v[4:5], v[12:13]
	v_pk_add_f32 v[6:7], v[6:7], v[14:15]
	s_waitcnt lgkmcnt(0)
	v_pk_add_f32 v[4:5], v[4:5], v[22:23]
	v_mov_b64_e32 v[22:23], s[10:11]
	v_pk_fma_f32 v[4:5], v[4:5], s[68:69], v[22:23] op_sel_hi:[1,0,0]
	v_pk_add_f32 v[6:7], v[6:7], v[24:25]
	v_mul_f32_e32 v8, 0x4b800000, v4
	v_cmp_gt_f32_e64 s[0:1], s92, v4
	v_cmp_gt_f32_e32 vcc, s92, v5
	v_pk_fma_f32 v[6:7], v[6:7], s[68:69], v[22:23] op_sel_hi:[1,0,0]
	v_cndmask_b32_e64 v4, v4, v8, s[0:1]
	v_rsq_f32_e32 v4, v4
	v_mul_f32_e32 v10, 0x4b800000, v6
	s_cmpk_eq_i32 s6, 0x100
	v_mul_f32_e32 v8, 0x45800000, v4
	v_cndmask_b32_e64 v4, v4, v8, s[0:1]
	v_mul_f32_e32 v8, v67, v4
	v_mul_f32_e32 v4, v66, v4
	v_cmp_gt_f32_e64 s[0:1], s92, v6
	s_waitcnt vmcnt(1)
	v_mul_f32_e32 v8, v41, v8
	v_cvt_pk_bf16_f32 v8, v8, v8
	global_store_short v[26:27], v8, off
	s_waitcnt vmcnt(1)
	v_mul_f32_e32 v4, v34, v4
	v_cvt_pk_bf16_f32 v4, v4, v4
	global_store_short v[32:33], v4, off
	v_mul_f32_e32 v4, 0x4b800000, v5
	v_cndmask_b32_e32 v4, v5, v4, vcc
	v_rsq_f32_e32 v4, v4
	v_cndmask_b32_e64 v6, v6, v10, s[0:1]
	v_rsq_f32_e32 v6, v6
	v_mul_f32_e32 v5, 0x45800000, v4
	v_cndmask_b32_e32 v12, v4, v5, vcc
	v_or_b32_e32 v4, s7, v61
	v_mul_f32_e32 v8, v65, v12
	v_lshlrev_b32_e32 v4, 11, v4
	v_mov_b32_e32 v5, v229
	v_mul_f32_e32 v8, v41, v8
	v_lshl_add_u64 v[4:5], v[16:17], 0, v[4:5]
	v_cvt_pk_bf16_f32 v13, v8, v8
	v_lshl_add_u64 v[8:9], v[4:5], 0, v[18:19]
	global_store_short v[8:9], v13, off
	v_mul_f32_e32 v8, v63, v12
	v_mul_f32_e32 v8, v34, v8
	v_mul_f32_e32 v10, 0x45800000, v6
	v_cndmask_b32_e64 v6, v6, v10, s[0:1]
	v_cvt_pk_bf16_f32 v8, v8, v8
	v_lshl_add_u64 v[4:5], v[4:5], 0, v[20:21]
	v_mul_f32_e32 v10, v60, v6
	global_store_short v[4:5], v8, off
	v_or_b32_e32 v4, 0x1000, v228
	v_mov_b32_e32 v5, v229
	v_mul_f32_e32 v10, v41, v10
	v_lshl_add_u64 v[4:5], v[16:17], 0, v[4:5]
	v_mul_f32_e32 v6, v59, v6
	v_lshl_add_u64 v[8:9], v[4:5], 0, v[18:19]
	v_cvt_pk_bf16_f32 v10, v10, v10
	v_mul_f32_e32 v6, v34, v6
	global_store_short v[8:9], v10, off
	v_lshl_add_u64 v[4:5], v[4:5], 0, v[20:21]
	v_cvt_pk_bf16_f32 v6, v6, v6
	v_cmp_gt_f32_e32 vcc, s92, v7
	global_store_short v[4:5], v6, off
	v_mul_f32_e32 v4, 0x4b800000, v7
	v_cndmask_b32_e32 v4, v7, v4, vcc
	v_rsq_f32_e32 v4, v4
	ds_read_b128 v[12:15], v52 offset:52128
	v_mul_f32_e32 v5, 0x45800000, v4
	v_cndmask_b32_e32 v8, v4, v5, vcc
	v_mul_f32_e32 v6, v64, v8
	v_or_b32_e32 v4, 0x1800, v228
	v_mov_b32_e32 v5, v229
	v_mul_f32_e32 v6, v41, v6
	v_lshl_add_u64 v[4:5], v[16:17], 0, v[4:5]
	v_cvt_pk_bf16_f32 v9, v6, v6
	v_lshl_add_u64 v[6:7], v[4:5], 0, v[18:19]
	global_store_short v[6:7], v9, off
	v_mul_f32_e32 v6, v62, v8
	v_mul_f32_e32 v6, v34, v6
	v_cvt_pk_bf16_f32 v6, v6, v6
	v_lshl_add_u64 v[4:5], v[4:5], 0, v[20:21]
	global_store_short v[4:5], v6, off
	v_or_b32_e32 v4, 0x4000, v228
	v_mov_b32_e32 v5, v229
	v_lshl_add_u64 v[4:5], v[16:17], 0, v[4:5]
	v_lshl_add_u64 v[26:27], v[4:5], 0, v[18:19]
	v_lshl_add_u64 v[24:25], v[4:5], 0, v[20:21]
	ds_read_b128 v[4:7], v52 offset:51872
	ds_read_b128 v[8:11], v52 offset:52000
	s_waitcnt lgkmcnt(1)
	v_pk_add_f32 v[0:1], v[0:1], v[4:5]
	s_waitcnt lgkmcnt(0)
	v_pk_add_f32 v[0:1], v[0:1], v[8:9]
	v_pk_add_f32 v[2:3], v[2:3], v[6:7]
	v_pk_add_f32 v[0:1], v[0:1], v[12:13]
	v_pk_add_f32 v[2:3], v[2:3], v[10:11]
	v_pk_fma_f32 v[0:1], v[0:1], s[68:69], v[22:23] op_sel_hi:[1,0,0]
	v_pk_add_f32 v[2:3], v[2:3], v[14:15]
	v_mul_f32_e32 v4, 0x4b800000, v0
	v_cmp_gt_f32_e64 s[0:1], s92, v0
	v_cmp_gt_f32_e32 vcc, s92, v1
	v_pk_fma_f32 v[2:3], v[2:3], s[68:69], v[22:23] op_sel_hi:[1,0,0]
	v_cndmask_b32_e64 v0, v0, v4, s[0:1]
	v_rsq_f32_e32 v0, v0
	v_mul_f32_e32 v6, 0x4b800000, v2
	v_mul_f32_e32 v4, 0x45800000, v0
	v_cndmask_b32_e64 v0, v0, v4, s[0:1]
	v_mul_f32_e32 v4, v48, v0
	v_mul_f32_e32 v4, v41, v4
	v_mul_f32_e32 v0, v45, v0
	v_cvt_pk_bf16_f32 v4, v4, v4
	v_mul_f32_e32 v0, v34, v0
	global_store_short v[26:27], v4, off
	v_cvt_pk_bf16_f32 v0, v0, v0
	global_store_short v[24:25], v0, off
	v_mul_f32_e32 v0, 0x4b800000, v1
	v_cndmask_b32_e32 v0, v1, v0, vcc
	v_rsq_f32_e32 v0, v0
	v_cmp_gt_f32_e64 s[0:1], s92, v2
	v_mul_f32_e32 v1, 0x45800000, v0
	v_cndmask_b32_e32 v8, v0, v1, vcc
	v_mul_f32_e32 v4, v51, v8
	v_cndmask_b32_e64 v2, v2, v6, s[0:1]
	v_or_b32_e32 v0, 0x4800, v228
	v_mov_b32_e32 v1, v229
	v_mul_f32_e32 v4, v41, v4
	v_rsq_f32_e32 v2, v2
	v_lshl_add_u64 v[0:1], v[16:17], 0, v[0:1]
	v_cvt_pk_bf16_f32 v9, v4, v4
	v_lshl_add_u64 v[4:5], v[0:1], 0, v[18:19]
	global_store_short v[4:5], v9, off
	v_mul_f32_e32 v4, v49, v8
	v_mul_f32_e32 v4, v34, v4
	v_mul_f32_e32 v6, 0x45800000, v2
	v_cndmask_b32_e64 v2, v2, v6, s[0:1]
	v_cvt_pk_bf16_f32 v4, v4, v4
	v_lshl_add_u64 v[0:1], v[0:1], 0, v[20:21]
	v_mul_f32_e32 v6, v46, v2
	global_store_short v[0:1], v4, off
	v_or_b32_e32 v0, 0x5000, v228
	v_mov_b32_e32 v1, v229
	v_mul_f32_e32 v6, v41, v6
	v_lshl_add_u64 v[0:1], v[16:17], 0, v[0:1]
	v_mul_f32_e32 v2, v44, v2
	v_lshl_add_u64 v[4:5], v[0:1], 0, v[18:19]
	v_cvt_pk_bf16_f32 v6, v6, v6
	v_mul_f32_e32 v2, v34, v2
	global_store_short v[4:5], v6, off
	v_lshl_add_u64 v[0:1], v[0:1], 0, v[20:21]
	v_cvt_pk_bf16_f32 v2, v2, v2
	v_cmp_gt_f32_e32 vcc, s92, v3
	global_store_short v[0:1], v2, off
	v_mul_f32_e32 v0, 0x4b800000, v3
	v_cndmask_b32_e32 v0, v3, v0, vcc
	v_rsq_f32_e32 v0, v0
	s_nop 0
	v_mul_f32_e32 v1, 0x45800000, v0
	v_cndmask_b32_e32 v4, v0, v1, vcc
	v_mul_f32_e32 v2, v50, v4
	v_or_b32_e32 v0, 0x5800, v228
	v_mov_b32_e32 v1, v229
	v_mul_f32_e32 v2, v41, v2
	v_lshl_add_u64 v[0:1], v[16:17], 0, v[0:1]
	v_cvt_pk_bf16_f32 v5, v2, v2
	v_lshl_add_u64 v[2:3], v[0:1], 0, v[18:19]
	global_store_short v[2:3], v5, off
	v_mul_f32_e32 v2, v47, v4
	v_mul_f32_e32 v2, v34, v2
	v_cvt_pk_bf16_f32 v2, v2, v2
	v_lshl_add_u64 v[0:1], v[0:1], 0, v[20:21]
	global_store_short v[0:1], v2, off
	v_or_b32_e32 v0, 0x8000, v228
	v_mov_b32_e32 v1, v229
	v_lshl_add_u64 v[0:1], v[16:17], 0, v[0:1]
	v_lshl_add_u64 v[24:25], v[0:1], 0, v[18:19]
	v_lshl_add_u64 v[26:27], v[0:1], 0, v[20:21]
	ds_read_b128 v[0:3], v52 offset:51776
	ds_read_b128 v[4:7], v52 offset:51904
	ds_read_b128 v[8:11], v52 offset:52032
	ds_read_b128 v[12:15], v52 offset:52160
	s_waitcnt lgkmcnt(2)
	v_pk_add_f32 v[0:1], v[0:1], v[4:5]
	s_waitcnt lgkmcnt(1)
	v_pk_add_f32 v[0:1], v[0:1], v[8:9]
	v_pk_add_f32 v[2:3], v[2:3], v[6:7]
	s_waitcnt lgkmcnt(0)
	v_pk_add_f32 v[0:1], v[0:1], v[12:13]
	v_pk_add_f32 v[2:3], v[2:3], v[10:11]
	v_pk_fma_f32 v[0:1], v[0:1], s[68:69], v[22:23] op_sel_hi:[1,0,0]
	v_pk_add_f32 v[2:3], v[2:3], v[14:15]
	v_mul_f32_e32 v4, 0x4b800000, v0
	v_cmp_gt_f32_e64 s[0:1], s92, v0
	v_cmp_gt_f32_e32 vcc, s92, v1
	v_pk_fma_f32 v[2:3], v[2:3], s[68:69], v[22:23] op_sel_hi:[1,0,0]
	v_cndmask_b32_e64 v0, v0, v4, s[0:1]
	v_rsq_f32_e32 v0, v0
	v_mul_f32_e32 v6, 0x4b800000, v2
	v_mul_f32_e32 v4, 0x45800000, v0
	v_cndmask_b32_e64 v0, v0, v4, s[0:1]
	v_mul_f32_e32 v4, v43, v0
	v_mul_f32_e32 v4, v41, v4
	v_mul_f32_e32 v0, v42, v0
	v_cvt_pk_bf16_f32 v4, v4, v4
	v_mul_f32_e32 v0, v34, v0
	global_store_short v[24:25], v4, off
	v_cvt_pk_bf16_f32 v0, v0, v0
	global_store_short v[26:27], v0, off
	v_mul_f32_e32 v0, 0x4b800000, v1
	v_cndmask_b32_e32 v0, v1, v0, vcc
	v_rsq_f32_e32 v0, v0
	v_cmp_gt_f32_e64 s[0:1], s92, v2
	v_mul_f32_e32 v1, 0x45800000, v0
	v_cndmask_b32_e32 v8, v0, v1, vcc
	v_mul_f32_e32 v4, v54, v8
	v_cndmask_b32_e64 v2, v2, v6, s[0:1]
	v_or_b32_e32 v0, 0x8800, v228
	v_mov_b32_e32 v1, v229
	v_mul_f32_e32 v4, v41, v4
	v_rsq_f32_e32 v2, v2
	v_lshl_add_u64 v[0:1], v[16:17], 0, v[0:1]
	v_cvt_pk_bf16_f32 v9, v4, v4
	v_lshl_add_u64 v[4:5], v[0:1], 0, v[18:19]
	global_store_short v[4:5], v9, off
	v_mul_f32_e32 v4, v53, v8
	v_mul_f32_e32 v4, v34, v4
	v_mul_f32_e32 v6, 0x45800000, v2
	v_cndmask_b32_e64 v2, v2, v6, s[0:1]
	v_cvt_pk_bf16_f32 v4, v4, v4
	v_lshl_add_u64 v[0:1], v[0:1], 0, v[20:21]
	v_mul_f32_e32 v6, v56, v2
	global_store_short v[0:1], v4, off
	v_or_b32_e32 v0, 0x9000, v228
	v_mov_b32_e32 v1, v229
	v_mul_f32_e32 v6, v41, v6
	v_lshl_add_u64 v[0:1], v[16:17], 0, v[0:1]
	v_mul_f32_e32 v2, v55, v2
	v_lshl_add_u64 v[4:5], v[0:1], 0, v[18:19]
	v_cvt_pk_bf16_f32 v6, v6, v6
	v_mul_f32_e32 v2, v34, v2
	global_store_short v[4:5], v6, off
	v_lshl_add_u64 v[0:1], v[0:1], 0, v[20:21]
	v_cvt_pk_bf16_f32 v2, v2, v2
	v_cmp_gt_f32_e32 vcc, s92, v3
	global_store_short v[0:1], v2, off
	v_mul_f32_e32 v0, 0x4b800000, v3
	v_cndmask_b32_e32 v0, v3, v0, vcc
	v_rsq_f32_e32 v0, v0
	s_nop 0
	v_mul_f32_e32 v1, 0x45800000, v0
	v_cndmask_b32_e32 v4, v0, v1, vcc
	v_mul_f32_e32 v2, v58, v4
	v_or_b32_e32 v0, 0x9800, v228
	v_mov_b32_e32 v1, v229
	v_mul_f32_e32 v2, v41, v2
	v_lshl_add_u64 v[0:1], v[16:17], 0, v[0:1]
	v_cvt_pk_bf16_f32 v5, v2, v2
	v_lshl_add_u64 v[2:3], v[0:1], 0, v[18:19]
	global_store_short v[2:3], v5, off
	v_mul_f32_e32 v2, v57, v4
	v_mul_f32_e32 v2, v34, v2
	v_cvt_pk_bf16_f32 v2, v2, v2
	v_lshl_add_u64 v[0:1], v[0:1], 0, v[20:21]
	global_store_short v[0:1], v2, off
	v_or_b32_e32 v0, 0xc000, v228
	v_mov_b32_e32 v1, v229
	v_lshl_add_u64 v[0:1], v[16:17], 0, v[0:1]
	v_lshl_add_u64 v[26:27], v[0:1], 0, v[18:19]
	v_lshl_add_u64 v[24:25], v[0:1], 0, v[20:21]
	ds_read_b128 v[0:3], v52 offset:51808
	ds_read_b128 v[4:7], v52 offset:51936
	ds_read_b128 v[8:11], v52 offset:52064
	ds_read_b128 v[12:15], v52 offset:52192
	s_waitcnt lgkmcnt(2)
	v_pk_add_f32 v[0:1], v[0:1], v[4:5]
	s_waitcnt lgkmcnt(1)
	v_pk_add_f32 v[0:1], v[0:1], v[8:9]
	v_pk_add_f32 v[2:3], v[2:3], v[6:7]
	s_waitcnt lgkmcnt(0)
	v_pk_add_f32 v[0:1], v[0:1], v[12:13]
	v_pk_add_f32 v[2:3], v[2:3], v[10:11]
	v_pk_fma_f32 v[0:1], v[0:1], s[68:69], v[22:23] op_sel_hi:[1,0,0]
	v_pk_add_f32 v[2:3], v[2:3], v[14:15]
	v_mul_f32_e32 v4, 0x4b800000, v0
	v_cmp_gt_f32_e64 s[0:1], s92, v0
	v_cmp_gt_f32_e32 vcc, s92, v1
	v_pk_fma_f32 v[2:3], v[2:3], s[68:69], v[22:23] op_sel_hi:[1,0,0]
	v_cndmask_b32_e64 v0, v0, v4, s[0:1]
	v_rsq_f32_e32 v0, v0
	v_mul_f32_e32 v6, 0x4b800000, v2
	v_mul_f32_e32 v4, 0x45800000, v0
	v_cndmask_b32_e64 v0, v0, v4, s[0:1]
	v_mul_f32_e32 v4, v38, v0
	v_mul_f32_e32 v4, v41, v4
	v_mul_f32_e32 v0, v37, v0
	v_cvt_pk_bf16_f32 v4, v4, v4
	v_mul_f32_e32 v0, v34, v0
	global_store_short v[26:27], v4, off
	v_cvt_pk_bf16_f32 v0, v0, v0
	global_store_short v[24:25], v0, off
	v_mul_f32_e32 v0, 0x4b800000, v1
	v_cndmask_b32_e32 v0, v1, v0, vcc
	v_rsq_f32_e32 v0, v0
	v_cmp_gt_f32_e64 s[0:1], s92, v2
	v_mul_f32_e32 v1, 0x45800000, v0
	v_cndmask_b32_e32 v8, v0, v1, vcc
	v_mul_f32_e32 v4, v40, v8
	v_cndmask_b32_e64 v2, v2, v6, s[0:1]
	v_or_b32_e32 v0, 0xc800, v228
	v_mov_b32_e32 v1, v229
	v_mul_f32_e32 v4, v41, v4
	v_rsq_f32_e32 v2, v2
	v_lshl_add_u64 v[0:1], v[16:17], 0, v[0:1]
	v_cvt_pk_bf16_f32 v9, v4, v4
	v_lshl_add_u64 v[4:5], v[0:1], 0, v[18:19]
	global_store_short v[4:5], v9, off
	v_mul_f32_e32 v4, v39, v8
	v_mul_f32_e32 v4, v34, v4
	v_mul_f32_e32 v6, 0x45800000, v2
	v_cndmask_b32_e64 v2, v2, v6, s[0:1]
	v_cvt_pk_bf16_f32 v4, v4, v4
	v_lshl_add_u64 v[0:1], v[0:1], 0, v[20:21]
	v_mul_f32_e32 v6, v29, v2
	global_store_short v[0:1], v4, off
	v_or_b32_e32 v0, 0xd000, v228
	v_mov_b32_e32 v1, v229
	v_mul_f32_e32 v6, v41, v6
	v_lshl_add_u64 v[0:1], v[16:17], 0, v[0:1]
	v_mul_f32_e32 v2, v28, v2
	v_lshl_add_u64 v[4:5], v[0:1], 0, v[18:19]
	v_cvt_pk_bf16_f32 v6, v6, v6
	v_mul_f32_e32 v2, v34, v2
	global_store_short v[4:5], v6, off
	v_lshl_add_u64 v[0:1], v[0:1], 0, v[20:21]
	v_cvt_pk_bf16_f32 v2, v2, v2
	v_cmp_gt_f32_e32 vcc, s92, v3
	global_store_short v[0:1], v2, off
	v_mul_f32_e32 v0, 0x4b800000, v3
	v_cndmask_b32_e32 v0, v3, v0, vcc
	v_rsq_f32_e32 v0, v0
	v_or_b32_e32 v228, 0xd800, v228
	v_mul_f32_e32 v1, 0x45800000, v0
	v_cndmask_b32_e32 v4, v0, v1, vcc
	v_mul_f32_e32 v2, v31, v4
	v_mul_f32_e32 v2, v41, v2
	v_lshl_add_u64 v[0:1], v[16:17], 0, v[228:229]
	v_cvt_pk_bf16_f32 v5, v2, v2
	v_lshl_add_u64 v[2:3], v[0:1], 0, v[18:19]
	global_store_short v[2:3], v5, off
	v_mul_f32_e32 v2, v30, v4
	v_mul_f32_e32 v2, v34, v2
	v_cvt_pk_bf16_f32 v2, v2, v2
	v_lshl_add_u64 v[0:1], v[0:1], 0, v[20:21]
	global_store_short v[0:1], v2, off
	s_barrier
	s_cbranch_scc1 .LBB0_1193

.LBB0_1146:
	v_pk_mul_f32 v[134:135], v[132:133], v[134:135] op_sel_hi:[1,0]
	v_add_u32_e32 v175, s0, v65
	v_pk_fma_f32 v[172:173], v[128:129], v[130:131], v[134:135] op_sel_hi:[1,0,1]
	v_pk_fma_f32 v[130:131], v[128:129], v[130:131], v[134:135] op_sel_hi:[1,0,1] neg_lo:[0,0,1] neg_hi:[0,0,1]
	v_cvt_pk_bf16_f32 v174, v130, v173
	v_pk_mul_f32 v[134:135], v[132:133], v[172:173] op_sel:[0,1]
	v_add_u32_e32 v176, 0x400, v175
	v_pk_fma_f32 v[172:173], v[128:129], v[130:131], v[134:135] op_sel_hi:[1,0,1]
	v_pk_fma_f32 v[130:131], v[128:129], v[130:131], v[134:135] op_sel_hi:[1,0,1] neg_lo:[0,0,1] neg_hi:[0,0,1]
	v_cvt_pk_bf16_f32 v134, v130, v173
	ds_write2_b32 v176, v134, v174 offset0:152 offset1:220
	v_pk_mul_f32 v[134:135], v[132:133], v[172:173] op_sel:[0,1]
	s_addk_i32 s0, 0xf780
	v_pk_fma_f32 v[172:173], v[128:129], v[130:131], v[134:135] op_sel_hi:[1,0,1]
	v_pk_fma_f32 v[130:131], v[128:129], v[130:131], v[134:135] op_sel_hi:[1,0,1] neg_lo:[0,0,1] neg_hi:[0,0,1]
	v_cvt_pk_bf16_f32 v174, v130, v173
	v_pk_mul_f32 v[134:135], v[132:133], v[172:173] op_sel:[0,1]
	s_cmpk_lg_i32 s0, 0xf780
	v_pk_fma_f32 v[172:173], v[128:129], v[130:131], v[134:135] op_sel_hi:[1,0,1]
	v_pk_fma_f32 v[130:131], v[128:129], v[130:131], v[134:135] op_sel_hi:[1,0,1] neg_lo:[0,0,1] neg_hi:[0,0,1]
	v_cvt_pk_bf16_f32 v134, v130, v173
	ds_write2_b32 v176, v134, v174 offset0:16 offset1:84
	v_pk_mul_f32 v[134:135], v[132:133], v[172:173] op_sel:[0,1]
	s_nop 0
	v_pk_fma_f32 v[172:173], v[128:129], v[130:131], v[134:135] op_sel_hi:[1,0,1]
	v_pk_fma_f32 v[130:131], v[128:129], v[130:131], v[134:135] op_sel_hi:[1,0,1] neg_lo:[0,0,1] neg_hi:[0,0,1]
	v_cvt_pk_bf16_f32 v174, v130, v173
	v_pk_mul_f32 v[134:135], v[132:133], v[172:173] op_sel:[0,1]
	s_nop 0
	v_pk_fma_f32 v[172:173], v[128:129], v[130:131], v[134:135] op_sel_hi:[1,0,1]
	v_pk_fma_f32 v[130:131], v[128:129], v[130:131], v[134:135] op_sel_hi:[1,0,1] neg_lo:[0,0,1] neg_hi:[0,0,1]
	v_cvt_pk_bf16_f32 v134, v130, v173
	ds_write2_b32 v175, v134, v174 offset0:136 offset1:204
	v_pk_mul_f32 v[134:135], v[132:133], v[172:173] op_sel:[0,1]
	s_nop 0
	v_pk_fma_f32 v[172:173], v[128:129], v[130:131], v[134:135] op_sel_hi:[1,0,1]
	v_pk_fma_f32 v[130:131], v[128:129], v[130:131], v[134:135] op_sel_hi:[1,0,1] neg_lo:[0,0,1] neg_hi:[0,0,1]
	v_bfe_u32 v135, v173, 16, 1
	v_bfe_u32 v134, v130, 16, 1
	v_add3_u32 v134, v130, v134, s89
	v_lshrrev_b32_e32 v134, 16, v134
	v_add3_u32 v135, v173, v135, s89
	v_pk_mul_f32 v[172:173], v[132:133], v[172:173] op_sel:[0,1]
	v_and_or_b32 v174, v135, s75, v134
	v_pk_fma_f32 v[134:135], v[128:129], v[130:131], v[172:173] op_sel_hi:[1,0,1]
	v_pk_fma_f32 v[130:131], v[128:129], v[130:131], v[172:173] op_sel_hi:[1,0,1] neg_lo:[0,0,1] neg_hi:[0,0,1]
	v_cvt_pk_bf16_f32 v131, v130, v135
	v_mov_b32_e32 v134, v135
	ds_write2_b32 v175, v131, v174 offset1:68
	s_cbranch_scc1 .LBB0_1146
	s_waitcnt lgkmcnt(11)
	v_mfma_f32_16x16x32_bf16 v[60:63], v[60:63], v[12:15], 0
	v_add_u32_e32 v131, v170, v171
	v_add_f32_e32 v128, v156, v157
	s_waitcnt lgkmcnt(10)
	v_mfma_f32_16x16x32_bf16 v[56:59], v[56:59], v[8:11], v[60:63]
	v_add_f32_e32 v129, v160, v161
	v_add_f32_e32 v160, v154, v155
	v_lshlrev_b32_e32 v130, 1, v139
	s_nop 0
	ds_read_b128 v[60:63], v131
	s_waitcnt lgkmcnt(8)
	v_mfma_f32_16x16x32_bf16 v[52:55], v[52:55], v[4:7], v[56:59]
	v_add_f32_e32 v158, v158, v159
	v_lshlrev_b32_e32 v159, 1, v64
	v_add_f32_e32 v172, v166, v167
	ds_read_b128 v[56:59], v131 offset:64
	v_mfma_f32_16x16x32_bf16 v[12:15], v[44:47], v[12:15], 0
	v_add_f32_e32 v171, v164, v165
	v_add_f32_e32 v170, v162, v163
	v_add_f32_e32 v169, v168, v169
	s_waitcnt lgkmcnt(8)
	v_mfma_f32_16x16x32_bf16 v[48:51], v[48:51], v[0:3], v[52:55]
	s_mov_b32 s0, 0
	s_nop 1
	ds_read_b128 v[52:55], v131 offset:128
	v_mfma_f32_16x16x32_bf16 v[8:11], v[40:43], v[8:11], v[12:15]
	s_waitcnt vmcnt(3) lgkmcnt(2)
	v_mfma_f32_16x16x32_bf16 v[48:51], v[60:63], v[28:31], v[48:51]
	ds_read_b128 v[60:63], v131 offset:192
	v_mfma_f32_16x16x32_bf16 v[4:7], v[36:39], v[4:7], v[8:11]
	s_waitcnt vmcnt(2) lgkmcnt(2)
	v_mfma_f32_16x16x32_bf16 v[48:51], v[56:59], v[24:27], v[48:51]
	ds_read_b128 v[56:59], v131 offset:4352
	ds_read_b128 v[132:135], v131 offset:4416
	v_mfma_f32_16x16x32_bf16 v[0:3], v[32:35], v[0:3], v[4:7]
	s_waitcnt vmcnt(1) lgkmcnt(3)
	v_mfma_f32_16x16x32_bf16 v[48:51], v[52:55], v[20:23], v[48:51]
	ds_read_b128 v[52:55], v131 offset:4480
	ds_read_b128 v[154:157], v131 offset:4544
	s_waitcnt lgkmcnt(3)
	v_mfma_f32_16x16x32_bf16 v[0:3], v[56:59], v[28:31], v[0:3]
	s_waitcnt vmcnt(0)
	v_mfma_f32_16x16x32_bf16 v[48:51], v[60:63], v[16:19], v[48:51]
	s_waitcnt lgkmcnt(2)
	v_mfma_f32_16x16x32_bf16 v[0:3], v[132:135], v[24:27], v[0:3]
	v_mul_u32_u24_e32 v132, 0x840, v149
	s_nop 4
	v_add_f32_e32 v48, v128, v48
	v_fmac_f32_e32 v48, v153, v148
	v_mul_f32_e32 v60, 0x3d372713, v48
	v_mul_f32_e32 v44, v48, v60
	v_add_f32_e32 v13, v160, v49
	s_waitcnt lgkmcnt(1)
	v_mfma_f32_16x16x32_bf16 v[0:3], v[52:55], v[20:23], v[0:3]
	v_fma_f32 v44, v48, v44, v48
	v_fmac_f32_e32 v13, v152, v148
	v_mul_f32_e32 v44, 0xbfcc422a, v44
	v_mul_f32_e32 v9, 0x3d372713, v13
	v_add_f32_e32 v21, v129, v50
	v_mul_f32_e32 v44, 0x3fb8aa3b, v44
	v_mul_f32_e32 v4, v13, v9
	v_fmac_f32_e32 v21, v151, v148
	v_exp_f32_e32 v12, v44
	v_fma_f32 v4, v13, v4, v13
	s_waitcnt lgkmcnt(0)
	v_mfma_f32_16x16x32_bf16 v[16:19], v[154:157], v[16:19], v[0:3]
	v_mul_f32_e32 v4, 0xbfcc422a, v4
	v_mul_f32_e32 v4, 0x3fb8aa3b, v4
	v_exp_f32_e32 v4, v4
	v_mul_f32_e32 v0, 0x3d372713, v21
	v_mul_f32_e32 v0, v21, v0
	v_fma_f32 v0, v21, v0, v21
	v_mul_f32_e32 v0, 0xbfcc422a, v0
	v_add_f32_e32 v8, 1.0, v12
	v_mul_f32_e32 v0, 0x3fb8aa3b, v0
	v_rcp_f32_e32 v8, v8
	v_exp_f32_e32 v0, v0
	v_add_f32_e32 v4, 1.0, v4
	v_rcp_f32_e32 v4, v4
	v_lshlrev_b32_e32 v128, 4, v143
	v_mul_f32_e32 v5, v48, v8
	v_add_f32_e32 v0, 1.0, v0
	v_ashrrev_i32_e32 v129, 31, v128
	v_rcp_f32_e32 v25, v0
	v_lshlrev_b64 v[0:1], 2, v[128:129]
	v_cvt_pk_bf16_f32 v5, v5, v5
	v_add3_u32 v24, v130, v159, v132
	v_lshl_add_u64 v[2:3], v[76:77], 0, v[0:1]
	ds_write_b16 v24, v5 offset:34816
	v_mul_f32_e32 v22, v13, v4
	v_lshl_add_u64 v[4:5], v[2:3], 0, v[80:81]
	v_lshl_add_u64 v[0:1], v[78:79], 0, v[0:1]
	v_add_co_u32_e32 v6, vcc, s92, v4
	v_add_f32_e32 v26, v158, v51
	s_nop 0
	v_addc_co_u32_e32 v7, vcc, 0, v5, vcc
	global_load_dword v157, v[4:5], off
	global_load_dword v158, v[6:7], off
	v_lshl_add_u64 v[4:5], v[0:1], 0, v[82:83]
	global_load_dword v151, v[4:5], off
	v_lshl_add_u64 v[4:5], v[2:3], 0, v[84:85]
	v_add_co_u32_e32 v6, vcc, s92, v4
	v_fmac_f32_e32 v26, v150, v148
	s_nop 0
	v_addc_co_u32_e32 v7, vcc, 0, v5, vcc
	global_load_dword v153, v[4:5], off
	global_load_dword v154, v[6:7], off
	v_lshl_add_u64 v[4:5], v[0:1], 0, v[86:87]
	global_load_dword v152, v[4:5], off
	v_lshl_add_u64 v[4:5], v[2:3], 0, v[88:89]
	v_add_co_u32_e32 v6, vcc, s92, v4
	v_add_u32_e32 v20, s5, v128
	s_nop 0
	v_addc_co_u32_e32 v7, vcc, 0, v5, vcc
	global_load_dword v159, v[4:5], off
	global_load_dword v160, v[6:7], off
	v_lshl_add_u64 v[4:5], v[0:1], 0, v[90:91]
	global_load_dword v150, v[4:5], off
	v_lshl_add_u64 v[4:5], v[2:3], 0, v[92:93]
	v_add_co_u32_e32 v6, vcc, s92, v4
	v_mul_f32_e32 v27, 0x3d372713, v26
	s_nop 0
	v_addc_co_u32_e32 v7, vcc, 0, v5, vcc
	global_load_dword v155, v[4:5], off
	global_load_dword v156, v[6:7], off
	v_lshl_add_u64 v[4:5], v[0:1], 0, v[94:95]
	global_load_dword v149, v[4:5], off
	v_lshl_add_u64 v[4:5], v[2:3], 0, v[96:97]
	v_add_co_u32_e32 v6, vcc, s92, v4
	v_mul_f32_e32 v27, v26, v27
	s_nop 0
	v_addc_co_u32_e32 v7, vcc, 0, v5, vcc
	global_load_dword v164, v[4:5], off
	global_load_dword v166, v[6:7], off
	v_lshl_add_u64 v[4:5], v[0:1], 0, v[98:99]
	global_load_dword v135, v[4:5], off
	v_lshl_add_u64 v[4:5], v[2:3], 0, v[100:101]
	v_add_co_u32_e32 v6, vcc, s92, v4
	v_fma_f32 v27, v26, v27, v26
	s_nop 0
	v_addc_co_u32_e32 v7, vcc, 0, v5, vcc
	global_load_dword v161, v[4:5], off
	global_load_dword v162, v[6:7], off
	v_lshl_add_u64 v[4:5], v[0:1], 0, v[102:103]
	global_load_dword v134, v[4:5], off
	v_lshl_add_u64 v[4:5], v[2:3], 0, v[104:105]
	v_add_co_u32_e32 v6, vcc, s92, v4
	v_lshl_add_u64 v[2:3], v[2:3], 0, v[110:111]
	s_nop 0
	v_addc_co_u32_e32 v7, vcc, 0, v5, vcc
	global_load_dword v167, v[4:5], off
	global_load_dword v168, v[6:7], off
	v_lshl_add_u64 v[4:5], v[0:1], 0, v[106:107]
	global_load_dword v129, v[4:5], off
	v_add_co_u32_e32 v4, vcc, s92, v2
	v_lshl_add_u64 v[0:1], v[0:1], 0, v[108:109]
	s_nop 0
	v_addc_co_u32_e32 v5, vcc, 0, v3, vcc
	global_load_dword v163, v[2:3], off
	global_load_dword v165, v[4:5], off
	ds_read_b64 v[2:3], v229 offset:63640
	global_load_dword v133, v[0:1], off
	v_add_u32_e32 v0, v128, v140
	v_ashrrev_i32_e32 v1, 31, v0
	v_mul_f32_e32 v27, 0xbfcc422a, v27
	s_waitcnt lgkmcnt(0)
	v_lshl_add_u64 v[0:1], v[0:1], 2, v[2:3]
	global_load_dword v143, v[0:1], off
	v_or_b32_e32 v0, v20, v139
	v_ashrrev_i32_e32 v1, 31, v0
	v_lshlrev_b64 v[0:1], 8, v[0:1]
	v_lshl_add_u64 v[0:1], v[72:73], 0, v[0:1]
	global_load_dwordx4 v[12:15], v[0:1], off
	global_load_dwordx4 v[8:11], v[0:1], off offset:64
	global_load_dwordx4 v[4:7], v[0:1], off offset:128
	s_nop 0
	global_load_dwordx4 v[0:3], v[0:1], off offset:192
	v_mul_f32_e32 v27, 0x3fb8aa3b, v27
	v_exp_f32_e32 v27, v27
	v_cvt_pk_bf16_f32 v22, v22, v22
	ds_write_b16 v24, v22 offset:35344
	v_add_f32_e32 v22, 1.0, v27
	v_rcp_f32_e32 v22, v22
	v_mul_f32_e32 v21, v21, v25
	v_add_f32_e32 v16, v172, v16
	v_cvt_pk_bf16_f32 v21, v21, v21
	v_fmac_f32_e32 v16, v144, v148
	ds_write_b16 v24, v21 offset:35872
	v_mul_f32_e32 v21, v26, v22
	v_mul_f32_e32 v22, 0x3d372713, v16
	v_mul_f32_e32 v22, v16, v22
	v_fma_f32 v22, v16, v22, v16
	v_mul_f32_e32 v22, 0xbfcc422a, v22
	v_mul_f32_e32 v22, 0x3fb8aa3b, v22
	v_exp_f32_e32 v22, v22
	v_add_f32_e32 v17, v170, v17
	v_cvt_pk_bf16_f32 v21, v21, v21
	v_fmac_f32_e32 v17, v145, v148
	ds_write_b16 v24, v21 offset:36400
	v_add_f32_e32 v21, 1.0, v22
	v_mul_f32_e32 v22, 0x3d372713, v17
	v_mul_f32_e32 v22, v17, v22
	v_fma_f32 v22, v17, v22, v17
	v_rcp_f32_e32 v21, v21
	v_mul_f32_e32 v22, 0xbfcc422a, v22
	v_mul_f32_e32 v22, 0x3fb8aa3b, v22
	v_exp_f32_e32 v22, v22
	v_mul_f32_e32 v16, v16, v21
	v_add_f32_e32 v18, v169, v18
	v_fmac_f32_e32 v18, v146, v148
	v_cvt_pk_bf16_f32 v16, v16, v16
	v_add_f32_e32 v21, 1.0, v22
	v_mul_f32_e32 v22, 0x3d372713, v18
	v_mul_f32_e32 v22, v18, v22
	v_fma_f32 v22, v18, v22, v18
	v_mul_f32_e32 v22, 0xbfcc422a, v22
	v_mul_f32_e32 v22, 0x3fb8aa3b, v22
	v_rcp_f32_e32 v21, v21
	v_exp_f32_e32 v22, v22
	v_add_f32_e32 v19, v171, v19
	v_fmac_f32_e32 v19, v147, v148
	ds_write_b16 v24, v16 offset:43264
	v_mul_f32_e32 v16, v17, v21
	v_add_f32_e32 v21, 1.0, v22
	v_mul_f32_e32 v22, 0x3d372713, v19
	v_mul_f32_e32 v22, v19, v22
	v_fma_f32 v22, v19, v22, v19
	v_mul_f32_e32 v22, 0xbfcc422a, v22
	v_mul_f32_e32 v22, 0x3fb8aa3b, v22
	v_exp_f32_e32 v22, v22
	v_rcp_f32_e32 v21, v21
	v_cvt_pk_bf16_f32 v16, v16, v16
	v_add_f32_e32 v17, 1.0, v22
	v_rcp_f32_e32 v17, v17
	ds_write_b16 v24, v16 offset:43792
	v_mul_f32_e32 v16, v18, v21
	v_cvt_pk_bf16_f32 v16, v16, v16
	ds_write_b16 v24, v16 offset:44320
	v_mul_f32_e32 v16, v19, v17
	v_cvt_pk_bf16_f32 v16, v16, v16
	ds_write_b16 v24, v16 offset:44848
	v_pk_mov_b32 v[16:17], v[124:125], v[124:125] op_sel:[1,0]
	v_mov_b32_e32 v18, v127

.LBB0_1150:
	v_pk_mul_f32 v[126:127], v[124:125], v[126:127] op_sel_hi:[1,0]
	v_add_u32_e32 v147, s0, v65
	v_pk_fma_f32 v[144:145], v[120:121], v[122:123], v[126:127] op_sel_hi:[1,0,1]
	v_pk_fma_f32 v[122:123], v[120:121], v[122:123], v[126:127] op_sel_hi:[1,0,1] neg_lo:[0,0,1] neg_hi:[0,0,1]
	v_cvt_pk_bf16_f32 v146, v122, v145
	v_pk_mul_f32 v[126:127], v[124:125], v[144:145] op_sel:[0,1]
	v_add_u32_e32 v148, 0x400, v147
	v_pk_fma_f32 v[144:145], v[120:121], v[122:123], v[126:127] op_sel_hi:[1,0,1]
	v_pk_fma_f32 v[122:123], v[120:121], v[122:123], v[126:127] op_sel_hi:[1,0,1] neg_lo:[0,0,1] neg_hi:[0,0,1]
	v_cvt_pk_bf16_f32 v126, v122, v145
	ds_write2_b32 v148, v126, v146 offset0:152 offset1:220
	v_pk_mul_f32 v[126:127], v[124:125], v[144:145] op_sel:[0,1]
	s_addk_i32 s0, 0xf780
	v_pk_fma_f32 v[144:145], v[120:121], v[122:123], v[126:127] op_sel_hi:[1,0,1]
	v_pk_fma_f32 v[122:123], v[120:121], v[122:123], v[126:127] op_sel_hi:[1,0,1] neg_lo:[0,0,1] neg_hi:[0,0,1]
	v_cvt_pk_bf16_f32 v146, v122, v145
	v_pk_mul_f32 v[126:127], v[124:125], v[144:145] op_sel:[0,1]
	s_cmpk_lg_i32 s0, 0xf780
	v_pk_fma_f32 v[144:145], v[120:121], v[122:123], v[126:127] op_sel_hi:[1,0,1]
	v_pk_fma_f32 v[122:123], v[120:121], v[122:123], v[126:127] op_sel_hi:[1,0,1] neg_lo:[0,0,1] neg_hi:[0,0,1]
	v_cvt_pk_bf16_f32 v126, v122, v145
	ds_write2_b32 v148, v126, v146 offset0:16 offset1:84
	v_pk_mul_f32 v[126:127], v[124:125], v[144:145] op_sel:[0,1]
	s_nop 0
	v_pk_fma_f32 v[144:145], v[120:121], v[122:123], v[126:127] op_sel_hi:[1,0,1]
	v_pk_fma_f32 v[122:123], v[120:121], v[122:123], v[126:127] op_sel_hi:[1,0,1] neg_lo:[0,0,1] neg_hi:[0,0,1]
	v_cvt_pk_bf16_f32 v146, v122, v145
	v_pk_mul_f32 v[126:127], v[124:125], v[144:145] op_sel:[0,1]
	s_nop 0
	v_pk_fma_f32 v[144:145], v[120:121], v[122:123], v[126:127] op_sel_hi:[1,0,1]
	v_pk_fma_f32 v[122:123], v[120:121], v[122:123], v[126:127] op_sel_hi:[1,0,1] neg_lo:[0,0,1] neg_hi:[0,0,1]
	v_cvt_pk_bf16_f32 v126, v122, v145
	ds_write2_b32 v147, v126, v146 offset0:136 offset1:204
	v_pk_mul_f32 v[126:127], v[124:125], v[144:145] op_sel:[0,1]
	s_nop 0
	v_pk_fma_f32 v[144:145], v[120:121], v[122:123], v[126:127] op_sel_hi:[1,0,1]
	v_pk_fma_f32 v[122:123], v[120:121], v[122:123], v[126:127] op_sel_hi:[1,0,1] neg_lo:[0,0,1] neg_hi:[0,0,1]
	v_bfe_u32 v127, v145, 16, 1
	v_bfe_u32 v126, v122, 16, 1
	v_add3_u32 v126, v122, v126, s89
	v_lshrrev_b32_e32 v126, 16, v126
	v_add3_u32 v127, v145, v127, s89
	v_pk_mul_f32 v[144:145], v[124:125], v[144:145] op_sel:[0,1]
	v_and_or_b32 v146, v127, s75, v126
	v_pk_fma_f32 v[126:127], v[120:121], v[122:123], v[144:145] op_sel_hi:[1,0,1]
	v_pk_fma_f32 v[122:123], v[120:121], v[122:123], v[144:145] op_sel_hi:[1,0,1] neg_lo:[0,0,1] neg_hi:[0,0,1]
	v_cvt_pk_bf16_f32 v123, v122, v127
	v_mov_b32_e32 v126, v127
	ds_write2_b32 v147, v123, v146 offset1:68
	s_cbranch_scc1 .LBB0_1150
	s_waitcnt vmcnt(7) lgkmcnt(11)
	v_mfma_f32_16x16x32_bf16 v[56:59], v[56:59], v[12:15], 0
	v_add_f32_e32 v144, v157, v158
	v_add_f32_e32 v146, v153, v154
	s_waitcnt vmcnt(6) lgkmcnt(10)
	v_mfma_f32_16x16x32_bf16 v[56:59], v[60:63], v[8:11], v[56:59]
	ds_read_b128 v[60:63], v131
	v_add_f32_e32 v145, v159, v160
	v_lshlrev_b32_e32 v128, 1, v128
	s_waitcnt vmcnt(5) lgkmcnt(8)
	v_mfma_f32_16x16x32_bf16 v[52:55], v[52:55], v[4:7], v[56:59]
	v_add_f32_e32 v147, v155, v156
	v_add_f32_e32 v164, v164, v166
	v_add_f32_e32 v161, v161, v162
	ds_read_b128 v[56:59], v131 offset:64
	s_waitcnt vmcnt(4) lgkmcnt(8)
	v_mfma_f32_16x16x32_bf16 v[48:51], v[48:51], v[0:3], v[52:55]
	v_add_f32_e32 v160, v167, v168
	v_add_f32_e32 v162, v163, v165
	s_mov_b32 s0, 0
	ds_read_b128 v[52:55], v131 offset:128
	s_waitcnt vmcnt(3) lgkmcnt(2)
	v_mfma_f32_16x16x32_bf16 v[48:51], v[60:63], v[28:31], v[48:51]
	ds_read_b128 v[60:63], v131 offset:192
	s_waitcnt vmcnt(2) lgkmcnt(2)
	v_mfma_f32_16x16x32_bf16 v[48:51], v[56:59], v[24:27], v[48:51]
	ds_read_b128 v[56:59], v131 offset:4352
	ds_read_b128 v[120:123], v131 offset:4416
	s_waitcnt vmcnt(1) lgkmcnt(3)
	v_mfma_f32_16x16x32_bf16 v[48:51], v[52:55], v[20:23], v[48:51]
	ds_read_b128 v[52:55], v131 offset:4480
	ds_read_b128 v[124:127], v131 offset:4544
	v_mfma_f32_16x16x32_bf16 v[12:15], v[44:47], v[12:15], 0
	s_waitcnt vmcnt(0) lgkmcnt(4)
	v_mfma_f32_16x16x32_bf16 v[48:51], v[60:63], v[16:19], v[48:51]
	v_mfma_f32_16x16x32_bf16 v[8:11], v[40:43], v[8:11], v[12:15]
	v_mfma_f32_16x16x32_bf16 v[4:7], v[36:39], v[4:7], v[8:11]
	s_nop 5
	v_add_f32_e32 v48, v144, v48
	v_fmac_f32_e32 v48, v151, v143
	v_mul_f32_e32 v60, 0x3d372713, v48
	v_mul_f32_e32 v44, v48, v60
	v_fma_f32 v44, v48, v44, v48
	v_mfma_f32_16x16x32_bf16 v[0:3], v[32:35], v[0:3], v[4:7]
	v_mul_f32_e32 v44, 0xbfcc422a, v44
	v_mul_f32_e32 v44, 0x3fb8aa3b, v44
	v_exp_f32_e32 v12, v44
	s_waitcnt lgkmcnt(3)
	v_mfma_f32_16x16x32_bf16 v[0:3], v[56:59], v[28:31], v[0:3]
	v_add_f32_e32 v49, v146, v49
	v_fmac_f32_e32 v49, v152, v143
	v_add_f32_e32 v8, 1.0, v12
	v_rcp_f32_e32 v8, v8
	s_waitcnt lgkmcnt(2)
	v_mfma_f32_16x16x32_bf16 v[0:3], v[120:123], v[24:27], v[0:3]
	v_mul_f32_e32 v61, 0x3d372713, v49
	v_add_f32_e32 v24, v145, v50
	v_mul_f32_e32 v5, v48, v8
	s_waitcnt lgkmcnt(1)
	v_mfma_f32_16x16x32_bf16 v[0:3], v[52:55], v[20:23], v[0:3]
	v_mul_f32_e32 v13, v49, v61
	v_fmac_f32_e32 v24, v150, v143
	v_fma_f32 v13, v49, v13, v49
	v_cvt_pk_bf16_f32 v5, v5, v5
	v_mul_f32_e32 v6, 0x3d372713, v24
	v_mul_f32_e32 v9, 0xbfcc422a, v13
	v_mul_f32_e32 v6, v24, v6
	v_mul_f32_e32 v4, 0x3fb8aa3b, v9
	s_waitcnt lgkmcnt(0)
	v_mfma_f32_16x16x32_bf16 v[16:19], v[124:127], v[16:19], v[0:3]
	v_exp_f32_e32 v4, v4
	v_lshlrev_b32_e32 v120, 4, v142
	v_ashrrev_i32_e32 v121, 31, v120
	v_fma_f32 v0, v24, v6, v24
	v_mul_f32_e32 v0, 0xbfcc422a, v0
	v_mul_f32_e32 v0, 0x3fb8aa3b, v0
	v_exp_f32_e32 v0, v0
	v_add_f32_e32 v4, 1.0, v4
	v_rcp_f32_e32 v4, v4
	v_add3_u32 v28, v130, v128, v132
	v_add_f32_e32 v0, 1.0, v0
	v_rcp_f32_e32 v23, v0
	v_lshlrev_b64 v[0:1], 2, v[120:121]
	v_lshl_add_u64 v[2:3], v[76:77], 0, v[0:1]
	ds_write_b16 v28, v5 offset:34816
	v_mul_f32_e32 v21, v49, v4
	v_lshl_add_u64 v[4:5], v[2:3], 0, v[80:81]
	v_add_f32_e32 v25, v147, v51
	v_lshl_add_u64 v[0:1], v[78:79], 0, v[0:1]
	v_add_co_u32_e32 v6, vcc, s92, v4
	v_fmac_f32_e32 v25, v149, v143
	s_nop 0
	v_addc_co_u32_e32 v7, vcc, 0, v5, vcc
	global_load_dword v148, v[4:5], off
	global_load_dword v149, v[6:7], off
	v_lshl_add_u64 v[4:5], v[0:1], 0, v[82:83]
	global_load_dword v128, v[4:5], off
	v_lshl_add_u64 v[4:5], v[2:3], 0, v[84:85]
	v_add_co_u32_e32 v6, vcc, s92, v4
	v_add_u32_e32 v20, s5, v120
	s_nop 0
	v_addc_co_u32_e32 v7, vcc, 0, v5, vcc
	global_load_dword v144, v[4:5], off
	global_load_dword v145, v[6:7], off
	v_lshl_add_u64 v[4:5], v[0:1], 0, v[86:87]
	global_load_dword v142, v[4:5], off
	v_lshl_add_u64 v[4:5], v[2:3], 0, v[88:89]
	v_add_co_u32_e32 v6, vcc, s92, v4
	v_mul_f32_e32 v26, 0x3d372713, v25
	s_nop 0
	v_addc_co_u32_e32 v7, vcc, 0, v5, vcc
	global_load_dword v150, v[4:5], off
	global_load_dword v151, v[6:7], off
	v_lshl_add_u64 v[4:5], v[0:1], 0, v[90:91]
	global_load_dword v127, v[4:5], off
	v_lshl_add_u64 v[4:5], v[2:3], 0, v[92:93]
	v_add_co_u32_e32 v6, vcc, s92, v4
	v_mul_f32_e32 v26, v25, v26
	s_nop 0
	v_addc_co_u32_e32 v7, vcc, 0, v5, vcc
	global_load_dword v146, v[4:5], off
	global_load_dword v147, v[6:7], off
	v_lshl_add_u64 v[4:5], v[0:1], 0, v[94:95]
	global_load_dword v126, v[4:5], off
	v_lshl_add_u64 v[4:5], v[2:3], 0, v[96:97]
	v_add_co_u32_e32 v6, vcc, s92, v4
	v_fma_f32 v26, v25, v26, v25
	s_nop 0
	v_addc_co_u32_e32 v7, vcc, 0, v5, vcc
	global_load_dword v155, v[4:5], off
	global_load_dword v157, v[6:7], off
	v_lshl_add_u64 v[4:5], v[0:1], 0, v[98:99]
	global_load_dword v124, v[4:5], off
	v_lshl_add_u64 v[4:5], v[2:3], 0, v[100:101]
	v_add_co_u32_e32 v6, vcc, s92, v4
	v_mul_f32_e32 v26, 0xbfcc422a, v26
	s_nop 0
	v_addc_co_u32_e32 v7, vcc, 0, v5, vcc
	global_load_dword v152, v[4:5], off
	global_load_dword v153, v[6:7], off
	v_lshl_add_u64 v[4:5], v[0:1], 0, v[102:103]
	global_load_dword v123, v[4:5], off
	v_lshl_add_u64 v[4:5], v[2:3], 0, v[104:105]
	v_add_co_u32_e32 v6, vcc, s92, v4
	v_lshl_add_u64 v[2:3], v[2:3], 0, v[110:111]
	s_nop 0
	v_addc_co_u32_e32 v7, vcc, 0, v5, vcc
	global_load_dword v158, v[4:5], off
	global_load_dword v159, v[6:7], off
	v_lshl_add_u64 v[4:5], v[0:1], 0, v[106:107]
	global_load_dword v121, v[4:5], off
	v_add_co_u32_e32 v4, vcc, s92, v2
	v_lshl_add_u64 v[0:1], v[0:1], 0, v[108:109]
	s_nop 0
	v_addc_co_u32_e32 v5, vcc, 0, v3, vcc
	global_load_dword v154, v[2:3], off
	global_load_dword v156, v[4:5], off
	ds_read_b64 v[2:3], v229 offset:63640
	global_load_dword v122, v[0:1], off
	v_add_u32_e32 v0, v120, v140
	v_ashrrev_i32_e32 v1, 31, v0
	v_mul_f32_e32 v26, 0x3fb8aa3b, v26
	s_waitcnt lgkmcnt(0)
	v_lshl_add_u64 v[0:1], v[0:1], 2, v[2:3]
	global_load_dword v125, v[0:1], off
	v_or_b32_e32 v0, v20, v139
	v_ashrrev_i32_e32 v1, 31, v0
	v_lshlrev_b64 v[0:1], 8, v[0:1]
	v_lshl_add_u64 v[0:1], v[72:73], 0, v[0:1]
	global_load_dwordx4 v[12:15], v[0:1], off
	global_load_dwordx4 v[8:11], v[0:1], off offset:64
	global_load_dwordx4 v[4:7], v[0:1], off offset:128
	s_nop 0
	global_load_dwordx4 v[0:3], v[0:1], off offset:192
	v_exp_f32_e32 v26, v26
	v_cvt_pk_bf16_f32 v21, v21, v21
	ds_write_b16 v28, v21 offset:35344
	v_add_f32_e32 v22, 1.0, v26
	v_rcp_f32_e32 v22, v22
	v_mul_f32_e32 v21, v24, v23
	v_add_f32_e32 v16, v164, v16
	v_cvt_pk_bf16_f32 v21, v21, v21
	v_fmac_f32_e32 v16, v135, v143
	ds_write_b16 v28, v21 offset:35872
	v_mul_f32_e32 v21, v25, v22
	v_mul_f32_e32 v22, 0x3d372713, v16
	v_mul_f32_e32 v22, v16, v22
	v_fma_f32 v22, v16, v22, v16
	v_mul_f32_e32 v22, 0xbfcc422a, v22
	v_mul_f32_e32 v22, 0x3fb8aa3b, v22
	v_exp_f32_e32 v22, v22
	v_add_f32_e32 v17, v161, v17
	v_cvt_pk_bf16_f32 v21, v21, v21
	v_fmac_f32_e32 v17, v134, v143
	ds_write_b16 v28, v21 offset:36400
	v_add_f32_e32 v21, 1.0, v22
	v_mul_f32_e32 v22, 0x3d372713, v17
	v_mul_f32_e32 v22, v17, v22
	v_fma_f32 v22, v17, v22, v17
	v_rcp_f32_e32 v21, v21
	v_mul_f32_e32 v22, 0xbfcc422a, v22
	v_mul_f32_e32 v22, 0x3fb8aa3b, v22
	v_exp_f32_e32 v22, v22
	v_mul_f32_e32 v16, v16, v21
	v_add_f32_e32 v18, v160, v18
	v_fmac_f32_e32 v18, v129, v143
	v_cvt_pk_bf16_f32 v16, v16, v16
	v_add_f32_e32 v21, 1.0, v22
	v_mul_f32_e32 v22, 0x3d372713, v18
	v_mul_f32_e32 v22, v18, v22
	v_fma_f32 v22, v18, v22, v18
	v_mul_f32_e32 v22, 0xbfcc422a, v22
	v_mul_f32_e32 v22, 0x3fb8aa3b, v22
	v_rcp_f32_e32 v21, v21
	v_exp_f32_e32 v22, v22
	v_add_f32_e32 v19, v162, v19
	v_fmac_f32_e32 v19, v133, v143
	ds_write_b16 v28, v16 offset:43264
	v_mul_f32_e32 v16, v17, v21
	v_add_f32_e32 v21, 1.0, v22
	v_mul_f32_e32 v22, 0x3d372713, v19
	v_mul_f32_e32 v22, v19, v22
	v_fma_f32 v22, v19, v22, v19
	v_mul_f32_e32 v22, 0xbfcc422a, v22
	v_mul_f32_e32 v22, 0x3fb8aa3b, v22
	v_exp_f32_e32 v22, v22
	v_rcp_f32_e32 v21, v21
	v_cvt_pk_bf16_f32 v16, v16, v16
	v_add_f32_e32 v17, 1.0, v22
	v_rcp_f32_e32 v17, v17
	ds_write_b16 v28, v16 offset:43792
	v_mul_f32_e32 v16, v18, v21
	v_cvt_pk_bf16_f32 v16, v16, v16
	ds_write_b16 v28, v16 offset:44320
	v_mul_f32_e32 v16, v19, v17
	v_cvt_pk_bf16_f32 v16, v16, v16
	ds_write_b16 v28, v16 offset:44848
	v_pk_mov_b32 v[16:17], v[116:117], v[116:117] op_sel:[1,0]
	v_mov_b32_e32 v18, v119

.LBB0_1154:
	v_pk_mul_f32 v[118:119], v[116:117], v[118:119] op_sel_hi:[1,0]
	v_add_u32_e32 v133, s0, v65
	v_pk_fma_f32 v[134:135], v[112:113], v[114:115], v[118:119] op_sel_hi:[1,0,1]
	v_pk_fma_f32 v[114:115], v[112:113], v[114:115], v[118:119] op_sel_hi:[1,0,1] neg_lo:[0,0,1] neg_hi:[0,0,1]
	v_cvt_pk_bf16_f32 v129, v114, v135
	v_pk_mul_f32 v[118:119], v[116:117], v[134:135] op_sel:[0,1]
	v_add_u32_e32 v143, 0x400, v133
	v_pk_fma_f32 v[134:135], v[112:113], v[114:115], v[118:119] op_sel_hi:[1,0,1]
	v_pk_fma_f32 v[114:115], v[112:113], v[114:115], v[118:119] op_sel_hi:[1,0,1] neg_lo:[0,0,1] neg_hi:[0,0,1]
	v_cvt_pk_bf16_f32 v118, v114, v135
	ds_write2_b32 v143, v118, v129 offset0:152 offset1:220
	v_pk_mul_f32 v[118:119], v[116:117], v[134:135] op_sel:[0,1]
	s_addk_i32 s0, 0xf780
	v_pk_fma_f32 v[134:135], v[112:113], v[114:115], v[118:119] op_sel_hi:[1,0,1]
	v_pk_fma_f32 v[114:115], v[112:113], v[114:115], v[118:119] op_sel_hi:[1,0,1] neg_lo:[0,0,1] neg_hi:[0,0,1]
	v_cvt_pk_bf16_f32 v129, v114, v135
	v_pk_mul_f32 v[118:119], v[116:117], v[134:135] op_sel:[0,1]
	s_cmpk_lg_i32 s0, 0xf780
	v_pk_fma_f32 v[134:135], v[112:113], v[114:115], v[118:119] op_sel_hi:[1,0,1]
	v_pk_fma_f32 v[114:115], v[112:113], v[114:115], v[118:119] op_sel_hi:[1,0,1] neg_lo:[0,0,1] neg_hi:[0,0,1]
	v_cvt_pk_bf16_f32 v118, v114, v135
	ds_write2_b32 v143, v118, v129 offset0:16 offset1:84
	v_pk_mul_f32 v[118:119], v[116:117], v[134:135] op_sel:[0,1]
	s_nop 0
	v_pk_fma_f32 v[134:135], v[112:113], v[114:115], v[118:119] op_sel_hi:[1,0,1]
	v_pk_fma_f32 v[114:115], v[112:113], v[114:115], v[118:119] op_sel_hi:[1,0,1] neg_lo:[0,0,1] neg_hi:[0,0,1]
	v_cvt_pk_bf16_f32 v129, v114, v135
	v_pk_mul_f32 v[118:119], v[116:117], v[134:135] op_sel:[0,1]
	s_nop 0
	v_pk_fma_f32 v[134:135], v[112:113], v[114:115], v[118:119] op_sel_hi:[1,0,1]
	v_pk_fma_f32 v[114:115], v[112:113], v[114:115], v[118:119] op_sel_hi:[1,0,1] neg_lo:[0,0,1] neg_hi:[0,0,1]
	v_cvt_pk_bf16_f32 v118, v114, v135
	ds_write2_b32 v133, v118, v129 offset0:136 offset1:204
	v_pk_mul_f32 v[118:119], v[116:117], v[134:135] op_sel:[0,1]
	s_nop 0
	v_pk_fma_f32 v[134:135], v[112:113], v[114:115], v[118:119] op_sel_hi:[1,0,1]
	v_pk_fma_f32 v[114:115], v[112:113], v[114:115], v[118:119] op_sel_hi:[1,0,1] neg_lo:[0,0,1] neg_hi:[0,0,1]
	v_bfe_u32 v119, v135, 16, 1
	v_bfe_u32 v118, v114, 16, 1
	v_add3_u32 v118, v114, v118, s89
	v_lshrrev_b32_e32 v118, 16, v118
	v_add3_u32 v119, v135, v119, s89
	v_pk_mul_f32 v[134:135], v[116:117], v[134:135] op_sel:[0,1]
	v_and_or_b32 v129, v119, s75, v118
	v_pk_fma_f32 v[118:119], v[112:113], v[114:115], v[134:135] op_sel_hi:[1,0,1]
	v_pk_fma_f32 v[114:115], v[112:113], v[114:115], v[134:135] op_sel_hi:[1,0,1] neg_lo:[0,0,1] neg_hi:[0,0,1]
	v_cvt_pk_bf16_f32 v115, v114, v119
	v_mov_b32_e32 v118, v119
	ds_write2_b32 v133, v115, v129 offset1:68
	s_cbranch_scc1 .LBB0_1154
	s_waitcnt vmcnt(7) lgkmcnt(11)
	v_mfma_f32_16x16x32_bf16 v[56:59], v[56:59], v[12:15], 0
	v_add_f32_e32 v129, v148, v149
	v_add_f32_e32 v143, v144, v145
	s_waitcnt vmcnt(6) lgkmcnt(10)
	v_mfma_f32_16x16x32_bf16 v[56:59], v[60:63], v[8:11], v[56:59]
	ds_read_b128 v[60:63], v131
	v_add_f32_e32 v134, v150, v151
	v_lshlrev_b32_e32 v120, 1, v120
	s_waitcnt vmcnt(5) lgkmcnt(8)
	v_mfma_f32_16x16x32_bf16 v[52:55], v[52:55], v[4:7], v[56:59]
	v_add_f32_e32 v144, v146, v147
	v_add_f32_e32 v133, v155, v157
	v_add_f32_e32 v145, v152, v153
	ds_read_b128 v[56:59], v131 offset:64
	s_waitcnt vmcnt(4) lgkmcnt(8)
	v_mfma_f32_16x16x32_bf16 v[48:51], v[48:51], v[0:3], v[52:55]
	v_add_f32_e32 v135, v158, v159
	v_add_f32_e32 v146, v154, v156
	s_mov_b32 s0, 0
	ds_read_b128 v[52:55], v131 offset:128
	s_waitcnt vmcnt(3) lgkmcnt(2)
	v_mfma_f32_16x16x32_bf16 v[48:51], v[60:63], v[28:31], v[48:51]
	ds_read_b128 v[60:63], v131 offset:192
	s_waitcnt vmcnt(2) lgkmcnt(2)
	v_mfma_f32_16x16x32_bf16 v[48:51], v[56:59], v[24:27], v[48:51]
	ds_read_b128 v[56:59], v131 offset:4352
	ds_read_b128 v[112:115], v131 offset:4416
	s_waitcnt vmcnt(1) lgkmcnt(3)
	v_mfma_f32_16x16x32_bf16 v[48:51], v[52:55], v[20:23], v[48:51]
	ds_read_b128 v[52:55], v131 offset:4480
	ds_read_b128 v[116:119], v131 offset:4544
	v_mfma_f32_16x16x32_bf16 v[12:15], v[44:47], v[12:15], 0
	s_waitcnt vmcnt(0) lgkmcnt(4)
	v_mfma_f32_16x16x32_bf16 v[48:51], v[60:63], v[16:19], v[48:51]
	v_mfma_f32_16x16x32_bf16 v[8:11], v[40:43], v[8:11], v[12:15]
	v_mfma_f32_16x16x32_bf16 v[4:7], v[36:39], v[4:7], v[8:11]
	s_nop 5
	v_add_f32_e32 v48, v129, v48
	v_fmac_f32_e32 v48, v128, v125
	v_mul_f32_e32 v60, 0x3d372713, v48
	v_mul_f32_e32 v44, v48, v60
	v_fma_f32 v44, v48, v44, v48
	v_mfma_f32_16x16x32_bf16 v[0:3], v[32:35], v[0:3], v[4:7]
	v_mul_f32_e32 v44, 0xbfcc422a, v44
	v_mul_f32_e32 v44, 0x3fb8aa3b, v44
	v_exp_f32_e32 v12, v44
	s_waitcnt lgkmcnt(3)
	v_mfma_f32_16x16x32_bf16 v[0:3], v[56:59], v[28:31], v[0:3]
	v_add_f32_e32 v49, v143, v49
	v_fmac_f32_e32 v49, v142, v125
	v_add_f32_e32 v8, 1.0, v12
	v_rcp_f32_e32 v8, v8
	s_waitcnt lgkmcnt(2)
	v_mfma_f32_16x16x32_bf16 v[0:3], v[112:115], v[24:27], v[0:3]
	v_mul_f32_e32 v61, 0x3d372713, v49
	v_add_f32_e32 v24, v134, v50
	v_mul_f32_e32 v5, v48, v8
	s_waitcnt lgkmcnt(1)
	v_mfma_f32_16x16x32_bf16 v[0:3], v[52:55], v[20:23], v[0:3]
	v_mul_f32_e32 v13, v49, v61
	v_fmac_f32_e32 v24, v127, v125
	v_fma_f32 v13, v49, v13, v49
	v_cvt_pk_bf16_f32 v5, v5, v5
	v_mul_f32_e32 v6, 0x3d372713, v24
	v_mul_f32_e32 v9, 0xbfcc422a, v13
	v_mul_f32_e32 v6, v24, v6
	v_mul_f32_e32 v4, 0x3fb8aa3b, v9
	s_waitcnt lgkmcnt(0)
	v_mfma_f32_16x16x32_bf16 v[16:19], v[116:119], v[16:19], v[0:3]
	v_exp_f32_e32 v4, v4
	v_lshlrev_b32_e32 v112, 4, v141
	v_ashrrev_i32_e32 v113, 31, v112
	v_fma_f32 v0, v24, v6, v24
	v_mul_f32_e32 v0, 0xbfcc422a, v0
	v_mul_f32_e32 v0, 0x3fb8aa3b, v0
	v_exp_f32_e32 v0, v0
	v_add_f32_e32 v4, 1.0, v4
	v_rcp_f32_e32 v4, v4
	v_add3_u32 v28, v130, v120, v132
	v_add_f32_e32 v0, 1.0, v0
	v_rcp_f32_e32 v23, v0
	v_lshlrev_b64 v[0:1], 2, v[112:113]
	v_lshl_add_u64 v[2:3], v[76:77], 0, v[0:1]
	ds_write_b16 v28, v5 offset:34816
	v_mul_f32_e32 v21, v49, v4
	v_lshl_add_u64 v[4:5], v[2:3], 0, v[80:81]
	v_lshl_add_u64 v[0:1], v[78:79], 0, v[0:1]
	v_add_co_u32_e32 v6, vcc, s92, v4
	v_add_u32_e32 v20, s5, v112
	s_nop 0
	v_addc_co_u32_e32 v7, vcc, 0, v5, vcc
	global_load_dword v114, v[4:5], off
	global_load_dword v115, v[6:7], off
	v_lshl_add_u64 v[4:5], v[0:1], 0, v[82:83]
	global_load_dword v113, v[4:5], off
	v_lshl_add_u64 v[4:5], v[2:3], 0, v[84:85]
	v_add_co_u32_e32 v6, vcc, s92, v4
	v_add_f32_e32 v25, v144, v51
	s_nop 0
	v_addc_co_u32_e32 v7, vcc, 0, v5, vcc
	global_load_dword v84, v[4:5], off
	global_load_dword v85, v[6:7], off
	v_lshl_add_u64 v[4:5], v[0:1], 0, v[86:87]
	global_load_dword v83, v[4:5], off
	v_lshl_add_u64 v[4:5], v[2:3], 0, v[88:89]
	v_add_co_u32_e32 v6, vcc, s92, v4
	v_fmac_f32_e32 v25, v126, v125
	s_nop 0
	v_addc_co_u32_e32 v7, vcc, 0, v5, vcc
	global_load_dword v86, v[4:5], off
	global_load_dword v87, v[6:7], off
	v_lshl_add_u64 v[4:5], v[0:1], 0, v[90:91]
	global_load_dword v82, v[4:5], off
	v_lshl_add_u64 v[4:5], v[2:3], 0, v[92:93]
	v_add_co_u32_e32 v6, vcc, s92, v4
	v_mul_f32_e32 v26, 0x3d372713, v25
	s_nop 0
	v_addc_co_u32_e32 v7, vcc, 0, v5, vcc
	global_load_dword v88, v[4:5], off
	global_load_dword v89, v[6:7], off
	v_lshl_add_u64 v[4:5], v[0:1], 0, v[94:95]
	global_load_dword v81, v[4:5], off
	v_lshl_add_u64 v[4:5], v[2:3], 0, v[96:97]
	v_add_co_u32_e32 v6, vcc, s92, v4
	v_mul_f32_e32 v26, v25, v26
	s_nop 0
	v_addc_co_u32_e32 v7, vcc, 0, v5, vcc
	global_load_dword v90, v[4:5], off
	global_load_dword v91, v[6:7], off
	v_lshl_add_u64 v[4:5], v[0:1], 0, v[98:99]
	global_load_dword v80, v[4:5], off
	v_lshl_add_u64 v[4:5], v[2:3], 0, v[100:101]
	v_add_co_u32_e32 v6, vcc, s92, v4
	v_fma_f32 v26, v25, v26, v25
	s_nop 0
	v_addc_co_u32_e32 v7, vcc, 0, v5, vcc
	global_load_dword v92, v[4:5], off
	global_load_dword v93, v[6:7], off
	v_lshl_add_u64 v[4:5], v[0:1], 0, v[102:103]
	global_load_dword v79, v[4:5], off
	v_lshl_add_u64 v[4:5], v[2:3], 0, v[104:105]
	v_add_co_u32_e32 v6, vcc, s92, v4
	v_lshl_add_u64 v[2:3], v[2:3], 0, v[110:111]
	s_nop 0
	v_addc_co_u32_e32 v7, vcc, 0, v5, vcc
	global_load_dword v94, v[4:5], off
	global_load_dword v95, v[6:7], off
	v_lshl_add_u64 v[4:5], v[0:1], 0, v[106:107]
	global_load_dword v78, v[4:5], off
	v_add_co_u32_e32 v4, vcc, s92, v2
	v_lshl_add_u64 v[0:1], v[0:1], 0, v[108:109]
	s_nop 0
	v_addc_co_u32_e32 v5, vcc, 0, v3, vcc
	global_load_dword v96, v[2:3], off
	global_load_dword v97, v[4:5], off
	ds_read_b64 v[2:3], v229 offset:63640
	global_load_dword v76, v[0:1], off
	v_add_u32_e32 v0, v112, v140
	v_ashrrev_i32_e32 v1, 31, v0
	v_mul_f32_e32 v26, 0xbfcc422a, v26
	s_waitcnt lgkmcnt(0)
	v_lshl_add_u64 v[0:1], v[0:1], 2, v[2:3]
	global_load_dword v77, v[0:1], off
	v_or_b32_e32 v0, v20, v139
	v_ashrrev_i32_e32 v1, 31, v0
	v_lshlrev_b64 v[0:1], 8, v[0:1]
	v_lshl_add_u64 v[0:1], v[72:73], 0, v[0:1]
	global_load_dwordx4 v[12:15], v[0:1], off
	global_load_dwordx4 v[8:11], v[0:1], off offset:64
	global_load_dwordx4 v[4:7], v[0:1], off offset:128
	s_nop 0
	global_load_dwordx4 v[0:3], v[0:1], off offset:192
	v_mul_f32_e32 v26, 0x3fb8aa3b, v26
	v_exp_f32_e32 v26, v26
	v_cvt_pk_bf16_f32 v21, v21, v21
	ds_write_b16 v28, v21 offset:35344
	v_add_f32_e32 v22, 1.0, v26
	v_rcp_f32_e32 v22, v22
	v_mul_f32_e32 v21, v24, v23
	v_add_f32_e32 v16, v133, v16
	v_cvt_pk_bf16_f32 v21, v21, v21
	v_fmac_f32_e32 v16, v124, v125
	ds_write_b16 v28, v21 offset:35872
	v_mul_f32_e32 v21, v25, v22
	v_mul_f32_e32 v22, 0x3d372713, v16
	v_mul_f32_e32 v22, v16, v22
	v_fma_f32 v22, v16, v22, v16
	v_mul_f32_e32 v22, 0xbfcc422a, v22
	v_mul_f32_e32 v22, 0x3fb8aa3b, v22
	v_exp_f32_e32 v22, v22
	v_add_f32_e32 v17, v145, v17
	v_cvt_pk_bf16_f32 v21, v21, v21
	v_fmac_f32_e32 v17, v123, v125
	ds_write_b16 v28, v21 offset:36400
	v_add_f32_e32 v21, 1.0, v22
	v_mul_f32_e32 v22, 0x3d372713, v17
	v_mul_f32_e32 v22, v17, v22
	v_fma_f32 v22, v17, v22, v17
	v_rcp_f32_e32 v21, v21
	v_mul_f32_e32 v22, 0xbfcc422a, v22
	v_mul_f32_e32 v22, 0x3fb8aa3b, v22
	v_exp_f32_e32 v22, v22
	v_mul_f32_e32 v16, v16, v21
	v_add_f32_e32 v18, v135, v18
	v_fmac_f32_e32 v18, v121, v125
	v_cvt_pk_bf16_f32 v16, v16, v16
	v_add_f32_e32 v21, 1.0, v22
	v_mul_f32_e32 v22, 0x3d372713, v18
	v_mul_f32_e32 v22, v18, v22
	v_fma_f32 v22, v18, v22, v18
	v_mul_f32_e32 v22, 0xbfcc422a, v22
	v_mul_f32_e32 v22, 0x3fb8aa3b, v22
	v_rcp_f32_e32 v21, v21
	v_exp_f32_e32 v22, v22
	v_add_f32_e32 v19, v146, v19
	v_fmac_f32_e32 v19, v122, v125
	ds_write_b16 v28, v16 offset:43264
	v_mul_f32_e32 v16, v17, v21
	v_add_f32_e32 v21, 1.0, v22
	v_mul_f32_e32 v22, 0x3d372713, v19
	v_mul_f32_e32 v22, v19, v22
	v_fma_f32 v22, v19, v22, v19
	v_mul_f32_e32 v22, 0xbfcc422a, v22
	v_mul_f32_e32 v22, 0x3fb8aa3b, v22
	v_exp_f32_e32 v22, v22
	v_rcp_f32_e32 v21, v21
	v_cvt_pk_bf16_f32 v16, v16, v16
	v_add_f32_e32 v17, 1.0, v22
	v_rcp_f32_e32 v17, v17
	ds_write_b16 v28, v16 offset:43792
	v_mul_f32_e32 v16, v18, v21
	v_cvt_pk_bf16_f32 v16, v16, v16
	ds_write_b16 v28, v16 offset:44320
	v_mul_f32_e32 v16, v19, v17
	v_cvt_pk_bf16_f32 v16, v16, v16
	ds_write_b16 v28, v16 offset:44848
	v_pk_mov_b32 v[16:17], v[70:71], v[70:71] op_sel:[1,0]
	v_mov_b32_e32 v18, v75

.LBB0_1158:
	v_pk_mul_f32 v[72:73], v[70:71], v[72:73] op_sel_hi:[1,0]
	v_add_u32_e32 v99, s0, v65
	v_pk_fma_f32 v[74:75], v[66:67], v[68:69], v[72:73] op_sel_hi:[1,0,1]
	v_pk_fma_f32 v[68:69], v[66:67], v[68:69], v[72:73] op_sel_hi:[1,0,1] neg_lo:[0,0,1] neg_hi:[0,0,1]
	v_cvt_pk_bf16_f32 v98, v68, v75
	v_pk_mul_f32 v[72:73], v[70:71], v[74:75] op_sel:[0,1]
	v_add_u32_e32 v100, 0x400, v99
	v_pk_fma_f32 v[74:75], v[66:67], v[68:69], v[72:73] op_sel_hi:[1,0,1]
	v_pk_fma_f32 v[68:69], v[66:67], v[68:69], v[72:73] op_sel_hi:[1,0,1] neg_lo:[0,0,1] neg_hi:[0,0,1]
	v_cvt_pk_bf16_f32 v72, v68, v75
	ds_write2_b32 v100, v72, v98 offset0:152 offset1:220
	v_pk_mul_f32 v[72:73], v[70:71], v[74:75] op_sel:[0,1]
	s_addk_i32 s0, 0xf780
	v_pk_fma_f32 v[74:75], v[66:67], v[68:69], v[72:73] op_sel_hi:[1,0,1]
	v_pk_fma_f32 v[68:69], v[66:67], v[68:69], v[72:73] op_sel_hi:[1,0,1] neg_lo:[0,0,1] neg_hi:[0,0,1]
	v_cvt_pk_bf16_f32 v98, v68, v75
	v_pk_mul_f32 v[72:73], v[70:71], v[74:75] op_sel:[0,1]
	s_cmpk_lg_i32 s0, 0xf780
	v_pk_fma_f32 v[74:75], v[66:67], v[68:69], v[72:73] op_sel_hi:[1,0,1]
	v_pk_fma_f32 v[68:69], v[66:67], v[68:69], v[72:73] op_sel_hi:[1,0,1] neg_lo:[0,0,1] neg_hi:[0,0,1]
	v_cvt_pk_bf16_f32 v72, v68, v75
	ds_write2_b32 v100, v72, v98 offset0:16 offset1:84
	v_pk_mul_f32 v[72:73], v[70:71], v[74:75] op_sel:[0,1]
	s_nop 0
	v_pk_fma_f32 v[74:75], v[66:67], v[68:69], v[72:73] op_sel_hi:[1,0,1]
	v_pk_fma_f32 v[68:69], v[66:67], v[68:69], v[72:73] op_sel_hi:[1,0,1] neg_lo:[0,0,1] neg_hi:[0,0,1]
	v_cvt_pk_bf16_f32 v98, v68, v75
	v_pk_mul_f32 v[72:73], v[70:71], v[74:75] op_sel:[0,1]
	s_nop 0
	v_pk_fma_f32 v[74:75], v[66:67], v[68:69], v[72:73] op_sel_hi:[1,0,1]
	v_pk_fma_f32 v[68:69], v[66:67], v[68:69], v[72:73] op_sel_hi:[1,0,1] neg_lo:[0,0,1] neg_hi:[0,0,1]
	v_cvt_pk_bf16_f32 v72, v68, v75
	ds_write2_b32 v99, v72, v98 offset0:136 offset1:204
	v_pk_mul_f32 v[72:73], v[70:71], v[74:75] op_sel:[0,1]
	s_nop 0
	v_pk_fma_f32 v[74:75], v[66:67], v[68:69], v[72:73] op_sel_hi:[1,0,1]
	v_pk_fma_f32 v[68:69], v[66:67], v[68:69], v[72:73] op_sel_hi:[1,0,1] neg_lo:[0,0,1] neg_hi:[0,0,1]
	v_bfe_u32 v73, v75, 16, 1
	v_bfe_u32 v72, v68, 16, 1
	v_add3_u32 v72, v68, v72, s89
	v_lshrrev_b32_e32 v72, 16, v72
	v_add3_u32 v73, v75, v73, s89
	v_pk_mul_f32 v[74:75], v[70:71], v[74:75] op_sel:[0,1]
	v_and_or_b32 v98, v73, s75, v72
	v_pk_fma_f32 v[72:73], v[66:67], v[68:69], v[74:75] op_sel_hi:[1,0,1]
	v_pk_fma_f32 v[68:69], v[66:67], v[68:69], v[74:75] op_sel_hi:[1,0,1] neg_lo:[0,0,1] neg_hi:[0,0,1]
	v_cvt_pk_bf16_f32 v69, v68, v73
	v_mov_b32_e32 v72, v73
	ds_write2_b32 v99, v69, v98 offset1:68
	s_cbranch_scc1 .LBB0_1158
	s_waitcnt vmcnt(7) lgkmcnt(11)
	v_mfma_f32_16x16x32_bf16 v[56:59], v[56:59], v[12:15], 0
	v_add_f32_e32 v65, v114, v115
	v_add_f32_e32 v69, v84, v85
	s_waitcnt lgkmcnt(9)
	v_mfma_f32_16x16x32_bf16 v[12:15], v[60:63], v[12:15], 0
	v_add_f32_e32 v67, v86, v87
	v_add_f32_e32 v70, v88, v89
	v_add_f32_e32 v66, v90, v91
	s_waitcnt vmcnt(6)
	v_mfma_f32_16x16x32_bf16 v[32:35], v[32:35], v[8:11], v[56:59]
	v_add_f32_e32 v71, v92, v93
	v_add_f32_e32 v68, v94, v95
	v_add_f32_e32 v72, v96, v97
	s_waitcnt lgkmcnt(8)
	v_mfma_f32_16x16x32_bf16 v[8:11], v[40:43], v[8:11], v[12:15]
	v_and_b32_e32 v40, 31, v137
	v_lshrrev_b32_e32 v42, 5, v138
	s_mov_b64 s[0:1], 0
	s_waitcnt vmcnt(5) lgkmcnt(7)
	v_mfma_f32_16x16x32_bf16 v[12:15], v[44:47], v[4:7], v[32:35]
	s_waitcnt lgkmcnt(5)
	v_mfma_f32_16x16x32_bf16 v[4:7], v[52:55], v[4:7], v[8:11]
	s_nop 0
	v_and_b32_e32 v34, 0xffffffdf, v137
	v_or_b32_e32 v32, 32, v137
	v_ashrrev_i32_e32 v35, 31, v34
	s_waitcnt vmcnt(4)
	v_mfma_f32_16x16x32_bf16 v[8:11], v[36:39], v[0:3], v[12:15]
	v_ashrrev_i32_e32 v33, 31, v32
	s_waitcnt lgkmcnt(4)
	v_mfma_f32_16x16x32_bf16 v[0:3], v[48:51], v[0:3], v[4:7]
	s_nop 2
	ds_read_b128 v[4:7], v131
	s_waitcnt vmcnt(3) lgkmcnt(0)
	v_mfma_f32_16x16x32_bf16 v[4:7], v[4:7], v[28:31], v[8:11]
	s_nop 2
	ds_read_b128 v[8:11], v131 offset:4352
	s_waitcnt lgkmcnt(0)
	v_mfma_f32_16x16x32_bf16 v[0:3], v[8:11], v[28:31], v[0:3]
	ds_read_b128 v[8:11], v131 offset:64
	s_waitcnt vmcnt(2) lgkmcnt(0)
	v_mfma_f32_16x16x32_bf16 v[4:7], v[8:11], v[24:27], v[4:7]
	ds_read_b128 v[8:11], v131 offset:4416
	s_waitcnt lgkmcnt(0)
	v_mfma_f32_16x16x32_bf16 v[0:3], v[8:11], v[24:27], v[0:3]
	ds_read_b128 v[8:11], v131 offset:128
	s_waitcnt vmcnt(1) lgkmcnt(0)
	v_mfma_f32_16x16x32_bf16 v[4:7], v[8:11], v[20:23], v[4:7]
	ds_read_b128 v[8:11], v131 offset:4480
	s_waitcnt lgkmcnt(0)
	v_mfma_f32_16x16x32_bf16 v[0:3], v[8:11], v[20:23], v[0:3]
	ds_read_b128 v[8:11], v131 offset:192
	s_waitcnt vmcnt(0) lgkmcnt(0)
	v_mfma_f32_16x16x32_bf16 v[4:7], v[8:11], v[16:19], v[4:7]
	ds_read_b128 v[8:11], v131 offset:4544
	s_nop 6
	v_add_f32_e32 v4, v65, v4
	v_fmac_f32_e32 v4, v113, v77
	s_waitcnt lgkmcnt(0)
	v_mfma_f32_16x16x32_bf16 v[0:3], v[8:11], v[16:19], v[0:3]
	v_mul_f32_e32 v9, 0x3d372713, v4
	v_mul_f32_e32 v9, v4, v9
	v_fma_f32 v9, v4, v9, v4
	v_mul_f32_e32 v9, 0xbfcc422a, v9
	v_mul_f32_e32 v9, 0x3fb8aa3b, v9
	v_exp_f32_e32 v9, v9
	v_lshlrev_b32_e32 v8, 1, v112
	v_add3_u32 v8, v130, v8, v132
	v_add_f32_e32 v0, v66, v0
	v_add_f32_e32 v9, 1.0, v9
	v_rcp_f32_e32 v9, v9
	v_fmac_f32_e32 v0, v80, v77
	v_mul_f32_e32 v4, v4, v9
	v_cvt_pk_bf16_f32 v4, v4, v4
	ds_write_b16 v8, v4 offset:34816
	v_add_f32_e32 v4, v69, v5
	v_fmac_f32_e32 v4, v83, v77
	v_mul_f32_e32 v5, 0x3d372713, v4
	v_mul_f32_e32 v5, v4, v5
	v_fma_f32 v5, v4, v5, v4
	v_mul_f32_e32 v5, 0xbfcc422a, v5
	v_mul_f32_e32 v5, 0x3fb8aa3b, v5
	v_exp_f32_e32 v5, v5
	s_nop 0
	v_add_f32_e32 v5, 1.0, v5
	v_rcp_f32_e32 v5, v5
	s_nop 0
	v_mul_f32_e32 v4, v4, v5
	v_cvt_pk_bf16_f32 v4, v4, v4
	ds_write_b16 v8, v4 offset:35344
	v_add_f32_e32 v4, v67, v6
	v_fmac_f32_e32 v4, v82, v77
	v_mul_f32_e32 v5, 0x3d372713, v4
	v_mul_f32_e32 v5, v4, v5
	v_fma_f32 v5, v4, v5, v4
	v_mul_f32_e32 v5, 0xbfcc422a, v5
	v_mul_f32_e32 v5, 0x3fb8aa3b, v5
	v_exp_f32_e32 v5, v5
	v_mul_u32_u24_e32 v6, 0x210, v40
	v_add_f32_e32 v5, 1.0, v5
	v_rcp_f32_e32 v5, v5
	s_nop 0
	v_mul_f32_e32 v4, v4, v5
	v_cvt_pk_bf16_f32 v4, v4, v4
	ds_write_b16 v8, v4 offset:35872
	v_add_f32_e32 v4, v70, v7
	v_fmac_f32_e32 v4, v81, v77
	v_mul_f32_e32 v5, 0x3d372713, v4
	v_mul_f32_e32 v5, v4, v5
	v_fma_f32 v5, v4, v5, v4
	v_mul_f32_e32 v5, 0xbfcc422a, v5
	v_mul_f32_e32 v5, 0x3fb8aa3b, v5
	v_exp_f32_e32 v5, v5
	v_lshlrev_b32_e32 v7, 4, v42
	v_add3_u32 v41, v6, v7, s26
	v_lshrrev_b32_e32 v6, 1, v137
	v_add_f32_e32 v5, 1.0, v5
	v_rcp_f32_e32 v5, v5
	v_and_b32_e32 v6, 16, v6
	v_mul_f32_e32 v4, v4, v5
	v_cvt_pk_bf16_f32 v4, v4, v4
	ds_write_b16 v8, v4 offset:36400
	v_mul_f32_e32 v4, 0x3d372713, v0
	v_mul_f32_e32 v4, v0, v4
	v_fma_f32 v4, v0, v4, v0
	v_mul_f32_e32 v4, 0xbfcc422a, v4
	v_mul_f32_e32 v4, 0x3fb8aa3b, v4
	v_exp_f32_e32 v4, v4
	s_nop 0
	v_add_f32_e32 v4, 1.0, v4
	v_rcp_f32_e32 v4, v4
	s_nop 0
	v_mul_f32_e32 v0, v0, v4
	v_cvt_pk_bf16_f32 v0, v0, v0
	ds_write_b16 v8, v0 offset:43264
	v_add_f32_e32 v0, v71, v1
	v_fmac_f32_e32 v0, v79, v77
	v_mul_f32_e32 v1, 0x3d372713, v0
	v_mul_f32_e32 v1, v0, v1
	v_fma_f32 v1, v0, v1, v0
	v_mul_f32_e32 v1, 0xbfcc422a, v1
	v_mul_f32_e32 v1, 0x3fb8aa3b, v1
	v_exp_f32_e32 v1, v1
	v_lshlrev_b64 v[4:5], 9, v[32:33]
	v_or_b32_e32 v4, v4, v6
	v_add_f32_e32 v1, 1.0, v1
	v_rcp_f32_e32 v1, v1
	s_nop 0
	v_mul_f32_e32 v0, v0, v1
	v_cvt_pk_bf16_f32 v0, v0, v0
	ds_write_b16 v8, v0 offset:43792
	v_add_f32_e32 v0, v68, v2
	v_fmac_f32_e32 v0, v78, v77
	v_mul_f32_e32 v1, 0x3d372713, v0
	v_mul_f32_e32 v1, v0, v1
	v_fma_f32 v1, v0, v1, v0
	v_mul_f32_e32 v1, 0xbfcc422a, v1
	v_mul_f32_e32 v1, 0x3fb8aa3b, v1
	v_exp_f32_e32 v1, v1
	s_nop 0
	v_add_f32_e32 v1, 1.0, v1
	v_rcp_f32_e32 v1, v1
	s_nop 0
	v_mul_f32_e32 v0, v0, v1
	v_cvt_pk_bf16_f32 v0, v0, v0
	ds_write_b16 v8, v0 offset:44320
	v_add_f32_e32 v0, v72, v3
	v_fmac_f32_e32 v0, v76, v77
	v_mul_f32_e32 v1, 0x3d372713, v0
	v_mul_f32_e32 v1, v0, v1
	v_fma_f32 v1, v0, v1, v0
	v_mul_f32_e32 v1, 0xbfcc422a, v1
	v_mul_f32_e32 v1, 0x3fb8aa3b, v1
	v_exp_f32_e32 v1, v1
	v_lshlrev_b64 v[2:3], 9, v[34:35]
	v_or_b32_e32 v2, v2, v6
	v_add_f32_e32 v1, 1.0, v1
	v_rcp_f32_e32 v1, v1
	s_nop 0
	v_mul_f32_e32 v0, v0, v1
	v_cvt_pk_bf16_f32 v0, v0, v0
	ds_write_b16 v8, v0 offset:44848
	s_waitcnt lgkmcnt(0)
	s_barrier
	ds_read_b64 v[0:1], v229 offset:63760
	s_waitcnt lgkmcnt(0)
	v_lshl_add_u64 v[36:37], v[0:1], 0, v[4:5]
	v_lshl_add_u64 v[38:39], v[0:1], 0, v[2:3]
	v_mov_b32_e32 v0, 0
	v_mov_b32_e32 v1, v0
	v_mov_b32_e32 v2, v0
	v_mov_b32_e32 v3, v0
	v_mov_b32_e32 v4, v0
	v_mov_b32_e32 v5, v0
	v_mov_b32_e32 v6, v0
	v_mov_b32_e32 v7, v0
	v_mov_b32_e32 v8, v0
	v_mov_b32_e32 v9, v0
	v_mov_b32_e32 v10, v0
	v_mov_b32_e32 v11, v0
	v_mov_b32_e32 v12, v0
	v_mov_b32_e32 v13, v0
	v_mov_b32_e32 v14, v0
	v_mov_b32_e32 v15, v0
	v_mov_b32_e32 v16, v0
	v_mov_b32_e32 v17, v0
	v_mov_b32_e32 v18, v0
	v_mov_b32_e32 v19, v0
	v_mov_b32_e32 v20, v0
	v_mov_b32_e32 v21, v0
	v_mov_b32_e32 v22, v0
	v_mov_b32_e32 v23, v0
	v_mov_b32_e32 v24, v0
	v_mov_b32_e32 v25, v0
	v_mov_b32_e32 v26, v0
	v_mov_b32_e32 v27, v0
	v_mov_b32_e32 v28, v0
	v_mov_b32_e32 v29, v0
	v_mov_b32_e32 v30, v0
	v_mov_b32_e32 v31, v0

.LBB0_1196:
	s_or_b64 exec, exec, s[72:73]
	v_add_f32_e32 v32, v37, v39
	v_mul_f32_e32 v35, 0x3fb8aa3b, v32
	v_exp_f32_e32 v35, v35
	v_mul_f32_e32 v32, 0xbfb8aa3b, v32
	v_exp_f32_e32 v32, v32
	v_cndmask_b32_e64 v36, v36, v38, s[68:69]
	v_mul_f32_e32 v33, v33, v35
	s_mulk_i32 s77, 0x48
	v_mul_f32_e32 v34, v34, v36
	v_cvt_pk_bf16_f32 v33, v33, v33
	v_add_u32_e32 v35, s77, v66
	v_lshl_add_u32 v35, v35, 1, v76
	v_mul_f32_e32 v32, v34, v32
	ds_write_b16 v35, v33
	v_cvt_pk_bf16_f32 v32, v32, v32
	ds_write_b16 v35, v32 offset:4608
	ds_read_b128 v[32:35], v81 offset:4608
	ds_read_b128 v[60:63], v81
	ds_read_b128 v[56:59], v81 offset:32
	ds_read_b128 v[48:51], v81 offset:4640
	s_waitcnt lgkmcnt(2)
	v_mfma_f32_32x32x16_bf16 v[32:47], v[32:35], v[60:63], 0
	v_readlane_b32 s0, v255, 35
	v_readlane_b32 s1, v255, 36
	ds_read_b128 v[84:87], v81 offset:4672
	ds_read_b128 v[52:55], v81 offset:64
	v_cndmask_b32_e64 v71, 0, 1, s[0:1]
	v_readlane_b32 s0, v255, 33
	v_readlane_b32 s1, v255, 34
	s_waitcnt lgkmcnt(2)
	v_mfma_f32_32x32x16_bf16 v[32:47], v[48:51], v[56:59], v[32:47]
	ds_read_b128 v[88:91], v81 offset:4704
	ds_read_b128 v[48:51], v81 offset:96
	v_cndmask_b32_e64 v73, 0, 1, s[0:1]
	v_readlane_b32 s0, v255, 39
	v_readlane_b32 s1, v255, 40
	v_cndmask_b32_e64 v71, v73, v71, s[70:71]
	v_and_b32_e32 v71, 1, v71
	v_cndmask_b32_e64 v92, 0, 1, s[0:1]
	v_readlane_b32 s0, v255, 37
	v_readlane_b32 s1, v255, 38
	s_waitcnt lgkmcnt(2)
	v_mfma_f32_32x32x16_bf16 v[32:47], v[84:87], v[52:55], v[32:47]
	v_cmp_eq_u32_e32 vcc, 1, v71
	v_cndmask_b32_e64 v93, 0, 1, s[0:1]
	v_readlane_b32 s0, v255, 43
	v_readlane_b32 s1, v255, 44
	v_cndmask_b32_e64 v73, v93, v92, s[70:71]
	v_and_b32_e32 v73, 1, v73
	v_cndmask_b32_e64 v94, 0, 1, s[0:1]
	v_readlane_b32 s0, v255, 41
	v_readlane_b32 s1, v255, 42
	s_waitcnt lgkmcnt(0)
	v_mfma_f32_32x32x16_bf16 v[32:47], v[88:91], v[48:51], v[32:47]
	v_cndmask_b32_e64 v89, 0, 1, s[26:27]
	v_cndmask_b32_e64 v95, 0, 1, s[0:1]
	v_readlane_b32 s0, v255, 47
	v_readlane_b32 s1, v255, 48
	v_cndmask_b32_e64 v85, v95, v94, s[70:71]
	v_and_b32_e32 v85, 1, v85
	v_cndmask_b32_e64 v96, 0, 1, s[0:1]
	v_readlane_b32 s0, v255, 45
	v_readlane_b32 s1, v255, 46
	s_nop 2
	v_cndmask_b32_e32 v32, 0, v32, vcc
	v_cmp_eq_u32_e32 vcc, 1, v73
	v_cndmask_b32_e64 v84, 0, 1, s[0:1]
	v_readlane_b32 s0, v255, 51
	v_cndmask_b32_e64 v84, v84, v96, s[70:71]
	v_readlane_b32 s1, v255, 52
	v_and_b32_e32 v86, 1, v84
	v_bfe_u32 v71, v32, 16, 1
	v_cndmask_b32_e64 v84, 0, 1, s[0:1]
	v_readlane_b32 s0, v255, 49
	v_readlane_b32 s1, v255, 50
	v_cndmask_b32_e32 v33, 0, v33, vcc
	v_add3_u32 v32, v32, v71, s89
	v_cndmask_b32_e64 v87, 0, 1, s[0:1]
	v_readlane_b32 s0, v255, 53
	v_cndmask_b32_e64 v84, v87, v84, s[70:71]
	v_readlane_b32 s1, v255, 54
	v_and_b32_e32 v87, 1, v84
	v_cndmask_b32_e64 v84, 0, 1, s[24:25]
	v_cndmask_b32_e64 v88, 0, 1, s[0:1]
	v_cndmask_b32_e64 v84, v88, v84, s[70:71]
	v_and_b32_e32 v88, 1, v84
	v_cndmask_b32_e64 v84, 0, 1, s[28:29]
	v_cndmask_b32_e64 v84, v89, v84, s[70:71]
	v_and_b32_e32 v96, 1, v84
	v_cndmask_b32_e64 v84, 0, 1, s[34:35]
	v_cndmask_b32_e64 v89, 0, 1, s[30:31]
	v_cndmask_b32_e64 v84, v89, v84, s[70:71]
	v_and_b32_e32 v97, 1, v84
	v_cndmask_b32_e64 v84, 0, 1, s[38:39]
	v_cndmask_b32_e64 v89, 0, 1, s[36:37]
	v_cndmask_b32_e64 v84, v89, v84, s[70:71]
	v_and_b32_e32 v102, 1, v84
	v_cndmask_b32_e64 v84, 0, 1, s[42:43]
	v_cndmask_b32_e64 v89, 0, 1, s[40:41]
	v_cndmask_b32_e64 v84, v89, v84, s[70:71]
	v_and_b32_e32 v103, 1, v84
	v_cndmask_b32_e64 v84, 0, 1, s[46:47]
	v_cndmask_b32_e64 v89, 0, 1, s[44:45]
	v_cndmask_b32_e64 v84, v89, v84, s[70:71]
	v_and_b32_e32 v104, 1, v84
	v_cndmask_b32_e64 v84, 0, 1, s[22:23]
	v_cndmask_b32_e64 v89, 0, 1, s[48:49]
	v_cndmask_b32_e64 v84, v89, v84, s[70:71]
	v_and_b32_e32 v105, 1, v84
	v_cndmask_b32_e64 v84, 0, 1, s[54:55]
	v_cndmask_b32_e64 v89, 0, 1, s[52:53]
	v_cndmask_b32_e64 v84, v89, v84, s[70:71]
	v_and_b32_e32 v106, 1, v84
	v_cndmask_b32_e64 v84, 0, 1, s[58:59]
	v_cndmask_b32_e64 v89, 0, 1, s[56:57]
	v_bfe_u32 v71, v33, 16, 1
	v_cndmask_b32_e64 v84, v89, v84, s[70:71]
	v_lshrrev_b32_e32 v32, 16, v32
	v_add3_u32 v33, v33, v71, s89
	v_cmp_eq_u32_e32 vcc, 1, v85
	v_and_b32_e32 v107, 1, v84
	v_and_or_b32 v84, v33, s75, v32
	v_cndmask_b32_e32 v32, 0, v34, vcc
	v_bfe_u32 v33, v32, 16, 1
	v_cmp_eq_u32_e32 vcc, 1, v86
	v_add3_u32 v32, v32, v33, s89
	v_lshrrev_b32_e32 v32, 16, v32
	v_cndmask_b32_e32 v33, 0, v35, vcc
	v_bfe_u32 v34, v33, 16, 1
	v_add3_u32 v33, v33, v34, s89
	v_cmp_eq_u32_e32 vcc, 1, v87
	v_and_or_b32 v85, v33, s75, v32
	v_mov_b32_e32 v71, v229
	v_cndmask_b32_e32 v32, 0, v36, vcc
	v_bfe_u32 v33, v32, 16, 1
	v_cmp_eq_u32_e32 vcc, 1, v88
	v_add3_u32 v32, v32, v33, s89
	v_lshrrev_b32_e32 v32, 16, v32
	v_cndmask_b32_e32 v33, 0, v37, vcc
	v_bfe_u32 v34, v33, 16, 1
	v_add3_u32 v33, v33, v34, s89
	v_and_or_b32 v86, v33, s75, v32
	v_lshl_add_u32 v32, s76, 2, v82
	v_ashrrev_i32_e32 v33, 31, v32
	v_lshlrev_b64 v[32:33], 14, v[32:33]
	v_lshl_add_u64 v[100:101], v[68:69], 0, v[32:33]
	v_lshl_add_u64 v[32:33], v[100:101], 0, v[70:71]
	global_load_dwordx4 v[88:91], v[32:33], off offset:16
	global_load_dwordx4 v[92:95], v[32:33], off
	v_cmp_eq_u32_e32 vcc, 1, v96
	v_add_u32_e32 v71, 0x2000, v83
	v_add_u32_e32 v110, 0x2800, v83
	v_cndmask_b32_e32 v34, 0, v38, vcc
	v_bfe_u32 v35, v34, 16, 1
	v_add3_u32 v38, v34, v35, s89
	ds_read2_b64 v[34:37], v71 offset0:128 offset1:130
	v_cmp_eq_u32_e32 vcc, 1, v97
	ds_read2_b64 v[96:99], v110 offset0:192 offset1:194
	v_lshrrev_b32_e32 v38, 16, v38
	v_cndmask_b32_e32 v39, 0, v39, vcc
	v_bfe_u32 v73, v39, 16, 1
	v_add3_u32 v39, v39, v73, s89
	v_cndmask_b32_e64 v108, 0, 1, s[62:63]
	v_cndmask_b32_e64 v109, 0, 1, s[60:61]
	v_and_or_b32 v87, v39, s75, v38
	v_mov_b32_e32 v73, v229
	v_cmp_eq_u32_e32 vcc, 1, v102
	s_waitcnt lgkmcnt(1)
	v_mfma_f32_32x32x16_bf16 v[16:31], v[34:37], v[84:87], v[16:31]
	v_cndmask_b32_e64 v34, v109, v108, s[70:71]
	v_and_b32_e32 v108, 1, v34
	v_cndmask_b32_e64 v34, 0, 1, s[66:67]
	v_cndmask_b32_e64 v35, 0, 1, s[64:65]
	v_cndmask_b32_e64 v34, v35, v34, s[70:71]
	v_and_b32_e32 v109, 1, v34
	v_lshl_add_u64 v[34:35], v[100:101], 0, v[72:73]
	ds_read2_b64 v[36:39], v71 offset0:132 offset1:134
	s_waitcnt lgkmcnt(1)
	v_mfma_f32_32x32x16_bf16 v[0:15], v[96:99], v[84:87], v[0:15]
	global_load_dwordx4 v[84:87], v[34:35], off offset:16
	global_load_dwordx4 v[96:99], v[34:35], off
	v_cndmask_b32_e32 v40, 0, v40, vcc
	v_cmp_eq_u32_e32 vcc, 1, v103
	v_bfe_u32 v71, v40, 16, 1
	v_add3_u32 v40, v40, v71, s89
	v_cndmask_b32_e32 v41, 0, v41, vcc
	v_bfe_u32 v71, v41, 16, 1
	v_lshrrev_b32_e32 v40, 16, v40
	v_add3_u32 v41, v41, v71, s89
	v_cmp_eq_u32_e32 vcc, 1, v104
	v_and_or_b32 v40, v41, s75, v40
	global_load_dwordx4 v[100:103], v[32:33], off offset:64
	v_cndmask_b32_e32 v41, 0, v42, vcc
	v_bfe_u32 v42, v41, 16, 1
	v_cmp_eq_u32_e32 vcc, 1, v105
	v_add3_u32 v41, v41, v42, s89
	v_lshrrev_b32_e32 v41, 16, v41
	v_cndmask_b32_e32 v42, 0, v43, vcc
	v_bfe_u32 v43, v42, 16, 1
	v_add3_u32 v42, v42, v43, s89
	v_cmp_eq_u32_e32 vcc, 1, v106
	v_and_or_b32 v41, v42, s75, v41
	s_xor_b64 s[0:1], s[70:71], -1
	v_cndmask_b32_e32 v42, 0, v44, vcc
	v_bfe_u32 v43, v42, 16, 1
	v_cmp_eq_u32_e32 vcc, 1, v107
	v_add3_u32 v42, v42, v43, s89
	v_lshrrev_b32_e32 v42, 16, v42
	v_cndmask_b32_e32 v43, 0, v45, vcc
	v_bfe_u32 v44, v43, 16, 1
	v_add3_u32 v43, v43, v44, s89
	v_cmp_eq_u32_e32 vcc, 1, v108
	v_and_or_b32 v42, v43, s75, v42
	s_mov_b64 s[70:71], 0
	v_cndmask_b32_e32 v43, 0, v46, vcc
	v_bfe_u32 v44, v43, 16, 1
	v_cmp_eq_u32_e32 vcc, 1, v109
	v_add3_u32 v43, v43, v44, s89
	v_lshrrev_b32_e32 v43, 16, v43
	v_cndmask_b32_e32 v44, 0, v47, vcc
	v_bfe_u32 v45, v44, 16, 1
	v_add3_u32 v44, v44, v45, s89
	v_and_or_b32 v43, v44, s75, v43
	global_load_dwordx4 v[44:47], v[32:33], off offset:80
	s_andn2_b64 vcc, exec, s[0:1]
	s_waitcnt lgkmcnt(0)
	v_mfma_f32_32x32x16_bf16 v[16:31], v[36:39], v[40:43], v[16:31]
	ds_read2_b64 v[36:39], v110 offset0:196 offset1:198
	s_mov_b32 s76, 1
	s_waitcnt vmcnt(5)
	v_bfe_u32 v71, v91, 16, 1
	v_add3_u32 v71, v91, v71, s89
	s_waitcnt lgkmcnt(0)
	v_mfma_f32_32x32x16_bf16 v[0:15], v[36:39], v[40:43], v[0:15]
	s_waitcnt vmcnt(4)
	v_bfe_u32 v36, v92, 16, 1
	v_add3_u32 v36, v92, v36, s89
	v_bfe_u32 v37, v93, 16, 1
	v_lshrrev_b32_e32 v36, 16, v36
	v_add3_u32 v37, v93, v37, s89
	v_and_or_b32 v36, v37, s75, v36
	v_bfe_u32 v37, v94, 16, 1
	v_add3_u32 v37, v94, v37, s89
	v_bfe_u32 v38, v95, 16, 1
	global_load_dwordx4 v[40:43], v[34:35], off offset:64
	v_lshrrev_b32_e32 v37, 16, v37
	v_add3_u32 v38, v95, v38, s89
	v_and_or_b32 v37, v38, s75, v37
	v_bfe_u32 v38, v88, 16, 1
	v_add3_u32 v38, v88, v38, s89
	v_bfe_u32 v39, v89, 16, 1
	v_lshrrev_b32_e32 v38, 16, v38
	v_add3_u32 v39, v89, v39, s89
	v_and_or_b32 v38, v39, s75, v38
	v_bfe_u32 v39, v90, 16, 1
	v_add3_u32 v39, v90, v39, s89
	global_load_dwordx4 v[88:91], v[34:35], off offset:80
	v_lshrrev_b32_e32 v39, 16, v39
	v_and_or_b32 v39, v71, s75, v39
	global_load_dwordx4 v[92:95], v[32:33], off offset:128
	s_waitcnt vmcnt(6)
	v_bfe_u32 v71, v87, 16, 1
	v_mfma_f32_32x32x16_bf16 v[16:31], v[36:39], v[60:63], v[16:31]
	s_waitcnt vmcnt(5)
	v_bfe_u32 v36, v96, 16, 1
	v_add3_u32 v36, v96, v36, s89
	v_bfe_u32 v37, v97, 16, 1
	v_lshrrev_b32_e32 v36, 16, v36
	v_add3_u32 v37, v97, v37, s89
	v_and_or_b32 v36, v37, s75, v36
	v_bfe_u32 v37, v98, 16, 1
	v_add3_u32 v37, v98, v37, s89
	v_bfe_u32 v38, v99, 16, 1
	v_lshrrev_b32_e32 v37, 16, v37
	v_add3_u32 v38, v99, v38, s89
	v_and_or_b32 v37, v38, s75, v37
	v_bfe_u32 v38, v84, 16, 1
	v_add3_u32 v38, v84, v38, s89
	v_bfe_u32 v39, v85, 16, 1
	v_lshrrev_b32_e32 v38, 16, v38
	v_add3_u32 v39, v85, v39, s89
	v_and_or_b32 v38, v39, s75, v38
	v_bfe_u32 v39, v86, 16, 1
	v_add3_u32 v39, v86, v39, s89
	v_add3_u32 v71, v87, v71, s89
	global_load_dwordx4 v[84:87], v[32:33], off offset:144
	v_lshrrev_b32_e32 v39, 16, v39
	v_and_or_b32 v39, v71, s75, v39
	s_nop 1
	v_mfma_f32_32x32x16_bf16 v[0:15], v[36:39], v[60:63], v[0:15]
	s_waitcnt vmcnt(5)
	v_bfe_u32 v36, v100, 16, 1
	global_load_dwordx4 v[60:63], v[34:35], off offset:144
	global_load_dwordx4 v[96:99], v[34:35], off offset:128
	v_add3_u32 v36, v100, v36, s89
	v_bfe_u32 v37, v101, 16, 1
	v_lshrrev_b32_e32 v36, 16, v36
	v_add3_u32 v37, v101, v37, s89
	v_and_or_b32 v36, v37, s75, v36
	v_bfe_u32 v37, v102, 16, 1
	v_add3_u32 v37, v102, v37, s89
	v_bfe_u32 v38, v103, 16, 1
	v_lshrrev_b32_e32 v37, 16, v37
	v_add3_u32 v38, v103, v38, s89
	v_and_or_b32 v37, v38, s75, v37
	s_waitcnt vmcnt(6)
	v_bfe_u32 v38, v44, 16, 1
	v_add3_u32 v38, v44, v38, s89
	v_bfe_u32 v39, v45, 16, 1
	v_lshrrev_b32_e32 v38, 16, v38
	v_add3_u32 v39, v45, v39, s89
	v_and_or_b32 v38, v39, s75, v38
	v_bfe_u32 v39, v46, 16, 1
	v_add3_u32 v39, v46, v39, s89
	v_bfe_u32 v44, v47, 16, 1
	v_lshrrev_b32_e32 v39, 16, v39
	v_add3_u32 v44, v47, v44, s89
	v_and_or_b32 v39, v44, s75, v39
	global_load_dwordx4 v[44:47], v[32:33], off offset:208
	global_load_dwordx4 v[100:103], v[32:33], off offset:192
	v_mfma_f32_32x32x16_bf16 v[16:31], v[36:39], v[56:59], v[16:31]
	s_waitcnt vmcnt(7)
	v_bfe_u32 v36, v40, 16, 1
	v_add3_u32 v36, v40, v36, s89
	v_bfe_u32 v37, v41, 16, 1
	v_lshrrev_b32_e32 v36, 16, v36
	v_add3_u32 v37, v41, v37, s89
	v_and_or_b32 v36, v37, s75, v36
	v_bfe_u32 v37, v42, 16, 1
	v_add3_u32 v37, v42, v37, s89
	v_bfe_u32 v38, v43, 16, 1
	v_lshrrev_b32_e32 v37, 16, v37
	v_add3_u32 v32, v43, v38, s89
	v_and_or_b32 v37, v32, s75, v37
	s_waitcnt vmcnt(6)
	v_bfe_u32 v32, v88, 16, 1
	v_add3_u32 v32, v88, v32, s89
	v_bfe_u32 v33, v89, 16, 1
	v_lshrrev_b32_e32 v32, 16, v32
	v_add3_u32 v33, v89, v33, s89
	v_and_or_b32 v38, v33, s75, v32
	v_bfe_u32 v32, v90, 16, 1
	v_add3_u32 v32, v90, v32, s89
	v_bfe_u32 v33, v91, 16, 1
	v_lshrrev_b32_e32 v32, 16, v32
	v_add3_u32 v33, v91, v33, s89
	v_and_or_b32 v39, v33, s75, v32
	s_waitcnt vmcnt(5)
	v_bfe_u32 v32, v92, 16, 1
	v_add3_u32 v32, v92, v32, s89
	v_mfma_f32_32x32x16_bf16 v[0:15], v[36:39], v[56:59], v[0:15]
	global_load_dwordx4 v[36:39], v[34:35], off offset:208
	global_load_dwordx4 v[40:43], v[34:35], off offset:192
	v_bfe_u32 v33, v93, 16, 1
	v_lshrrev_b32_e32 v32, 16, v32
	v_add3_u32 v33, v93, v33, s89
	v_and_or_b32 v32, v33, s75, v32
	v_bfe_u32 v33, v94, 16, 1
	v_add3_u32 v33, v94, v33, s89
	v_bfe_u32 v34, v95, 16, 1
	v_lshrrev_b32_e32 v33, 16, v33
	v_add3_u32 v34, v95, v34, s89
	v_and_or_b32 v33, v34, s75, v33
	s_waitcnt vmcnt(6)
	v_bfe_u32 v34, v84, 16, 1
	v_add3_u32 v34, v84, v34, s89
	v_bfe_u32 v35, v85, 16, 1
	v_lshrrev_b32_e32 v34, 16, v34
	v_add3_u32 v35, v85, v35, s89
	v_and_or_b32 v34, v35, s75, v34
	v_bfe_u32 v35, v86, 16, 1
	v_add3_u32 v35, v86, v35, s89
	v_bfe_u32 v56, v87, 16, 1
	v_lshrrev_b32_e32 v35, 16, v35
	v_add3_u32 v56, v87, v56, s89
	v_and_or_b32 v35, v56, s75, v35
	s_waitcnt vmcnt(5)
	v_bfe_u32 v56, v63, 16, 1
	v_add3_u32 v56, v63, v56, s89
	v_mfma_f32_32x32x16_bf16 v[16:31], v[32:35], v[52:55], v[16:31]
	s_waitcnt vmcnt(4)
	v_bfe_u32 v32, v96, 16, 1
	v_add3_u32 v32, v96, v32, s89
	v_bfe_u32 v33, v97, 16, 1
	v_lshrrev_b32_e32 v32, 16, v32
	v_add3_u32 v33, v97, v33, s89
	v_and_or_b32 v32, v33, s75, v32
	v_bfe_u32 v33, v98, 16, 1
	v_add3_u32 v33, v98, v33, s89
	v_bfe_u32 v34, v99, 16, 1
	v_lshrrev_b32_e32 v33, 16, v33
	v_add3_u32 v34, v99, v34, s89
	v_and_or_b32 v33, v34, s75, v33
	v_bfe_u32 v34, v60, 16, 1
	v_add3_u32 v34, v60, v34, s89
	v_bfe_u32 v35, v61, 16, 1
	v_lshrrev_b32_e32 v34, 16, v34
	v_add3_u32 v35, v61, v35, s89
	v_and_or_b32 v34, v35, s75, v34
	v_bfe_u32 v35, v62, 16, 1
	v_add3_u32 v35, v62, v35, s89
	v_lshrrev_b32_e32 v35, 16, v35
	v_and_or_b32 v35, v56, s75, v35
	s_nop 1
	v_mfma_f32_32x32x16_bf16 v[0:15], v[32:35], v[52:55], v[0:15]
	s_waitcnt vmcnt(2)
	v_bfe_u32 v32, v100, 16, 1
	v_add3_u32 v32, v100, v32, s89
	v_bfe_u32 v33, v101, 16, 1
	v_lshrrev_b32_e32 v32, 16, v32
	v_add3_u32 v33, v101, v33, s89
	v_and_or_b32 v32, v33, s75, v32
	v_bfe_u32 v33, v102, 16, 1
	v_add3_u32 v33, v102, v33, s89
	v_bfe_u32 v34, v103, 16, 1
	v_lshrrev_b32_e32 v33, 16, v33
	v_add3_u32 v34, v103, v34, s89
	v_and_or_b32 v33, v34, s75, v33
	v_bfe_u32 v34, v44, 16, 1
	v_add3_u32 v34, v44, v34, s89
	v_bfe_u32 v35, v45, 16, 1
	v_lshrrev_b32_e32 v34, 16, v34
	v_add3_u32 v35, v45, v35, s89
	v_and_or_b32 v34, v35, s75, v34
	v_bfe_u32 v35, v46, 16, 1
	v_add3_u32 v35, v46, v35, s89
	v_bfe_u32 v44, v47, 16, 1
	v_lshrrev_b32_e32 v35, 16, v35
	v_add3_u32 v44, v47, v44, s89
	v_and_or_b32 v35, v44, s75, v35
	s_nop 1
	v_mfma_f32_32x32x16_bf16 v[16:31], v[32:35], v[48:51], v[16:31]
	s_waitcnt vmcnt(0)
	v_bfe_u32 v32, v40, 16, 1
	v_add3_u32 v32, v40, v32, s89
	v_bfe_u32 v33, v41, 16, 1
	v_lshrrev_b32_e32 v32, 16, v32
	v_add3_u32 v33, v41, v33, s89
	v_and_or_b32 v32, v33, s75, v32
	v_bfe_u32 v33, v42, 16, 1
	v_add3_u32 v33, v42, v33, s89
	v_bfe_u32 v34, v43, 16, 1
	v_lshrrev_b32_e32 v33, 16, v33
	v_add3_u32 v34, v43, v34, s89
	v_and_or_b32 v33, v34, s75, v33
	v_bfe_u32 v34, v36, 16, 1
	v_add3_u32 v34, v36, v34, s89
	v_bfe_u32 v35, v37, 16, 1
	v_lshrrev_b32_e32 v34, 16, v34
	v_add3_u32 v35, v37, v35, s89
	v_and_or_b32 v34, v35, s75, v34
	v_bfe_u32 v35, v38, 16, 1
	v_add3_u32 v35, v38, v35, s89
	v_bfe_u32 v36, v39, 16, 1
	v_lshrrev_b32_e32 v35, 16, v35
	v_add3_u32 v36, v39, v36, s89
	v_and_or_b32 v35, v36, s75, v35
	s_nop 1
	v_mfma_f32_32x32x16_bf16 v[0:15], v[32:35], v[48:51], v[0:15]
	s_cbranch_vccz .LBB0_1194

.LBB0_1205:
	s_or_b64 exec, exec, s[82:83]
	v_cndmask_b32_e64 v115, v116, v117, s[68:69]
	v_mul_f32_e32 v116, v34, v115
	v_add_f32_e32 v115, 0, v118
	v_mul_f32_e32 v117, 0x3fb8aa3b, v115
	v_exp_f32_e32 v117, v117
	s_mulk_i32 s20, 0x48
	s_waitcnt vmcnt(61)
	v_cmp_le_f32_e64 s[68:69], 0, v113
	v_mul_f32_e32 v114, v114, v117
	v_cvt_pk_bf16_f32 v114, v114, v114
	v_add_u32_e32 v117, s20, v66
	v_lshl_add_u32 v117, v117, 1, v76
	ds_write_b16 v117, v114
	v_mul_f32_e32 v114, 0xbfb8aa3b, v115
	v_exp_f32_e32 v114, v114
	s_nop 0
	v_mul_f32_e32 v114, v116, v114
	v_cvt_pk_bf16_f32 v114, v114, v114
	ds_write_b16 v117, v114 offset:4608
	v_mul_f32_e64 v114, |v113|, s81
	v_exp_f32_e32 v116, v114
	s_nop 0
	v_add_f32_e32 v118, 1.0, v116
	v_rcp_f32_e32 v114, v118
	s_nop 0
	v_mul_f32_e32 v116, v116, v114
	s_and_saveexec_b64 s[0:1], vcc
	s_xor_b64 s[82:83], exec, s[0:1]
	s_cbranch_execz .LBB0_1207
	v_cndmask_b32_e64 v113, v116, v114, s[68:69]
	v_fma_f32 v113, v34, v113, v32
	v_cmp_gt_f32_e64 s[0:1], s92, v113
	s_nop 1
	v_cndmask_b32_e64 v117, 0, 32, s[0:1]
	v_ldexp_f32 v113, v113, v117
	v_log_f32_e32 v113, v113
	s_nop 0
	v_mul_f32_e32 v117, 0x3f317217, v113
	v_fma_f32 v117, v113, s96, -v117
	v_fmac_f32_e32 v117, 0x3377d1cf, v113
	v_fmac_f32_e32 v117, 0x3f317217, v113
	v_cmp_lt_f32_e64 s[72:73], |v113|, s33
	s_nop 1
	v_cndmask_b32_e64 v113, v113, v117, s[72:73]
	v_cndmask_b32_e64 v117, 0, v249, s[0:1]
	v_sub_f32_e32 v117, v113, v117

.LBB0_1209:
	s_or_b64 exec, exec, s[82:83]
	v_cndmask_b32_e64 v113, v114, v116, s[68:69]
	v_mul_f32_e32 v114, v34, v113
	v_add_f32_e32 v113, v115, v117
	v_mul_f32_e32 v115, 0x3fb8aa3b, v113
	v_exp_f32_e32 v115, v115
	s_mulk_i32 s19, 0x48
	s_waitcnt vmcnt(59)
	v_cmp_le_f32_e64 s[68:69], 0, v111
	v_mul_f32_e32 v112, v112, v115
	v_cvt_pk_bf16_f32 v112, v112, v112
	v_add_u32_e32 v115, s19, v66
	v_lshl_add_u32 v115, v115, 1, v76
	ds_write_b16 v115, v112
	v_mul_f32_e32 v112, 0xbfb8aa3b, v113
	v_exp_f32_e32 v112, v112
	s_nop 0
	v_mul_f32_e32 v112, v114, v112
	v_cvt_pk_bf16_f32 v112, v112, v112
	ds_write_b16 v115, v112 offset:4608
	v_mul_f32_e64 v112, |v111|, s81
	v_exp_f32_e32 v114, v112
	s_nop 0
	v_add_f32_e32 v116, 1.0, v114
	v_rcp_f32_e32 v112, v116
	s_nop 0
	v_mul_f32_e32 v114, v114, v112
	s_and_saveexec_b64 s[0:1], vcc
	s_xor_b64 s[82:83], exec, s[0:1]
	s_cbranch_execz .LBB0_1211
	v_cndmask_b32_e64 v111, v114, v112, s[68:69]
	v_fma_f32 v111, v34, v111, v32
	v_cmp_gt_f32_e64 s[0:1], s92, v111
	s_nop 1
	v_cndmask_b32_e64 v115, 0, 32, s[0:1]
	v_ldexp_f32 v111, v111, v115
	v_log_f32_e32 v111, v111
	s_nop 0
	v_mul_f32_e32 v115, 0x3f317217, v111
	v_fma_f32 v115, v111, s96, -v115
	v_fmac_f32_e32 v115, 0x3377d1cf, v111
	v_fmac_f32_e32 v115, 0x3f317217, v111
	v_cmp_lt_f32_e64 s[72:73], |v111|, s33
	s_nop 1
	v_cndmask_b32_e64 v111, v111, v115, s[72:73]
	v_cndmask_b32_e64 v115, 0, v249, s[0:1]
	v_sub_f32_e32 v115, v111, v115

.LBB0_1213:
	s_or_b64 exec, exec, s[82:83]
	v_cndmask_b32_e64 v111, v112, v114, s[68:69]
	v_mul_f32_e32 v112, v34, v111
	v_add_f32_e32 v111, v113, v115
	v_mul_f32_e32 v113, 0x3fb8aa3b, v111
	v_exp_f32_e32 v113, v113
	s_mulk_i32 s18, 0x48
	s_waitcnt vmcnt(57)
	v_cmp_le_f32_e64 s[68:69], 0, v109
	v_mul_f32_e32 v110, v110, v113
	v_cvt_pk_bf16_f32 v110, v110, v110
	v_add_u32_e32 v113, s18, v66
	v_lshl_add_u32 v113, v113, 1, v76
	ds_write_b16 v113, v110
	v_mul_f32_e32 v110, 0xbfb8aa3b, v111
	v_exp_f32_e32 v110, v110
	s_nop 0
	v_mul_f32_e32 v110, v112, v110
	v_cvt_pk_bf16_f32 v110, v110, v110
	ds_write_b16 v113, v110 offset:4608
	v_mul_f32_e64 v110, |v109|, s81
	v_exp_f32_e32 v112, v110
	s_nop 0
	v_add_f32_e32 v114, 1.0, v112
	v_rcp_f32_e32 v110, v114
	s_nop 0
	v_mul_f32_e32 v112, v112, v110
	s_and_saveexec_b64 s[0:1], vcc
	s_xor_b64 s[82:83], exec, s[0:1]
	s_cbranch_execz .LBB0_1215
	v_cndmask_b32_e64 v109, v112, v110, s[68:69]
	v_fma_f32 v109, v34, v109, v32
	v_cmp_gt_f32_e64 s[0:1], s92, v109
	s_nop 1
	v_cndmask_b32_e64 v113, 0, 32, s[0:1]
	v_ldexp_f32 v109, v109, v113
	v_log_f32_e32 v109, v109
	s_nop 0
	v_mul_f32_e32 v113, 0x3f317217, v109
	v_fma_f32 v113, v109, s96, -v113
	v_fmac_f32_e32 v113, 0x3377d1cf, v109
	v_fmac_f32_e32 v113, 0x3f317217, v109
	v_cmp_lt_f32_e64 s[72:73], |v109|, s33
	s_nop 1
	v_cndmask_b32_e64 v109, v109, v113, s[72:73]
	v_cndmask_b32_e64 v113, 0, v249, s[0:1]
	v_sub_f32_e32 v113, v109, v113

.LBB0_1217:
	s_or_b64 exec, exec, s[82:83]
	v_cndmask_b32_e64 v109, v110, v112, s[68:69]
	v_mul_f32_e32 v110, v34, v109
	v_add_f32_e32 v109, v111, v113
	v_mul_f32_e32 v111, 0x3fb8aa3b, v109
	v_exp_f32_e32 v111, v111
	s_mulk_i32 s17, 0x48
	s_waitcnt vmcnt(55)
	v_cmp_le_f32_e64 s[68:69], 0, v107
	v_mul_f32_e32 v108, v108, v111
	v_cvt_pk_bf16_f32 v108, v108, v108
	v_add_u32_e32 v111, s17, v66
	v_lshl_add_u32 v111, v111, 1, v76
	ds_write_b16 v111, v108
	v_mul_f32_e32 v108, 0xbfb8aa3b, v109
	v_exp_f32_e32 v108, v108
	s_nop 0
	v_mul_f32_e32 v108, v110, v108
	v_cvt_pk_bf16_f32 v108, v108, v108
	ds_write_b16 v111, v108 offset:4608
	v_mul_f32_e64 v108, |v107|, s81
	v_exp_f32_e32 v110, v108
	s_nop 0
	v_add_f32_e32 v112, 1.0, v110
	v_rcp_f32_e32 v108, v112
	s_nop 0
	v_mul_f32_e32 v110, v110, v108
	s_and_saveexec_b64 s[0:1], vcc
	s_xor_b64 s[82:83], exec, s[0:1]
	s_cbranch_execz .LBB0_1219
	v_cndmask_b32_e64 v107, v110, v108, s[68:69]
	v_fma_f32 v107, v34, v107, v32
	v_cmp_gt_f32_e64 s[0:1], s92, v107
	s_nop 1
	v_cndmask_b32_e64 v111, 0, 32, s[0:1]
	v_ldexp_f32 v107, v107, v111
	v_log_f32_e32 v107, v107
	s_nop 0
	v_mul_f32_e32 v111, 0x3f317217, v107
	v_fma_f32 v111, v107, s96, -v111
	v_fmac_f32_e32 v111, 0x3377d1cf, v107
	v_fmac_f32_e32 v111, 0x3f317217, v107
	v_cmp_lt_f32_e64 s[72:73], |v107|, s33
	s_nop 1
	v_cndmask_b32_e64 v107, v107, v111, s[72:73]
	v_cndmask_b32_e64 v111, 0, v249, s[0:1]
	v_sub_f32_e32 v111, v107, v111

.LBB0_1221:
	s_or_b64 exec, exec, s[82:83]
	v_cndmask_b32_e64 v107, v108, v110, s[68:69]
	v_mul_f32_e32 v108, v34, v107
	v_add_f32_e32 v107, v109, v111
	v_mul_f32_e32 v109, 0x3fb8aa3b, v107
	v_exp_f32_e32 v109, v109
	s_mulk_i32 s16, 0x48
	s_waitcnt vmcnt(53)
	v_cmp_le_f32_e64 s[68:69], 0, v105
	v_mul_f32_e32 v106, v106, v109
	v_cvt_pk_bf16_f32 v106, v106, v106
	v_add_u32_e32 v109, s16, v66
	v_lshl_add_u32 v109, v109, 1, v76
	ds_write_b16 v109, v106
	v_mul_f32_e32 v106, 0xbfb8aa3b, v107
	v_exp_f32_e32 v106, v106
	s_nop 0
	v_mul_f32_e32 v106, v108, v106
	v_cvt_pk_bf16_f32 v106, v106, v106
	ds_write_b16 v109, v106 offset:4608
	v_mul_f32_e64 v106, |v105|, s81
	v_exp_f32_e32 v108, v106
	s_nop 0
	v_add_f32_e32 v110, 1.0, v108
	v_rcp_f32_e32 v106, v110
	s_nop 0
	v_mul_f32_e32 v108, v108, v106
	s_and_saveexec_b64 s[0:1], vcc
	s_xor_b64 s[82:83], exec, s[0:1]
	s_cbranch_execz .LBB0_1223
	v_cndmask_b32_e64 v105, v108, v106, s[68:69]
	v_fma_f32 v105, v34, v105, v32
	v_cmp_gt_f32_e64 s[0:1], s92, v105
	s_nop 1
	v_cndmask_b32_e64 v109, 0, 32, s[0:1]
	v_ldexp_f32 v105, v105, v109
	v_log_f32_e32 v105, v105
	s_nop 0
	v_mul_f32_e32 v109, 0x3f317217, v105
	v_fma_f32 v109, v105, s96, -v109
	v_fmac_f32_e32 v109, 0x3377d1cf, v105
	v_fmac_f32_e32 v109, 0x3f317217, v105
	v_cmp_lt_f32_e64 s[72:73], |v105|, s33
	s_nop 1
	v_cndmask_b32_e64 v105, v105, v109, s[72:73]
	v_cndmask_b32_e64 v109, 0, v249, s[0:1]
	v_sub_f32_e32 v109, v105, v109

.LBB0_1225:
	s_or_b64 exec, exec, s[82:83]
	v_cndmask_b32_e64 v105, v106, v108, s[68:69]
	v_mul_f32_e32 v106, v34, v105
	v_add_f32_e32 v105, v107, v109
	v_mul_f32_e32 v107, 0x3fb8aa3b, v105
	v_exp_f32_e32 v107, v107
	s_mulk_i32 s15, 0x48
	s_waitcnt vmcnt(51)
	v_cmp_le_f32_e64 s[68:69], 0, v103
	v_mul_f32_e32 v104, v104, v107
	v_cvt_pk_bf16_f32 v104, v104, v104
	v_add_u32_e32 v107, s15, v66
	v_lshl_add_u32 v107, v107, 1, v76
	ds_write_b16 v107, v104
	v_mul_f32_e32 v104, 0xbfb8aa3b, v105
	v_exp_f32_e32 v104, v104
	s_nop 0
	v_mul_f32_e32 v104, v106, v104
	v_cvt_pk_bf16_f32 v104, v104, v104
	ds_write_b16 v107, v104 offset:4608
	v_mul_f32_e64 v104, |v103|, s81
	v_exp_f32_e32 v106, v104
	s_nop 0
	v_add_f32_e32 v108, 1.0, v106
	v_rcp_f32_e32 v104, v108
	s_nop 0
	v_mul_f32_e32 v106, v106, v104
	s_and_saveexec_b64 s[0:1], vcc
	s_xor_b64 s[82:83], exec, s[0:1]
	s_cbranch_execz .LBB0_1227
	v_cndmask_b32_e64 v103, v106, v104, s[68:69]
	v_fma_f32 v103, v34, v103, v32
	v_cmp_gt_f32_e64 s[0:1], s92, v103
	s_nop 1
	v_cndmask_b32_e64 v107, 0, 32, s[0:1]
	v_ldexp_f32 v103, v103, v107
	v_log_f32_e32 v103, v103
	s_nop 0
	v_mul_f32_e32 v107, 0x3f317217, v103
	v_fma_f32 v107, v103, s96, -v107
	v_fmac_f32_e32 v107, 0x3377d1cf, v103
	v_fmac_f32_e32 v107, 0x3f317217, v103
	v_cmp_lt_f32_e64 s[72:73], |v103|, s33
	s_nop 1
	v_cndmask_b32_e64 v103, v103, v107, s[72:73]
	v_cndmask_b32_e64 v107, 0, v249, s[0:1]
	v_sub_f32_e32 v107, v103, v107

.LBB0_1229:
	s_or_b64 exec, exec, s[82:83]
	v_cndmask_b32_e64 v103, v104, v106, s[68:69]
	v_mul_f32_e32 v104, v34, v103
	v_add_f32_e32 v103, v105, v107
	v_mul_f32_e32 v105, 0x3fb8aa3b, v103
	v_exp_f32_e32 v105, v105
	s_mulk_i32 s14, 0x48
	s_waitcnt vmcnt(49)
	v_cmp_le_f32_e64 s[68:69], 0, v101
	v_mul_f32_e32 v102, v102, v105
	v_cvt_pk_bf16_f32 v102, v102, v102
	v_add_u32_e32 v105, s14, v66
	v_lshl_add_u32 v105, v105, 1, v76
	ds_write_b16 v105, v102
	v_mul_f32_e32 v102, 0xbfb8aa3b, v103
	v_exp_f32_e32 v102, v102
	s_nop 0
	v_mul_f32_e32 v102, v104, v102
	v_cvt_pk_bf16_f32 v102, v102, v102
	ds_write_b16 v105, v102 offset:4608
	v_mul_f32_e64 v102, |v101|, s81
	v_exp_f32_e32 v104, v102
	s_nop 0
	v_add_f32_e32 v106, 1.0, v104
	v_rcp_f32_e32 v102, v106
	s_nop 0
	v_mul_f32_e32 v104, v104, v102
	s_and_saveexec_b64 s[0:1], vcc
	s_xor_b64 s[82:83], exec, s[0:1]
	s_cbranch_execz .LBB0_1231
	v_cndmask_b32_e64 v101, v104, v102, s[68:69]
	v_fma_f32 v101, v34, v101, v32
	v_cmp_gt_f32_e64 s[0:1], s92, v101
	s_nop 1
	v_cndmask_b32_e64 v105, 0, 32, s[0:1]
	v_ldexp_f32 v101, v101, v105
	v_log_f32_e32 v101, v101
	s_nop 0
	v_mul_f32_e32 v105, 0x3f317217, v101
	v_fma_f32 v105, v101, s96, -v105
	v_fmac_f32_e32 v105, 0x3377d1cf, v101
	v_fmac_f32_e32 v105, 0x3f317217, v101
	v_cmp_lt_f32_e64 s[72:73], |v101|, s33
	s_nop 1
	v_cndmask_b32_e64 v101, v101, v105, s[72:73]
	v_cndmask_b32_e64 v105, 0, v249, s[0:1]
	v_sub_f32_e32 v105, v101, v105

.LBB0_1233:
	s_or_b64 exec, exec, s[82:83]
	v_cndmask_b32_e64 v101, v102, v104, s[68:69]
	v_mul_f32_e32 v102, v34, v101
	v_add_f32_e32 v101, v103, v105
	v_mul_f32_e32 v103, 0x3fb8aa3b, v101
	v_exp_f32_e32 v103, v103
	s_mulk_i32 s13, 0x48
	s_waitcnt vmcnt(47)
	v_cmp_le_f32_e64 s[68:69], 0, v99
	v_mul_f32_e32 v100, v100, v103
	v_cvt_pk_bf16_f32 v100, v100, v100
	v_add_u32_e32 v103, s13, v66
	v_lshl_add_u32 v103, v103, 1, v76
	ds_write_b16 v103, v100
	v_mul_f32_e32 v100, 0xbfb8aa3b, v101
	v_exp_f32_e32 v100, v100
	s_nop 0
	v_mul_f32_e32 v100, v102, v100
	v_cvt_pk_bf16_f32 v100, v100, v100
	ds_write_b16 v103, v100 offset:4608
	v_mul_f32_e64 v100, |v99|, s81
	v_exp_f32_e32 v102, v100
	s_nop 0
	v_add_f32_e32 v104, 1.0, v102
	v_rcp_f32_e32 v100, v104
	s_nop 0
	v_mul_f32_e32 v102, v102, v100
	s_and_saveexec_b64 s[0:1], vcc
	s_xor_b64 s[82:83], exec, s[0:1]
	s_cbranch_execz .LBB0_1235
	v_cndmask_b32_e64 v99, v102, v100, s[68:69]
	v_fma_f32 v99, v34, v99, v32
	v_cmp_gt_f32_e64 s[0:1], s92, v99
	s_nop 1
	v_cndmask_b32_e64 v103, 0, 32, s[0:1]
	v_ldexp_f32 v99, v99, v103
	v_log_f32_e32 v99, v99
	s_nop 0
	v_mul_f32_e32 v103, 0x3f317217, v99
	v_fma_f32 v103, v99, s96, -v103
	v_fmac_f32_e32 v103, 0x3377d1cf, v99
	v_fmac_f32_e32 v103, 0x3f317217, v99
	v_cmp_lt_f32_e64 s[72:73], |v99|, s33
	s_nop 1
	v_cndmask_b32_e64 v99, v99, v103, s[72:73]
	v_cndmask_b32_e64 v103, 0, v249, s[0:1]
	v_sub_f32_e32 v103, v99, v103

.LBB0_1237:
	s_or_b64 exec, exec, s[82:83]
	v_cndmask_b32_e64 v99, v100, v102, s[68:69]
	v_mul_f32_e32 v100, v34, v99
	v_add_f32_e32 v99, v101, v103
	v_mul_f32_e32 v101, 0x3fb8aa3b, v99
	v_exp_f32_e32 v101, v101
	s_mulk_i32 s12, 0x48
	s_waitcnt vmcnt(45)
	v_cmp_le_f32_e64 s[68:69], 0, v97
	v_mul_f32_e32 v98, v98, v101
	v_cvt_pk_bf16_f32 v98, v98, v98
	v_add_u32_e32 v101, s12, v66
	v_lshl_add_u32 v101, v101, 1, v76
	ds_write_b16 v101, v98
	v_mul_f32_e32 v98, 0xbfb8aa3b, v99
	v_exp_f32_e32 v98, v98
	s_nop 0
	v_mul_f32_e32 v98, v100, v98
	v_cvt_pk_bf16_f32 v98, v98, v98
	ds_write_b16 v101, v98 offset:4608
	v_mul_f32_e64 v98, |v97|, s81
	v_exp_f32_e32 v100, v98
	s_nop 0
	v_add_f32_e32 v102, 1.0, v100
	v_rcp_f32_e32 v98, v102
	s_nop 0
	v_mul_f32_e32 v100, v100, v98
	s_and_saveexec_b64 s[0:1], vcc
	s_xor_b64 s[82:83], exec, s[0:1]
	s_cbranch_execz .LBB0_1239
	v_cndmask_b32_e64 v97, v100, v98, s[68:69]
	v_fma_f32 v97, v34, v97, v32
	v_cmp_gt_f32_e64 s[0:1], s92, v97
	s_nop 1
	v_cndmask_b32_e64 v101, 0, 32, s[0:1]
	v_ldexp_f32 v97, v97, v101
	v_log_f32_e32 v97, v97
	s_nop 0
	v_mul_f32_e32 v101, 0x3f317217, v97
	v_fma_f32 v101, v97, s96, -v101
	v_fmac_f32_e32 v101, 0x3377d1cf, v97
	v_fmac_f32_e32 v101, 0x3f317217, v97
	v_cmp_lt_f32_e64 s[72:73], |v97|, s33
	s_nop 1
	v_cndmask_b32_e64 v97, v97, v101, s[72:73]
	v_cndmask_b32_e64 v101, 0, v249, s[0:1]
	v_sub_f32_e32 v101, v97, v101

.LBB0_1241:
	s_or_b64 exec, exec, s[82:83]
	v_cndmask_b32_e64 v97, v98, v100, s[68:69]
	v_mul_f32_e32 v98, v34, v97
	v_add_f32_e32 v97, v99, v101
	v_mul_f32_e32 v99, 0x3fb8aa3b, v97
	v_exp_f32_e32 v99, v99
	s_mulk_i32 s11, 0x48
	s_waitcnt vmcnt(43)
	v_cmp_le_f32_e64 s[68:69], 0, v95
	v_mul_f32_e32 v96, v96, v99
	v_cvt_pk_bf16_f32 v96, v96, v96
	v_add_u32_e32 v99, s11, v66
	v_lshl_add_u32 v99, v99, 1, v76
	ds_write_b16 v99, v96
	v_mul_f32_e32 v96, 0xbfb8aa3b, v97
	v_exp_f32_e32 v96, v96
	s_nop 0
	v_mul_f32_e32 v96, v98, v96
	v_cvt_pk_bf16_f32 v96, v96, v96
	ds_write_b16 v99, v96 offset:4608
	v_mul_f32_e64 v96, |v95|, s81
	v_exp_f32_e32 v98, v96
	s_nop 0
	v_add_f32_e32 v100, 1.0, v98
	v_rcp_f32_e32 v96, v100
	s_nop 0
	v_mul_f32_e32 v98, v98, v96
	s_and_saveexec_b64 s[0:1], vcc
	s_xor_b64 s[82:83], exec, s[0:1]
	s_cbranch_execz .LBB0_1243
	v_cndmask_b32_e64 v95, v98, v96, s[68:69]
	v_fma_f32 v95, v34, v95, v32
	v_cmp_gt_f32_e64 s[0:1], s92, v95
	s_nop 1
	v_cndmask_b32_e64 v99, 0, 32, s[0:1]
	v_ldexp_f32 v95, v95, v99
	v_log_f32_e32 v95, v95
	s_nop 0
	v_mul_f32_e32 v99, 0x3f317217, v95
	v_fma_f32 v99, v95, s96, -v99
	v_fmac_f32_e32 v99, 0x3377d1cf, v95
	v_fmac_f32_e32 v99, 0x3f317217, v95
	v_cmp_lt_f32_e64 s[72:73], |v95|, s33
	s_nop 1
	v_cndmask_b32_e64 v95, v95, v99, s[72:73]
	v_cndmask_b32_e64 v99, 0, v249, s[0:1]
	v_sub_f32_e32 v99, v95, v99

.LBB0_1245:
	s_or_b64 exec, exec, s[82:83]
	v_cndmask_b32_e64 v95, v96, v98, s[68:69]
	v_mul_f32_e32 v96, v34, v95
	v_add_f32_e32 v95, v97, v99
	v_mul_f32_e32 v97, 0x3fb8aa3b, v95
	v_exp_f32_e32 v97, v97
	s_mulk_i32 s10, 0x48
	s_waitcnt vmcnt(41)
	v_cmp_le_f32_e64 s[68:69], 0, v93
	v_mul_f32_e32 v94, v94, v97
	v_cvt_pk_bf16_f32 v94, v94, v94
	v_add_u32_e32 v97, s10, v66
	v_lshl_add_u32 v97, v97, 1, v76
	ds_write_b16 v97, v94
	v_mul_f32_e32 v94, 0xbfb8aa3b, v95
	v_exp_f32_e32 v94, v94
	s_nop 0
	v_mul_f32_e32 v94, v96, v94
	v_cvt_pk_bf16_f32 v94, v94, v94
	ds_write_b16 v97, v94 offset:4608
	v_mul_f32_e64 v94, |v93|, s81
	v_exp_f32_e32 v96, v94
	s_nop 0
	v_add_f32_e32 v98, 1.0, v96
	v_rcp_f32_e32 v94, v98
	s_nop 0
	v_mul_f32_e32 v96, v96, v94
	s_and_saveexec_b64 s[0:1], vcc
	s_xor_b64 s[82:83], exec, s[0:1]
	s_cbranch_execz .LBB0_1247
	v_cndmask_b32_e64 v93, v96, v94, s[68:69]
	v_fma_f32 v93, v34, v93, v32
	v_cmp_gt_f32_e64 s[0:1], s92, v93
	s_nop 1
	v_cndmask_b32_e64 v97, 0, 32, s[0:1]
	v_ldexp_f32 v93, v93, v97
	v_log_f32_e32 v93, v93
	s_nop 0
	v_mul_f32_e32 v97, 0x3f317217, v93
	v_fma_f32 v97, v93, s96, -v97
	v_fmac_f32_e32 v97, 0x3377d1cf, v93
	v_fmac_f32_e32 v97, 0x3f317217, v93
	v_cmp_lt_f32_e64 s[72:73], |v93|, s33
	s_nop 1
	v_cndmask_b32_e64 v93, v93, v97, s[72:73]
	v_cndmask_b32_e64 v97, 0, v249, s[0:1]
	v_sub_f32_e32 v97, v93, v97

.LBB0_1249:
	s_or_b64 exec, exec, s[82:83]
	v_cndmask_b32_e64 v93, v94, v96, s[68:69]
	v_mul_f32_e32 v94, v34, v93
	v_add_f32_e32 v93, v95, v97
	v_mul_f32_e32 v95, 0x3fb8aa3b, v93
	v_exp_f32_e32 v95, v95
	s_mulk_i32 s9, 0x48
	s_waitcnt vmcnt(39)
	v_cmp_le_f32_e64 s[68:69], 0, v91
	v_mul_f32_e32 v92, v92, v95
	v_cvt_pk_bf16_f32 v92, v92, v92
	v_add_u32_e32 v95, s9, v66
	v_lshl_add_u32 v95, v95, 1, v76
	ds_write_b16 v95, v92
	v_mul_f32_e32 v92, 0xbfb8aa3b, v93
	v_exp_f32_e32 v92, v92
	s_nop 0
	v_mul_f32_e32 v92, v94, v92
	v_cvt_pk_bf16_f32 v92, v92, v92
	ds_write_b16 v95, v92 offset:4608
	v_mul_f32_e64 v92, |v91|, s81
	v_exp_f32_e32 v94, v92
	s_nop 0
	v_add_f32_e32 v96, 1.0, v94
	v_rcp_f32_e32 v92, v96
	s_nop 0
	v_mul_f32_e32 v94, v94, v92
	s_and_saveexec_b64 s[0:1], vcc
	s_xor_b64 s[82:83], exec, s[0:1]
	s_cbranch_execz .LBB0_1251
	v_cndmask_b32_e64 v91, v94, v92, s[68:69]
	v_fma_f32 v91, v34, v91, v32
	v_cmp_gt_f32_e64 s[0:1], s92, v91
	s_nop 1
	v_cndmask_b32_e64 v95, 0, 32, s[0:1]
	v_ldexp_f32 v91, v91, v95
	v_log_f32_e32 v91, v91
	s_nop 0
	v_mul_f32_e32 v95, 0x3f317217, v91
	v_fma_f32 v95, v91, s96, -v95
	v_fmac_f32_e32 v95, 0x3377d1cf, v91
	v_fmac_f32_e32 v95, 0x3f317217, v91
	v_cmp_lt_f32_e64 s[72:73], |v91|, s33
	s_nop 1
	v_cndmask_b32_e64 v91, v91, v95, s[72:73]
	v_cndmask_b32_e64 v95, 0, v249, s[0:1]
	v_sub_f32_e32 v95, v91, v95

.LBB0_1253:
	s_or_b64 exec, exec, s[82:83]
	v_cndmask_b32_e64 v91, v92, v94, s[68:69]
	v_mul_f32_e32 v92, v34, v91
	v_add_f32_e32 v91, v93, v95
	v_mul_f32_e32 v93, 0x3fb8aa3b, v91
	v_exp_f32_e32 v93, v93
	s_mulk_i32 s8, 0x48
	s_waitcnt vmcnt(37)
	v_cmp_le_f32_e64 s[68:69], 0, v89
	v_mul_f32_e32 v90, v90, v93
	v_cvt_pk_bf16_f32 v90, v90, v90
	v_add_u32_e32 v93, s8, v66
	v_lshl_add_u32 v93, v93, 1, v76
	ds_write_b16 v93, v90
	v_mul_f32_e32 v90, 0xbfb8aa3b, v91
	v_exp_f32_e32 v90, v90
	s_nop 0
	v_mul_f32_e32 v90, v92, v90
	v_cvt_pk_bf16_f32 v90, v90, v90
	ds_write_b16 v93, v90 offset:4608
	v_mul_f32_e64 v90, |v89|, s81
	v_exp_f32_e32 v92, v90
	s_nop 0
	v_add_f32_e32 v94, 1.0, v92
	v_rcp_f32_e32 v90, v94
	s_nop 0
	v_mul_f32_e32 v92, v92, v90
	s_and_saveexec_b64 s[0:1], vcc
	s_xor_b64 s[82:83], exec, s[0:1]
	s_cbranch_execz .LBB0_1255
	v_cndmask_b32_e64 v89, v92, v90, s[68:69]
	v_fma_f32 v89, v34, v89, v32
	v_cmp_gt_f32_e64 s[0:1], s92, v89
	s_nop 1
	v_cndmask_b32_e64 v93, 0, 32, s[0:1]
	v_ldexp_f32 v89, v89, v93
	v_log_f32_e32 v89, v89
	s_nop 0
	v_mul_f32_e32 v93, 0x3f317217, v89
	v_fma_f32 v93, v89, s96, -v93
	v_fmac_f32_e32 v93, 0x3377d1cf, v89
	v_fmac_f32_e32 v93, 0x3f317217, v89
	v_cmp_lt_f32_e64 s[72:73], |v89|, s33
	s_nop 1
	v_cndmask_b32_e64 v89, v89, v93, s[72:73]
	v_cndmask_b32_e64 v93, 0, v249, s[0:1]
	v_sub_f32_e32 v93, v89, v93

.LBB0_1257:
	s_or_b64 exec, exec, s[82:83]
	v_cndmask_b32_e64 v89, v90, v92, s[68:69]
	v_mul_f32_e32 v90, v34, v89
	v_add_f32_e32 v89, v91, v93
	v_mul_f32_e32 v91, 0x3fb8aa3b, v89
	v_exp_f32_e32 v91, v91
	s_mulk_i32 s7, 0x48
	s_waitcnt vmcnt(35)
	v_cmp_le_f32_e64 s[68:69], 0, v87
	v_mul_f32_e32 v88, v88, v91
	v_cvt_pk_bf16_f32 v88, v88, v88
	v_add_u32_e32 v91, s7, v66
	v_lshl_add_u32 v91, v91, 1, v76
	ds_write_b16 v91, v88
	v_mul_f32_e32 v88, 0xbfb8aa3b, v89
	v_exp_f32_e32 v88, v88
	s_nop 0
	v_mul_f32_e32 v88, v90, v88
	v_cvt_pk_bf16_f32 v88, v88, v88
	ds_write_b16 v91, v88 offset:4608
	v_mul_f32_e64 v88, |v87|, s81
	v_exp_f32_e32 v90, v88
	s_nop 0
	v_add_f32_e32 v92, 1.0, v90
	v_rcp_f32_e32 v88, v92
	s_nop 0
	v_mul_f32_e32 v90, v90, v88
	s_and_saveexec_b64 s[0:1], vcc
	s_xor_b64 s[82:83], exec, s[0:1]
	s_cbranch_execz .LBB0_1259
	v_cndmask_b32_e64 v87, v90, v88, s[68:69]
	v_fma_f32 v87, v34, v87, v32
	v_cmp_gt_f32_e64 s[0:1], s92, v87
	s_nop 1
	v_cndmask_b32_e64 v91, 0, 32, s[0:1]
	v_ldexp_f32 v87, v87, v91
	v_log_f32_e32 v87, v87
	s_nop 0
	v_mul_f32_e32 v91, 0x3f317217, v87
	v_fma_f32 v91, v87, s96, -v91
	v_fmac_f32_e32 v91, 0x3377d1cf, v87
	v_fmac_f32_e32 v91, 0x3f317217, v87
	v_cmp_lt_f32_e64 s[72:73], |v87|, s33
	s_nop 1
	v_cndmask_b32_e64 v87, v87, v91, s[72:73]
	v_cndmask_b32_e64 v91, 0, v249, s[0:1]
	v_sub_f32_e32 v91, v87, v91

.LBB0_1261:
	s_or_b64 exec, exec, s[82:83]
	v_cndmask_b32_e64 v87, v88, v90, s[68:69]
	v_mul_f32_e32 v88, v34, v87
	v_add_f32_e32 v87, v89, v91
	v_mul_f32_e32 v89, 0x3fb8aa3b, v87
	v_exp_f32_e32 v89, v89
	s_mulk_i32 s6, 0x48
	s_waitcnt vmcnt(33)
	v_cmp_le_f32_e64 s[68:69], 0, v85
	v_mul_f32_e32 v86, v86, v89
	v_cvt_pk_bf16_f32 v86, v86, v86
	v_add_u32_e32 v89, s6, v66
	v_lshl_add_u32 v89, v89, 1, v76
	ds_write_b16 v89, v86
	v_mul_f32_e32 v86, 0xbfb8aa3b, v87
	v_exp_f32_e32 v86, v86
	s_nop 0
	v_mul_f32_e32 v86, v88, v86
	v_cvt_pk_bf16_f32 v86, v86, v86
	ds_write_b16 v89, v86 offset:4608
	v_mul_f32_e64 v86, |v85|, s81
	v_exp_f32_e32 v88, v86
	s_nop 0
	v_add_f32_e32 v90, 1.0, v88
	v_rcp_f32_e32 v86, v90
	s_nop 0
	v_mul_f32_e32 v88, v88, v86
	s_and_saveexec_b64 s[0:1], vcc
	s_xor_b64 s[82:83], exec, s[0:1]
	s_cbranch_execz .LBB0_1263
	v_cndmask_b32_e64 v85, v88, v86, s[68:69]
	v_fma_f32 v85, v34, v85, v32
	v_cmp_gt_f32_e64 s[0:1], s92, v85
	s_nop 1
	v_cndmask_b32_e64 v89, 0, 32, s[0:1]
	v_ldexp_f32 v85, v85, v89
	v_log_f32_e32 v85, v85
	s_nop 0
	v_mul_f32_e32 v89, 0x3f317217, v85
	v_fma_f32 v89, v85, s96, -v89
	v_fmac_f32_e32 v89, 0x3377d1cf, v85
	v_fmac_f32_e32 v89, 0x3f317217, v85
	v_cmp_lt_f32_e64 s[72:73], |v85|, s33
	s_nop 1
	v_cndmask_b32_e64 v85, v85, v89, s[72:73]
	v_cndmask_b32_e64 v89, 0, v249, s[0:1]
	v_sub_f32_e32 v89, v85, v89

.LBB0_1265:
	s_or_b64 exec, exec, s[82:83]
	v_cndmask_b32_e64 v85, v86, v88, s[68:69]
	v_mul_f32_e32 v86, v34, v85
	v_add_f32_e32 v85, v87, v89
	v_mul_f32_e32 v87, 0x3fb8aa3b, v85
	v_exp_f32_e32 v87, v87
	s_mulk_i32 s5, 0x48
	s_waitcnt vmcnt(31)
	v_cmp_le_f32_e64 s[68:69], 0, v73
	v_mul_f32_e32 v84, v84, v87
	v_cvt_pk_bf16_f32 v84, v84, v84
	v_add_u32_e32 v87, s5, v66
	v_lshl_add_u32 v87, v87, 1, v76
	ds_write_b16 v87, v84
	v_mul_f32_e32 v84, 0xbfb8aa3b, v85
	v_exp_f32_e32 v84, v84
	s_nop 0
	v_mul_f32_e32 v84, v86, v84
	v_cvt_pk_bf16_f32 v84, v84, v84
	ds_write_b16 v87, v84 offset:4608
	v_mul_f32_e64 v84, |v73|, s81
	v_exp_f32_e32 v86, v84
	s_nop 0
	v_add_f32_e32 v88, 1.0, v86
	v_rcp_f32_e32 v84, v88
	s_nop 0
	v_mul_f32_e32 v86, v86, v84
	s_and_saveexec_b64 s[0:1], vcc
	s_xor_b64 s[82:83], exec, s[0:1]
	s_cbranch_execz .LBB0_1267
	v_cndmask_b32_e64 v73, v86, v84, s[68:69]
	v_fma_f32 v73, v34, v73, v32
	v_cmp_gt_f32_e64 s[0:1], s92, v73
	s_nop 1
	v_cndmask_b32_e64 v87, 0, 32, s[0:1]
	v_ldexp_f32 v73, v73, v87
	v_log_f32_e32 v73, v73
	s_nop 0
	v_mul_f32_e32 v87, 0x3f317217, v73
	v_fma_f32 v87, v73, s96, -v87
	v_fmac_f32_e32 v87, 0x3377d1cf, v73
	v_fmac_f32_e32 v87, 0x3f317217, v73
	v_cmp_lt_f32_e64 s[72:73], |v73|, s33
	s_nop 1
	v_cndmask_b32_e64 v73, v73, v87, s[72:73]
	v_cndmask_b32_e64 v87, 0, v249, s[0:1]
	v_sub_f32_e32 v87, v73, v87

.LBB0_1269:
	s_or_b64 exec, exec, s[82:83]
	v_cndmask_b32_e64 v73, v84, v86, s[68:69]
	v_mul_f32_e32 v84, v34, v73
	v_add_f32_e32 v73, v85, v87
	v_mul_f32_e32 v85, 0x3fb8aa3b, v73
	v_exp_f32_e32 v85, v85
	s_mulk_i32 s4, 0x48
	s_waitcnt vmcnt(29)
	v_cmp_le_f32_e64 s[68:69], 0, v63
	v_mul_f32_e32 v71, v71, v85
	v_cvt_pk_bf16_f32 v71, v71, v71
	v_add_u32_e32 v85, s4, v66
	v_lshl_add_u32 v85, v85, 1, v76
	ds_write_b16 v85, v71
	v_mul_f32_e32 v71, 0xbfb8aa3b, v73
	v_exp_f32_e32 v71, v71
	s_nop 0
	v_mul_f32_e32 v71, v84, v71
	v_cvt_pk_bf16_f32 v71, v71, v71
	ds_write_b16 v85, v71 offset:4608
	v_mul_f32_e64 v71, |v63|, s81
	v_exp_f32_e32 v84, v71
	s_nop 0
	v_add_f32_e32 v86, 1.0, v84
	v_rcp_f32_e32 v71, v86
	s_nop 0
	v_mul_f32_e32 v84, v84, v71
	s_and_saveexec_b64 s[0:1], vcc
	s_xor_b64 s[82:83], exec, s[0:1]
	s_cbranch_execz .LBB0_1271
	v_cndmask_b32_e64 v63, v84, v71, s[68:69]
	v_fma_f32 v63, v34, v63, v32
	v_cmp_gt_f32_e64 s[0:1], s92, v63
	s_nop 1
	v_cndmask_b32_e64 v85, 0, 32, s[0:1]
	v_ldexp_f32 v63, v63, v85
	v_log_f32_e32 v63, v63
	s_nop 0
	v_mul_f32_e32 v85, 0x3f317217, v63
	v_fma_f32 v85, v63, s96, -v85
	v_fmac_f32_e32 v85, 0x3377d1cf, v63
	v_fmac_f32_e32 v85, 0x3f317217, v63
	v_cmp_lt_f32_e64 s[72:73], |v63|, s33
	s_nop 1
	v_cndmask_b32_e64 v63, v63, v85, s[72:73]
	v_cndmask_b32_e64 v85, 0, v249, s[0:1]
	v_sub_f32_e32 v85, v63, v85

.LBB0_1273:
	s_or_b64 exec, exec, s[82:83]
	v_cndmask_b32_e64 v63, v71, v84, s[68:69]
	v_mul_f32_e32 v71, v34, v63
	v_add_f32_e32 v63, v73, v85
	v_mul_f32_e32 v73, 0x3fb8aa3b, v63
	v_exp_f32_e32 v73, v73
	s_mulk_i32 s3, 0x48
	s_waitcnt vmcnt(27)
	v_cmp_le_f32_e64 s[68:69], 0, v61
	v_mul_f32_e32 v62, v62, v73
	v_cvt_pk_bf16_f32 v62, v62, v62
	v_add_u32_e32 v73, s3, v66
	v_lshl_add_u32 v73, v73, 1, v76
	ds_write_b16 v73, v62
	v_mul_f32_e32 v62, 0xbfb8aa3b, v63
	v_exp_f32_e32 v62, v62
	s_nop 0
	v_mul_f32_e32 v62, v71, v62
	v_cvt_pk_bf16_f32 v62, v62, v62
	ds_write_b16 v73, v62 offset:4608
	v_mul_f32_e64 v62, |v61|, s81
	v_exp_f32_e32 v71, v62
	s_nop 0
	v_add_f32_e32 v84, 1.0, v71
	v_rcp_f32_e32 v62, v84
	s_nop 0
	v_mul_f32_e32 v71, v71, v62
	s_and_saveexec_b64 s[0:1], vcc
	s_xor_b64 s[82:83], exec, s[0:1]
	s_cbranch_execz .LBB0_1275
	v_cndmask_b32_e64 v61, v71, v62, s[68:69]
	v_fma_f32 v61, v34, v61, v32
	v_cmp_gt_f32_e64 s[0:1], s92, v61
	s_nop 1
	v_cndmask_b32_e64 v73, 0, 32, s[0:1]
	v_ldexp_f32 v61, v61, v73
	v_log_f32_e32 v61, v61
	s_nop 0
	v_mul_f32_e32 v73, 0x3f317217, v61
	v_fma_f32 v73, v61, s96, -v73
	v_fmac_f32_e32 v73, 0x3377d1cf, v61
	v_fmac_f32_e32 v73, 0x3f317217, v61
	v_cmp_lt_f32_e64 s[72:73], |v61|, s33
	s_nop 1
	v_cndmask_b32_e64 v61, v61, v73, s[72:73]
	v_cndmask_b32_e64 v73, 0, v249, s[0:1]
	v_sub_f32_e32 v73, v61, v73

.LBB0_1277:
	s_or_b64 exec, exec, s[82:83]
	v_cndmask_b32_e64 v61, v62, v71, s[68:69]
	v_mul_f32_e32 v62, v34, v61
	v_add_f32_e32 v61, v63, v73
	v_mul_f32_e32 v63, 0x3fb8aa3b, v61
	v_exp_f32_e32 v63, v63
	s_mulk_i32 s2, 0x48
	s_waitcnt vmcnt(25)
	v_cmp_le_f32_e64 s[68:69], 0, v59
	v_mul_f32_e32 v60, v60, v63
	v_cvt_pk_bf16_f32 v60, v60, v60
	v_add_u32_e32 v63, s2, v66
	v_lshl_add_u32 v63, v63, 1, v76
	ds_write_b16 v63, v60
	v_mul_f32_e32 v60, 0xbfb8aa3b, v61
	v_exp_f32_e32 v60, v60
	s_nop 0
	v_mul_f32_e32 v60, v62, v60
	v_cvt_pk_bf16_f32 v60, v60, v60
	ds_write_b16 v63, v60 offset:4608
	v_mul_f32_e64 v60, |v59|, s81
	v_exp_f32_e32 v62, v60
	s_nop 0
	v_add_f32_e32 v71, 1.0, v62
	v_rcp_f32_e32 v60, v71
	s_nop 0
	v_mul_f32_e32 v62, v62, v60
	s_and_saveexec_b64 s[0:1], vcc
	s_xor_b64 s[82:83], exec, s[0:1]
	s_cbranch_execz .LBB0_1279
	v_cndmask_b32_e64 v59, v62, v60, s[68:69]
	v_fma_f32 v59, v34, v59, v32
	v_cmp_gt_f32_e64 s[0:1], s92, v59
	s_nop 1
	v_cndmask_b32_e64 v63, 0, 32, s[0:1]
	v_ldexp_f32 v59, v59, v63
	v_log_f32_e32 v59, v59
	s_nop 0
	v_mul_f32_e32 v63, 0x3f317217, v59
	v_fma_f32 v63, v59, s96, -v63
	v_fmac_f32_e32 v63, 0x3377d1cf, v59
	v_fmac_f32_e32 v63, 0x3f317217, v59
	v_cmp_lt_f32_e64 s[72:73], |v59|, s33
	s_nop 1
	v_cndmask_b32_e64 v59, v59, v63, s[72:73]
	v_cndmask_b32_e64 v63, 0, v249, s[0:1]
	v_sub_f32_e32 v63, v59, v63

.LBB0_1281:
	s_or_b64 exec, exec, s[82:83]
	v_cndmask_b32_e64 v59, v60, v62, s[68:69]
	v_mul_f32_e32 v60, v34, v59
	v_add_f32_e32 v59, v61, v63
	v_mul_f32_e32 v61, 0x3fb8aa3b, v59
	v_exp_f32_e32 v61, v61
	s_mulk_i32 s87, 0x48
	s_waitcnt vmcnt(23)
	v_cmp_le_f32_e64 s[68:69], 0, v57
	v_mul_f32_e32 v58, v58, v61
	v_cvt_pk_bf16_f32 v58, v58, v58
	v_add_u32_e32 v61, s87, v66
	v_lshl_add_u32 v61, v61, 1, v76
	ds_write_b16 v61, v58
	v_mul_f32_e32 v58, 0xbfb8aa3b, v59
	v_exp_f32_e32 v58, v58
	s_nop 0
	v_mul_f32_e32 v58, v60, v58
	v_cvt_pk_bf16_f32 v58, v58, v58
	ds_write_b16 v61, v58 offset:4608
	v_mul_f32_e64 v58, |v57|, s81
	v_exp_f32_e32 v60, v58
	s_nop 0
	v_add_f32_e32 v62, 1.0, v60
	v_rcp_f32_e32 v58, v62
	s_nop 0
	v_mul_f32_e32 v60, v60, v58
	s_and_saveexec_b64 s[0:1], vcc
	s_xor_b64 s[82:83], exec, s[0:1]
	s_cbranch_execz .LBB0_1283
	v_cndmask_b32_e64 v57, v60, v58, s[68:69]
	v_fma_f32 v57, v34, v57, v32
	v_cmp_gt_f32_e64 s[0:1], s92, v57
	s_nop 1
	v_cndmask_b32_e64 v61, 0, 32, s[0:1]
	v_ldexp_f32 v57, v57, v61
	v_log_f32_e32 v57, v57
	s_nop 0
	v_mul_f32_e32 v61, 0x3f317217, v57
	v_fma_f32 v61, v57, s96, -v61
	v_fmac_f32_e32 v61, 0x3377d1cf, v57
	v_fmac_f32_e32 v61, 0x3f317217, v57
	v_cmp_lt_f32_e64 s[72:73], |v57|, s33
	s_nop 1
	v_cndmask_b32_e64 v57, v57, v61, s[72:73]
	v_cndmask_b32_e64 v61, 0, v249, s[0:1]
	v_sub_f32_e32 v61, v57, v61

.LBB0_1285:
	s_or_b64 exec, exec, s[82:83]
	v_cndmask_b32_e64 v57, v58, v60, s[68:69]
	v_mul_f32_e32 v58, v34, v57
	v_add_f32_e32 v57, v59, v61
	v_mul_f32_e32 v59, 0x3fb8aa3b, v57
	v_exp_f32_e32 v59, v59
	s_mulk_i32 s86, 0x48
	s_waitcnt vmcnt(21)
	v_cmp_le_f32_e64 s[68:69], 0, v55
	v_mul_f32_e32 v56, v56, v59
	v_cvt_pk_bf16_f32 v56, v56, v56
	v_add_u32_e32 v59, s86, v66
	v_lshl_add_u32 v59, v59, 1, v76
	ds_write_b16 v59, v56
	v_mul_f32_e32 v56, 0xbfb8aa3b, v57
	v_exp_f32_e32 v56, v56
	s_nop 0
	v_mul_f32_e32 v56, v58, v56
	v_cvt_pk_bf16_f32 v56, v56, v56
	ds_write_b16 v59, v56 offset:4608
	v_mul_f32_e64 v56, |v55|, s81
	v_exp_f32_e32 v58, v56
	s_nop 0
	v_add_f32_e32 v60, 1.0, v58
	v_rcp_f32_e32 v56, v60
	s_nop 0
	v_mul_f32_e32 v58, v58, v56
	s_and_saveexec_b64 s[0:1], vcc
	s_xor_b64 s[82:83], exec, s[0:1]
	s_cbranch_execz .LBB0_1287
	v_cndmask_b32_e64 v55, v58, v56, s[68:69]
	v_fma_f32 v55, v34, v55, v32
	v_cmp_gt_f32_e64 s[0:1], s92, v55
	s_nop 1
	v_cndmask_b32_e64 v59, 0, 32, s[0:1]
	v_ldexp_f32 v55, v55, v59
	v_log_f32_e32 v55, v55
	s_nop 0
	v_mul_f32_e32 v59, 0x3f317217, v55
	v_fma_f32 v59, v55, s96, -v59
	v_fmac_f32_e32 v59, 0x3377d1cf, v55
	v_fmac_f32_e32 v59, 0x3f317217, v55
	v_cmp_lt_f32_e64 s[72:73], |v55|, s33
	s_nop 1
	v_cndmask_b32_e64 v55, v55, v59, s[72:73]
	v_cndmask_b32_e64 v59, 0, v249, s[0:1]
	v_sub_f32_e32 v59, v55, v59

.LBB0_1289:
	s_or_b64 exec, exec, s[82:83]
	v_cndmask_b32_e64 v55, v56, v58, s[68:69]
	v_mul_f32_e32 v56, v34, v55
	v_add_f32_e32 v55, v57, v59
	v_mul_f32_e32 v57, 0x3fb8aa3b, v55
	v_exp_f32_e32 v57, v57
	s_mulk_i32 s85, 0x48
	s_waitcnt vmcnt(19)
	v_cmp_le_f32_e64 s[68:69], 0, v53
	v_mul_f32_e32 v54, v54, v57
	v_cvt_pk_bf16_f32 v54, v54, v54
	v_add_u32_e32 v57, s85, v66
	v_lshl_add_u32 v57, v57, 1, v76
	ds_write_b16 v57, v54
	v_mul_f32_e32 v54, 0xbfb8aa3b, v55
	v_exp_f32_e32 v54, v54
	s_nop 0
	v_mul_f32_e32 v54, v56, v54
	v_cvt_pk_bf16_f32 v54, v54, v54
	ds_write_b16 v57, v54 offset:4608
	v_mul_f32_e64 v54, |v53|, s81
	v_exp_f32_e32 v56, v54
	s_nop 0
	v_add_f32_e32 v58, 1.0, v56
	v_rcp_f32_e32 v54, v58
	s_nop 0
	v_mul_f32_e32 v56, v56, v54
	s_and_saveexec_b64 s[0:1], vcc
	s_xor_b64 s[82:83], exec, s[0:1]
	s_cbranch_execz .LBB0_1291
	v_cndmask_b32_e64 v53, v56, v54, s[68:69]
	v_fma_f32 v53, v34, v53, v32
	v_cmp_gt_f32_e64 s[0:1], s92, v53
	s_nop 1
	v_cndmask_b32_e64 v57, 0, 32, s[0:1]
	v_ldexp_f32 v53, v53, v57
	v_log_f32_e32 v53, v53
	s_nop 0
	v_mul_f32_e32 v57, 0x3f317217, v53
	v_fma_f32 v57, v53, s96, -v57
	v_fmac_f32_e32 v57, 0x3377d1cf, v53
	v_fmac_f32_e32 v57, 0x3f317217, v53
	v_cmp_lt_f32_e64 s[72:73], |v53|, s33
	s_nop 1
	v_cndmask_b32_e64 v53, v53, v57, s[72:73]
	v_cndmask_b32_e64 v57, 0, v249, s[0:1]
	v_sub_f32_e32 v57, v53, v57

.LBB0_1293:
	s_or_b64 exec, exec, s[82:83]
	v_cndmask_b32_e64 v53, v54, v56, s[68:69]
	v_mul_f32_e32 v54, v34, v53
	v_add_f32_e32 v53, v55, v57
	v_mul_f32_e32 v55, 0x3fb8aa3b, v53
	v_exp_f32_e32 v55, v55
	s_mulk_i32 s94, 0x48
	s_waitcnt vmcnt(17)
	v_cmp_le_f32_e64 s[68:69], 0, v51
	v_mul_f32_e32 v52, v52, v55
	v_cvt_pk_bf16_f32 v52, v52, v52
	v_add_u32_e32 v55, s94, v66
	v_lshl_add_u32 v55, v55, 1, v76
	ds_write_b16 v55, v52
	v_mul_f32_e32 v52, 0xbfb8aa3b, v53
	v_exp_f32_e32 v52, v52
	s_nop 0
	v_mul_f32_e32 v52, v54, v52
	v_cvt_pk_bf16_f32 v52, v52, v52
	ds_write_b16 v55, v52 offset:4608
	v_mul_f32_e64 v52, |v51|, s81
	v_exp_f32_e32 v54, v52
	s_nop 0
	v_add_f32_e32 v56, 1.0, v54
	v_rcp_f32_e32 v52, v56
	s_nop 0
	v_mul_f32_e32 v54, v54, v52
	s_and_saveexec_b64 s[0:1], vcc
	s_xor_b64 s[82:83], exec, s[0:1]
	s_cbranch_execz .LBB0_1295
	v_cndmask_b32_e64 v51, v54, v52, s[68:69]
	v_fma_f32 v51, v34, v51, v32
	v_cmp_gt_f32_e64 s[0:1], s92, v51
	s_nop 1
	v_cndmask_b32_e64 v55, 0, 32, s[0:1]
	v_ldexp_f32 v51, v51, v55
	v_log_f32_e32 v51, v51
	s_nop 0
	v_mul_f32_e32 v55, 0x3f317217, v51
	v_fma_f32 v55, v51, s96, -v55
	v_fmac_f32_e32 v55, 0x3377d1cf, v51
	v_fmac_f32_e32 v55, 0x3f317217, v51
	v_cmp_lt_f32_e64 s[72:73], |v51|, s33
	s_nop 1
	v_cndmask_b32_e64 v51, v51, v55, s[72:73]
	v_cndmask_b32_e64 v55, 0, v249, s[0:1]
	v_sub_f32_e32 v55, v51, v55

.LBB0_1297:
	s_or_b64 exec, exec, s[82:83]
	v_cndmask_b32_e64 v51, v52, v54, s[68:69]
	v_mul_f32_e32 v52, v34, v51
	v_add_f32_e32 v51, v53, v55
	v_mul_f32_e32 v53, 0x3fb8aa3b, v51
	v_exp_f32_e32 v53, v53
	s_mulk_i32 s97, 0x48
	s_waitcnt vmcnt(15)
	v_cmp_le_f32_e64 s[68:69], 0, v49
	v_mul_f32_e32 v50, v50, v53
	v_cvt_pk_bf16_f32 v50, v50, v50
	v_add_u32_e32 v53, s97, v66
	v_lshl_add_u32 v53, v53, 1, v76
	ds_write_b16 v53, v50
	v_mul_f32_e32 v50, 0xbfb8aa3b, v51
	v_exp_f32_e32 v50, v50
	s_nop 0
	v_mul_f32_e32 v50, v52, v50
	v_cvt_pk_bf16_f32 v50, v50, v50
	ds_write_b16 v53, v50 offset:4608
	v_mul_f32_e64 v50, |v49|, s81
	v_exp_f32_e32 v52, v50
	s_nop 0
	v_add_f32_e32 v54, 1.0, v52
	v_rcp_f32_e32 v50, v54
	s_nop 0
	v_mul_f32_e32 v52, v52, v50
	s_and_saveexec_b64 s[0:1], vcc
	s_xor_b64 s[82:83], exec, s[0:1]
	s_cbranch_execz .LBB0_1299
	v_cndmask_b32_e64 v49, v52, v50, s[68:69]
	v_fma_f32 v49, v34, v49, v32
	v_cmp_gt_f32_e64 s[0:1], s92, v49
	s_nop 1
	v_cndmask_b32_e64 v53, 0, 32, s[0:1]
	v_ldexp_f32 v49, v49, v53
	v_log_f32_e32 v49, v49
	s_nop 0
	v_mul_f32_e32 v53, 0x3f317217, v49
	v_fma_f32 v53, v49, s96, -v53
	v_fmac_f32_e32 v53, 0x3377d1cf, v49
	v_fmac_f32_e32 v53, 0x3f317217, v49
	v_cmp_lt_f32_e64 s[72:73], |v49|, s33
	s_nop 1
	v_cndmask_b32_e64 v49, v49, v53, s[72:73]
	v_cndmask_b32_e64 v53, 0, v249, s[0:1]
	v_sub_f32_e32 v53, v49, v53

.LBB0_1301:
	s_or_b64 exec, exec, s[82:83]
	v_cndmask_b32_e64 v49, v50, v52, s[68:69]
	v_mul_f32_e32 v50, v34, v49
	v_add_f32_e32 v49, v51, v53
	v_mul_f32_e32 v51, 0x3fb8aa3b, v49
	v_exp_f32_e32 v51, v51
	s_mulk_i32 s88, 0x48
	s_waitcnt vmcnt(13)
	v_cmp_le_f32_e64 s[68:69], 0, v47
	v_mul_f32_e32 v48, v48, v51
	v_cvt_pk_bf16_f32 v48, v48, v48
	v_add_u32_e32 v51, s88, v66
	v_lshl_add_u32 v51, v51, 1, v76
	ds_write_b16 v51, v48
	v_mul_f32_e32 v48, 0xbfb8aa3b, v49
	v_exp_f32_e32 v48, v48
	s_nop 0
	v_mul_f32_e32 v48, v50, v48
	v_cvt_pk_bf16_f32 v48, v48, v48
	ds_write_b16 v51, v48 offset:4608
	v_mul_f32_e64 v48, |v47|, s81
	v_exp_f32_e32 v50, v48
	s_nop 0
	v_add_f32_e32 v52, 1.0, v50
	v_rcp_f32_e32 v48, v52
	s_nop 0
	v_mul_f32_e32 v50, v50, v48
	s_and_saveexec_b64 s[0:1], vcc
	s_xor_b64 s[82:83], exec, s[0:1]
	s_cbranch_execz .LBB0_1303
	v_cndmask_b32_e64 v47, v50, v48, s[68:69]
	v_fma_f32 v47, v34, v47, v32
	v_cmp_gt_f32_e64 s[0:1], s92, v47
	s_nop 1
	v_cndmask_b32_e64 v51, 0, 32, s[0:1]
	v_ldexp_f32 v47, v47, v51
	v_log_f32_e32 v47, v47
	s_nop 0
	v_mul_f32_e32 v51, 0x3f317217, v47
	v_fma_f32 v51, v47, s96, -v51
	v_fmac_f32_e32 v51, 0x3377d1cf, v47
	v_fmac_f32_e32 v51, 0x3f317217, v47
	v_cmp_lt_f32_e64 s[72:73], |v47|, s33
	s_nop 1
	v_cndmask_b32_e64 v47, v47, v51, s[72:73]
	v_cndmask_b32_e64 v51, 0, v249, s[0:1]
	v_sub_f32_e32 v51, v47, v51

.LBB0_1305:
	s_or_b64 exec, exec, s[82:83]
	v_cndmask_b32_e64 v47, v48, v50, s[68:69]
	v_mul_f32_e32 v48, v34, v47
	v_add_f32_e32 v47, v49, v51
	v_mul_f32_e32 v49, 0x3fb8aa3b, v47
	v_exp_f32_e32 v49, v49
	s_mulk_i32 s91, 0x48
	s_waitcnt vmcnt(11)
	v_cmp_le_f32_e64 s[68:69], 0, v45
	v_mul_f32_e32 v46, v46, v49
	v_cvt_pk_bf16_f32 v46, v46, v46
	v_add_u32_e32 v49, s91, v66
	v_lshl_add_u32 v49, v49, 1, v76
	ds_write_b16 v49, v46
	v_mul_f32_e32 v46, 0xbfb8aa3b, v47
	v_exp_f32_e32 v46, v46
	s_nop 0
	v_mul_f32_e32 v46, v48, v46
	v_cvt_pk_bf16_f32 v46, v46, v46
	ds_write_b16 v49, v46 offset:4608
	v_mul_f32_e64 v46, |v45|, s81
	v_exp_f32_e32 v48, v46
	s_nop 0
	v_add_f32_e32 v50, 1.0, v48
	v_rcp_f32_e32 v46, v50
	s_nop 0
	v_mul_f32_e32 v48, v48, v46
	s_and_saveexec_b64 s[0:1], vcc
	s_xor_b64 s[82:83], exec, s[0:1]
	s_cbranch_execz .LBB0_1307
	v_cndmask_b32_e64 v45, v48, v46, s[68:69]
	v_fma_f32 v45, v34, v45, v32
	v_cmp_gt_f32_e64 s[0:1], s92, v45
	s_nop 1
	v_cndmask_b32_e64 v49, 0, 32, s[0:1]
	v_ldexp_f32 v45, v45, v49
	v_log_f32_e32 v45, v45
	s_nop 0
	v_mul_f32_e32 v49, 0x3f317217, v45
	v_fma_f32 v49, v45, s96, -v49
	v_fmac_f32_e32 v49, 0x3377d1cf, v45
	v_fmac_f32_e32 v49, 0x3f317217, v45
	v_cmp_lt_f32_e64 s[72:73], |v45|, s33
	s_nop 1
	v_cndmask_b32_e64 v45, v45, v49, s[72:73]
	v_cndmask_b32_e64 v49, 0, v249, s[0:1]
	v_sub_f32_e32 v49, v45, v49

.LBB0_1309:
	s_or_b64 exec, exec, s[82:83]
	v_cndmask_b32_e64 v45, v46, v48, s[68:69]
	v_mul_f32_e32 v46, v34, v45
	v_add_f32_e32 v45, v47, v49
	v_mul_f32_e32 v47, 0x3fb8aa3b, v45
	v_exp_f32_e32 v47, v47
	s_mulk_i32 s90, 0x48
	s_waitcnt vmcnt(9)
	v_cmp_le_f32_e64 s[68:69], 0, v43
	v_mul_f32_e32 v44, v44, v47
	v_cvt_pk_bf16_f32 v44, v44, v44
	v_add_u32_e32 v47, s90, v66
	v_lshl_add_u32 v47, v47, 1, v76
	ds_write_b16 v47, v44
	v_mul_f32_e32 v44, 0xbfb8aa3b, v45
	v_exp_f32_e32 v44, v44
	s_nop 0
	v_mul_f32_e32 v44, v46, v44
	v_cvt_pk_bf16_f32 v44, v44, v44
	ds_write_b16 v47, v44 offset:4608
	v_mul_f32_e64 v44, |v43|, s81
	v_exp_f32_e32 v46, v44
	s_nop 0
	v_add_f32_e32 v48, 1.0, v46
	v_rcp_f32_e32 v44, v48
	s_nop 0
	v_mul_f32_e32 v46, v46, v44
	s_and_saveexec_b64 s[0:1], vcc
	s_xor_b64 s[82:83], exec, s[0:1]
	s_cbranch_execz .LBB0_1311
	v_cndmask_b32_e64 v43, v46, v44, s[68:69]
	v_fma_f32 v43, v34, v43, v32
	v_cmp_gt_f32_e64 s[0:1], s92, v43
	s_nop 1
	v_cndmask_b32_e64 v47, 0, 32, s[0:1]
	v_ldexp_f32 v43, v43, v47
	v_log_f32_e32 v43, v43
	s_nop 0
	v_mul_f32_e32 v47, 0x3f317217, v43
	v_fma_f32 v47, v43, s96, -v47
	v_fmac_f32_e32 v47, 0x3377d1cf, v43
	v_fmac_f32_e32 v47, 0x3f317217, v43
	v_cmp_lt_f32_e64 s[72:73], |v43|, s33
	s_nop 1
	v_cndmask_b32_e64 v43, v43, v47, s[72:73]
	v_cndmask_b32_e64 v47, 0, v249, s[0:1]
	v_sub_f32_e32 v47, v43, v47

.LBB0_1313:
	s_or_b64 exec, exec, s[82:83]
	v_cndmask_b32_e64 v43, v44, v46, s[68:69]
	v_mul_f32_e32 v44, v34, v43
	v_add_f32_e32 v43, v45, v47
	v_mul_f32_e32 v45, 0x3fb8aa3b, v43
	v_exp_f32_e32 v45, v45
	s_mulk_i32 s74, 0x48
	s_waitcnt vmcnt(7)
	v_cmp_le_f32_e64 s[68:69], 0, v41
	v_mul_f32_e32 v42, v42, v45
	v_cvt_pk_bf16_f32 v42, v42, v42
	v_add_u32_e32 v45, s74, v66
	v_lshl_add_u32 v45, v45, 1, v76
	ds_write_b16 v45, v42
	v_mul_f32_e32 v42, 0xbfb8aa3b, v43
	v_exp_f32_e32 v42, v42
	s_nop 0
	v_mul_f32_e32 v42, v44, v42
	v_cvt_pk_bf16_f32 v42, v42, v42
	ds_write_b16 v45, v42 offset:4608
	v_mul_f32_e64 v42, |v41|, s81
	v_exp_f32_e32 v44, v42
	s_nop 0
	v_add_f32_e32 v46, 1.0, v44
	v_rcp_f32_e32 v42, v46
	s_nop 0
	v_mul_f32_e32 v44, v44, v42
	s_and_saveexec_b64 s[0:1], vcc
	s_xor_b64 s[82:83], exec, s[0:1]
	s_cbranch_execz .LBB0_1315
	v_cndmask_b32_e64 v41, v44, v42, s[68:69]
	v_fma_f32 v41, v34, v41, v32
	v_cmp_gt_f32_e64 s[0:1], s92, v41
	s_nop 1
	v_cndmask_b32_e64 v45, 0, 32, s[0:1]
	v_ldexp_f32 v41, v41, v45
	v_log_f32_e32 v41, v41
	s_nop 0
	v_mul_f32_e32 v45, 0x3f317217, v41
	v_fma_f32 v45, v41, s96, -v45
	v_fmac_f32_e32 v45, 0x3377d1cf, v41
	v_fmac_f32_e32 v45, 0x3f317217, v41
	v_cmp_lt_f32_e64 s[72:73], |v41|, s33
	s_nop 1
	v_cndmask_b32_e64 v41, v41, v45, s[72:73]
	v_cndmask_b32_e64 v45, 0, v249, s[0:1]
	v_sub_f32_e32 v45, v41, v45

.LBB0_1317:
	s_or_b64 exec, exec, s[82:83]
	v_cndmask_b32_e64 v41, v42, v44, s[68:69]
	v_mul_f32_e32 v42, v34, v41
	v_add_f32_e32 v41, v43, v45
	v_mul_f32_e32 v43, 0x3fb8aa3b, v41
	v_exp_f32_e32 v43, v43
	s_mulk_i32 s80, 0x48
	s_waitcnt vmcnt(5)
	v_cmp_le_f32_e64 s[68:69], 0, v39
	v_mul_f32_e32 v40, v40, v43
	v_cvt_pk_bf16_f32 v40, v40, v40
	v_add_u32_e32 v43, s80, v66
	v_lshl_add_u32 v43, v43, 1, v76
	ds_write_b16 v43, v40
	v_mul_f32_e32 v40, 0xbfb8aa3b, v41
	v_exp_f32_e32 v40, v40
	s_nop 0
	v_mul_f32_e32 v40, v42, v40
	v_cvt_pk_bf16_f32 v40, v40, v40
	ds_write_b16 v43, v40 offset:4608
	v_mul_f32_e64 v40, |v39|, s81
	v_exp_f32_e32 v42, v40
	s_nop 0
	v_add_f32_e32 v44, 1.0, v42
	v_rcp_f32_e32 v40, v44
	s_nop 0
	v_mul_f32_e32 v42, v42, v40
	s_and_saveexec_b64 s[0:1], vcc
	s_xor_b64 s[82:83], exec, s[0:1]
	s_cbranch_execz .LBB0_1319
	v_cndmask_b32_e64 v39, v42, v40, s[68:69]
	v_fma_f32 v39, v34, v39, v32
	v_cmp_gt_f32_e64 s[0:1], s92, v39
	s_nop 1
	v_cndmask_b32_e64 v43, 0, 32, s[0:1]
	v_ldexp_f32 v39, v39, v43
	v_log_f32_e32 v39, v39
	s_nop 0
	v_mul_f32_e32 v43, 0x3f317217, v39
	v_fma_f32 v43, v39, s96, -v43
	v_fmac_f32_e32 v43, 0x3377d1cf, v39
	v_fmac_f32_e32 v43, 0x3f317217, v39
	v_cmp_lt_f32_e64 s[72:73], |v39|, s33
	s_nop 1
	v_cndmask_b32_e64 v39, v39, v43, s[72:73]
	v_cndmask_b32_e64 v43, 0, v249, s[0:1]
	v_sub_f32_e32 v43, v39, v43

.LBB0_1321:
	s_or_b64 exec, exec, s[82:83]
	v_cndmask_b32_e64 v39, v40, v42, s[68:69]
	v_mul_f32_e32 v40, v34, v39
	v_add_f32_e32 v39, v41, v43
	v_mul_f32_e32 v41, 0x3fb8aa3b, v39
	v_exp_f32_e32 v41, v41
	s_mulk_i32 s93, 0x48
	s_waitcnt vmcnt(3)
	v_cmp_le_f32_e64 s[68:69], 0, v37
	v_mul_f32_e32 v38, v38, v41
	v_cvt_pk_bf16_f32 v38, v38, v38
	v_add_u32_e32 v41, s93, v66
	v_lshl_add_u32 v41, v41, 1, v76
	ds_write_b16 v41, v38
	v_mul_f32_e32 v38, 0xbfb8aa3b, v39
	v_exp_f32_e32 v38, v38
	s_nop 0
	v_mul_f32_e32 v38, v40, v38
	v_cvt_pk_bf16_f32 v38, v38, v38
	ds_write_b16 v41, v38 offset:4608
	v_mul_f32_e64 v38, |v37|, s81
	v_exp_f32_e32 v40, v38
	s_nop 0
	v_add_f32_e32 v42, 1.0, v40
	v_rcp_f32_e32 v38, v42
	s_nop 0
	v_mul_f32_e32 v40, v40, v38
	s_and_saveexec_b64 s[0:1], vcc
	s_xor_b64 s[82:83], exec, s[0:1]
	s_cbranch_execz .LBB0_1323
	v_cndmask_b32_e64 v37, v40, v38, s[68:69]
	v_fma_f32 v37, v34, v37, v32
	v_cmp_gt_f32_e64 s[0:1], s92, v37
	s_nop 1
	v_cndmask_b32_e64 v41, 0, 32, s[0:1]
	v_ldexp_f32 v37, v37, v41
	v_log_f32_e32 v37, v37
	s_nop 0
	v_mul_f32_e32 v41, 0x3f317217, v37
	v_fma_f32 v41, v37, s96, -v41
	v_fmac_f32_e32 v41, 0x3377d1cf, v37
	v_fmac_f32_e32 v41, 0x3f317217, v37
	v_cmp_lt_f32_e64 s[72:73], |v37|, s33
	s_nop 1
	v_cndmask_b32_e64 v37, v37, v41, s[72:73]
	v_cndmask_b32_e64 v41, 0, v249, s[0:1]
	v_sub_f32_e32 v41, v37, v41

.LBB0_1325:
	s_or_b64 exec, exec, s[82:83]
	v_cndmask_b32_e64 v37, v38, v40, s[68:69]
	v_mul_f32_e32 v38, v34, v37
	v_add_f32_e32 v37, v39, v41
	v_mul_f32_e32 v39, 0x3fb8aa3b, v37
	v_exp_f32_e32 v39, v39
	s_mulk_i32 s84, 0x48
	s_waitcnt vmcnt(0)
	v_cmp_le_f32_e64 s[68:69], 0, v35
	v_mul_f32_e32 v36, v36, v39
	v_cvt_pk_bf16_f32 v36, v36, v36
	v_add_u32_e32 v39, s84, v66
	v_lshl_add_u32 v39, v39, 1, v76
	ds_write_b16 v39, v36
	v_mul_f32_e32 v36, 0xbfb8aa3b, v37
	v_exp_f32_e32 v36, v36
	s_nop 0
	v_mul_f32_e32 v36, v38, v36
	v_cvt_pk_bf16_f32 v36, v36, v36
	ds_write_b16 v39, v36 offset:4608
	v_mul_f32_e64 v36, |v35|, s81
	v_exp_f32_e32 v38, v36
	s_nop 0
	v_add_f32_e32 v40, 1.0, v38
	v_rcp_f32_e32 v36, v40
	s_nop 0
	v_mul_f32_e32 v38, v38, v36
	s_and_saveexec_b64 s[0:1], vcc
	s_xor_b64 s[72:73], exec, s[0:1]
	s_cbranch_execz .LBB0_1327
	v_cndmask_b32_e64 v35, v38, v36, s[68:69]
	v_fmac_f32_e32 v32, v34, v35
	v_cmp_gt_f32_e32 vcc, s92, v32
	s_nop 1
	v_cndmask_b32_e64 v35, 0, 32, vcc
	v_ldexp_f32 v32, v32, v35
	v_log_f32_e32 v32, v32
	s_nop 0
	v_mul_f32_e32 v35, 0x3f317217, v32
	v_fma_f32 v35, v32, s96, -v35
	v_fmac_f32_e32 v35, 0x3377d1cf, v32
	v_fmac_f32_e32 v35, 0x3f317217, v32
	v_cmp_lt_f32_e64 s[0:1], |v32|, s33
	s_nop 1
	v_cndmask_b32_e64 v32, v32, v35, s[0:1]
	v_cndmask_b32_e32 v35, 0, v249, vcc
	v_sub_f32_e32 v39, v32, v35

.LBB0_1336:
	s_or_b64 exec, exec, s[72:73]
	v_add_f32_e32 v32, v37, v39
	v_mul_f32_e32 v35, 0x3fb8aa3b, v32
	v_exp_f32_e32 v35, v35
	v_mul_f32_e32 v32, 0xbfb8aa3b, v32
	v_exp_f32_e32 v32, v32
	v_cndmask_b32_e64 v36, v36, v38, s[68:69]
	v_mul_f32_e32 v33, v33, v35
	s_mulk_i32 s76, 0x48
	v_mul_f32_e32 v34, v34, v36
	v_cvt_pk_bf16_f32 v33, v33, v33
	v_add_u32_e32 v35, s76, v68
	v_lshl_add_u32 v35, v35, 1, v76
	v_mul_f32_e32 v32, v34, v32
	ds_write_b16 v35, v33
	v_cvt_pk_bf16_f32 v32, v32, v32
	ds_write_b16 v35, v32 offset:4608
	ds_read_b128 v[32:35], v80 offset:4608
	ds_read_b128 v[60:63], v80
	ds_read_b128 v[56:59], v80 offset:32
	ds_read_b128 v[48:51], v80 offset:4640
	s_waitcnt lgkmcnt(2)
	v_mfma_f32_32x32x16_bf16 v[32:47], v[32:35], v[60:63], 0
	v_readlane_b32 s0, v255, 35
	v_readlane_b32 s1, v255, 36
	ds_read_b128 v[84:87], v80 offset:4672
	ds_read_b128 v[52:55], v80 offset:64
	v_cndmask_b32_e64 v73, 0, 1, s[0:1]
	v_readlane_b32 s0, v255, 33
	v_readlane_b32 s1, v255, 34
	s_waitcnt lgkmcnt(2)
	v_mfma_f32_32x32x16_bf16 v[32:47], v[48:51], v[56:59], v[32:47]
	ds_read_b128 v[88:91], v80 offset:4704
	ds_read_b128 v[48:51], v80 offset:96
	v_cndmask_b32_e64 v75, 0, 1, s[0:1]
	v_readlane_b32 s0, v255, 39
	v_readlane_b32 s1, v255, 40
	v_cndmask_b32_e64 v73, v75, v73, s[94:95]
	v_and_b32_e32 v73, 1, v73
	v_cndmask_b32_e64 v83, 0, 1, s[0:1]
	v_readlane_b32 s0, v255, 37
	v_readlane_b32 s1, v255, 38
	s_waitcnt lgkmcnt(2)
	v_mfma_f32_32x32x16_bf16 v[32:47], v[84:87], v[52:55], v[32:47]
	v_cmp_eq_u32_e32 vcc, 1, v73
	v_cndmask_b32_e64 v92, 0, 1, s[0:1]
	v_readlane_b32 s0, v255, 43
	v_readlane_b32 s1, v255, 44
	v_cndmask_b32_e64 v75, v92, v83, s[94:95]
	v_and_b32_e32 v75, 1, v75
	v_cndmask_b32_e64 v93, 0, 1, s[0:1]
	v_readlane_b32 s0, v255, 41
	v_readlane_b32 s1, v255, 42
	s_waitcnt lgkmcnt(0)
	v_mfma_f32_32x32x16_bf16 v[32:47], v[88:91], v[48:51], v[32:47]
	v_cndmask_b32_e64 v88, 0, 1, s[26:27]
	v_cndmask_b32_e64 v94, 0, 1, s[0:1]
	v_readlane_b32 s0, v255, 47
	v_readlane_b32 s1, v255, 48
	v_cndmask_b32_e64 v83, v94, v93, s[94:95]
	v_and_b32_e32 v83, 1, v83
	v_cndmask_b32_e64 v95, 0, 1, s[0:1]
	v_readlane_b32 s0, v255, 45
	v_readlane_b32 s1, v255, 46
	s_nop 2
	v_cndmask_b32_e32 v32, 0, v32, vcc
	v_cmp_eq_u32_e32 vcc, 1, v75
	v_cndmask_b32_e64 v84, 0, 1, s[0:1]
	v_readlane_b32 s0, v255, 51
	v_cndmask_b32_e64 v84, v84, v95, s[94:95]
	v_readlane_b32 s1, v255, 52
	v_and_b32_e32 v85, 1, v84
	v_bfe_u32 v73, v32, 16, 1
	v_cndmask_b32_e64 v84, 0, 1, s[0:1]
	v_readlane_b32 s0, v255, 49
	v_readlane_b32 s1, v255, 50
	v_cndmask_b32_e32 v33, 0, v33, vcc
	v_add3_u32 v32, v32, v73, s89
	v_cndmask_b32_e64 v86, 0, 1, s[0:1]
	v_readlane_b32 s0, v255, 53
	v_cndmask_b32_e64 v84, v86, v84, s[94:95]
	v_readlane_b32 s1, v255, 54
	v_and_b32_e32 v86, 1, v84
	v_cndmask_b32_e64 v84, 0, 1, s[24:25]
	v_cndmask_b32_e64 v87, 0, 1, s[0:1]
	v_cndmask_b32_e64 v84, v87, v84, s[94:95]
	v_and_b32_e32 v87, 1, v84
	v_cndmask_b32_e64 v84, 0, 1, s[28:29]
	v_cndmask_b32_e64 v84, v88, v84, s[94:95]
	v_and_b32_e32 v96, 1, v84
	v_cndmask_b32_e64 v84, 0, 1, s[34:35]
	v_cndmask_b32_e64 v88, 0, 1, s[30:31]
	v_cndmask_b32_e64 v84, v88, v84, s[94:95]
	v_and_b32_e32 v97, 1, v84
	v_cndmask_b32_e64 v84, 0, 1, s[38:39]
	v_cndmask_b32_e64 v88, 0, 1, s[36:37]
	v_cndmask_b32_e64 v84, v88, v84, s[94:95]
	v_and_b32_e32 v102, 1, v84
	v_cndmask_b32_e64 v84, 0, 1, s[42:43]
	v_cndmask_b32_e64 v88, 0, 1, s[40:41]
	v_cndmask_b32_e64 v84, v88, v84, s[94:95]
	v_and_b32_e32 v103, 1, v84
	v_cndmask_b32_e64 v84, 0, 1, s[46:47]
	v_cndmask_b32_e64 v88, 0, 1, s[44:45]
	v_cndmask_b32_e64 v84, v88, v84, s[94:95]
	v_and_b32_e32 v104, 1, v84
	v_cndmask_b32_e64 v84, 0, 1, s[22:23]
	v_cndmask_b32_e64 v88, 0, 1, s[48:49]
	v_cndmask_b32_e64 v84, v88, v84, s[94:95]
	v_and_b32_e32 v105, 1, v84
	v_cndmask_b32_e64 v84, 0, 1, s[54:55]
	v_cndmask_b32_e64 v88, 0, 1, s[52:53]
	v_cndmask_b32_e64 v84, v88, v84, s[94:95]
	v_and_b32_e32 v106, 1, v84
	v_cndmask_b32_e64 v84, 0, 1, s[58:59]
	v_cndmask_b32_e64 v88, 0, 1, s[56:57]
	v_bfe_u32 v73, v33, 16, 1
	v_cndmask_b32_e64 v84, v88, v84, s[94:95]
	v_lshrrev_b32_e32 v32, 16, v32
	v_add3_u32 v33, v33, v73, s89
	v_cmp_eq_u32_e32 vcc, 1, v83
	v_and_b32_e32 v107, 1, v84
	v_and_or_b32 v84, v33, s75, v32
	v_cndmask_b32_e32 v32, 0, v34, vcc
	v_bfe_u32 v33, v32, 16, 1
	v_cmp_eq_u32_e32 vcc, 1, v85
	v_add3_u32 v32, v32, v33, s89
	v_lshrrev_b32_e32 v32, 16, v32
	v_cndmask_b32_e32 v33, 0, v35, vcc
	v_bfe_u32 v34, v33, 16, 1
	v_add3_u32 v33, v33, v34, s89
	v_cmp_eq_u32_e32 vcc, 1, v86
	v_and_or_b32 v85, v33, s75, v32
	v_mov_b32_e32 v73, v229
	v_cndmask_b32_e32 v32, 0, v36, vcc
	v_bfe_u32 v33, v32, 16, 1
	v_cmp_eq_u32_e32 vcc, 1, v87
	v_add3_u32 v32, v32, v33, s89
	v_lshrrev_b32_e32 v32, 16, v32
	v_cndmask_b32_e32 v33, 0, v37, vcc
	v_bfe_u32 v34, v33, 16, 1
	v_add3_u32 v33, v33, v34, s89
	v_and_or_b32 v86, v33, s75, v32
	v_lshl_add_u32 v32, s71, 2, v81
	v_ashrrev_i32_e32 v33, 31, v32
	v_lshlrev_b64 v[32:33], 14, v[32:33]
	v_lshl_add_u64 v[100:101], v[70:71], 0, v[32:33]
	v_lshl_add_u64 v[32:33], v[100:101], 0, v[72:73]
	global_load_dwordx4 v[88:91], v[32:33], off offset:16
	global_load_dwordx4 v[92:95], v[32:33], off
	v_cmp_eq_u32_e32 vcc, 1, v96
	v_add_u32_e32 v73, 0x2000, v82
	v_add_u32_e32 v83, 0x2800, v82
	v_cndmask_b32_e32 v34, 0, v38, vcc
	v_bfe_u32 v35, v34, 16, 1
	v_add3_u32 v38, v34, v35, s89
	ds_read2_b64 v[34:37], v73 offset0:128 offset1:130
	v_cmp_eq_u32_e32 vcc, 1, v97
	ds_read2_b64 v[96:99], v83 offset0:192 offset1:194
	v_lshrrev_b32_e32 v38, 16, v38
	v_cndmask_b32_e32 v39, 0, v39, vcc
	v_bfe_u32 v75, v39, 16, 1
	v_add3_u32 v39, v39, v75, s89
	v_cndmask_b32_e64 v108, 0, 1, s[62:63]
	v_cndmask_b32_e64 v109, 0, 1, s[60:61]
	v_and_or_b32 v87, v39, s75, v38
	v_mov_b32_e32 v75, v229
	v_cmp_eq_u32_e32 vcc, 1, v102
	s_waitcnt lgkmcnt(1)
	v_mfma_f32_32x32x16_bf16 v[16:31], v[34:37], v[84:87], v[16:31]
	v_cndmask_b32_e64 v34, v109, v108, s[94:95]
	v_and_b32_e32 v108, 1, v34
	v_cndmask_b32_e64 v34, 0, 1, s[66:67]
	v_cndmask_b32_e64 v35, 0, 1, s[64:65]
	v_cndmask_b32_e64 v34, v35, v34, s[94:95]
	v_and_b32_e32 v109, 1, v34
	v_lshl_add_u64 v[34:35], v[100:101], 0, v[74:75]
	ds_read2_b64 v[36:39], v73 offset0:132 offset1:134
	s_waitcnt lgkmcnt(1)
	v_mfma_f32_32x32x16_bf16 v[0:15], v[96:99], v[84:87], v[0:15]
	global_load_dwordx4 v[84:87], v[34:35], off offset:16
	global_load_dwordx4 v[96:99], v[34:35], off
	v_cndmask_b32_e32 v40, 0, v40, vcc
	v_cmp_eq_u32_e32 vcc, 1, v103
	v_bfe_u32 v73, v40, 16, 1
	v_add3_u32 v40, v40, v73, s89
	v_cndmask_b32_e32 v41, 0, v41, vcc
	v_bfe_u32 v73, v41, 16, 1
	v_lshrrev_b32_e32 v40, 16, v40
	v_add3_u32 v41, v41, v73, s89
	v_cmp_eq_u32_e32 vcc, 1, v104
	v_and_or_b32 v40, v41, s75, v40
	global_load_dwordx4 v[100:103], v[32:33], off offset:64
	v_cndmask_b32_e32 v41, 0, v42, vcc
	v_bfe_u32 v42, v41, 16, 1
	v_cmp_eq_u32_e32 vcc, 1, v105
	v_add3_u32 v41, v41, v42, s89
	v_lshrrev_b32_e32 v41, 16, v41
	v_cndmask_b32_e32 v42, 0, v43, vcc
	v_bfe_u32 v43, v42, 16, 1
	v_add3_u32 v42, v42, v43, s89
	v_cmp_eq_u32_e32 vcc, 1, v106
	v_and_or_b32 v41, v42, s75, v41
	s_xor_b64 s[0:1], s[94:95], -1
	v_cndmask_b32_e32 v42, 0, v44, vcc
	v_bfe_u32 v43, v42, 16, 1
	v_cmp_eq_u32_e32 vcc, 1, v107
	v_add3_u32 v42, v42, v43, s89
	v_lshrrev_b32_e32 v42, 16, v42
	v_cndmask_b32_e32 v43, 0, v45, vcc
	v_bfe_u32 v44, v43, 16, 1
	v_add3_u32 v43, v43, v44, s89
	v_cmp_eq_u32_e32 vcc, 1, v108
	v_and_or_b32 v42, v43, s75, v42
	s_mov_b64 s[94:95], 0
	v_cndmask_b32_e32 v43, 0, v46, vcc
	v_bfe_u32 v44, v43, 16, 1
	v_cmp_eq_u32_e32 vcc, 1, v109
	v_add3_u32 v43, v43, v44, s89
	v_lshrrev_b32_e32 v43, 16, v43
	v_cndmask_b32_e32 v44, 0, v47, vcc
	v_bfe_u32 v45, v44, 16, 1
	v_add3_u32 v44, v44, v45, s89
	v_and_or_b32 v43, v44, s75, v43
	global_load_dwordx4 v[44:47], v[32:33], off offset:80
	s_andn2_b64 vcc, exec, s[0:1]
	s_waitcnt lgkmcnt(0)
	v_mfma_f32_32x32x16_bf16 v[16:31], v[36:39], v[40:43], v[16:31]
	ds_read2_b64 v[36:39], v83 offset0:196 offset1:198
	s_mov_b32 s71, 1
	s_waitcnt vmcnt(5)
	v_bfe_u32 v73, v91, 16, 1
	v_add3_u32 v73, v91, v73, s89
	s_waitcnt lgkmcnt(0)
	v_mfma_f32_32x32x16_bf16 v[0:15], v[36:39], v[40:43], v[0:15]
	s_waitcnt vmcnt(4)
	v_bfe_u32 v36, v92, 16, 1
	v_add3_u32 v36, v92, v36, s89
	v_bfe_u32 v37, v93, 16, 1
	v_lshrrev_b32_e32 v36, 16, v36
	v_add3_u32 v37, v93, v37, s89
	v_and_or_b32 v36, v37, s75, v36
	v_bfe_u32 v37, v94, 16, 1
	v_add3_u32 v37, v94, v37, s89
	v_bfe_u32 v38, v95, 16, 1
	global_load_dwordx4 v[40:43], v[34:35], off offset:64
	v_lshrrev_b32_e32 v37, 16, v37
	v_add3_u32 v38, v95, v38, s89
	v_and_or_b32 v37, v38, s75, v37
	v_bfe_u32 v38, v88, 16, 1
	v_add3_u32 v38, v88, v38, s89
	v_bfe_u32 v39, v89, 16, 1
	v_lshrrev_b32_e32 v38, 16, v38
	v_add3_u32 v39, v89, v39, s89
	v_and_or_b32 v38, v39, s75, v38
	v_bfe_u32 v39, v90, 16, 1
	v_add3_u32 v39, v90, v39, s89
	global_load_dwordx4 v[88:91], v[34:35], off offset:80
	v_lshrrev_b32_e32 v39, 16, v39
	v_and_or_b32 v39, v73, s75, v39
	global_load_dwordx4 v[92:95], v[32:33], off offset:128
	s_waitcnt vmcnt(6)
	v_bfe_u32 v73, v87, 16, 1
	v_mfma_f32_32x32x16_bf16 v[16:31], v[36:39], v[60:63], v[16:31]
	s_waitcnt vmcnt(5)
	v_bfe_u32 v36, v96, 16, 1
	v_add3_u32 v36, v96, v36, s89
	v_bfe_u32 v37, v97, 16, 1
	v_lshrrev_b32_e32 v36, 16, v36
	v_add3_u32 v37, v97, v37, s89
	v_and_or_b32 v36, v37, s75, v36
	v_bfe_u32 v37, v98, 16, 1
	v_add3_u32 v37, v98, v37, s89
	v_bfe_u32 v38, v99, 16, 1
	v_lshrrev_b32_e32 v37, 16, v37
	v_add3_u32 v38, v99, v38, s89
	v_and_or_b32 v37, v38, s75, v37
	v_bfe_u32 v38, v84, 16, 1
	v_add3_u32 v38, v84, v38, s89
	v_bfe_u32 v39, v85, 16, 1
	v_lshrrev_b32_e32 v38, 16, v38
	v_add3_u32 v39, v85, v39, s89
	v_and_or_b32 v38, v39, s75, v38
	v_bfe_u32 v39, v86, 16, 1
	v_add3_u32 v39, v86, v39, s89
	v_add3_u32 v73, v87, v73, s89
	global_load_dwordx4 v[84:87], v[32:33], off offset:144
	v_lshrrev_b32_e32 v39, 16, v39
	v_and_or_b32 v39, v73, s75, v39
	s_nop 1
	v_mfma_f32_32x32x16_bf16 v[0:15], v[36:39], v[60:63], v[0:15]
	s_waitcnt vmcnt(5)
	v_bfe_u32 v36, v100, 16, 1
	global_load_dwordx4 v[60:63], v[34:35], off offset:144
	global_load_dwordx4 v[96:99], v[34:35], off offset:128
	v_add3_u32 v36, v100, v36, s89
	v_bfe_u32 v37, v101, 16, 1
	v_lshrrev_b32_e32 v36, 16, v36
	v_add3_u32 v37, v101, v37, s89
	v_and_or_b32 v36, v37, s75, v36
	v_bfe_u32 v37, v102, 16, 1
	v_add3_u32 v37, v102, v37, s89
	v_bfe_u32 v38, v103, 16, 1
	v_lshrrev_b32_e32 v37, 16, v37
	v_add3_u32 v38, v103, v38, s89
	v_and_or_b32 v37, v38, s75, v37
	s_waitcnt vmcnt(6)
	v_bfe_u32 v38, v44, 16, 1
	v_add3_u32 v38, v44, v38, s89
	v_bfe_u32 v39, v45, 16, 1
	v_lshrrev_b32_e32 v38, 16, v38
	v_add3_u32 v39, v45, v39, s89
	v_and_or_b32 v38, v39, s75, v38
	v_bfe_u32 v39, v46, 16, 1
	v_add3_u32 v39, v46, v39, s89
	v_bfe_u32 v44, v47, 16, 1
	v_lshrrev_b32_e32 v39, 16, v39
	v_add3_u32 v44, v47, v44, s89
	v_and_or_b32 v39, v44, s75, v39
	global_load_dwordx4 v[44:47], v[32:33], off offset:208
	global_load_dwordx4 v[100:103], v[32:33], off offset:192
	v_mfma_f32_32x32x16_bf16 v[16:31], v[36:39], v[56:59], v[16:31]
	s_waitcnt vmcnt(7)
	v_bfe_u32 v36, v40, 16, 1
	v_add3_u32 v36, v40, v36, s89
	v_bfe_u32 v37, v41, 16, 1
	v_lshrrev_b32_e32 v36, 16, v36
	v_add3_u32 v37, v41, v37, s89
	v_and_or_b32 v36, v37, s75, v36
	v_bfe_u32 v37, v42, 16, 1
	v_add3_u32 v37, v42, v37, s89
	v_bfe_u32 v38, v43, 16, 1
	v_lshrrev_b32_e32 v37, 16, v37
	v_add3_u32 v32, v43, v38, s89
	v_and_or_b32 v37, v32, s75, v37
	s_waitcnt vmcnt(6)
	v_bfe_u32 v32, v88, 16, 1
	v_add3_u32 v32, v88, v32, s89
	v_bfe_u32 v33, v89, 16, 1
	v_lshrrev_b32_e32 v32, 16, v32
	v_add3_u32 v33, v89, v33, s89
	v_and_or_b32 v38, v33, s75, v32
	v_bfe_u32 v32, v90, 16, 1
	v_add3_u32 v32, v90, v32, s89
	v_bfe_u32 v33, v91, 16, 1
	v_lshrrev_b32_e32 v32, 16, v32
	v_add3_u32 v33, v91, v33, s89
	v_and_or_b32 v39, v33, s75, v32
	s_waitcnt vmcnt(5)
	v_bfe_u32 v32, v92, 16, 1
	v_add3_u32 v32, v92, v32, s89
	v_mfma_f32_32x32x16_bf16 v[0:15], v[36:39], v[56:59], v[0:15]
	global_load_dwordx4 v[36:39], v[34:35], off offset:208
	global_load_dwordx4 v[40:43], v[34:35], off offset:192
	v_bfe_u32 v33, v93, 16, 1
	v_lshrrev_b32_e32 v32, 16, v32
	v_add3_u32 v33, v93, v33, s89
	v_and_or_b32 v32, v33, s75, v32
	v_bfe_u32 v33, v94, 16, 1
	v_add3_u32 v33, v94, v33, s89
	v_bfe_u32 v34, v95, 16, 1
	v_lshrrev_b32_e32 v33, 16, v33
	v_add3_u32 v34, v95, v34, s89
	v_and_or_b32 v33, v34, s75, v33
	s_waitcnt vmcnt(6)
	v_bfe_u32 v34, v84, 16, 1
	v_add3_u32 v34, v84, v34, s89
	v_bfe_u32 v35, v85, 16, 1
	v_lshrrev_b32_e32 v34, 16, v34
	v_add3_u32 v35, v85, v35, s89
	v_and_or_b32 v34, v35, s75, v34
	v_bfe_u32 v35, v86, 16, 1
	v_add3_u32 v35, v86, v35, s89
	v_bfe_u32 v56, v87, 16, 1
	v_lshrrev_b32_e32 v35, 16, v35
	v_add3_u32 v56, v87, v56, s89
	v_and_or_b32 v35, v56, s75, v35
	s_waitcnt vmcnt(5)
	v_bfe_u32 v56, v63, 16, 1
	v_add3_u32 v56, v63, v56, s89
	v_mfma_f32_32x32x16_bf16 v[16:31], v[32:35], v[52:55], v[16:31]
	s_waitcnt vmcnt(4)
	v_bfe_u32 v32, v96, 16, 1
	v_add3_u32 v32, v96, v32, s89
	v_bfe_u32 v33, v97, 16, 1
	v_lshrrev_b32_e32 v32, 16, v32
	v_add3_u32 v33, v97, v33, s89
	v_and_or_b32 v32, v33, s75, v32
	v_bfe_u32 v33, v98, 16, 1
	v_add3_u32 v33, v98, v33, s89
	v_bfe_u32 v34, v99, 16, 1
	v_lshrrev_b32_e32 v33, 16, v33
	v_add3_u32 v34, v99, v34, s89
	v_and_or_b32 v33, v34, s75, v33
	v_bfe_u32 v34, v60, 16, 1
	v_add3_u32 v34, v60, v34, s89
	v_bfe_u32 v35, v61, 16, 1
	v_lshrrev_b32_e32 v34, 16, v34
	v_add3_u32 v35, v61, v35, s89
	v_and_or_b32 v34, v35, s75, v34
	v_bfe_u32 v35, v62, 16, 1
	v_add3_u32 v35, v62, v35, s89
	v_lshrrev_b32_e32 v35, 16, v35
	v_and_or_b32 v35, v56, s75, v35
	s_nop 1
	v_mfma_f32_32x32x16_bf16 v[0:15], v[32:35], v[52:55], v[0:15]
	s_waitcnt vmcnt(2)
	v_bfe_u32 v32, v100, 16, 1
	v_add3_u32 v32, v100, v32, s89
	v_bfe_u32 v33, v101, 16, 1
	v_lshrrev_b32_e32 v32, 16, v32
	v_add3_u32 v33, v101, v33, s89
	v_and_or_b32 v32, v33, s75, v32
	v_bfe_u32 v33, v102, 16, 1
	v_add3_u32 v33, v102, v33, s89
	v_bfe_u32 v34, v103, 16, 1
	v_lshrrev_b32_e32 v33, 16, v33
	v_add3_u32 v34, v103, v34, s89
	v_and_or_b32 v33, v34, s75, v33
	v_bfe_u32 v34, v44, 16, 1
	v_add3_u32 v34, v44, v34, s89
	v_bfe_u32 v35, v45, 16, 1
	v_lshrrev_b32_e32 v34, 16, v34
	v_add3_u32 v35, v45, v35, s89
	v_and_or_b32 v34, v35, s75, v34
	v_bfe_u32 v35, v46, 16, 1
	v_add3_u32 v35, v46, v35, s89
	v_bfe_u32 v44, v47, 16, 1
	v_lshrrev_b32_e32 v35, 16, v35
	v_add3_u32 v44, v47, v44, s89
	v_and_or_b32 v35, v44, s75, v35
	s_nop 1
	v_mfma_f32_32x32x16_bf16 v[16:31], v[32:35], v[48:51], v[16:31]
	s_waitcnt vmcnt(0)
	v_bfe_u32 v32, v40, 16, 1
	v_add3_u32 v32, v40, v32, s89
	v_bfe_u32 v33, v41, 16, 1
	v_lshrrev_b32_e32 v32, 16, v32
	v_add3_u32 v33, v41, v33, s89
	v_and_or_b32 v32, v33, s75, v32
	v_bfe_u32 v33, v42, 16, 1
	v_add3_u32 v33, v42, v33, s89
	v_bfe_u32 v34, v43, 16, 1
	v_lshrrev_b32_e32 v33, 16, v33
	v_add3_u32 v34, v43, v34, s89
	v_and_or_b32 v33, v34, s75, v33
	v_bfe_u32 v34, v36, 16, 1
	v_add3_u32 v34, v36, v34, s89
	v_bfe_u32 v35, v37, 16, 1
	v_lshrrev_b32_e32 v34, 16, v34
	v_add3_u32 v35, v37, v35, s89
	v_and_or_b32 v34, v35, s75, v34
	v_bfe_u32 v35, v38, 16, 1
	v_add3_u32 v35, v38, v35, s89
	v_bfe_u32 v36, v39, 16, 1
	v_lshrrev_b32_e32 v35, 16, v35
	v_add3_u32 v36, v39, v36, s89
	v_and_or_b32 v35, v36, s75, v35
	s_nop 1
	v_mfma_f32_32x32x16_bf16 v[0:15], v[32:35], v[48:51], v[0:15]
	s_cbranch_vccz .LBB0_1334

.LBB0_1345:
	s_or_b64 exec, exec, s[82:83]
	v_cndmask_b32_e64 v114, v115, v116, s[68:69]
	v_mul_f32_e32 v115, v34, v114
	v_add_f32_e32 v114, 0, v117
	v_mul_f32_e32 v116, 0x3fb8aa3b, v114
	v_exp_f32_e32 v116, v116
	s_mulk_i32 s20, 0x48
	s_waitcnt vmcnt(61)
	v_cmp_le_f32_e64 s[68:69], 0, v112
	v_mul_f32_e32 v113, v113, v116
	v_cvt_pk_bf16_f32 v113, v113, v113
	v_add_u32_e32 v116, s20, v68
	v_lshl_add_u32 v116, v116, 1, v76
	ds_write_b16 v116, v113
	v_mul_f32_e32 v113, 0xbfb8aa3b, v114
	v_exp_f32_e32 v113, v113
	s_nop 0
	v_mul_f32_e32 v113, v115, v113
	v_cvt_pk_bf16_f32 v113, v113, v113
	ds_write_b16 v116, v113 offset:4608
	v_mul_f32_e64 v113, |v112|, s81
	v_exp_f32_e32 v115, v113
	s_nop 0
	v_add_f32_e32 v117, 1.0, v115
	v_rcp_f32_e32 v113, v117
	s_nop 0
	v_mul_f32_e32 v115, v115, v113
	s_and_saveexec_b64 s[0:1], vcc
	s_xor_b64 s[82:83], exec, s[0:1]
	s_cbranch_execz .LBB0_1347
	v_cndmask_b32_e64 v112, v115, v113, s[68:69]
	v_fma_f32 v112, v34, v112, v32
	v_cmp_gt_f32_e64 s[0:1], s92, v112
	s_nop 1
	v_cndmask_b32_e64 v116, 0, 32, s[0:1]
	v_ldexp_f32 v112, v112, v116
	v_log_f32_e32 v112, v112
	s_nop 0
	v_mul_f32_e32 v116, 0x3f317217, v112
	v_fma_f32 v116, v112, s96, -v116
	v_fmac_f32_e32 v116, 0x3377d1cf, v112
	v_fmac_f32_e32 v116, 0x3f317217, v112
	v_cmp_lt_f32_e64 s[72:73], |v112|, s33
	s_nop 1
	v_cndmask_b32_e64 v112, v112, v116, s[72:73]
	v_cndmask_b32_e64 v116, 0, v249, s[0:1]
	v_sub_f32_e32 v116, v112, v116

.LBB0_1349:
	s_or_b64 exec, exec, s[82:83]
	v_cndmask_b32_e64 v112, v113, v115, s[68:69]
	v_mul_f32_e32 v113, v34, v112
	v_add_f32_e32 v112, v114, v116
	v_mul_f32_e32 v114, 0x3fb8aa3b, v112
	v_exp_f32_e32 v114, v114
	s_mulk_i32 s19, 0x48
	s_waitcnt vmcnt(59)
	v_cmp_le_f32_e64 s[68:69], 0, v110
	v_mul_f32_e32 v111, v111, v114
	v_cvt_pk_bf16_f32 v111, v111, v111
	v_add_u32_e32 v114, s19, v68
	v_lshl_add_u32 v114, v114, 1, v76
	ds_write_b16 v114, v111
	v_mul_f32_e32 v111, 0xbfb8aa3b, v112
	v_exp_f32_e32 v111, v111
	s_nop 0
	v_mul_f32_e32 v111, v113, v111
	v_cvt_pk_bf16_f32 v111, v111, v111
	ds_write_b16 v114, v111 offset:4608
	v_mul_f32_e64 v111, |v110|, s81
	v_exp_f32_e32 v113, v111
	s_nop 0
	v_add_f32_e32 v115, 1.0, v113
	v_rcp_f32_e32 v111, v115
	s_nop 0
	v_mul_f32_e32 v113, v113, v111
	s_and_saveexec_b64 s[0:1], vcc
	s_xor_b64 s[82:83], exec, s[0:1]
	s_cbranch_execz .LBB0_1351
	v_cndmask_b32_e64 v110, v113, v111, s[68:69]
	v_fma_f32 v110, v34, v110, v32
	v_cmp_gt_f32_e64 s[0:1], s92, v110
	s_nop 1
	v_cndmask_b32_e64 v114, 0, 32, s[0:1]
	v_ldexp_f32 v110, v110, v114
	v_log_f32_e32 v110, v110
	s_nop 0
	v_mul_f32_e32 v114, 0x3f317217, v110
	v_fma_f32 v114, v110, s96, -v114
	v_fmac_f32_e32 v114, 0x3377d1cf, v110
	v_fmac_f32_e32 v114, 0x3f317217, v110
	v_cmp_lt_f32_e64 s[72:73], |v110|, s33
	s_nop 1
	v_cndmask_b32_e64 v110, v110, v114, s[72:73]
	v_cndmask_b32_e64 v114, 0, v249, s[0:1]
	v_sub_f32_e32 v114, v110, v114

.LBB0_1353:
	s_or_b64 exec, exec, s[82:83]
	v_cndmask_b32_e64 v110, v111, v113, s[68:69]
	v_mul_f32_e32 v111, v34, v110
	v_add_f32_e32 v110, v112, v114
	v_mul_f32_e32 v112, 0x3fb8aa3b, v110
	v_exp_f32_e32 v112, v112
	s_mulk_i32 s18, 0x48
	s_waitcnt vmcnt(57)
	v_cmp_le_f32_e64 s[68:69], 0, v108
	v_mul_f32_e32 v109, v109, v112
	v_cvt_pk_bf16_f32 v109, v109, v109
	v_add_u32_e32 v112, s18, v68
	v_lshl_add_u32 v112, v112, 1, v76
	ds_write_b16 v112, v109
	v_mul_f32_e32 v109, 0xbfb8aa3b, v110
	v_exp_f32_e32 v109, v109
	s_nop 0
	v_mul_f32_e32 v109, v111, v109
	v_cvt_pk_bf16_f32 v109, v109, v109
	ds_write_b16 v112, v109 offset:4608
	v_mul_f32_e64 v109, |v108|, s81
	v_exp_f32_e32 v111, v109
	s_nop 0
	v_add_f32_e32 v113, 1.0, v111
	v_rcp_f32_e32 v109, v113
	s_nop 0
	v_mul_f32_e32 v111, v111, v109
	s_and_saveexec_b64 s[0:1], vcc
	s_xor_b64 s[82:83], exec, s[0:1]
	s_cbranch_execz .LBB0_1355
	v_cndmask_b32_e64 v108, v111, v109, s[68:69]
	v_fma_f32 v108, v34, v108, v32
	v_cmp_gt_f32_e64 s[0:1], s92, v108
	s_nop 1
	v_cndmask_b32_e64 v112, 0, 32, s[0:1]
	v_ldexp_f32 v108, v108, v112
	v_log_f32_e32 v108, v108
	s_nop 0
	v_mul_f32_e32 v112, 0x3f317217, v108
	v_fma_f32 v112, v108, s96, -v112
	v_fmac_f32_e32 v112, 0x3377d1cf, v108
	v_fmac_f32_e32 v112, 0x3f317217, v108
	v_cmp_lt_f32_e64 s[72:73], |v108|, s33
	s_nop 1
	v_cndmask_b32_e64 v108, v108, v112, s[72:73]
	v_cndmask_b32_e64 v112, 0, v249, s[0:1]
	v_sub_f32_e32 v112, v108, v112

.LBB0_1357:
	s_or_b64 exec, exec, s[82:83]
	v_cndmask_b32_e64 v108, v109, v111, s[68:69]
	v_mul_f32_e32 v109, v34, v108
	v_add_f32_e32 v108, v110, v112
	v_mul_f32_e32 v110, 0x3fb8aa3b, v108
	v_exp_f32_e32 v110, v110
	s_mulk_i32 s17, 0x48
	s_waitcnt vmcnt(55)
	v_cmp_le_f32_e64 s[68:69], 0, v106
	v_mul_f32_e32 v107, v107, v110
	v_cvt_pk_bf16_f32 v107, v107, v107
	v_add_u32_e32 v110, s17, v68
	v_lshl_add_u32 v110, v110, 1, v76
	ds_write_b16 v110, v107
	v_mul_f32_e32 v107, 0xbfb8aa3b, v108
	v_exp_f32_e32 v107, v107
	s_nop 0
	v_mul_f32_e32 v107, v109, v107
	v_cvt_pk_bf16_f32 v107, v107, v107
	ds_write_b16 v110, v107 offset:4608
	v_mul_f32_e64 v107, |v106|, s81
	v_exp_f32_e32 v109, v107
	s_nop 0
	v_add_f32_e32 v111, 1.0, v109
	v_rcp_f32_e32 v107, v111
	s_nop 0
	v_mul_f32_e32 v109, v109, v107
	s_and_saveexec_b64 s[0:1], vcc
	s_xor_b64 s[82:83], exec, s[0:1]
	s_cbranch_execz .LBB0_1359
	v_cndmask_b32_e64 v106, v109, v107, s[68:69]
	v_fma_f32 v106, v34, v106, v32
	v_cmp_gt_f32_e64 s[0:1], s92, v106
	s_nop 1
	v_cndmask_b32_e64 v110, 0, 32, s[0:1]
	v_ldexp_f32 v106, v106, v110
	v_log_f32_e32 v106, v106
	s_nop 0
	v_mul_f32_e32 v110, 0x3f317217, v106
	v_fma_f32 v110, v106, s96, -v110
	v_fmac_f32_e32 v110, 0x3377d1cf, v106
	v_fmac_f32_e32 v110, 0x3f317217, v106
	v_cmp_lt_f32_e64 s[72:73], |v106|, s33
	s_nop 1
	v_cndmask_b32_e64 v106, v106, v110, s[72:73]
	v_cndmask_b32_e64 v110, 0, v249, s[0:1]
	v_sub_f32_e32 v110, v106, v110

.LBB0_1361:
	s_or_b64 exec, exec, s[82:83]
	v_cndmask_b32_e64 v106, v107, v109, s[68:69]
	v_mul_f32_e32 v107, v34, v106
	v_add_f32_e32 v106, v108, v110
	v_mul_f32_e32 v108, 0x3fb8aa3b, v106
	v_exp_f32_e32 v108, v108
	s_mulk_i32 s16, 0x48
	s_waitcnt vmcnt(53)
	v_cmp_le_f32_e64 s[68:69], 0, v104
	v_mul_f32_e32 v105, v105, v108
	v_cvt_pk_bf16_f32 v105, v105, v105
	v_add_u32_e32 v108, s16, v68
	v_lshl_add_u32 v108, v108, 1, v76
	ds_write_b16 v108, v105
	v_mul_f32_e32 v105, 0xbfb8aa3b, v106
	v_exp_f32_e32 v105, v105
	s_nop 0
	v_mul_f32_e32 v105, v107, v105
	v_cvt_pk_bf16_f32 v105, v105, v105
	ds_write_b16 v108, v105 offset:4608
	v_mul_f32_e64 v105, |v104|, s81
	v_exp_f32_e32 v107, v105
	s_nop 0
	v_add_f32_e32 v109, 1.0, v107
	v_rcp_f32_e32 v105, v109
	s_nop 0
	v_mul_f32_e32 v107, v107, v105
	s_and_saveexec_b64 s[0:1], vcc
	s_xor_b64 s[82:83], exec, s[0:1]
	s_cbranch_execz .LBB0_1363
	v_cndmask_b32_e64 v104, v107, v105, s[68:69]
	v_fma_f32 v104, v34, v104, v32
	v_cmp_gt_f32_e64 s[0:1], s92, v104
	s_nop 1
	v_cndmask_b32_e64 v108, 0, 32, s[0:1]
	v_ldexp_f32 v104, v104, v108
	v_log_f32_e32 v104, v104
	s_nop 0
	v_mul_f32_e32 v108, 0x3f317217, v104
	v_fma_f32 v108, v104, s96, -v108
	v_fmac_f32_e32 v108, 0x3377d1cf, v104
	v_fmac_f32_e32 v108, 0x3f317217, v104
	v_cmp_lt_f32_e64 s[72:73], |v104|, s33
	s_nop 1
	v_cndmask_b32_e64 v104, v104, v108, s[72:73]
	v_cndmask_b32_e64 v108, 0, v249, s[0:1]
	v_sub_f32_e32 v108, v104, v108

.LBB0_1365:
	s_or_b64 exec, exec, s[82:83]
	v_cndmask_b32_e64 v104, v105, v107, s[68:69]
	v_mul_f32_e32 v105, v34, v104
	v_add_f32_e32 v104, v106, v108
	v_mul_f32_e32 v106, 0x3fb8aa3b, v104
	v_exp_f32_e32 v106, v106
	s_mulk_i32 s15, 0x48
	s_waitcnt vmcnt(51)
	v_cmp_le_f32_e64 s[68:69], 0, v102
	v_mul_f32_e32 v103, v103, v106
	v_cvt_pk_bf16_f32 v103, v103, v103
	v_add_u32_e32 v106, s15, v68
	v_lshl_add_u32 v106, v106, 1, v76
	ds_write_b16 v106, v103
	v_mul_f32_e32 v103, 0xbfb8aa3b, v104
	v_exp_f32_e32 v103, v103
	s_nop 0
	v_mul_f32_e32 v103, v105, v103
	v_cvt_pk_bf16_f32 v103, v103, v103
	ds_write_b16 v106, v103 offset:4608
	v_mul_f32_e64 v103, |v102|, s81
	v_exp_f32_e32 v105, v103
	s_nop 0
	v_add_f32_e32 v107, 1.0, v105
	v_rcp_f32_e32 v103, v107
	s_nop 0
	v_mul_f32_e32 v105, v105, v103
	s_and_saveexec_b64 s[0:1], vcc
	s_xor_b64 s[82:83], exec, s[0:1]
	s_cbranch_execz .LBB0_1367
	v_cndmask_b32_e64 v102, v105, v103, s[68:69]
	v_fma_f32 v102, v34, v102, v32
	v_cmp_gt_f32_e64 s[0:1], s92, v102
	s_nop 1
	v_cndmask_b32_e64 v106, 0, 32, s[0:1]
	v_ldexp_f32 v102, v102, v106
	v_log_f32_e32 v102, v102
	s_nop 0
	v_mul_f32_e32 v106, 0x3f317217, v102
	v_fma_f32 v106, v102, s96, -v106
	v_fmac_f32_e32 v106, 0x3377d1cf, v102
	v_fmac_f32_e32 v106, 0x3f317217, v102
	v_cmp_lt_f32_e64 s[72:73], |v102|, s33
	s_nop 1
	v_cndmask_b32_e64 v102, v102, v106, s[72:73]
	v_cndmask_b32_e64 v106, 0, v249, s[0:1]
	v_sub_f32_e32 v106, v102, v106

.LBB0_1369:
	s_or_b64 exec, exec, s[82:83]
	v_cndmask_b32_e64 v102, v103, v105, s[68:69]
	v_mul_f32_e32 v103, v34, v102
	v_add_f32_e32 v102, v104, v106
	v_mul_f32_e32 v104, 0x3fb8aa3b, v102
	v_exp_f32_e32 v104, v104
	s_mulk_i32 s14, 0x48
	s_waitcnt vmcnt(49)
	v_cmp_le_f32_e64 s[68:69], 0, v100
	v_mul_f32_e32 v101, v101, v104
	v_cvt_pk_bf16_f32 v101, v101, v101
	v_add_u32_e32 v104, s14, v68
	v_lshl_add_u32 v104, v104, 1, v76
	ds_write_b16 v104, v101
	v_mul_f32_e32 v101, 0xbfb8aa3b, v102
	v_exp_f32_e32 v101, v101
	s_nop 0
	v_mul_f32_e32 v101, v103, v101
	v_cvt_pk_bf16_f32 v101, v101, v101
	ds_write_b16 v104, v101 offset:4608
	v_mul_f32_e64 v101, |v100|, s81
	v_exp_f32_e32 v103, v101
	s_nop 0
	v_add_f32_e32 v105, 1.0, v103
	v_rcp_f32_e32 v101, v105
	s_nop 0
	v_mul_f32_e32 v103, v103, v101
	s_and_saveexec_b64 s[0:1], vcc
	s_xor_b64 s[82:83], exec, s[0:1]
	s_cbranch_execz .LBB0_1371
	v_cndmask_b32_e64 v100, v103, v101, s[68:69]
	v_fma_f32 v100, v34, v100, v32
	v_cmp_gt_f32_e64 s[0:1], s92, v100
	s_nop 1
	v_cndmask_b32_e64 v104, 0, 32, s[0:1]
	v_ldexp_f32 v100, v100, v104
	v_log_f32_e32 v100, v100
	s_nop 0
	v_mul_f32_e32 v104, 0x3f317217, v100
	v_fma_f32 v104, v100, s96, -v104
	v_fmac_f32_e32 v104, 0x3377d1cf, v100
	v_fmac_f32_e32 v104, 0x3f317217, v100
	v_cmp_lt_f32_e64 s[72:73], |v100|, s33
	s_nop 1
	v_cndmask_b32_e64 v100, v100, v104, s[72:73]
	v_cndmask_b32_e64 v104, 0, v249, s[0:1]
	v_sub_f32_e32 v104, v100, v104

.LBB0_1373:
	s_or_b64 exec, exec, s[82:83]
	v_cndmask_b32_e64 v100, v101, v103, s[68:69]
	v_mul_f32_e32 v101, v34, v100
	v_add_f32_e32 v100, v102, v104
	v_mul_f32_e32 v102, 0x3fb8aa3b, v100
	v_exp_f32_e32 v102, v102
	s_mulk_i32 s13, 0x48
	s_waitcnt vmcnt(47)
	v_cmp_le_f32_e64 s[68:69], 0, v98
	v_mul_f32_e32 v99, v99, v102
	v_cvt_pk_bf16_f32 v99, v99, v99
	v_add_u32_e32 v102, s13, v68
	v_lshl_add_u32 v102, v102, 1, v76
	ds_write_b16 v102, v99
	v_mul_f32_e32 v99, 0xbfb8aa3b, v100
	v_exp_f32_e32 v99, v99
	s_nop 0
	v_mul_f32_e32 v99, v101, v99
	v_cvt_pk_bf16_f32 v99, v99, v99
	ds_write_b16 v102, v99 offset:4608
	v_mul_f32_e64 v99, |v98|, s81
	v_exp_f32_e32 v101, v99
	s_nop 0
	v_add_f32_e32 v103, 1.0, v101
	v_rcp_f32_e32 v99, v103
	s_nop 0
	v_mul_f32_e32 v101, v101, v99
	s_and_saveexec_b64 s[0:1], vcc
	s_xor_b64 s[82:83], exec, s[0:1]
	s_cbranch_execz .LBB0_1375
	v_cndmask_b32_e64 v98, v101, v99, s[68:69]
	v_fma_f32 v98, v34, v98, v32
	v_cmp_gt_f32_e64 s[0:1], s92, v98
	s_nop 1
	v_cndmask_b32_e64 v102, 0, 32, s[0:1]
	v_ldexp_f32 v98, v98, v102
	v_log_f32_e32 v98, v98
	s_nop 0
	v_mul_f32_e32 v102, 0x3f317217, v98
	v_fma_f32 v102, v98, s96, -v102
	v_fmac_f32_e32 v102, 0x3377d1cf, v98
	v_fmac_f32_e32 v102, 0x3f317217, v98
	v_cmp_lt_f32_e64 s[72:73], |v98|, s33
	s_nop 1
	v_cndmask_b32_e64 v98, v98, v102, s[72:73]
	v_cndmask_b32_e64 v102, 0, v249, s[0:1]
	v_sub_f32_e32 v102, v98, v102

.LBB0_1377:
	s_or_b64 exec, exec, s[82:83]
	v_cndmask_b32_e64 v98, v99, v101, s[68:69]
	v_mul_f32_e32 v99, v34, v98
	v_add_f32_e32 v98, v100, v102
	v_mul_f32_e32 v100, 0x3fb8aa3b, v98
	v_exp_f32_e32 v100, v100
	s_mulk_i32 s12, 0x48
	s_waitcnt vmcnt(45)
	v_cmp_le_f32_e64 s[68:69], 0, v96
	v_mul_f32_e32 v97, v97, v100
	v_cvt_pk_bf16_f32 v97, v97, v97
	v_add_u32_e32 v100, s12, v68
	v_lshl_add_u32 v100, v100, 1, v76
	ds_write_b16 v100, v97
	v_mul_f32_e32 v97, 0xbfb8aa3b, v98
	v_exp_f32_e32 v97, v97
	s_nop 0
	v_mul_f32_e32 v97, v99, v97
	v_cvt_pk_bf16_f32 v97, v97, v97
	ds_write_b16 v100, v97 offset:4608
	v_mul_f32_e64 v97, |v96|, s81
	v_exp_f32_e32 v99, v97
	s_nop 0
	v_add_f32_e32 v101, 1.0, v99
	v_rcp_f32_e32 v97, v101
	s_nop 0
	v_mul_f32_e32 v99, v99, v97
	s_and_saveexec_b64 s[0:1], vcc
	s_xor_b64 s[82:83], exec, s[0:1]
	s_cbranch_execz .LBB0_1379
	v_cndmask_b32_e64 v96, v99, v97, s[68:69]
	v_fma_f32 v96, v34, v96, v32
	v_cmp_gt_f32_e64 s[0:1], s92, v96
	s_nop 1
	v_cndmask_b32_e64 v100, 0, 32, s[0:1]
	v_ldexp_f32 v96, v96, v100
	v_log_f32_e32 v96, v96
	s_nop 0
	v_mul_f32_e32 v100, 0x3f317217, v96
	v_fma_f32 v100, v96, s96, -v100
	v_fmac_f32_e32 v100, 0x3377d1cf, v96
	v_fmac_f32_e32 v100, 0x3f317217, v96
	v_cmp_lt_f32_e64 s[72:73], |v96|, s33
	s_nop 1
	v_cndmask_b32_e64 v96, v96, v100, s[72:73]
	v_cndmask_b32_e64 v100, 0, v249, s[0:1]
	v_sub_f32_e32 v100, v96, v100

.LBB0_1381:
	s_or_b64 exec, exec, s[82:83]
	v_cndmask_b32_e64 v96, v97, v99, s[68:69]
	v_mul_f32_e32 v97, v34, v96
	v_add_f32_e32 v96, v98, v100
	v_mul_f32_e32 v98, 0x3fb8aa3b, v96
	v_exp_f32_e32 v98, v98
	s_mulk_i32 s11, 0x48
	s_waitcnt vmcnt(43)
	v_cmp_le_f32_e64 s[68:69], 0, v94
	v_mul_f32_e32 v95, v95, v98
	v_cvt_pk_bf16_f32 v95, v95, v95
	v_add_u32_e32 v98, s11, v68
	v_lshl_add_u32 v98, v98, 1, v76
	ds_write_b16 v98, v95
	v_mul_f32_e32 v95, 0xbfb8aa3b, v96
	v_exp_f32_e32 v95, v95
	s_nop 0
	v_mul_f32_e32 v95, v97, v95
	v_cvt_pk_bf16_f32 v95, v95, v95
	ds_write_b16 v98, v95 offset:4608
	v_mul_f32_e64 v95, |v94|, s81
	v_exp_f32_e32 v97, v95
	s_nop 0
	v_add_f32_e32 v99, 1.0, v97
	v_rcp_f32_e32 v95, v99
	s_nop 0
	v_mul_f32_e32 v97, v97, v95
	s_and_saveexec_b64 s[0:1], vcc
	s_xor_b64 s[82:83], exec, s[0:1]
	s_cbranch_execz .LBB0_1383
	v_cndmask_b32_e64 v94, v97, v95, s[68:69]
	v_fma_f32 v94, v34, v94, v32
	v_cmp_gt_f32_e64 s[0:1], s92, v94
	s_nop 1
	v_cndmask_b32_e64 v98, 0, 32, s[0:1]
	v_ldexp_f32 v94, v94, v98
	v_log_f32_e32 v94, v94
	s_nop 0
	v_mul_f32_e32 v98, 0x3f317217, v94
	v_fma_f32 v98, v94, s96, -v98
	v_fmac_f32_e32 v98, 0x3377d1cf, v94
	v_fmac_f32_e32 v98, 0x3f317217, v94
	v_cmp_lt_f32_e64 s[72:73], |v94|, s33
	s_nop 1
	v_cndmask_b32_e64 v94, v94, v98, s[72:73]
	v_cndmask_b32_e64 v98, 0, v249, s[0:1]
	v_sub_f32_e32 v98, v94, v98

.LBB0_1385:
	s_or_b64 exec, exec, s[82:83]
	v_cndmask_b32_e64 v94, v95, v97, s[68:69]
	v_mul_f32_e32 v95, v34, v94
	v_add_f32_e32 v94, v96, v98
	v_mul_f32_e32 v96, 0x3fb8aa3b, v94
	v_exp_f32_e32 v96, v96
	s_mulk_i32 s10, 0x48
	s_waitcnt vmcnt(41)
	v_cmp_le_f32_e64 s[68:69], 0, v92
	v_mul_f32_e32 v93, v93, v96
	v_cvt_pk_bf16_f32 v93, v93, v93
	v_add_u32_e32 v96, s10, v68
	v_lshl_add_u32 v96, v96, 1, v76
	ds_write_b16 v96, v93
	v_mul_f32_e32 v93, 0xbfb8aa3b, v94
	v_exp_f32_e32 v93, v93
	s_nop 0
	v_mul_f32_e32 v93, v95, v93
	v_cvt_pk_bf16_f32 v93, v93, v93
	ds_write_b16 v96, v93 offset:4608
	v_mul_f32_e64 v93, |v92|, s81
	v_exp_f32_e32 v95, v93
	s_nop 0
	v_add_f32_e32 v97, 1.0, v95
	v_rcp_f32_e32 v93, v97
	s_nop 0
	v_mul_f32_e32 v95, v95, v93
	s_and_saveexec_b64 s[0:1], vcc
	s_xor_b64 s[82:83], exec, s[0:1]
	s_cbranch_execz .LBB0_1387
	v_cndmask_b32_e64 v92, v95, v93, s[68:69]
	v_fma_f32 v92, v34, v92, v32
	v_cmp_gt_f32_e64 s[0:1], s92, v92
	s_nop 1
	v_cndmask_b32_e64 v96, 0, 32, s[0:1]
	v_ldexp_f32 v92, v92, v96
	v_log_f32_e32 v92, v92
	s_nop 0
	v_mul_f32_e32 v96, 0x3f317217, v92
	v_fma_f32 v96, v92, s96, -v96
	v_fmac_f32_e32 v96, 0x3377d1cf, v92
	v_fmac_f32_e32 v96, 0x3f317217, v92
	v_cmp_lt_f32_e64 s[72:73], |v92|, s33
	s_nop 1
	v_cndmask_b32_e64 v92, v92, v96, s[72:73]
	v_cndmask_b32_e64 v96, 0, v249, s[0:1]
	v_sub_f32_e32 v96, v92, v96

.LBB0_1389:
	s_or_b64 exec, exec, s[82:83]
	v_cndmask_b32_e64 v92, v93, v95, s[68:69]
	v_mul_f32_e32 v93, v34, v92
	v_add_f32_e32 v92, v94, v96
	v_mul_f32_e32 v94, 0x3fb8aa3b, v92
	v_exp_f32_e32 v94, v94
	s_mulk_i32 s9, 0x48
	s_waitcnt vmcnt(39)
	v_cmp_le_f32_e64 s[68:69], 0, v90
	v_mul_f32_e32 v91, v91, v94
	v_cvt_pk_bf16_f32 v91, v91, v91
	v_add_u32_e32 v94, s9, v68
	v_lshl_add_u32 v94, v94, 1, v76
	ds_write_b16 v94, v91
	v_mul_f32_e32 v91, 0xbfb8aa3b, v92
	v_exp_f32_e32 v91, v91
	s_nop 0
	v_mul_f32_e32 v91, v93, v91
	v_cvt_pk_bf16_f32 v91, v91, v91
	ds_write_b16 v94, v91 offset:4608
	v_mul_f32_e64 v91, |v90|, s81
	v_exp_f32_e32 v93, v91
	s_nop 0
	v_add_f32_e32 v95, 1.0, v93
	v_rcp_f32_e32 v91, v95
	s_nop 0
	v_mul_f32_e32 v93, v93, v91
	s_and_saveexec_b64 s[0:1], vcc
	s_xor_b64 s[82:83], exec, s[0:1]
	s_cbranch_execz .LBB0_1391
	v_cndmask_b32_e64 v90, v93, v91, s[68:69]
	v_fma_f32 v90, v34, v90, v32
	v_cmp_gt_f32_e64 s[0:1], s92, v90
	s_nop 1
	v_cndmask_b32_e64 v94, 0, 32, s[0:1]
	v_ldexp_f32 v90, v90, v94
	v_log_f32_e32 v90, v90
	s_nop 0
	v_mul_f32_e32 v94, 0x3f317217, v90
	v_fma_f32 v94, v90, s96, -v94
	v_fmac_f32_e32 v94, 0x3377d1cf, v90
	v_fmac_f32_e32 v94, 0x3f317217, v90
	v_cmp_lt_f32_e64 s[72:73], |v90|, s33
	s_nop 1
	v_cndmask_b32_e64 v90, v90, v94, s[72:73]
	v_cndmask_b32_e64 v94, 0, v249, s[0:1]
	v_sub_f32_e32 v94, v90, v94

.LBB0_1393:
	s_or_b64 exec, exec, s[82:83]
	v_cndmask_b32_e64 v90, v91, v93, s[68:69]
	v_mul_f32_e32 v91, v34, v90
	v_add_f32_e32 v90, v92, v94
	v_mul_f32_e32 v92, 0x3fb8aa3b, v90
	v_exp_f32_e32 v92, v92
	s_mulk_i32 s8, 0x48
	s_waitcnt vmcnt(37)
	v_cmp_le_f32_e64 s[68:69], 0, v88
	v_mul_f32_e32 v89, v89, v92
	v_cvt_pk_bf16_f32 v89, v89, v89
	v_add_u32_e32 v92, s8, v68
	v_lshl_add_u32 v92, v92, 1, v76
	ds_write_b16 v92, v89
	v_mul_f32_e32 v89, 0xbfb8aa3b, v90
	v_exp_f32_e32 v89, v89
	s_nop 0
	v_mul_f32_e32 v89, v91, v89
	v_cvt_pk_bf16_f32 v89, v89, v89
	ds_write_b16 v92, v89 offset:4608
	v_mul_f32_e64 v89, |v88|, s81
	v_exp_f32_e32 v91, v89
	s_nop 0
	v_add_f32_e32 v93, 1.0, v91
	v_rcp_f32_e32 v89, v93
	s_nop 0
	v_mul_f32_e32 v91, v91, v89
	s_and_saveexec_b64 s[0:1], vcc
	s_xor_b64 s[82:83], exec, s[0:1]
	s_cbranch_execz .LBB0_1395
	v_cndmask_b32_e64 v88, v91, v89, s[68:69]
	v_fma_f32 v88, v34, v88, v32
	v_cmp_gt_f32_e64 s[0:1], s92, v88
	s_nop 1
	v_cndmask_b32_e64 v92, 0, 32, s[0:1]
	v_ldexp_f32 v88, v88, v92
	v_log_f32_e32 v88, v88
	s_nop 0
	v_mul_f32_e32 v92, 0x3f317217, v88
	v_fma_f32 v92, v88, s96, -v92
	v_fmac_f32_e32 v92, 0x3377d1cf, v88
	v_fmac_f32_e32 v92, 0x3f317217, v88
	v_cmp_lt_f32_e64 s[72:73], |v88|, s33
	s_nop 1
	v_cndmask_b32_e64 v88, v88, v92, s[72:73]
	v_cndmask_b32_e64 v92, 0, v249, s[0:1]
	v_sub_f32_e32 v92, v88, v92

.LBB0_1397:
	s_or_b64 exec, exec, s[82:83]
	v_cndmask_b32_e64 v88, v89, v91, s[68:69]
	v_mul_f32_e32 v89, v34, v88
	v_add_f32_e32 v88, v90, v92
	v_mul_f32_e32 v90, 0x3fb8aa3b, v88
	v_exp_f32_e32 v90, v90
	s_mulk_i32 s7, 0x48
	s_waitcnt vmcnt(35)
	v_cmp_le_f32_e64 s[68:69], 0, v86
	v_mul_f32_e32 v87, v87, v90
	v_cvt_pk_bf16_f32 v87, v87, v87
	v_add_u32_e32 v90, s7, v68
	v_lshl_add_u32 v90, v90, 1, v76
	ds_write_b16 v90, v87
	v_mul_f32_e32 v87, 0xbfb8aa3b, v88
	v_exp_f32_e32 v87, v87
	s_nop 0
	v_mul_f32_e32 v87, v89, v87
	v_cvt_pk_bf16_f32 v87, v87, v87
	ds_write_b16 v90, v87 offset:4608
	v_mul_f32_e64 v87, |v86|, s81
	v_exp_f32_e32 v89, v87
	s_nop 0
	v_add_f32_e32 v91, 1.0, v89
	v_rcp_f32_e32 v87, v91
	s_nop 0
	v_mul_f32_e32 v89, v89, v87
	s_and_saveexec_b64 s[0:1], vcc
	s_xor_b64 s[82:83], exec, s[0:1]
	s_cbranch_execz .LBB0_1399
	v_cndmask_b32_e64 v86, v89, v87, s[68:69]
	v_fma_f32 v86, v34, v86, v32
	v_cmp_gt_f32_e64 s[0:1], s92, v86
	s_nop 1
	v_cndmask_b32_e64 v90, 0, 32, s[0:1]
	v_ldexp_f32 v86, v86, v90
	v_log_f32_e32 v86, v86
	s_nop 0
	v_mul_f32_e32 v90, 0x3f317217, v86
	v_fma_f32 v90, v86, s96, -v90
	v_fmac_f32_e32 v90, 0x3377d1cf, v86
	v_fmac_f32_e32 v90, 0x3f317217, v86
	v_cmp_lt_f32_e64 s[72:73], |v86|, s33
	s_nop 1
	v_cndmask_b32_e64 v86, v86, v90, s[72:73]
	v_cndmask_b32_e64 v90, 0, v249, s[0:1]
	v_sub_f32_e32 v90, v86, v90

.LBB0_1401:
	s_or_b64 exec, exec, s[82:83]
	v_cndmask_b32_e64 v86, v87, v89, s[68:69]
	v_mul_f32_e32 v87, v34, v86
	v_add_f32_e32 v86, v88, v90
	v_mul_f32_e32 v88, 0x3fb8aa3b, v86
	v_exp_f32_e32 v88, v88
	s_mulk_i32 s6, 0x48
	s_waitcnt vmcnt(33)
	v_cmp_le_f32_e64 s[68:69], 0, v84
	v_mul_f32_e32 v85, v85, v88
	v_cvt_pk_bf16_f32 v85, v85, v85
	v_add_u32_e32 v88, s6, v68
	v_lshl_add_u32 v88, v88, 1, v76
	ds_write_b16 v88, v85
	v_mul_f32_e32 v85, 0xbfb8aa3b, v86
	v_exp_f32_e32 v85, v85
	s_nop 0
	v_mul_f32_e32 v85, v87, v85
	v_cvt_pk_bf16_f32 v85, v85, v85
	ds_write_b16 v88, v85 offset:4608
	v_mul_f32_e64 v85, |v84|, s81
	v_exp_f32_e32 v87, v85
	s_nop 0
	v_add_f32_e32 v89, 1.0, v87
	v_rcp_f32_e32 v85, v89
	s_nop 0
	v_mul_f32_e32 v87, v87, v85
	s_and_saveexec_b64 s[0:1], vcc
	s_xor_b64 s[82:83], exec, s[0:1]
	s_cbranch_execz .LBB0_1403
	v_cndmask_b32_e64 v84, v87, v85, s[68:69]
	v_fma_f32 v84, v34, v84, v32
	v_cmp_gt_f32_e64 s[0:1], s92, v84
	s_nop 1
	v_cndmask_b32_e64 v88, 0, 32, s[0:1]
	v_ldexp_f32 v84, v84, v88
	v_log_f32_e32 v84, v84
	s_nop 0
	v_mul_f32_e32 v88, 0x3f317217, v84
	v_fma_f32 v88, v84, s96, -v88
	v_fmac_f32_e32 v88, 0x3377d1cf, v84
	v_fmac_f32_e32 v88, 0x3f317217, v84
	v_cmp_lt_f32_e64 s[72:73], |v84|, s33
	s_nop 1
	v_cndmask_b32_e64 v84, v84, v88, s[72:73]
	v_cndmask_b32_e64 v88, 0, v249, s[0:1]
	v_sub_f32_e32 v88, v84, v88

.LBB0_1405:
	s_or_b64 exec, exec, s[82:83]
	v_cndmask_b32_e64 v84, v85, v87, s[68:69]
	v_mul_f32_e32 v85, v34, v84
	v_add_f32_e32 v84, v86, v88
	v_mul_f32_e32 v86, 0x3fb8aa3b, v84
	v_exp_f32_e32 v86, v86
	s_mulk_i32 s5, 0x48
	s_waitcnt vmcnt(31)
	v_cmp_le_f32_e64 s[68:69], 0, v75
	v_mul_f32_e32 v83, v83, v86
	v_cvt_pk_bf16_f32 v83, v83, v83
	v_add_u32_e32 v86, s5, v68
	v_lshl_add_u32 v86, v86, 1, v76
	ds_write_b16 v86, v83
	v_mul_f32_e32 v83, 0xbfb8aa3b, v84
	v_exp_f32_e32 v83, v83
	s_nop 0
	v_mul_f32_e32 v83, v85, v83
	v_cvt_pk_bf16_f32 v83, v83, v83
	ds_write_b16 v86, v83 offset:4608
	v_mul_f32_e64 v83, |v75|, s81
	v_exp_f32_e32 v85, v83
	s_nop 0
	v_add_f32_e32 v87, 1.0, v85
	v_rcp_f32_e32 v83, v87
	s_nop 0
	v_mul_f32_e32 v85, v85, v83
	s_and_saveexec_b64 s[0:1], vcc
	s_xor_b64 s[82:83], exec, s[0:1]
	s_cbranch_execz .LBB0_1407
	v_cndmask_b32_e64 v75, v85, v83, s[68:69]
	v_fma_f32 v75, v34, v75, v32
	v_cmp_gt_f32_e64 s[0:1], s92, v75
	s_nop 1
	v_cndmask_b32_e64 v86, 0, 32, s[0:1]
	v_ldexp_f32 v75, v75, v86
	v_log_f32_e32 v75, v75
	s_nop 0
	v_mul_f32_e32 v86, 0x3f317217, v75
	v_fma_f32 v86, v75, s96, -v86
	v_fmac_f32_e32 v86, 0x3377d1cf, v75
	v_fmac_f32_e32 v86, 0x3f317217, v75
	v_cmp_lt_f32_e64 s[72:73], |v75|, s33
	s_nop 1
	v_cndmask_b32_e64 v75, v75, v86, s[72:73]
	v_cndmask_b32_e64 v86, 0, v249, s[0:1]
	v_sub_f32_e32 v86, v75, v86

.LBB0_1409:
	s_or_b64 exec, exec, s[82:83]
	v_cndmask_b32_e64 v75, v83, v85, s[68:69]
	v_mul_f32_e32 v83, v34, v75
	v_add_f32_e32 v75, v84, v86
	v_mul_f32_e32 v84, 0x3fb8aa3b, v75
	v_exp_f32_e32 v84, v84
	s_mulk_i32 s4, 0x48
	s_waitcnt vmcnt(29)
	v_cmp_le_f32_e64 s[68:69], 0, v63
	v_mul_f32_e32 v73, v73, v84
	v_cvt_pk_bf16_f32 v73, v73, v73
	v_add_u32_e32 v84, s4, v68
	v_lshl_add_u32 v84, v84, 1, v76
	ds_write_b16 v84, v73
	v_mul_f32_e32 v73, 0xbfb8aa3b, v75
	v_exp_f32_e32 v73, v73
	s_nop 0
	v_mul_f32_e32 v73, v83, v73
	v_cvt_pk_bf16_f32 v73, v73, v73
	ds_write_b16 v84, v73 offset:4608
	v_mul_f32_e64 v73, |v63|, s81
	v_exp_f32_e32 v83, v73
	s_nop 0
	v_add_f32_e32 v85, 1.0, v83
	v_rcp_f32_e32 v73, v85
	s_nop 0
	v_mul_f32_e32 v83, v83, v73
	s_and_saveexec_b64 s[0:1], vcc
	s_xor_b64 s[82:83], exec, s[0:1]
	s_cbranch_execz .LBB0_1411
	v_cndmask_b32_e64 v63, v83, v73, s[68:69]
	v_fma_f32 v63, v34, v63, v32
	v_cmp_gt_f32_e64 s[0:1], s92, v63
	s_nop 1
	v_cndmask_b32_e64 v84, 0, 32, s[0:1]
	v_ldexp_f32 v63, v63, v84
	v_log_f32_e32 v63, v63
	s_nop 0
	v_mul_f32_e32 v84, 0x3f317217, v63
	v_fma_f32 v84, v63, s96, -v84
	v_fmac_f32_e32 v84, 0x3377d1cf, v63
	v_fmac_f32_e32 v84, 0x3f317217, v63
	v_cmp_lt_f32_e64 s[72:73], |v63|, s33
	s_nop 1
	v_cndmask_b32_e64 v63, v63, v84, s[72:73]
	v_cndmask_b32_e64 v84, 0, v249, s[0:1]
	v_sub_f32_e32 v84, v63, v84

.LBB0_1413:
	s_or_b64 exec, exec, s[82:83]
	v_cndmask_b32_e64 v63, v73, v83, s[68:69]
	v_mul_f32_e32 v73, v34, v63
	v_add_f32_e32 v63, v75, v84
	v_mul_f32_e32 v75, 0x3fb8aa3b, v63
	v_exp_f32_e32 v75, v75
	s_mulk_i32 s87, 0x48
	s_waitcnt vmcnt(27)
	v_cmp_le_f32_e64 s[68:69], 0, v61
	v_mul_f32_e32 v62, v62, v75
	v_cvt_pk_bf16_f32 v62, v62, v62
	v_add_u32_e32 v75, s87, v68
	v_lshl_add_u32 v75, v75, 1, v76
	ds_write_b16 v75, v62
	v_mul_f32_e32 v62, 0xbfb8aa3b, v63
	v_exp_f32_e32 v62, v62
	s_nop 0
	v_mul_f32_e32 v62, v73, v62
	v_cvt_pk_bf16_f32 v62, v62, v62
	ds_write_b16 v75, v62 offset:4608
	v_mul_f32_e64 v62, |v61|, s81
	v_exp_f32_e32 v73, v62
	s_nop 0
	v_add_f32_e32 v83, 1.0, v73
	v_rcp_f32_e32 v62, v83
	s_nop 0
	v_mul_f32_e32 v73, v73, v62
	s_and_saveexec_b64 s[0:1], vcc
	s_xor_b64 s[82:83], exec, s[0:1]
	s_cbranch_execz .LBB0_1415
	v_cndmask_b32_e64 v61, v73, v62, s[68:69]
	v_fma_f32 v61, v34, v61, v32
	v_cmp_gt_f32_e64 s[0:1], s92, v61
	s_nop 1
	v_cndmask_b32_e64 v75, 0, 32, s[0:1]
	v_ldexp_f32 v61, v61, v75
	v_log_f32_e32 v61, v61
	s_nop 0
	v_mul_f32_e32 v75, 0x3f317217, v61
	v_fma_f32 v75, v61, s96, -v75
	v_fmac_f32_e32 v75, 0x3377d1cf, v61
	v_fmac_f32_e32 v75, 0x3f317217, v61
	v_cmp_lt_f32_e64 s[72:73], |v61|, s33
	s_nop 1
	v_cndmask_b32_e64 v61, v61, v75, s[72:73]
	v_cndmask_b32_e64 v75, 0, v249, s[0:1]
	v_sub_f32_e32 v75, v61, v75

.LBB0_1417:
	s_or_b64 exec, exec, s[82:83]
	v_cndmask_b32_e64 v61, v62, v73, s[68:69]
	v_mul_f32_e32 v62, v34, v61
	v_add_f32_e32 v61, v63, v75
	v_mul_f32_e32 v63, 0x3fb8aa3b, v61
	v_exp_f32_e32 v63, v63
	s_mulk_i32 s86, 0x48
	s_waitcnt vmcnt(25)
	v_cmp_le_f32_e64 s[68:69], 0, v59
	v_mul_f32_e32 v60, v60, v63
	v_cvt_pk_bf16_f32 v60, v60, v60
	v_add_u32_e32 v63, s86, v68
	v_lshl_add_u32 v63, v63, 1, v76
	ds_write_b16 v63, v60
	v_mul_f32_e32 v60, 0xbfb8aa3b, v61
	v_exp_f32_e32 v60, v60
	s_nop 0
	v_mul_f32_e32 v60, v62, v60
	v_cvt_pk_bf16_f32 v60, v60, v60
	ds_write_b16 v63, v60 offset:4608
	v_mul_f32_e64 v60, |v59|, s81
	v_exp_f32_e32 v62, v60
	s_nop 0
	v_add_f32_e32 v73, 1.0, v62
	v_rcp_f32_e32 v60, v73
	s_nop 0
	v_mul_f32_e32 v62, v62, v60
	s_and_saveexec_b64 s[0:1], vcc
	s_xor_b64 s[82:83], exec, s[0:1]
	s_cbranch_execz .LBB0_1419
	v_cndmask_b32_e64 v59, v62, v60, s[68:69]
	v_fma_f32 v59, v34, v59, v32
	v_cmp_gt_f32_e64 s[0:1], s92, v59
	s_nop 1
	v_cndmask_b32_e64 v63, 0, 32, s[0:1]
	v_ldexp_f32 v59, v59, v63
	v_log_f32_e32 v59, v59
	s_nop 0
	v_mul_f32_e32 v63, 0x3f317217, v59
	v_fma_f32 v63, v59, s96, -v63
	v_fmac_f32_e32 v63, 0x3377d1cf, v59
	v_fmac_f32_e32 v63, 0x3f317217, v59
	v_cmp_lt_f32_e64 s[72:73], |v59|, s33
	s_nop 1
	v_cndmask_b32_e64 v59, v59, v63, s[72:73]
	v_cndmask_b32_e64 v63, 0, v249, s[0:1]
	v_sub_f32_e32 v63, v59, v63

.LBB0_1421:
	s_or_b64 exec, exec, s[82:83]
	v_cndmask_b32_e64 v59, v60, v62, s[68:69]
	v_mul_f32_e32 v60, v34, v59
	v_add_f32_e32 v59, v61, v63
	v_mul_f32_e32 v61, 0x3fb8aa3b, v59
	v_exp_f32_e32 v61, v61
	s_mulk_i32 s85, 0x48
	s_waitcnt vmcnt(23)
	v_cmp_le_f32_e64 s[68:69], 0, v57
	v_mul_f32_e32 v58, v58, v61
	v_cvt_pk_bf16_f32 v58, v58, v58
	v_add_u32_e32 v61, s85, v68
	v_lshl_add_u32 v61, v61, 1, v76
	ds_write_b16 v61, v58
	v_mul_f32_e32 v58, 0xbfb8aa3b, v59
	v_exp_f32_e32 v58, v58
	s_nop 0
	v_mul_f32_e32 v58, v60, v58
	v_cvt_pk_bf16_f32 v58, v58, v58
	ds_write_b16 v61, v58 offset:4608
	v_mul_f32_e64 v58, |v57|, s81
	v_exp_f32_e32 v60, v58
	s_nop 0
	v_add_f32_e32 v62, 1.0, v60
	v_rcp_f32_e32 v58, v62
	s_nop 0
	v_mul_f32_e32 v60, v60, v58
	s_and_saveexec_b64 s[0:1], vcc
	s_xor_b64 s[82:83], exec, s[0:1]
	s_cbranch_execz .LBB0_1423
	v_cndmask_b32_e64 v57, v60, v58, s[68:69]
	v_fma_f32 v57, v34, v57, v32
	v_cmp_gt_f32_e64 s[0:1], s92, v57
	s_nop 1
	v_cndmask_b32_e64 v61, 0, 32, s[0:1]
	v_ldexp_f32 v57, v57, v61
	v_log_f32_e32 v57, v57
	s_nop 0
	v_mul_f32_e32 v61, 0x3f317217, v57
	v_fma_f32 v61, v57, s96, -v61
	v_fmac_f32_e32 v61, 0x3377d1cf, v57
	v_fmac_f32_e32 v61, 0x3f317217, v57
	v_cmp_lt_f32_e64 s[72:73], |v57|, s33
	s_nop 1
	v_cndmask_b32_e64 v57, v57, v61, s[72:73]
	v_cndmask_b32_e64 v61, 0, v249, s[0:1]
	v_sub_f32_e32 v61, v57, v61

.LBB0_1425:
	s_or_b64 exec, exec, s[82:83]
	v_cndmask_b32_e64 v57, v58, v60, s[68:69]
	v_mul_f32_e32 v58, v34, v57
	v_add_f32_e32 v57, v59, v61
	v_mul_f32_e32 v59, 0x3fb8aa3b, v57
	v_exp_f32_e32 v59, v59
	s_mulk_i32 s3, 0x48
	s_waitcnt vmcnt(21)
	v_cmp_le_f32_e64 s[68:69], 0, v55
	v_mul_f32_e32 v56, v56, v59
	v_cvt_pk_bf16_f32 v56, v56, v56
	v_add_u32_e32 v59, s3, v68
	v_lshl_add_u32 v59, v59, 1, v76
	ds_write_b16 v59, v56
	v_mul_f32_e32 v56, 0xbfb8aa3b, v57
	v_exp_f32_e32 v56, v56
	s_nop 0
	v_mul_f32_e32 v56, v58, v56
	v_cvt_pk_bf16_f32 v56, v56, v56
	ds_write_b16 v59, v56 offset:4608
	v_mul_f32_e64 v56, |v55|, s81
	v_exp_f32_e32 v58, v56
	s_nop 0
	v_add_f32_e32 v60, 1.0, v58
	v_rcp_f32_e32 v56, v60
	s_nop 0
	v_mul_f32_e32 v58, v58, v56
	s_and_saveexec_b64 s[0:1], vcc
	s_xor_b64 s[82:83], exec, s[0:1]
	s_cbranch_execz .LBB0_1427
	v_cndmask_b32_e64 v55, v58, v56, s[68:69]
	v_fma_f32 v55, v34, v55, v32
	v_cmp_gt_f32_e64 s[0:1], s92, v55
	s_nop 1
	v_cndmask_b32_e64 v59, 0, 32, s[0:1]
	v_ldexp_f32 v55, v55, v59
	v_log_f32_e32 v55, v55
	s_nop 0
	v_mul_f32_e32 v59, 0x3f317217, v55
	v_fma_f32 v59, v55, s96, -v59
	v_fmac_f32_e32 v59, 0x3377d1cf, v55
	v_fmac_f32_e32 v59, 0x3f317217, v55
	v_cmp_lt_f32_e64 s[72:73], |v55|, s33
	s_nop 1
	v_cndmask_b32_e64 v55, v55, v59, s[72:73]
	v_cndmask_b32_e64 v59, 0, v249, s[0:1]
	v_sub_f32_e32 v59, v55, v59

.LBB0_1429:
	s_or_b64 exec, exec, s[82:83]
	v_cndmask_b32_e64 v55, v56, v58, s[68:69]
	v_mul_f32_e32 v56, v34, v55
	v_add_f32_e32 v55, v57, v59
	v_mul_f32_e32 v57, 0x3fb8aa3b, v55
	v_exp_f32_e32 v57, v57
	s_mulk_i32 s2, 0x48
	s_waitcnt vmcnt(19)
	v_cmp_le_f32_e64 s[68:69], 0, v53
	v_mul_f32_e32 v54, v54, v57
	v_cvt_pk_bf16_f32 v54, v54, v54
	v_add_u32_e32 v57, s2, v68
	v_lshl_add_u32 v57, v57, 1, v76
	ds_write_b16 v57, v54
	v_mul_f32_e32 v54, 0xbfb8aa3b, v55
	v_exp_f32_e32 v54, v54
	s_nop 0
	v_mul_f32_e32 v54, v56, v54
	v_cvt_pk_bf16_f32 v54, v54, v54
	ds_write_b16 v57, v54 offset:4608
	v_mul_f32_e64 v54, |v53|, s81
	v_exp_f32_e32 v56, v54
	s_nop 0
	v_add_f32_e32 v58, 1.0, v56
	v_rcp_f32_e32 v54, v58
	s_nop 0
	v_mul_f32_e32 v56, v56, v54
	s_and_saveexec_b64 s[0:1], vcc
	s_xor_b64 s[82:83], exec, s[0:1]
	s_cbranch_execz .LBB0_1431
	v_cndmask_b32_e64 v53, v56, v54, s[68:69]
	v_fma_f32 v53, v34, v53, v32
	v_cmp_gt_f32_e64 s[0:1], s92, v53
	s_nop 1
	v_cndmask_b32_e64 v57, 0, 32, s[0:1]
	v_ldexp_f32 v53, v53, v57
	v_log_f32_e32 v53, v53
	s_nop 0
	v_mul_f32_e32 v57, 0x3f317217, v53
	v_fma_f32 v57, v53, s96, -v57
	v_fmac_f32_e32 v57, 0x3377d1cf, v53
	v_fmac_f32_e32 v57, 0x3f317217, v53
	v_cmp_lt_f32_e64 s[72:73], |v53|, s33
	s_nop 1
	v_cndmask_b32_e64 v53, v53, v57, s[72:73]
	v_cndmask_b32_e64 v57, 0, v249, s[0:1]
	v_sub_f32_e32 v57, v53, v57

.LBB0_1433:
	s_or_b64 exec, exec, s[82:83]
	v_cndmask_b32_e64 v53, v54, v56, s[68:69]
	v_mul_f32_e32 v54, v34, v53
	v_add_f32_e32 v53, v55, v57
	v_mul_f32_e32 v55, 0x3fb8aa3b, v53
	v_exp_f32_e32 v55, v55
	s_mulk_i32 s97, 0x48
	s_waitcnt vmcnt(17)
	v_cmp_le_f32_e64 s[68:69], 0, v51
	v_mul_f32_e32 v52, v52, v55
	v_cvt_pk_bf16_f32 v52, v52, v52
	v_add_u32_e32 v55, s97, v68
	v_lshl_add_u32 v55, v55, 1, v76
	ds_write_b16 v55, v52
	v_mul_f32_e32 v52, 0xbfb8aa3b, v53
	v_exp_f32_e32 v52, v52
	s_nop 0
	v_mul_f32_e32 v52, v54, v52
	v_cvt_pk_bf16_f32 v52, v52, v52
	ds_write_b16 v55, v52 offset:4608
	v_mul_f32_e64 v52, |v51|, s81
	v_exp_f32_e32 v54, v52
	s_nop 0
	v_add_f32_e32 v56, 1.0, v54
	v_rcp_f32_e32 v52, v56
	s_nop 0
	v_mul_f32_e32 v54, v54, v52
	s_and_saveexec_b64 s[0:1], vcc
	s_xor_b64 s[82:83], exec, s[0:1]
	s_cbranch_execz .LBB0_1435
	v_cndmask_b32_e64 v51, v54, v52, s[68:69]
	v_fma_f32 v51, v34, v51, v32
	v_cmp_gt_f32_e64 s[0:1], s92, v51
	s_nop 1
	v_cndmask_b32_e64 v55, 0, 32, s[0:1]
	v_ldexp_f32 v51, v51, v55
	v_log_f32_e32 v51, v51
	s_nop 0
	v_mul_f32_e32 v55, 0x3f317217, v51
	v_fma_f32 v55, v51, s96, -v55
	v_fmac_f32_e32 v55, 0x3377d1cf, v51
	v_fmac_f32_e32 v55, 0x3f317217, v51
	v_cmp_lt_f32_e64 s[72:73], |v51|, s33
	s_nop 1
	v_cndmask_b32_e64 v51, v51, v55, s[72:73]
	v_cndmask_b32_e64 v55, 0, v249, s[0:1]
	v_sub_f32_e32 v55, v51, v55

.LBB0_1437:
	s_or_b64 exec, exec, s[82:83]
	v_cndmask_b32_e64 v51, v52, v54, s[68:69]
	v_mul_f32_e32 v52, v34, v51
	v_add_f32_e32 v51, v53, v55
	v_mul_f32_e32 v53, 0x3fb8aa3b, v51
	v_exp_f32_e32 v53, v53
	s_mulk_i32 s88, 0x48
	s_waitcnt vmcnt(15)
	v_cmp_le_f32_e64 s[68:69], 0, v49
	v_mul_f32_e32 v50, v50, v53
	v_cvt_pk_bf16_f32 v50, v50, v50
	v_add_u32_e32 v53, s88, v68
	v_lshl_add_u32 v53, v53, 1, v76
	ds_write_b16 v53, v50
	v_mul_f32_e32 v50, 0xbfb8aa3b, v51
	v_exp_f32_e32 v50, v50
	s_nop 0
	v_mul_f32_e32 v50, v52, v50
	v_cvt_pk_bf16_f32 v50, v50, v50
	ds_write_b16 v53, v50 offset:4608
	v_mul_f32_e64 v50, |v49|, s81
	v_exp_f32_e32 v52, v50
	s_nop 0
	v_add_f32_e32 v54, 1.0, v52
	v_rcp_f32_e32 v50, v54
	s_nop 0
	v_mul_f32_e32 v52, v52, v50
	s_and_saveexec_b64 s[0:1], vcc
	s_xor_b64 s[82:83], exec, s[0:1]
	s_cbranch_execz .LBB0_1439
	v_cndmask_b32_e64 v49, v52, v50, s[68:69]
	v_fma_f32 v49, v34, v49, v32
	v_cmp_gt_f32_e64 s[0:1], s92, v49
	s_nop 1
	v_cndmask_b32_e64 v53, 0, 32, s[0:1]
	v_ldexp_f32 v49, v49, v53
	v_log_f32_e32 v49, v49
	s_nop 0
	v_mul_f32_e32 v53, 0x3f317217, v49
	v_fma_f32 v53, v49, s96, -v53
	v_fmac_f32_e32 v53, 0x3377d1cf, v49
	v_fmac_f32_e32 v53, 0x3f317217, v49
	v_cmp_lt_f32_e64 s[72:73], |v49|, s33
	s_nop 1
	v_cndmask_b32_e64 v49, v49, v53, s[72:73]
	v_cndmask_b32_e64 v53, 0, v249, s[0:1]
	v_sub_f32_e32 v53, v49, v53

.LBB0_1441:
	s_or_b64 exec, exec, s[82:83]
	v_cndmask_b32_e64 v49, v50, v52, s[68:69]
	v_mul_f32_e32 v50, v34, v49
	v_add_f32_e32 v49, v51, v53
	v_mul_f32_e32 v51, 0x3fb8aa3b, v49
	v_exp_f32_e32 v51, v51
	s_mulk_i32 s91, 0x48
	s_waitcnt vmcnt(13)
	v_cmp_le_f32_e64 s[68:69], 0, v47
	v_mul_f32_e32 v48, v48, v51
	v_cvt_pk_bf16_f32 v48, v48, v48
	v_add_u32_e32 v51, s91, v68
	v_lshl_add_u32 v51, v51, 1, v76
	ds_write_b16 v51, v48
	v_mul_f32_e32 v48, 0xbfb8aa3b, v49
	v_exp_f32_e32 v48, v48
	s_nop 0
	v_mul_f32_e32 v48, v50, v48
	v_cvt_pk_bf16_f32 v48, v48, v48
	ds_write_b16 v51, v48 offset:4608
	v_mul_f32_e64 v48, |v47|, s81
	v_exp_f32_e32 v50, v48
	s_nop 0
	v_add_f32_e32 v52, 1.0, v50
	v_rcp_f32_e32 v48, v52
	s_nop 0
	v_mul_f32_e32 v50, v50, v48
	s_and_saveexec_b64 s[0:1], vcc
	s_xor_b64 s[82:83], exec, s[0:1]
	s_cbranch_execz .LBB0_1443
	v_cndmask_b32_e64 v47, v50, v48, s[68:69]
	v_fma_f32 v47, v34, v47, v32
	v_cmp_gt_f32_e64 s[0:1], s92, v47
	s_nop 1
	v_cndmask_b32_e64 v51, 0, 32, s[0:1]
	v_ldexp_f32 v47, v47, v51
	v_log_f32_e32 v47, v47
	s_nop 0
	v_mul_f32_e32 v51, 0x3f317217, v47
	v_fma_f32 v51, v47, s96, -v51
	v_fmac_f32_e32 v51, 0x3377d1cf, v47
	v_fmac_f32_e32 v51, 0x3f317217, v47
	v_cmp_lt_f32_e64 s[72:73], |v47|, s33
	s_nop 1
	v_cndmask_b32_e64 v47, v47, v51, s[72:73]
	v_cndmask_b32_e64 v51, 0, v249, s[0:1]
	v_sub_f32_e32 v51, v47, v51

.LBB0_1445:
	s_or_b64 exec, exec, s[82:83]
	v_cndmask_b32_e64 v47, v48, v50, s[68:69]
	v_mul_f32_e32 v48, v34, v47
	v_add_f32_e32 v47, v49, v51
	v_mul_f32_e32 v49, 0x3fb8aa3b, v47
	v_exp_f32_e32 v49, v49
	s_mulk_i32 s90, 0x48
	s_waitcnt vmcnt(11)
	v_cmp_le_f32_e64 s[68:69], 0, v45
	v_mul_f32_e32 v46, v46, v49
	v_cvt_pk_bf16_f32 v46, v46, v46
	v_add_u32_e32 v49, s90, v68
	v_lshl_add_u32 v49, v49, 1, v76
	ds_write_b16 v49, v46
	v_mul_f32_e32 v46, 0xbfb8aa3b, v47
	v_exp_f32_e32 v46, v46
	s_nop 0
	v_mul_f32_e32 v46, v48, v46
	v_cvt_pk_bf16_f32 v46, v46, v46
	ds_write_b16 v49, v46 offset:4608
	v_mul_f32_e64 v46, |v45|, s81
	v_exp_f32_e32 v48, v46
	s_nop 0
	v_add_f32_e32 v50, 1.0, v48
	v_rcp_f32_e32 v46, v50
	s_nop 0
	v_mul_f32_e32 v48, v48, v46
	s_and_saveexec_b64 s[0:1], vcc
	s_xor_b64 s[82:83], exec, s[0:1]
	s_cbranch_execz .LBB0_1447
	v_cndmask_b32_e64 v45, v48, v46, s[68:69]
	v_fma_f32 v45, v34, v45, v32
	v_cmp_gt_f32_e64 s[0:1], s92, v45
	s_nop 1
	v_cndmask_b32_e64 v49, 0, 32, s[0:1]
	v_ldexp_f32 v45, v45, v49
	v_log_f32_e32 v45, v45
	s_nop 0
	v_mul_f32_e32 v49, 0x3f317217, v45
	v_fma_f32 v49, v45, s96, -v49
	v_fmac_f32_e32 v49, 0x3377d1cf, v45
	v_fmac_f32_e32 v49, 0x3f317217, v45
	v_cmp_lt_f32_e64 s[72:73], |v45|, s33
	s_nop 1
	v_cndmask_b32_e64 v45, v45, v49, s[72:73]
	v_cndmask_b32_e64 v49, 0, v249, s[0:1]
	v_sub_f32_e32 v49, v45, v49

.LBB0_1449:
	s_or_b64 exec, exec, s[82:83]
	v_cndmask_b32_e64 v45, v46, v48, s[68:69]
	v_mul_f32_e32 v46, v34, v45
	v_add_f32_e32 v45, v47, v49
	v_mul_f32_e32 v47, 0x3fb8aa3b, v45
	v_exp_f32_e32 v47, v47
	s_mulk_i32 s74, 0x48
	s_waitcnt vmcnt(9)
	v_cmp_le_f32_e64 s[68:69], 0, v43
	v_mul_f32_e32 v44, v44, v47
	v_cvt_pk_bf16_f32 v44, v44, v44
	v_add_u32_e32 v47, s74, v68
	v_lshl_add_u32 v47, v47, 1, v76
	ds_write_b16 v47, v44
	v_mul_f32_e32 v44, 0xbfb8aa3b, v45
	v_exp_f32_e32 v44, v44
	s_nop 0
	v_mul_f32_e32 v44, v46, v44
	v_cvt_pk_bf16_f32 v44, v44, v44
	ds_write_b16 v47, v44 offset:4608
	v_mul_f32_e64 v44, |v43|, s81
	v_exp_f32_e32 v46, v44
	s_nop 0
	v_add_f32_e32 v48, 1.0, v46
	v_rcp_f32_e32 v44, v48
	s_nop 0
	v_mul_f32_e32 v46, v46, v44
	s_and_saveexec_b64 s[0:1], vcc
	s_xor_b64 s[82:83], exec, s[0:1]
	s_cbranch_execz .LBB0_1451
	v_cndmask_b32_e64 v43, v46, v44, s[68:69]
	v_fma_f32 v43, v34, v43, v32
	v_cmp_gt_f32_e64 s[0:1], s92, v43
	s_nop 1
	v_cndmask_b32_e64 v47, 0, 32, s[0:1]
	v_ldexp_f32 v43, v43, v47
	v_log_f32_e32 v43, v43
	s_nop 0
	v_mul_f32_e32 v47, 0x3f317217, v43
	v_fma_f32 v47, v43, s96, -v47
	v_fmac_f32_e32 v47, 0x3377d1cf, v43
	v_fmac_f32_e32 v47, 0x3f317217, v43
	v_cmp_lt_f32_e64 s[72:73], |v43|, s33
	s_nop 1
	v_cndmask_b32_e64 v43, v43, v47, s[72:73]
	v_cndmask_b32_e64 v47, 0, v249, s[0:1]
	v_sub_f32_e32 v47, v43, v47

.LBB0_1453:
	s_or_b64 exec, exec, s[82:83]
	v_cndmask_b32_e64 v43, v44, v46, s[68:69]
	v_mul_f32_e32 v44, v34, v43
	v_add_f32_e32 v43, v45, v47
	v_mul_f32_e32 v45, 0x3fb8aa3b, v43
	v_exp_f32_e32 v45, v45
	s_mulk_i32 s80, 0x48
	s_waitcnt vmcnt(7)
	v_cmp_le_f32_e64 s[68:69], 0, v41
	v_mul_f32_e32 v42, v42, v45
	v_cvt_pk_bf16_f32 v42, v42, v42
	v_add_u32_e32 v45, s80, v68
	v_lshl_add_u32 v45, v45, 1, v76
	ds_write_b16 v45, v42
	v_mul_f32_e32 v42, 0xbfb8aa3b, v43
	v_exp_f32_e32 v42, v42
	s_nop 0
	v_mul_f32_e32 v42, v44, v42
	v_cvt_pk_bf16_f32 v42, v42, v42
	ds_write_b16 v45, v42 offset:4608
	v_mul_f32_e64 v42, |v41|, s81
	v_exp_f32_e32 v44, v42
	s_nop 0
	v_add_f32_e32 v46, 1.0, v44
	v_rcp_f32_e32 v42, v46
	s_nop 0
	v_mul_f32_e32 v44, v44, v42
	s_and_saveexec_b64 s[0:1], vcc
	s_xor_b64 s[82:83], exec, s[0:1]
	s_cbranch_execz .LBB0_1455
	v_cndmask_b32_e64 v41, v44, v42, s[68:69]
	v_fma_f32 v41, v34, v41, v32
	v_cmp_gt_f32_e64 s[0:1], s92, v41
	s_nop 1
	v_cndmask_b32_e64 v45, 0, 32, s[0:1]
	v_ldexp_f32 v41, v41, v45
	v_log_f32_e32 v41, v41
	s_nop 0
	v_mul_f32_e32 v45, 0x3f317217, v41
	v_fma_f32 v45, v41, s96, -v45
	v_fmac_f32_e32 v45, 0x3377d1cf, v41
	v_fmac_f32_e32 v45, 0x3f317217, v41
	v_cmp_lt_f32_e64 s[72:73], |v41|, s33
	s_nop 1
	v_cndmask_b32_e64 v41, v41, v45, s[72:73]
	v_cndmask_b32_e64 v45, 0, v249, s[0:1]
	v_sub_f32_e32 v45, v41, v45

.LBB0_1457:
	s_or_b64 exec, exec, s[82:83]
	v_cndmask_b32_e64 v41, v42, v44, s[68:69]
	v_mul_f32_e32 v42, v34, v41
	v_add_f32_e32 v41, v43, v45
	v_mul_f32_e32 v43, 0x3fb8aa3b, v41
	v_exp_f32_e32 v43, v43
	s_mulk_i32 s93, 0x48
	s_waitcnt vmcnt(5)
	v_cmp_le_f32_e64 s[68:69], 0, v39
	v_mul_f32_e32 v40, v40, v43
	v_cvt_pk_bf16_f32 v40, v40, v40
	v_add_u32_e32 v43, s93, v68
	v_lshl_add_u32 v43, v43, 1, v76
	ds_write_b16 v43, v40
	v_mul_f32_e32 v40, 0xbfb8aa3b, v41
	v_exp_f32_e32 v40, v40
	s_nop 0
	v_mul_f32_e32 v40, v42, v40
	v_cvt_pk_bf16_f32 v40, v40, v40
	ds_write_b16 v43, v40 offset:4608
	v_mul_f32_e64 v40, |v39|, s81
	v_exp_f32_e32 v42, v40
	s_nop 0
	v_add_f32_e32 v44, 1.0, v42
	v_rcp_f32_e32 v40, v44
	s_nop 0
	v_mul_f32_e32 v42, v42, v40
	s_and_saveexec_b64 s[0:1], vcc
	s_xor_b64 s[82:83], exec, s[0:1]
	s_cbranch_execz .LBB0_1459
	v_cndmask_b32_e64 v39, v42, v40, s[68:69]
	v_fma_f32 v39, v34, v39, v32
	v_cmp_gt_f32_e64 s[0:1], s92, v39
	s_nop 1
	v_cndmask_b32_e64 v43, 0, 32, s[0:1]
	v_ldexp_f32 v39, v39, v43
	v_log_f32_e32 v39, v39
	s_nop 0
	v_mul_f32_e32 v43, 0x3f317217, v39
	v_fma_f32 v43, v39, s96, -v43
	v_fmac_f32_e32 v43, 0x3377d1cf, v39
	v_fmac_f32_e32 v43, 0x3f317217, v39
	v_cmp_lt_f32_e64 s[72:73], |v39|, s33
	s_nop 1
	v_cndmask_b32_e64 v39, v39, v43, s[72:73]
	v_cndmask_b32_e64 v43, 0, v249, s[0:1]
	v_sub_f32_e32 v43, v39, v43

.LBB0_1461:
	s_or_b64 exec, exec, s[82:83]
	v_cndmask_b32_e64 v39, v40, v42, s[68:69]
	v_mul_f32_e32 v40, v34, v39
	v_add_f32_e32 v39, v41, v43
	v_mul_f32_e32 v41, 0x3fb8aa3b, v39
	v_exp_f32_e32 v41, v41
	s_mulk_i32 s84, 0x48
	s_waitcnt vmcnt(3)
	v_cmp_le_f32_e64 s[68:69], 0, v37
	v_mul_f32_e32 v38, v38, v41
	v_cvt_pk_bf16_f32 v38, v38, v38
	v_add_u32_e32 v41, s84, v68
	v_lshl_add_u32 v41, v41, 1, v76
	ds_write_b16 v41, v38
	v_mul_f32_e32 v38, 0xbfb8aa3b, v39
	v_exp_f32_e32 v38, v38
	s_nop 0
	v_mul_f32_e32 v38, v40, v38
	v_cvt_pk_bf16_f32 v38, v38, v38
	ds_write_b16 v41, v38 offset:4608
	v_mul_f32_e64 v38, |v37|, s81
	v_exp_f32_e32 v40, v38
	s_nop 0
	v_add_f32_e32 v42, 1.0, v40
	v_rcp_f32_e32 v38, v42
	s_nop 0
	v_mul_f32_e32 v40, v40, v38
	s_and_saveexec_b64 s[0:1], vcc
	s_xor_b64 s[82:83], exec, s[0:1]
	s_cbranch_execz .LBB0_1463
	v_cndmask_b32_e64 v37, v40, v38, s[68:69]
	v_fma_f32 v37, v34, v37, v32
	v_cmp_gt_f32_e64 s[0:1], s92, v37
	s_nop 1
	v_cndmask_b32_e64 v41, 0, 32, s[0:1]
	v_ldexp_f32 v37, v37, v41
	v_log_f32_e32 v37, v37
	s_nop 0
	v_mul_f32_e32 v41, 0x3f317217, v37
	v_fma_f32 v41, v37, s96, -v41
	v_fmac_f32_e32 v41, 0x3377d1cf, v37
	v_fmac_f32_e32 v41, 0x3f317217, v37
	v_cmp_lt_f32_e64 s[72:73], |v37|, s33
	s_nop 1
	v_cndmask_b32_e64 v37, v37, v41, s[72:73]
	v_cndmask_b32_e64 v41, 0, v249, s[0:1]
	v_sub_f32_e32 v41, v37, v41

.LBB0_1465:
	s_or_b64 exec, exec, s[82:83]
	v_cndmask_b32_e64 v37, v38, v40, s[68:69]
	v_mul_f32_e32 v38, v34, v37
	v_add_f32_e32 v37, v39, v41
	v_mul_f32_e32 v39, 0x3fb8aa3b, v37
	v_exp_f32_e32 v39, v39
	s_mulk_i32 s77, 0x48
	s_waitcnt vmcnt(0)
	v_cmp_le_f32_e64 s[68:69], 0, v35
	v_mul_f32_e32 v36, v36, v39
	v_cvt_pk_bf16_f32 v36, v36, v36
	v_add_u32_e32 v39, s77, v68
	v_lshl_add_u32 v39, v39, 1, v76
	ds_write_b16 v39, v36
	v_mul_f32_e32 v36, 0xbfb8aa3b, v37
	v_exp_f32_e32 v36, v36
	s_nop 0
	v_mul_f32_e32 v36, v38, v36
	v_cvt_pk_bf16_f32 v36, v36, v36
	ds_write_b16 v39, v36 offset:4608
	v_mul_f32_e64 v36, |v35|, s81
	v_exp_f32_e32 v38, v36
	s_nop 0
	v_add_f32_e32 v40, 1.0, v38
	v_rcp_f32_e32 v36, v40
	s_nop 0
	v_mul_f32_e32 v38, v38, v36
	s_and_saveexec_b64 s[0:1], vcc
	s_xor_b64 s[72:73], exec, s[0:1]
	s_cbranch_execz .LBB0_1467
	v_cndmask_b32_e64 v35, v38, v36, s[68:69]
	v_fmac_f32_e32 v32, v34, v35
	v_cmp_gt_f32_e32 vcc, s92, v32
	s_nop 1
	v_cndmask_b32_e64 v35, 0, 32, vcc
	v_ldexp_f32 v32, v32, v35
	v_log_f32_e32 v32, v32
	s_nop 0
	v_mul_f32_e32 v35, 0x3f317217, v32
	v_fma_f32 v35, v32, s96, -v35
	v_fmac_f32_e32 v35, 0x3377d1cf, v32
	v_fmac_f32_e32 v35, 0x3f317217, v32
	v_cmp_lt_f32_e64 s[0:1], |v32|, s33
	s_nop 1
	v_cndmask_b32_e64 v32, v32, v35, s[0:1]
	v_cndmask_b32_e32 v35, 0, v249, vcc
	v_sub_f32_e32 v39, v32, v35

.LBB0_1473:
	s_or_b64 exec, exec, s[0:1]
	s_waitcnt lgkmcnt(0)
	s_barrier
	ds_read_b64 v[2:3], v229 offset:63760
	v_readlane_b32 s0, v255, 27
	v_or_b32_e32 v18, s7, v0
	v_ashrrev_i32_e32 v19, 31, v18
	v_add_u32_e32 v4, s0, v34
	s_waitcnt lgkmcnt(0)
	v_lshl_add_u64 v[16:17], v[2:3], 0, s[58:59]
	ds_read_b64 v[2:3], v229 offset:63696
	v_ashrrev_i32_e32 v5, 31, v4
	v_lshlrev_b32_e32 v44, 2, v0
	v_lshlrev_b64 v[0:1], 11, v[18:19]
	v_lshlrev_b64 v[20:21], 1, v[34:35]
	s_waitcnt lgkmcnt(0)
	v_lshl_add_u64 v[4:5], v[4:5], 2, v[2:3]
	global_load_dword v19, v[4:5], off
	v_add_u32_e32 v4, s0, v32
	v_ashrrev_i32_e32 v5, 31, v4
	v_lshl_add_u64 v[2:3], v[4:5], 2, v[2:3]
	global_load_dword v34, v[2:3], off
	v_lshl_add_u64 v[0:1], v[16:17], 0, v[0:1]
	v_lshlrev_b64 v[22:23], 1, v[32:33]
	v_lshl_add_u64 v[28:29], v[0:1], 0, v[20:21]
	v_lshl_add_u64 v[32:33], v[0:1], 0, v[22:23]
	ds_read_b128 v[4:7], v44 offset:51712
	ds_read_b128 v[0:3], v44 offset:51744
	ds_read_b128 v[8:11], v44 offset:51840
	ds_read_b128 v[12:15], v44 offset:51968
	ds_read_b128 v[24:27], v44 offset:52096
	v_readlane_b32 s1, v255, 28
	s_mov_b32 s0, 0x358637bd
	s_waitcnt lgkmcnt(2)
	v_pk_add_f32 v[4:5], v[4:5], v[8:9]
	v_pk_add_f32 v[6:7], v[6:7], v[10:11]
	s_waitcnt lgkmcnt(1)
	v_pk_add_f32 v[4:5], v[4:5], v[12:13]
	v_pk_add_f32 v[6:7], v[6:7], v[14:15]
	s_waitcnt lgkmcnt(0)
	v_pk_add_f32 v[4:5], v[4:5], v[24:25]
	v_mov_b64_e32 v[24:25], s[0:1]
	v_pk_fma_f32 v[4:5], v[4:5], s[68:69], v[24:25] op_sel_hi:[1,0,0]
	v_pk_add_f32 v[6:7], v[6:7], v[26:27]
	v_mul_f32_e32 v8, 0x4b800000, v4
	v_cmp_gt_f32_e64 s[0:1], s92, v4
	v_cmp_gt_f32_e32 vcc, s92, v5
	v_pk_fma_f32 v[6:7], v[6:7], s[68:69], v[24:25] op_sel_hi:[1,0,0]
	v_cndmask_b32_e64 v4, v4, v8, s[0:1]
	v_rsq_f32_e32 v4, v4
	v_mul_f32_e32 v10, 0x4b800000, v6
	s_add_i32 s2, s2, s69
	s_cmpk_gt_i32 s2, 0xff
	v_mul_f32_e32 v8, 0x45800000, v4
	v_cndmask_b32_e64 v4, v4, v8, s[0:1]
	v_mul_f32_e32 v8, v67, v4
	v_mul_f32_e32 v4, v66, v4
	v_cmp_gt_f32_e64 s[0:1], s92, v6
	s_waitcnt vmcnt(1)
	v_mul_f32_e32 v8, v19, v8
	v_cvt_pk_bf16_f32 v8, v8, v8
	global_store_short v[28:29], v8, off
	s_waitcnt vmcnt(1)
	v_mul_f32_e32 v4, v34, v4
	v_cvt_pk_bf16_f32 v4, v4, v4
	global_store_short v[32:33], v4, off
	v_mul_f32_e32 v4, 0x4b800000, v5
	v_cndmask_b32_e32 v4, v5, v4, vcc
	v_rsq_f32_e32 v4, v4
	v_cndmask_b32_e64 v6, v6, v10, s[0:1]
	v_rsq_f32_e32 v6, v6
	v_mul_f32_e32 v5, 0x45800000, v4
	v_cndmask_b32_e32 v12, v4, v5, vcc
	v_or_b32_e32 v4, s7, v62
	v_ashrrev_i32_e32 v5, 31, v4
	v_mul_f32_e32 v8, v65, v12
	v_lshlrev_b64 v[4:5], 11, v[4:5]
	v_mul_f32_e32 v8, v19, v8
	v_lshl_add_u64 v[4:5], v[16:17], 0, v[4:5]
	v_cvt_pk_bf16_f32 v13, v8, v8
	v_lshl_add_u64 v[8:9], v[4:5], 0, v[20:21]
	global_store_short v[8:9], v13, off
	v_mul_f32_e32 v8, v63, v12
	v_mul_f32_e32 v8, v34, v8
	v_cvt_pk_bf16_f32 v8, v8, v8
	v_lshl_add_u64 v[4:5], v[4:5], 0, v[22:23]
	v_mul_f32_e32 v10, 0x45800000, v6
	global_store_short v[4:5], v8, off
	v_or_b32_e32 v4, 2, v18
	v_cndmask_b32_e64 v6, v6, v10, s[0:1]
	v_ashrrev_i32_e32 v5, 31, v4
	v_mul_f32_e32 v10, v60, v6
	v_lshlrev_b64 v[4:5], 11, v[4:5]
	v_mul_f32_e32 v10, v19, v10
	v_lshl_add_u64 v[4:5], v[16:17], 0, v[4:5]
	v_mul_f32_e32 v6, v59, v6
	v_lshl_add_u64 v[8:9], v[4:5], 0, v[20:21]
	v_cvt_pk_bf16_f32 v10, v10, v10
	v_mul_f32_e32 v6, v34, v6
	global_store_short v[8:9], v10, off
	v_lshl_add_u64 v[4:5], v[4:5], 0, v[22:23]
	v_cvt_pk_bf16_f32 v6, v6, v6
	v_cmp_gt_f32_e32 vcc, s92, v7
	global_store_short v[4:5], v6, off
	v_mul_f32_e32 v4, 0x4b800000, v7
	v_cndmask_b32_e32 v4, v7, v4, vcc
	v_rsq_f32_e32 v4, v4
	ds_read_b128 v[12:15], v44 offset:52128
	v_mul_f32_e32 v5, 0x45800000, v4
	v_cndmask_b32_e32 v8, v4, v5, vcc
	v_or_b32_e32 v4, 3, v18
	v_ashrrev_i32_e32 v5, 31, v4
	v_mul_f32_e32 v6, v64, v8
	v_lshlrev_b64 v[4:5], 11, v[4:5]
	v_mul_f32_e32 v6, v19, v6
	v_lshl_add_u64 v[4:5], v[16:17], 0, v[4:5]
	v_cvt_pk_bf16_f32 v9, v6, v6
	v_lshl_add_u64 v[6:7], v[4:5], 0, v[20:21]
	global_store_short v[6:7], v9, off
	v_mul_f32_e32 v6, v61, v8
	v_mul_f32_e32 v6, v34, v6
	v_cvt_pk_bf16_f32 v6, v6, v6
	v_lshl_add_u64 v[4:5], v[4:5], 0, v[22:23]
	global_store_short v[4:5], v6, off
	v_or_b32_e32 v4, 8, v18
	v_ashrrev_i32_e32 v5, 31, v4
	v_lshlrev_b64 v[4:5], 11, v[4:5]
	v_lshl_add_u64 v[4:5], v[16:17], 0, v[4:5]
	v_lshl_add_u64 v[28:29], v[4:5], 0, v[20:21]
	v_lshl_add_u64 v[26:27], v[4:5], 0, v[22:23]
	ds_read_b128 v[4:7], v44 offset:51872
	ds_read_b128 v[8:11], v44 offset:52000
	s_waitcnt lgkmcnt(1)
	v_pk_add_f32 v[0:1], v[0:1], v[4:5]
	s_waitcnt lgkmcnt(0)
	v_pk_add_f32 v[0:1], v[0:1], v[8:9]
	v_pk_add_f32 v[2:3], v[2:3], v[6:7]
	v_pk_add_f32 v[0:1], v[0:1], v[12:13]
	v_pk_add_f32 v[2:3], v[2:3], v[10:11]
	v_pk_fma_f32 v[0:1], v[0:1], s[68:69], v[24:25] op_sel_hi:[1,0,0]
	v_pk_add_f32 v[2:3], v[2:3], v[14:15]
	v_mul_f32_e32 v4, 0x4b800000, v0
	v_cmp_gt_f32_e64 s[0:1], s92, v0
	v_cmp_gt_f32_e32 vcc, s92, v1
	v_pk_fma_f32 v[2:3], v[2:3], s[68:69], v[24:25] op_sel_hi:[1,0,0]
	v_cndmask_b32_e64 v0, v0, v4, s[0:1]
	v_rsq_f32_e32 v0, v0
	v_mul_f32_e32 v6, 0x4b800000, v2
	v_mul_f32_e32 v4, 0x45800000, v0
	v_cndmask_b32_e64 v0, v0, v4, s[0:1]
	v_mul_f32_e32 v4, v51, v0
	v_mul_f32_e32 v4, v19, v4
	v_mul_f32_e32 v0, v49, v0
	v_cvt_pk_bf16_f32 v4, v4, v4
	v_mul_f32_e32 v0, v34, v0
	global_store_short v[28:29], v4, off
	v_cvt_pk_bf16_f32 v0, v0, v0
	global_store_short v[26:27], v0, off
	v_mul_f32_e32 v0, 0x4b800000, v1
	v_cndmask_b32_e32 v0, v1, v0, vcc
	v_rsq_f32_e32 v0, v0
	v_cmp_gt_f32_e64 s[0:1], s92, v2
	v_mul_f32_e32 v1, 0x45800000, v0
	v_cndmask_b32_e32 v8, v0, v1, vcc
	v_or_b32_e32 v0, 9, v18
	v_ashrrev_i32_e32 v1, 31, v0
	v_mul_f32_e32 v4, v52, v8
	v_lshlrev_b64 v[0:1], 11, v[0:1]
	v_mul_f32_e32 v4, v19, v4
	v_lshl_add_u64 v[0:1], v[16:17], 0, v[0:1]
	v_cndmask_b32_e64 v2, v2, v6, s[0:1]
	v_cvt_pk_bf16_f32 v9, v4, v4
	v_lshl_add_u64 v[4:5], v[0:1], 0, v[20:21]
	v_rsq_f32_e32 v2, v2
	global_store_short v[4:5], v9, off
	v_mul_f32_e32 v4, v50, v8
	v_mul_f32_e32 v4, v34, v4
	v_cvt_pk_bf16_f32 v4, v4, v4
	v_lshl_add_u64 v[0:1], v[0:1], 0, v[22:23]
	v_mul_f32_e32 v6, 0x45800000, v2
	global_store_short v[0:1], v4, off
	v_or_b32_e32 v0, 10, v18
	v_cndmask_b32_e64 v2, v2, v6, s[0:1]
	v_ashrrev_i32_e32 v1, 31, v0
	v_mul_f32_e32 v6, v47, v2
	v_lshlrev_b64 v[0:1], 11, v[0:1]
	v_mul_f32_e32 v6, v19, v6
	v_lshl_add_u64 v[0:1], v[16:17], 0, v[0:1]
	v_mul_f32_e32 v2, v45, v2
	v_lshl_add_u64 v[4:5], v[0:1], 0, v[20:21]
	v_cvt_pk_bf16_f32 v6, v6, v6
	v_mul_f32_e32 v2, v34, v2
	global_store_short v[4:5], v6, off
	v_lshl_add_u64 v[0:1], v[0:1], 0, v[22:23]
	v_cvt_pk_bf16_f32 v2, v2, v2
	v_cmp_gt_f32_e32 vcc, s92, v3
	global_store_short v[0:1], v2, off
	v_mul_f32_e32 v0, 0x4b800000, v3
	v_cndmask_b32_e32 v0, v3, v0, vcc
	v_rsq_f32_e32 v0, v0
	s_nop 0
	v_mul_f32_e32 v1, 0x45800000, v0
	v_cndmask_b32_e32 v4, v0, v1, vcc
	v_or_b32_e32 v0, 11, v18
	v_ashrrev_i32_e32 v1, 31, v0
	v_mul_f32_e32 v2, v48, v4
	v_lshlrev_b64 v[0:1], 11, v[0:1]
	v_mul_f32_e32 v2, v19, v2
	v_lshl_add_u64 v[0:1], v[16:17], 0, v[0:1]
	v_cvt_pk_bf16_f32 v5, v2, v2
	v_lshl_add_u64 v[2:3], v[0:1], 0, v[20:21]
	global_store_short v[2:3], v5, off
	v_mul_f32_e32 v2, v46, v4
	v_mul_f32_e32 v2, v34, v2
	v_cvt_pk_bf16_f32 v2, v2, v2
	v_lshl_add_u64 v[0:1], v[0:1], 0, v[22:23]
	global_store_short v[0:1], v2, off
	v_or_b32_e32 v0, 16, v18
	v_ashrrev_i32_e32 v1, 31, v0
	v_lshlrev_b64 v[0:1], 11, v[0:1]
	v_lshl_add_u64 v[0:1], v[16:17], 0, v[0:1]
	v_lshl_add_u64 v[26:27], v[0:1], 0, v[20:21]
	v_lshl_add_u64 v[28:29], v[0:1], 0, v[22:23]
	ds_read_b128 v[0:3], v44 offset:51776
	ds_read_b128 v[4:7], v44 offset:51904
	ds_read_b128 v[8:11], v44 offset:52032
	ds_read_b128 v[12:15], v44 offset:52160
	s_waitcnt lgkmcnt(2)
	v_pk_add_f32 v[0:1], v[0:1], v[4:5]
	s_waitcnt lgkmcnt(1)
	v_pk_add_f32 v[0:1], v[0:1], v[8:9]
	v_pk_add_f32 v[2:3], v[2:3], v[6:7]
	s_waitcnt lgkmcnt(0)
	v_pk_add_f32 v[0:1], v[0:1], v[12:13]
	v_pk_add_f32 v[2:3], v[2:3], v[10:11]
	v_pk_fma_f32 v[0:1], v[0:1], s[68:69], v[24:25] op_sel_hi:[1,0,0]
	v_pk_add_f32 v[2:3], v[2:3], v[14:15]
	v_mul_f32_e32 v4, 0x4b800000, v0
	v_cmp_gt_f32_e64 s[0:1], s92, v0
	v_cmp_gt_f32_e32 vcc, s92, v1
	v_pk_fma_f32 v[2:3], v[2:3], s[68:69], v[24:25] op_sel_hi:[1,0,0]
	v_cndmask_b32_e64 v0, v0, v4, s[0:1]
	v_rsq_f32_e32 v0, v0
	v_mul_f32_e32 v6, 0x4b800000, v2
	v_mul_f32_e32 v4, 0x45800000, v0
	v_cndmask_b32_e64 v0, v0, v4, s[0:1]
	v_mul_f32_e32 v4, v43, v0
	v_mul_f32_e32 v4, v19, v4
	v_mul_f32_e32 v0, v42, v0
	v_cvt_pk_bf16_f32 v4, v4, v4
	v_mul_f32_e32 v0, v34, v0
	global_store_short v[26:27], v4, off
	v_cvt_pk_bf16_f32 v0, v0, v0
	global_store_short v[28:29], v0, off
	v_mul_f32_e32 v0, 0x4b800000, v1
	v_cndmask_b32_e32 v0, v1, v0, vcc
	v_rsq_f32_e32 v0, v0
	v_cmp_gt_f32_e64 s[0:1], s92, v2
	v_mul_f32_e32 v1, 0x45800000, v0
	v_cndmask_b32_e32 v8, v0, v1, vcc
	v_or_b32_e32 v0, 17, v18
	v_ashrrev_i32_e32 v1, 31, v0
	v_mul_f32_e32 v4, v54, v8
	v_lshlrev_b64 v[0:1], 11, v[0:1]
	v_mul_f32_e32 v4, v19, v4
	v_lshl_add_u64 v[0:1], v[16:17], 0, v[0:1]
	v_cndmask_b32_e64 v2, v2, v6, s[0:1]
	v_cvt_pk_bf16_f32 v9, v4, v4
	v_lshl_add_u64 v[4:5], v[0:1], 0, v[20:21]
	v_rsq_f32_e32 v2, v2
	global_store_short v[4:5], v9, off
	v_mul_f32_e32 v4, v53, v8
	v_mul_f32_e32 v4, v34, v4
	v_cvt_pk_bf16_f32 v4, v4, v4
	v_lshl_add_u64 v[0:1], v[0:1], 0, v[22:23]
	v_mul_f32_e32 v6, 0x45800000, v2
	global_store_short v[0:1], v4, off
	v_or_b32_e32 v0, 18, v18
	v_cndmask_b32_e64 v2, v2, v6, s[0:1]
	v_ashrrev_i32_e32 v1, 31, v0
	v_mul_f32_e32 v6, v56, v2
	v_lshlrev_b64 v[0:1], 11, v[0:1]
	v_mul_f32_e32 v6, v19, v6
	v_lshl_add_u64 v[0:1], v[16:17], 0, v[0:1]
	v_mul_f32_e32 v2, v55, v2
	v_lshl_add_u64 v[4:5], v[0:1], 0, v[20:21]
	v_cvt_pk_bf16_f32 v6, v6, v6
	v_mul_f32_e32 v2, v34, v2
	global_store_short v[4:5], v6, off
	v_lshl_add_u64 v[0:1], v[0:1], 0, v[22:23]
	v_cvt_pk_bf16_f32 v2, v2, v2
	v_cmp_gt_f32_e32 vcc, s92, v3
	global_store_short v[0:1], v2, off
	v_mul_f32_e32 v0, 0x4b800000, v3
	v_cndmask_b32_e32 v0, v3, v0, vcc
	v_rsq_f32_e32 v0, v0
	s_nop 0
	v_mul_f32_e32 v1, 0x45800000, v0
	v_cndmask_b32_e32 v4, v0, v1, vcc
	v_or_b32_e32 v0, 19, v18
	v_ashrrev_i32_e32 v1, 31, v0
	v_mul_f32_e32 v2, v58, v4
	v_lshlrev_b64 v[0:1], 11, v[0:1]
	v_mul_f32_e32 v2, v19, v2
	v_lshl_add_u64 v[0:1], v[16:17], 0, v[0:1]
	v_cvt_pk_bf16_f32 v5, v2, v2
	v_lshl_add_u64 v[2:3], v[0:1], 0, v[20:21]
	global_store_short v[2:3], v5, off
	v_mul_f32_e32 v2, v57, v4
	v_mul_f32_e32 v2, v34, v2
	v_cvt_pk_bf16_f32 v2, v2, v2
	v_lshl_add_u64 v[0:1], v[0:1], 0, v[22:23]
	global_store_short v[0:1], v2, off
	v_or_b32_e32 v0, 24, v18
	v_ashrrev_i32_e32 v1, 31, v0
	v_lshlrev_b64 v[0:1], 11, v[0:1]
	v_lshl_add_u64 v[0:1], v[16:17], 0, v[0:1]
	v_lshl_add_u64 v[28:29], v[0:1], 0, v[20:21]
	v_lshl_add_u64 v[26:27], v[0:1], 0, v[22:23]
	ds_read_b128 v[0:3], v44 offset:51808
	ds_read_b128 v[4:7], v44 offset:51936
	ds_read_b128 v[8:11], v44 offset:52064
	ds_read_b128 v[12:15], v44 offset:52192
	s_waitcnt lgkmcnt(2)
	v_pk_add_f32 v[0:1], v[0:1], v[4:5]
	s_waitcnt lgkmcnt(1)
	v_pk_add_f32 v[0:1], v[0:1], v[8:9]
	v_pk_add_f32 v[2:3], v[2:3], v[6:7]
	s_waitcnt lgkmcnt(0)
	v_pk_add_f32 v[0:1], v[0:1], v[12:13]
	v_pk_add_f32 v[2:3], v[2:3], v[10:11]
	v_pk_fma_f32 v[0:1], v[0:1], s[68:69], v[24:25] op_sel_hi:[1,0,0]
	v_pk_add_f32 v[2:3], v[2:3], v[14:15]
	v_mul_f32_e32 v4, 0x4b800000, v0
	v_cmp_gt_f32_e64 s[0:1], s92, v0
	v_cmp_gt_f32_e32 vcc, s92, v1
	v_pk_fma_f32 v[2:3], v[2:3], s[68:69], v[24:25] op_sel_hi:[1,0,0]
	v_cndmask_b32_e64 v0, v0, v4, s[0:1]
	v_rsq_f32_e32 v0, v0
	v_mul_f32_e32 v6, 0x4b800000, v2
	v_mul_f32_e32 v4, 0x45800000, v0
	v_cndmask_b32_e64 v0, v0, v4, s[0:1]
	v_mul_f32_e32 v4, v40, v0
	v_mul_f32_e32 v4, v19, v4
	v_mul_f32_e32 v0, v38, v0
	v_cvt_pk_bf16_f32 v4, v4, v4
	v_mul_f32_e32 v0, v34, v0
	global_store_short v[28:29], v4, off
	v_cvt_pk_bf16_f32 v0, v0, v0
	global_store_short v[26:27], v0, off
	v_mul_f32_e32 v0, 0x4b800000, v1
	v_cndmask_b32_e32 v0, v1, v0, vcc
	v_rsq_f32_e32 v0, v0
	v_cmp_gt_f32_e64 s[0:1], s92, v2
	v_mul_f32_e32 v1, 0x45800000, v0
	v_cndmask_b32_e32 v8, v0, v1, vcc
	v_or_b32_e32 v0, 25, v18
	v_ashrrev_i32_e32 v1, 31, v0
	v_mul_f32_e32 v4, v41, v8
	v_lshlrev_b64 v[0:1], 11, v[0:1]
	v_mul_f32_e32 v4, v19, v4
	v_lshl_add_u64 v[0:1], v[16:17], 0, v[0:1]
	v_cndmask_b32_e64 v2, v2, v6, s[0:1]
	v_cvt_pk_bf16_f32 v9, v4, v4
	v_lshl_add_u64 v[4:5], v[0:1], 0, v[20:21]
	v_rsq_f32_e32 v2, v2
	global_store_short v[4:5], v9, off
	v_mul_f32_e32 v4, v39, v8
	v_mul_f32_e32 v4, v34, v4
	v_cvt_pk_bf16_f32 v4, v4, v4
	v_lshl_add_u64 v[0:1], v[0:1], 0, v[22:23]
	v_mul_f32_e32 v6, 0x45800000, v2
	global_store_short v[0:1], v4, off
	v_or_b32_e32 v0, 26, v18
	v_cndmask_b32_e64 v2, v2, v6, s[0:1]
	v_ashrrev_i32_e32 v1, 31, v0
	v_mul_f32_e32 v6, v36, v2
	v_lshlrev_b64 v[0:1], 11, v[0:1]
	v_mul_f32_e32 v6, v19, v6
	v_lshl_add_u64 v[0:1], v[16:17], 0, v[0:1]
	v_mul_f32_e32 v2, v30, v2
	v_lshl_add_u64 v[4:5], v[0:1], 0, v[20:21]
	v_cvt_pk_bf16_f32 v6, v6, v6
	v_mul_f32_e32 v2, v34, v2
	global_store_short v[4:5], v6, off
	v_lshl_add_u64 v[0:1], v[0:1], 0, v[22:23]
	v_cvt_pk_bf16_f32 v2, v2, v2
	v_cmp_gt_f32_e32 vcc, s92, v3
	global_store_short v[0:1], v2, off
	v_mul_f32_e32 v0, 0x4b800000, v3
	v_cndmask_b32_e32 v0, v3, v0, vcc
	v_rsq_f32_e32 v0, v0
	s_nop 0
	v_mul_f32_e32 v1, 0x45800000, v0
	v_cndmask_b32_e32 v4, v0, v1, vcc
	v_or_b32_e32 v0, 27, v18
	v_ashrrev_i32_e32 v1, 31, v0
	v_mul_f32_e32 v2, v37, v4
	v_lshlrev_b64 v[0:1], 11, v[0:1]
	v_mul_f32_e32 v2, v19, v2
	v_lshl_add_u64 v[0:1], v[16:17], 0, v[0:1]
	v_cvt_pk_bf16_f32 v5, v2, v2
	v_lshl_add_u64 v[2:3], v[0:1], 0, v[20:21]
	global_store_short v[2:3], v5, off
	v_mul_f32_e32 v2, v31, v4
	v_mul_f32_e32 v2, v34, v2
	v_bfe_u32 v3, v2, 16, 1
	v_add3_u32 v2, v2, v3, s89
	v_lshl_add_u64 v[0:1], v[0:1], 0, v[22:23]
	global_store_short_d16_hi v[0:1], v2, off
	s_barrier
	s_cbranch_scc1 .LBB0_1524

.LBB0_1477:
	v_pk_mul_f32 v[134:135], v[132:133], v[134:135] op_sel_hi:[1,0]
	v_add_u32_e32 v175, s0, v65
	v_pk_fma_f32 v[172:173], v[128:129], v[130:131], v[134:135] op_sel_hi:[1,0,1]
	v_pk_fma_f32 v[130:131], v[128:129], v[130:131], v[134:135] op_sel_hi:[1,0,1] neg_lo:[0,0,1] neg_hi:[0,0,1]
	v_cvt_pk_bf16_f32 v174, v130, v173
	v_pk_mul_f32 v[134:135], v[132:133], v[172:173] op_sel:[0,1]
	v_add_u32_e32 v176, 0x400, v175
	v_pk_fma_f32 v[172:173], v[128:129], v[130:131], v[134:135] op_sel_hi:[1,0,1]
	v_pk_fma_f32 v[130:131], v[128:129], v[130:131], v[134:135] op_sel_hi:[1,0,1] neg_lo:[0,0,1] neg_hi:[0,0,1]
	v_cvt_pk_bf16_f32 v134, v130, v173
	ds_write2_b32 v176, v134, v174 offset0:152 offset1:220
	v_pk_mul_f32 v[134:135], v[132:133], v[172:173] op_sel:[0,1]
	s_addk_i32 s0, 0xf780
	v_pk_fma_f32 v[172:173], v[128:129], v[130:131], v[134:135] op_sel_hi:[1,0,1]
	v_pk_fma_f32 v[130:131], v[128:129], v[130:131], v[134:135] op_sel_hi:[1,0,1] neg_lo:[0,0,1] neg_hi:[0,0,1]
	v_cvt_pk_bf16_f32 v174, v130, v173
	v_pk_mul_f32 v[134:135], v[132:133], v[172:173] op_sel:[0,1]
	s_cmpk_lg_i32 s0, 0xf780
	v_pk_fma_f32 v[172:173], v[128:129], v[130:131], v[134:135] op_sel_hi:[1,0,1]
	v_pk_fma_f32 v[130:131], v[128:129], v[130:131], v[134:135] op_sel_hi:[1,0,1] neg_lo:[0,0,1] neg_hi:[0,0,1]
	v_cvt_pk_bf16_f32 v134, v130, v173
	ds_write2_b32 v176, v134, v174 offset0:16 offset1:84
	v_pk_mul_f32 v[134:135], v[132:133], v[172:173] op_sel:[0,1]
	s_nop 0
	v_pk_fma_f32 v[172:173], v[128:129], v[130:131], v[134:135] op_sel_hi:[1,0,1]
	v_pk_fma_f32 v[130:131], v[128:129], v[130:131], v[134:135] op_sel_hi:[1,0,1] neg_lo:[0,0,1] neg_hi:[0,0,1]
	v_cvt_pk_bf16_f32 v174, v130, v173
	v_pk_mul_f32 v[134:135], v[132:133], v[172:173] op_sel:[0,1]
	s_nop 0
	v_pk_fma_f32 v[172:173], v[128:129], v[130:131], v[134:135] op_sel_hi:[1,0,1]
	v_pk_fma_f32 v[130:131], v[128:129], v[130:131], v[134:135] op_sel_hi:[1,0,1] neg_lo:[0,0,1] neg_hi:[0,0,1]
	v_cvt_pk_bf16_f32 v134, v130, v173
	ds_write2_b32 v175, v134, v174 offset0:136 offset1:204
	v_pk_mul_f32 v[134:135], v[132:133], v[172:173] op_sel:[0,1]
	s_nop 0
	v_pk_fma_f32 v[172:173], v[128:129], v[130:131], v[134:135] op_sel_hi:[1,0,1]
	v_pk_fma_f32 v[130:131], v[128:129], v[130:131], v[134:135] op_sel_hi:[1,0,1] neg_lo:[0,0,1] neg_hi:[0,0,1]
	v_bfe_u32 v135, v173, 16, 1
	v_bfe_u32 v134, v130, 16, 1
	v_add3_u32 v134, v130, v134, s89
	v_lshrrev_b32_e32 v134, 16, v134
	v_add3_u32 v135, v173, v135, s89
	v_pk_mul_f32 v[172:173], v[132:133], v[172:173] op_sel:[0,1]
	v_and_or_b32 v174, v135, s75, v134
	v_pk_fma_f32 v[134:135], v[128:129], v[130:131], v[172:173] op_sel_hi:[1,0,1]
	v_pk_fma_f32 v[130:131], v[128:129], v[130:131], v[172:173] op_sel_hi:[1,0,1] neg_lo:[0,0,1] neg_hi:[0,0,1]
	v_cvt_pk_bf16_f32 v131, v130, v135
	v_mov_b32_e32 v134, v135
	ds_write2_b32 v175, v131, v174 offset1:68
	s_cbranch_scc1 .LBB0_1477
	s_waitcnt lgkmcnt(11)
	v_mfma_f32_16x16x32_bf16 v[60:63], v[60:63], v[12:15], 0
	v_add_u32_e32 v131, v170, v171
	v_add_f32_e32 v128, v156, v157
	s_waitcnt lgkmcnt(10)
	v_mfma_f32_16x16x32_bf16 v[56:59], v[56:59], v[8:11], v[60:63]
	v_add_f32_e32 v129, v160, v161
	v_add_f32_e32 v160, v154, v155
	v_lshlrev_b32_e32 v130, 1, v139
	s_nop 0
	ds_read_b128 v[60:63], v131
	s_waitcnt lgkmcnt(8)
	v_mfma_f32_16x16x32_bf16 v[52:55], v[52:55], v[4:7], v[56:59]
	v_add_f32_e32 v158, v158, v159
	v_lshlrev_b32_e32 v159, 1, v64
	v_add_f32_e32 v171, v164, v166
	ds_read_b128 v[56:59], v131 offset:64
	v_mfma_f32_16x16x32_bf16 v[12:15], v[44:47], v[12:15], 0
	v_add_f32_e32 v170, v162, v163
	v_add_f32_e32 v172, v165, v167
	v_add_f32_e32 v169, v168, v169
	s_waitcnt lgkmcnt(8)
	v_mfma_f32_16x16x32_bf16 v[48:51], v[48:51], v[0:3], v[52:55]
	s_mov_b32 s0, 0
	s_nop 1
	ds_read_b128 v[52:55], v131 offset:128
	v_mfma_f32_16x16x32_bf16 v[8:11], v[40:43], v[8:11], v[12:15]
	s_waitcnt vmcnt(3) lgkmcnt(2)
	v_mfma_f32_16x16x32_bf16 v[48:51], v[60:63], v[28:31], v[48:51]
	ds_read_b128 v[60:63], v131 offset:192
	v_mfma_f32_16x16x32_bf16 v[4:7], v[36:39], v[4:7], v[8:11]
	s_waitcnt vmcnt(2) lgkmcnt(2)
	v_mfma_f32_16x16x32_bf16 v[48:51], v[56:59], v[24:27], v[48:51]
	ds_read_b128 v[56:59], v131 offset:4352
	ds_read_b128 v[132:135], v131 offset:4416
	v_mfma_f32_16x16x32_bf16 v[0:3], v[32:35], v[0:3], v[4:7]
	s_waitcnt vmcnt(1) lgkmcnt(3)
	v_mfma_f32_16x16x32_bf16 v[48:51], v[52:55], v[20:23], v[48:51]
	ds_read_b128 v[52:55], v131 offset:4480
	ds_read_b128 v[154:157], v131 offset:4544
	s_waitcnt lgkmcnt(3)
	v_mfma_f32_16x16x32_bf16 v[0:3], v[56:59], v[28:31], v[0:3]
	s_waitcnt vmcnt(0)
	v_mfma_f32_16x16x32_bf16 v[48:51], v[60:63], v[16:19], v[48:51]
	s_waitcnt lgkmcnt(2)
	v_mfma_f32_16x16x32_bf16 v[0:3], v[132:135], v[24:27], v[0:3]
	v_mul_u32_u24_e32 v132, 0x840, v149
	s_nop 4
	v_add_f32_e32 v48, v128, v48
	v_fmac_f32_e32 v48, v153, v148
	v_mul_f32_e32 v60, 0x3d372713, v48
	v_mul_f32_e32 v44, v48, v60
	v_add_f32_e32 v13, v160, v49
	s_waitcnt lgkmcnt(1)
	v_mfma_f32_16x16x32_bf16 v[0:3], v[52:55], v[20:23], v[0:3]
	v_fma_f32 v44, v48, v44, v48
	v_fmac_f32_e32 v13, v152, v148
	v_mul_f32_e32 v44, 0xbfcc422a, v44
	v_mul_f32_e32 v9, 0x3d372713, v13
	v_add_f32_e32 v21, v129, v50
	v_mul_f32_e32 v44, 0x3fb8aa3b, v44
	v_mul_f32_e32 v4, v13, v9
	v_fmac_f32_e32 v21, v151, v148
	v_exp_f32_e32 v12, v44
	v_fma_f32 v4, v13, v4, v13
	s_waitcnt lgkmcnt(0)
	v_mfma_f32_16x16x32_bf16 v[16:19], v[154:157], v[16:19], v[0:3]
	v_mul_f32_e32 v4, 0xbfcc422a, v4
	v_mul_f32_e32 v4, 0x3fb8aa3b, v4
	v_exp_f32_e32 v4, v4
	v_mul_f32_e32 v0, 0x3d372713, v21
	v_mul_f32_e32 v0, v21, v0
	v_fma_f32 v0, v21, v0, v21
	v_mul_f32_e32 v0, 0xbfcc422a, v0
	v_add_f32_e32 v8, 1.0, v12
	v_mul_f32_e32 v0, 0x3fb8aa3b, v0
	v_rcp_f32_e32 v8, v8
	v_exp_f32_e32 v0, v0
	v_add_f32_e32 v4, 1.0, v4
	v_rcp_f32_e32 v4, v4
	v_lshlrev_b32_e32 v128, 4, v143
	v_mul_f32_e32 v5, v48, v8
	v_add_f32_e32 v0, 1.0, v0
	v_ashrrev_i32_e32 v129, 31, v128
	v_rcp_f32_e32 v25, v0
	v_lshlrev_b64 v[0:1], 2, v[128:129]
	v_cvt_pk_bf16_f32 v5, v5, v5
	v_add3_u32 v24, v130, v159, v132
	v_lshl_add_u64 v[2:3], v[76:77], 0, v[0:1]
	ds_write_b16 v24, v5 offset:34816
	v_mul_f32_e32 v22, v13, v4
	v_lshl_add_u64 v[4:5], v[2:3], 0, v[80:81]
	v_lshl_add_u64 v[0:1], v[78:79], 0, v[0:1]
	v_add_co_u32_e32 v6, vcc, s92, v4
	v_add_f32_e32 v26, v158, v51
	s_nop 0
	v_addc_co_u32_e32 v7, vcc, 0, v5, vcc
	global_load_dword v157, v[4:5], off
	global_load_dword v158, v[6:7], off
	v_lshl_add_u64 v[4:5], v[0:1], 0, v[82:83]
	global_load_dword v151, v[4:5], off
	v_lshl_add_u64 v[4:5], v[2:3], 0, v[84:85]
	v_add_co_u32_e32 v6, vcc, s92, v4
	v_fmac_f32_e32 v26, v150, v148
	s_nop 0
	v_addc_co_u32_e32 v7, vcc, 0, v5, vcc
	global_load_dword v153, v[4:5], off
	global_load_dword v154, v[6:7], off
	v_lshl_add_u64 v[4:5], v[0:1], 0, v[86:87]
	global_load_dword v152, v[4:5], off
	v_lshl_add_u64 v[4:5], v[2:3], 0, v[88:89]
	v_add_co_u32_e32 v6, vcc, s92, v4
	v_add_u32_e32 v20, s6, v128
	s_nop 0
	v_addc_co_u32_e32 v7, vcc, 0, v5, vcc
	global_load_dword v159, v[4:5], off
	global_load_dword v160, v[6:7], off
	v_lshl_add_u64 v[4:5], v[0:1], 0, v[90:91]
	global_load_dword v150, v[4:5], off
	v_lshl_add_u64 v[4:5], v[2:3], 0, v[92:93]
	v_add_co_u32_e32 v6, vcc, s92, v4
	v_mul_f32_e32 v27, 0x3d372713, v26
	s_nop 0
	v_addc_co_u32_e32 v7, vcc, 0, v5, vcc
	global_load_dword v155, v[4:5], off
	global_load_dword v156, v[6:7], off
	v_lshl_add_u64 v[4:5], v[0:1], 0, v[94:95]
	global_load_dword v149, v[4:5], off
	v_lshl_add_u64 v[4:5], v[2:3], 0, v[96:97]
	v_add_co_u32_e32 v6, vcc, s92, v4
	v_mul_f32_e32 v27, v26, v27
	s_nop 0
	v_addc_co_u32_e32 v7, vcc, 0, v5, vcc
	global_load_dword v164, v[4:5], off
	global_load_dword v166, v[6:7], off
	v_lshl_add_u64 v[4:5], v[0:1], 0, v[98:99]
	global_load_dword v135, v[4:5], off
	v_lshl_add_u64 v[4:5], v[2:3], 0, v[100:101]
	v_add_co_u32_e32 v6, vcc, s92, v4
	v_fma_f32 v27, v26, v27, v26
	s_nop 0
	v_addc_co_u32_e32 v7, vcc, 0, v5, vcc
	global_load_dword v161, v[4:5], off
	global_load_dword v162, v[6:7], off
	v_lshl_add_u64 v[4:5], v[0:1], 0, v[102:103]
	global_load_dword v134, v[4:5], off
	v_lshl_add_u64 v[4:5], v[2:3], 0, v[104:105]
	v_add_co_u32_e32 v6, vcc, s92, v4
	v_lshl_add_u64 v[2:3], v[2:3], 0, v[110:111]
	s_nop 0
	v_addc_co_u32_e32 v7, vcc, 0, v5, vcc
	global_load_dword v167, v[4:5], off
	global_load_dword v168, v[6:7], off
	v_lshl_add_u64 v[4:5], v[0:1], 0, v[106:107]
	global_load_dword v129, v[4:5], off
	v_add_co_u32_e32 v4, vcc, s92, v2
	v_lshl_add_u64 v[0:1], v[0:1], 0, v[108:109]
	s_nop 0
	v_addc_co_u32_e32 v5, vcc, 0, v3, vcc
	global_load_dword v163, v[2:3], off
	global_load_dword v165, v[4:5], off
	ds_read_b64 v[2:3], v229 offset:63640
	global_load_dword v133, v[0:1], off
	v_add_u32_e32 v0, v128, v140
	v_ashrrev_i32_e32 v1, 31, v0
	v_mul_f32_e32 v27, 0xbfcc422a, v27
	s_waitcnt lgkmcnt(0)
	v_lshl_add_u64 v[0:1], v[0:1], 2, v[2:3]
	global_load_dword v143, v[0:1], off
	v_or_b32_e32 v0, v20, v139
	v_ashrrev_i32_e32 v1, 31, v0
	v_lshlrev_b64 v[0:1], 8, v[0:1]
	v_lshl_add_u64 v[0:1], v[72:73], 0, v[0:1]
	global_load_dwordx4 v[12:15], v[0:1], off
	global_load_dwordx4 v[8:11], v[0:1], off offset:64
	global_load_dwordx4 v[4:7], v[0:1], off offset:128
	s_nop 0
	global_load_dwordx4 v[0:3], v[0:1], off offset:192
	v_mul_f32_e32 v27, 0x3fb8aa3b, v27
	v_exp_f32_e32 v27, v27
	v_cvt_pk_bf16_f32 v22, v22, v22
	ds_write_b16 v24, v22 offset:35344
	v_add_f32_e32 v22, 1.0, v27
	v_rcp_f32_e32 v22, v22
	v_mul_f32_e32 v21, v21, v25
	v_add_f32_e32 v16, v172, v16
	v_cvt_pk_bf16_f32 v21, v21, v21
	v_fmac_f32_e32 v16, v144, v148
	ds_write_b16 v24, v21 offset:35872
	v_mul_f32_e32 v21, v26, v22
	v_mul_f32_e32 v22, 0x3d372713, v16
	v_mul_f32_e32 v22, v16, v22
	v_fma_f32 v22, v16, v22, v16
	v_mul_f32_e32 v22, 0xbfcc422a, v22
	v_mul_f32_e32 v22, 0x3fb8aa3b, v22
	v_exp_f32_e32 v22, v22
	v_add_f32_e32 v17, v170, v17
	v_cvt_pk_bf16_f32 v21, v21, v21
	v_fmac_f32_e32 v17, v145, v148
	ds_write_b16 v24, v21 offset:36400
	v_add_f32_e32 v21, 1.0, v22
	v_mul_f32_e32 v22, 0x3d372713, v17
	v_mul_f32_e32 v22, v17, v22
	v_fma_f32 v22, v17, v22, v17
	v_rcp_f32_e32 v21, v21
	v_mul_f32_e32 v22, 0xbfcc422a, v22
	v_mul_f32_e32 v22, 0x3fb8aa3b, v22
	v_exp_f32_e32 v22, v22
	v_mul_f32_e32 v16, v16, v21
	v_add_f32_e32 v18, v169, v18
	v_fmac_f32_e32 v18, v146, v148
	v_cvt_pk_bf16_f32 v16, v16, v16
	v_add_f32_e32 v21, 1.0, v22
	v_mul_f32_e32 v22, 0x3d372713, v18
	v_mul_f32_e32 v22, v18, v22
	v_fma_f32 v22, v18, v22, v18
	v_mul_f32_e32 v22, 0xbfcc422a, v22
	v_mul_f32_e32 v22, 0x3fb8aa3b, v22
	v_rcp_f32_e32 v21, v21
	v_exp_f32_e32 v22, v22
	v_add_f32_e32 v19, v171, v19
	v_fmac_f32_e32 v19, v147, v148
	ds_write_b16 v24, v16 offset:43264
	v_mul_f32_e32 v16, v17, v21
	v_add_f32_e32 v21, 1.0, v22
	v_mul_f32_e32 v22, 0x3d372713, v19
	v_mul_f32_e32 v22, v19, v22
	v_fma_f32 v22, v19, v22, v19
	v_mul_f32_e32 v22, 0xbfcc422a, v22
	v_mul_f32_e32 v22, 0x3fb8aa3b, v22
	v_exp_f32_e32 v22, v22
	v_rcp_f32_e32 v21, v21
	v_cvt_pk_bf16_f32 v16, v16, v16
	v_add_f32_e32 v17, 1.0, v22
	v_rcp_f32_e32 v17, v17
	ds_write_b16 v24, v16 offset:43792
	v_mul_f32_e32 v16, v18, v21
	v_cvt_pk_bf16_f32 v16, v16, v16
	ds_write_b16 v24, v16 offset:44320
	v_mul_f32_e32 v16, v19, v17
	v_cvt_pk_bf16_f32 v16, v16, v16
	ds_write_b16 v24, v16 offset:44848
	v_pk_mov_b32 v[16:17], v[124:125], v[124:125] op_sel:[1,0]
	v_mov_b32_e32 v18, v127

.LBB0_1481:
	v_pk_mul_f32 v[126:127], v[124:125], v[126:127] op_sel_hi:[1,0]
	v_add_u32_e32 v147, s0, v65
	v_pk_fma_f32 v[144:145], v[120:121], v[122:123], v[126:127] op_sel_hi:[1,0,1]
	v_pk_fma_f32 v[122:123], v[120:121], v[122:123], v[126:127] op_sel_hi:[1,0,1] neg_lo:[0,0,1] neg_hi:[0,0,1]
	v_cvt_pk_bf16_f32 v146, v122, v145
	v_pk_mul_f32 v[126:127], v[124:125], v[144:145] op_sel:[0,1]
	v_add_u32_e32 v148, 0x400, v147
	v_pk_fma_f32 v[144:145], v[120:121], v[122:123], v[126:127] op_sel_hi:[1,0,1]
	v_pk_fma_f32 v[122:123], v[120:121], v[122:123], v[126:127] op_sel_hi:[1,0,1] neg_lo:[0,0,1] neg_hi:[0,0,1]
	v_cvt_pk_bf16_f32 v126, v122, v145
	ds_write2_b32 v148, v126, v146 offset0:152 offset1:220
	v_pk_mul_f32 v[126:127], v[124:125], v[144:145] op_sel:[0,1]
	s_addk_i32 s0, 0xf780
	v_pk_fma_f32 v[144:145], v[120:121], v[122:123], v[126:127] op_sel_hi:[1,0,1]
	v_pk_fma_f32 v[122:123], v[120:121], v[122:123], v[126:127] op_sel_hi:[1,0,1] neg_lo:[0,0,1] neg_hi:[0,0,1]
	v_cvt_pk_bf16_f32 v146, v122, v145
	v_pk_mul_f32 v[126:127], v[124:125], v[144:145] op_sel:[0,1]
	s_cmpk_lg_i32 s0, 0xf780
	v_pk_fma_f32 v[144:145], v[120:121], v[122:123], v[126:127] op_sel_hi:[1,0,1]
	v_pk_fma_f32 v[122:123], v[120:121], v[122:123], v[126:127] op_sel_hi:[1,0,1] neg_lo:[0,0,1] neg_hi:[0,0,1]
	v_cvt_pk_bf16_f32 v126, v122, v145
	ds_write2_b32 v148, v126, v146 offset0:16 offset1:84
	v_pk_mul_f32 v[126:127], v[124:125], v[144:145] op_sel:[0,1]
	s_nop 0
	v_pk_fma_f32 v[144:145], v[120:121], v[122:123], v[126:127] op_sel_hi:[1,0,1]
	v_pk_fma_f32 v[122:123], v[120:121], v[122:123], v[126:127] op_sel_hi:[1,0,1] neg_lo:[0,0,1] neg_hi:[0,0,1]
	v_cvt_pk_bf16_f32 v146, v122, v145
	v_pk_mul_f32 v[126:127], v[124:125], v[144:145] op_sel:[0,1]
	s_nop 0
	v_pk_fma_f32 v[144:145], v[120:121], v[122:123], v[126:127] op_sel_hi:[1,0,1]
	v_pk_fma_f32 v[122:123], v[120:121], v[122:123], v[126:127] op_sel_hi:[1,0,1] neg_lo:[0,0,1] neg_hi:[0,0,1]
	v_cvt_pk_bf16_f32 v126, v122, v145
	ds_write2_b32 v147, v126, v146 offset0:136 offset1:204
	v_pk_mul_f32 v[126:127], v[124:125], v[144:145] op_sel:[0,1]
	s_nop 0
	v_pk_fma_f32 v[144:145], v[120:121], v[122:123], v[126:127] op_sel_hi:[1,0,1]
	v_pk_fma_f32 v[122:123], v[120:121], v[122:123], v[126:127] op_sel_hi:[1,0,1] neg_lo:[0,0,1] neg_hi:[0,0,1]
	v_bfe_u32 v127, v145, 16, 1
	v_bfe_u32 v126, v122, 16, 1
	v_add3_u32 v126, v122, v126, s89
	v_lshrrev_b32_e32 v126, 16, v126
	v_add3_u32 v127, v145, v127, s89
	v_pk_mul_f32 v[144:145], v[124:125], v[144:145] op_sel:[0,1]
	v_and_or_b32 v146, v127, s75, v126
	v_pk_fma_f32 v[126:127], v[120:121], v[122:123], v[144:145] op_sel_hi:[1,0,1]
	v_pk_fma_f32 v[122:123], v[120:121], v[122:123], v[144:145] op_sel_hi:[1,0,1] neg_lo:[0,0,1] neg_hi:[0,0,1]
	v_cvt_pk_bf16_f32 v123, v122, v127
	v_mov_b32_e32 v126, v127
	ds_write2_b32 v147, v123, v146 offset1:68
	s_cbranch_scc1 .LBB0_1481
	s_waitcnt vmcnt(7) lgkmcnt(11)
	v_mfma_f32_16x16x32_bf16 v[56:59], v[56:59], v[12:15], 0
	v_add_f32_e32 v144, v157, v158
	v_add_f32_e32 v146, v153, v154
	s_waitcnt vmcnt(6) lgkmcnt(10)
	v_mfma_f32_16x16x32_bf16 v[56:59], v[60:63], v[8:11], v[56:59]
	ds_read_b128 v[60:63], v131
	v_add_f32_e32 v145, v159, v160
	v_lshlrev_b32_e32 v128, 1, v128
	s_waitcnt vmcnt(5) lgkmcnt(8)
	v_mfma_f32_16x16x32_bf16 v[52:55], v[52:55], v[4:7], v[56:59]
	v_add_f32_e32 v147, v155, v156
	v_add_f32_e32 v164, v164, v166
	v_add_f32_e32 v161, v161, v162
	ds_read_b128 v[56:59], v131 offset:64
	s_waitcnt vmcnt(4) lgkmcnt(8)
	v_mfma_f32_16x16x32_bf16 v[48:51], v[48:51], v[0:3], v[52:55]
	v_add_f32_e32 v160, v167, v168
	v_add_f32_e32 v162, v163, v165
	s_mov_b32 s0, 0
	ds_read_b128 v[52:55], v131 offset:128
	s_waitcnt vmcnt(3) lgkmcnt(2)
	v_mfma_f32_16x16x32_bf16 v[48:51], v[60:63], v[28:31], v[48:51]
	ds_read_b128 v[60:63], v131 offset:192
	s_waitcnt vmcnt(2) lgkmcnt(2)
	v_mfma_f32_16x16x32_bf16 v[48:51], v[56:59], v[24:27], v[48:51]
	ds_read_b128 v[56:59], v131 offset:4352
	ds_read_b128 v[120:123], v131 offset:4416
	s_waitcnt vmcnt(1) lgkmcnt(3)
	v_mfma_f32_16x16x32_bf16 v[48:51], v[52:55], v[20:23], v[48:51]
	ds_read_b128 v[52:55], v131 offset:4480
	ds_read_b128 v[124:127], v131 offset:4544
	v_mfma_f32_16x16x32_bf16 v[12:15], v[44:47], v[12:15], 0
	s_waitcnt vmcnt(0) lgkmcnt(4)
	v_mfma_f32_16x16x32_bf16 v[48:51], v[60:63], v[16:19], v[48:51]
	v_mfma_f32_16x16x32_bf16 v[8:11], v[40:43], v[8:11], v[12:15]
	v_mfma_f32_16x16x32_bf16 v[4:7], v[36:39], v[4:7], v[8:11]
	s_nop 5
	v_add_f32_e32 v48, v144, v48
	v_fmac_f32_e32 v48, v151, v143
	v_mul_f32_e32 v60, 0x3d372713, v48
	v_mul_f32_e32 v44, v48, v60
	v_fma_f32 v44, v48, v44, v48
	v_mfma_f32_16x16x32_bf16 v[0:3], v[32:35], v[0:3], v[4:7]
	v_mul_f32_e32 v44, 0xbfcc422a, v44
	v_mul_f32_e32 v44, 0x3fb8aa3b, v44
	v_exp_f32_e32 v12, v44
	s_waitcnt lgkmcnt(3)
	v_mfma_f32_16x16x32_bf16 v[0:3], v[56:59], v[28:31], v[0:3]
	v_add_f32_e32 v49, v146, v49
	v_fmac_f32_e32 v49, v152, v143
	v_add_f32_e32 v8, 1.0, v12
	v_rcp_f32_e32 v8, v8
	s_waitcnt lgkmcnt(2)
	v_mfma_f32_16x16x32_bf16 v[0:3], v[120:123], v[24:27], v[0:3]
	v_mul_f32_e32 v61, 0x3d372713, v49
	v_add_f32_e32 v24, v145, v50
	v_mul_f32_e32 v5, v48, v8
	s_waitcnt lgkmcnt(1)
	v_mfma_f32_16x16x32_bf16 v[0:3], v[52:55], v[20:23], v[0:3]
	v_mul_f32_e32 v13, v49, v61
	v_fmac_f32_e32 v24, v150, v143
	v_fma_f32 v13, v49, v13, v49
	v_cvt_pk_bf16_f32 v5, v5, v5
	v_mul_f32_e32 v6, 0x3d372713, v24
	v_mul_f32_e32 v9, 0xbfcc422a, v13
	v_mul_f32_e32 v6, v24, v6
	v_mul_f32_e32 v4, 0x3fb8aa3b, v9
	s_waitcnt lgkmcnt(0)
	v_mfma_f32_16x16x32_bf16 v[16:19], v[124:127], v[16:19], v[0:3]
	v_exp_f32_e32 v4, v4
	v_lshlrev_b32_e32 v120, 4, v142
	v_ashrrev_i32_e32 v121, 31, v120
	v_fma_f32 v0, v24, v6, v24
	v_mul_f32_e32 v0, 0xbfcc422a, v0
	v_mul_f32_e32 v0, 0x3fb8aa3b, v0
	v_exp_f32_e32 v0, v0
	v_add_f32_e32 v4, 1.0, v4
	v_rcp_f32_e32 v4, v4
	v_add3_u32 v28, v130, v128, v132
	v_add_f32_e32 v0, 1.0, v0
	v_rcp_f32_e32 v23, v0
	v_lshlrev_b64 v[0:1], 2, v[120:121]
	v_lshl_add_u64 v[2:3], v[76:77], 0, v[0:1]
	ds_write_b16 v28, v5 offset:34816
	v_mul_f32_e32 v21, v49, v4
	v_lshl_add_u64 v[4:5], v[2:3], 0, v[80:81]
	v_add_f32_e32 v25, v147, v51
	v_lshl_add_u64 v[0:1], v[78:79], 0, v[0:1]
	v_add_co_u32_e32 v6, vcc, s92, v4
	v_fmac_f32_e32 v25, v149, v143
	s_nop 0
	v_addc_co_u32_e32 v7, vcc, 0, v5, vcc
	global_load_dword v148, v[4:5], off
	global_load_dword v149, v[6:7], off
	v_lshl_add_u64 v[4:5], v[0:1], 0, v[82:83]
	global_load_dword v128, v[4:5], off
	v_lshl_add_u64 v[4:5], v[2:3], 0, v[84:85]
	v_add_co_u32_e32 v6, vcc, s92, v4
	v_add_u32_e32 v20, s6, v120
	s_nop 0
	v_addc_co_u32_e32 v7, vcc, 0, v5, vcc
	global_load_dword v144, v[4:5], off
	global_load_dword v145, v[6:7], off
	v_lshl_add_u64 v[4:5], v[0:1], 0, v[86:87]
	global_load_dword v142, v[4:5], off
	v_lshl_add_u64 v[4:5], v[2:3], 0, v[88:89]
	v_add_co_u32_e32 v6, vcc, s92, v4
	v_mul_f32_e32 v26, 0x3d372713, v25
	s_nop 0
	v_addc_co_u32_e32 v7, vcc, 0, v5, vcc
	global_load_dword v150, v[4:5], off
	global_load_dword v151, v[6:7], off
	v_lshl_add_u64 v[4:5], v[0:1], 0, v[90:91]
	global_load_dword v127, v[4:5], off
	v_lshl_add_u64 v[4:5], v[2:3], 0, v[92:93]
	v_add_co_u32_e32 v6, vcc, s92, v4
	v_mul_f32_e32 v26, v25, v26
	s_nop 0
	v_addc_co_u32_e32 v7, vcc, 0, v5, vcc
	global_load_dword v146, v[4:5], off
	global_load_dword v147, v[6:7], off
	v_lshl_add_u64 v[4:5], v[0:1], 0, v[94:95]
	global_load_dword v126, v[4:5], off
	v_lshl_add_u64 v[4:5], v[2:3], 0, v[96:97]
	v_add_co_u32_e32 v6, vcc, s92, v4
	v_fma_f32 v26, v25, v26, v25
	s_nop 0
	v_addc_co_u32_e32 v7, vcc, 0, v5, vcc
	global_load_dword v155, v[4:5], off
	global_load_dword v157, v[6:7], off
	v_lshl_add_u64 v[4:5], v[0:1], 0, v[98:99]
	global_load_dword v124, v[4:5], off
	v_lshl_add_u64 v[4:5], v[2:3], 0, v[100:101]
	v_add_co_u32_e32 v6, vcc, s92, v4
	v_mul_f32_e32 v26, 0xbfcc422a, v26
	s_nop 0
	v_addc_co_u32_e32 v7, vcc, 0, v5, vcc
	global_load_dword v152, v[4:5], off
	global_load_dword v153, v[6:7], off
	v_lshl_add_u64 v[4:5], v[0:1], 0, v[102:103]
	global_load_dword v123, v[4:5], off
	v_lshl_add_u64 v[4:5], v[2:3], 0, v[104:105]
	v_add_co_u32_e32 v6, vcc, s92, v4
	v_lshl_add_u64 v[2:3], v[2:3], 0, v[110:111]
	s_nop 0
	v_addc_co_u32_e32 v7, vcc, 0, v5, vcc
	global_load_dword v158, v[4:5], off
	global_load_dword v159, v[6:7], off
	v_lshl_add_u64 v[4:5], v[0:1], 0, v[106:107]
	global_load_dword v121, v[4:5], off
	v_add_co_u32_e32 v4, vcc, s92, v2
	v_lshl_add_u64 v[0:1], v[0:1], 0, v[108:109]
	s_nop 0
	v_addc_co_u32_e32 v5, vcc, 0, v3, vcc
	global_load_dword v154, v[2:3], off
	global_load_dword v156, v[4:5], off
	ds_read_b64 v[2:3], v229 offset:63640
	global_load_dword v122, v[0:1], off
	v_add_u32_e32 v0, v120, v140
	v_ashrrev_i32_e32 v1, 31, v0
	v_mul_f32_e32 v26, 0x3fb8aa3b, v26
	s_waitcnt lgkmcnt(0)
	v_lshl_add_u64 v[0:1], v[0:1], 2, v[2:3]
	global_load_dword v125, v[0:1], off
	v_or_b32_e32 v0, v20, v139
	v_ashrrev_i32_e32 v1, 31, v0
	v_lshlrev_b64 v[0:1], 8, v[0:1]
	v_lshl_add_u64 v[0:1], v[72:73], 0, v[0:1]
	global_load_dwordx4 v[12:15], v[0:1], off
	global_load_dwordx4 v[8:11], v[0:1], off offset:64
	global_load_dwordx4 v[4:7], v[0:1], off offset:128
	s_nop 0
	global_load_dwordx4 v[0:3], v[0:1], off offset:192
	v_exp_f32_e32 v26, v26
	v_cvt_pk_bf16_f32 v21, v21, v21
	ds_write_b16 v28, v21 offset:35344
	v_add_f32_e32 v22, 1.0, v26
	v_rcp_f32_e32 v22, v22
	v_mul_f32_e32 v21, v24, v23
	v_add_f32_e32 v16, v164, v16
	v_cvt_pk_bf16_f32 v21, v21, v21
	v_fmac_f32_e32 v16, v135, v143
	ds_write_b16 v28, v21 offset:35872
	v_mul_f32_e32 v21, v25, v22
	v_mul_f32_e32 v22, 0x3d372713, v16
	v_mul_f32_e32 v22, v16, v22
	v_fma_f32 v22, v16, v22, v16
	v_mul_f32_e32 v22, 0xbfcc422a, v22
	v_mul_f32_e32 v22, 0x3fb8aa3b, v22
	v_exp_f32_e32 v22, v22
	v_add_f32_e32 v17, v161, v17
	v_cvt_pk_bf16_f32 v21, v21, v21
	v_fmac_f32_e32 v17, v134, v143
	ds_write_b16 v28, v21 offset:36400
	v_add_f32_e32 v21, 1.0, v22
	v_mul_f32_e32 v22, 0x3d372713, v17
	v_mul_f32_e32 v22, v17, v22
	v_fma_f32 v22, v17, v22, v17
	v_rcp_f32_e32 v21, v21
	v_mul_f32_e32 v22, 0xbfcc422a, v22
	v_mul_f32_e32 v22, 0x3fb8aa3b, v22
	v_exp_f32_e32 v22, v22
	v_mul_f32_e32 v16, v16, v21
	v_add_f32_e32 v18, v160, v18
	v_fmac_f32_e32 v18, v129, v143
	v_cvt_pk_bf16_f32 v16, v16, v16
	v_add_f32_e32 v21, 1.0, v22
	v_mul_f32_e32 v22, 0x3d372713, v18
	v_mul_f32_e32 v22, v18, v22
	v_fma_f32 v22, v18, v22, v18
	v_mul_f32_e32 v22, 0xbfcc422a, v22
	v_mul_f32_e32 v22, 0x3fb8aa3b, v22
	v_rcp_f32_e32 v21, v21
	v_exp_f32_e32 v22, v22
	v_add_f32_e32 v19, v162, v19
	v_fmac_f32_e32 v19, v133, v143
	ds_write_b16 v28, v16 offset:43264
	v_mul_f32_e32 v16, v17, v21
	v_add_f32_e32 v21, 1.0, v22
	v_mul_f32_e32 v22, 0x3d372713, v19
	v_mul_f32_e32 v22, v19, v22
	v_fma_f32 v22, v19, v22, v19
	v_mul_f32_e32 v22, 0xbfcc422a, v22
	v_mul_f32_e32 v22, 0x3fb8aa3b, v22
	v_exp_f32_e32 v22, v22
	v_rcp_f32_e32 v21, v21
	v_cvt_pk_bf16_f32 v16, v16, v16
	v_add_f32_e32 v17, 1.0, v22
	v_rcp_f32_e32 v17, v17
	ds_write_b16 v28, v16 offset:43792
	v_mul_f32_e32 v16, v18, v21
	v_cvt_pk_bf16_f32 v16, v16, v16
	ds_write_b16 v28, v16 offset:44320
	v_mul_f32_e32 v16, v19, v17
	v_cvt_pk_bf16_f32 v16, v16, v16
	ds_write_b16 v28, v16 offset:44848
	v_pk_mov_b32 v[16:17], v[116:117], v[116:117] op_sel:[1,0]
	v_mov_b32_e32 v18, v119

.LBB0_1485:
	v_pk_mul_f32 v[118:119], v[116:117], v[118:119] op_sel_hi:[1,0]
	v_add_u32_e32 v133, s0, v65
	v_pk_fma_f32 v[134:135], v[112:113], v[114:115], v[118:119] op_sel_hi:[1,0,1]
	v_pk_fma_f32 v[114:115], v[112:113], v[114:115], v[118:119] op_sel_hi:[1,0,1] neg_lo:[0,0,1] neg_hi:[0,0,1]
	v_cvt_pk_bf16_f32 v129, v114, v135
	v_pk_mul_f32 v[118:119], v[116:117], v[134:135] op_sel:[0,1]
	v_add_u32_e32 v143, 0x400, v133
	v_pk_fma_f32 v[134:135], v[112:113], v[114:115], v[118:119] op_sel_hi:[1,0,1]
	v_pk_fma_f32 v[114:115], v[112:113], v[114:115], v[118:119] op_sel_hi:[1,0,1] neg_lo:[0,0,1] neg_hi:[0,0,1]
	v_cvt_pk_bf16_f32 v118, v114, v135
	ds_write2_b32 v143, v118, v129 offset0:152 offset1:220
	v_pk_mul_f32 v[118:119], v[116:117], v[134:135] op_sel:[0,1]
	s_addk_i32 s0, 0xf780
	v_pk_fma_f32 v[134:135], v[112:113], v[114:115], v[118:119] op_sel_hi:[1,0,1]
	v_pk_fma_f32 v[114:115], v[112:113], v[114:115], v[118:119] op_sel_hi:[1,0,1] neg_lo:[0,0,1] neg_hi:[0,0,1]
	v_cvt_pk_bf16_f32 v129, v114, v135
	v_pk_mul_f32 v[118:119], v[116:117], v[134:135] op_sel:[0,1]
	s_cmpk_lg_i32 s0, 0xf780
	v_pk_fma_f32 v[134:135], v[112:113], v[114:115], v[118:119] op_sel_hi:[1,0,1]
	v_pk_fma_f32 v[114:115], v[112:113], v[114:115], v[118:119] op_sel_hi:[1,0,1] neg_lo:[0,0,1] neg_hi:[0,0,1]
	v_cvt_pk_bf16_f32 v118, v114, v135
	ds_write2_b32 v143, v118, v129 offset0:16 offset1:84
	v_pk_mul_f32 v[118:119], v[116:117], v[134:135] op_sel:[0,1]
	s_nop 0
	v_pk_fma_f32 v[134:135], v[112:113], v[114:115], v[118:119] op_sel_hi:[1,0,1]
	v_pk_fma_f32 v[114:115], v[112:113], v[114:115], v[118:119] op_sel_hi:[1,0,1] neg_lo:[0,0,1] neg_hi:[0,0,1]
	v_cvt_pk_bf16_f32 v129, v114, v135
	v_pk_mul_f32 v[118:119], v[116:117], v[134:135] op_sel:[0,1]
	s_nop 0
	v_pk_fma_f32 v[134:135], v[112:113], v[114:115], v[118:119] op_sel_hi:[1,0,1]
	v_pk_fma_f32 v[114:115], v[112:113], v[114:115], v[118:119] op_sel_hi:[1,0,1] neg_lo:[0,0,1] neg_hi:[0,0,1]
	v_cvt_pk_bf16_f32 v118, v114, v135
	ds_write2_b32 v133, v118, v129 offset0:136 offset1:204
	v_pk_mul_f32 v[118:119], v[116:117], v[134:135] op_sel:[0,1]
	s_nop 0
	v_pk_fma_f32 v[134:135], v[112:113], v[114:115], v[118:119] op_sel_hi:[1,0,1]
	v_pk_fma_f32 v[114:115], v[112:113], v[114:115], v[118:119] op_sel_hi:[1,0,1] neg_lo:[0,0,1] neg_hi:[0,0,1]
	v_bfe_u32 v119, v135, 16, 1
	v_bfe_u32 v118, v114, 16, 1
	v_add3_u32 v118, v114, v118, s89
	v_lshrrev_b32_e32 v118, 16, v118
	v_add3_u32 v119, v135, v119, s89
	v_pk_mul_f32 v[134:135], v[116:117], v[134:135] op_sel:[0,1]
	v_and_or_b32 v129, v119, s75, v118
	v_pk_fma_f32 v[118:119], v[112:113], v[114:115], v[134:135] op_sel_hi:[1,0,1]
	v_pk_fma_f32 v[114:115], v[112:113], v[114:115], v[134:135] op_sel_hi:[1,0,1] neg_lo:[0,0,1] neg_hi:[0,0,1]
	v_cvt_pk_bf16_f32 v115, v114, v119
	v_mov_b32_e32 v118, v119
	ds_write2_b32 v133, v115, v129 offset1:68
	s_cbranch_scc1 .LBB0_1485
	s_waitcnt vmcnt(7) lgkmcnt(11)
	v_mfma_f32_16x16x32_bf16 v[56:59], v[56:59], v[12:15], 0
	v_add_f32_e32 v129, v148, v149
	v_add_f32_e32 v143, v144, v145
	s_waitcnt vmcnt(6) lgkmcnt(10)
	v_mfma_f32_16x16x32_bf16 v[56:59], v[60:63], v[8:11], v[56:59]
	ds_read_b128 v[60:63], v131
	v_add_f32_e32 v134, v150, v151
	v_lshlrev_b32_e32 v120, 1, v120
	s_waitcnt vmcnt(5) lgkmcnt(8)
	v_mfma_f32_16x16x32_bf16 v[52:55], v[52:55], v[4:7], v[56:59]
	v_add_f32_e32 v144, v146, v147
	v_add_f32_e32 v133, v155, v157
	v_add_f32_e32 v145, v152, v153
	ds_read_b128 v[56:59], v131 offset:64
	s_waitcnt vmcnt(4) lgkmcnt(8)
	v_mfma_f32_16x16x32_bf16 v[48:51], v[48:51], v[0:3], v[52:55]
	v_add_f32_e32 v135, v158, v159
	v_add_f32_e32 v146, v154, v156
	s_mov_b32 s0, 0
	ds_read_b128 v[52:55], v131 offset:128
	s_waitcnt vmcnt(3) lgkmcnt(2)
	v_mfma_f32_16x16x32_bf16 v[48:51], v[60:63], v[28:31], v[48:51]
	ds_read_b128 v[60:63], v131 offset:192
	s_waitcnt vmcnt(2) lgkmcnt(2)
	v_mfma_f32_16x16x32_bf16 v[48:51], v[56:59], v[24:27], v[48:51]
	ds_read_b128 v[56:59], v131 offset:4352
	ds_read_b128 v[112:115], v131 offset:4416
	s_waitcnt vmcnt(1) lgkmcnt(3)
	v_mfma_f32_16x16x32_bf16 v[48:51], v[52:55], v[20:23], v[48:51]
	ds_read_b128 v[52:55], v131 offset:4480
	ds_read_b128 v[116:119], v131 offset:4544
	v_mfma_f32_16x16x32_bf16 v[12:15], v[44:47], v[12:15], 0
	s_waitcnt vmcnt(0) lgkmcnt(4)
	v_mfma_f32_16x16x32_bf16 v[48:51], v[60:63], v[16:19], v[48:51]
	v_mfma_f32_16x16x32_bf16 v[8:11], v[40:43], v[8:11], v[12:15]
	v_mfma_f32_16x16x32_bf16 v[4:7], v[36:39], v[4:7], v[8:11]
	s_nop 5
	v_add_f32_e32 v48, v129, v48
	v_fmac_f32_e32 v48, v128, v125
	v_mul_f32_e32 v60, 0x3d372713, v48
	v_mul_f32_e32 v44, v48, v60
	v_fma_f32 v44, v48, v44, v48
	v_mfma_f32_16x16x32_bf16 v[0:3], v[32:35], v[0:3], v[4:7]
	v_mul_f32_e32 v44, 0xbfcc422a, v44
	v_mul_f32_e32 v44, 0x3fb8aa3b, v44
	v_exp_f32_e32 v12, v44
	s_waitcnt lgkmcnt(3)
	v_mfma_f32_16x16x32_bf16 v[0:3], v[56:59], v[28:31], v[0:3]
	v_add_f32_e32 v49, v143, v49
	v_fmac_f32_e32 v49, v142, v125
	v_add_f32_e32 v8, 1.0, v12
	v_rcp_f32_e32 v8, v8
	s_waitcnt lgkmcnt(2)
	v_mfma_f32_16x16x32_bf16 v[0:3], v[112:115], v[24:27], v[0:3]
	v_mul_f32_e32 v61, 0x3d372713, v49
	v_add_f32_e32 v24, v134, v50
	v_mul_f32_e32 v5, v48, v8
	s_waitcnt lgkmcnt(1)
	v_mfma_f32_16x16x32_bf16 v[0:3], v[52:55], v[20:23], v[0:3]
	v_mul_f32_e32 v13, v49, v61
	v_fmac_f32_e32 v24, v127, v125
	v_fma_f32 v13, v49, v13, v49
	v_cvt_pk_bf16_f32 v5, v5, v5
	v_mul_f32_e32 v6, 0x3d372713, v24
	v_mul_f32_e32 v9, 0xbfcc422a, v13
	v_mul_f32_e32 v6, v24, v6
	v_mul_f32_e32 v4, 0x3fb8aa3b, v9
	s_waitcnt lgkmcnt(0)
	v_mfma_f32_16x16x32_bf16 v[16:19], v[116:119], v[16:19], v[0:3]
	v_exp_f32_e32 v4, v4
	v_lshlrev_b32_e32 v112, 4, v141
	v_ashrrev_i32_e32 v113, 31, v112
	v_fma_f32 v0, v24, v6, v24
	v_mul_f32_e32 v0, 0xbfcc422a, v0
	v_mul_f32_e32 v0, 0x3fb8aa3b, v0
	v_exp_f32_e32 v0, v0
	v_add_f32_e32 v4, 1.0, v4
	v_rcp_f32_e32 v4, v4
	v_add3_u32 v28, v130, v120, v132
	v_add_f32_e32 v0, 1.0, v0
	v_rcp_f32_e32 v23, v0
	v_lshlrev_b64 v[0:1], 2, v[112:113]
	v_lshl_add_u64 v[2:3], v[76:77], 0, v[0:1]
	ds_write_b16 v28, v5 offset:34816
	v_mul_f32_e32 v21, v49, v4
	v_lshl_add_u64 v[4:5], v[2:3], 0, v[80:81]
	v_lshl_add_u64 v[0:1], v[78:79], 0, v[0:1]
	v_add_co_u32_e32 v6, vcc, s92, v4
	v_add_u32_e32 v20, s6, v112
	s_nop 0
	v_addc_co_u32_e32 v7, vcc, 0, v5, vcc
	global_load_dword v114, v[4:5], off
	global_load_dword v115, v[6:7], off
	v_lshl_add_u64 v[4:5], v[0:1], 0, v[82:83]
	global_load_dword v113, v[4:5], off
	v_lshl_add_u64 v[4:5], v[2:3], 0, v[84:85]
	v_add_co_u32_e32 v6, vcc, s92, v4
	v_add_f32_e32 v25, v144, v51
	s_nop 0
	v_addc_co_u32_e32 v7, vcc, 0, v5, vcc
	global_load_dword v84, v[4:5], off
	global_load_dword v85, v[6:7], off
	v_lshl_add_u64 v[4:5], v[0:1], 0, v[86:87]
	global_load_dword v83, v[4:5], off
	v_lshl_add_u64 v[4:5], v[2:3], 0, v[88:89]
	v_add_co_u32_e32 v6, vcc, s92, v4
	v_fmac_f32_e32 v25, v126, v125
	s_nop 0
	v_addc_co_u32_e32 v7, vcc, 0, v5, vcc
	global_load_dword v86, v[4:5], off
	global_load_dword v87, v[6:7], off
	v_lshl_add_u64 v[4:5], v[0:1], 0, v[90:91]
	global_load_dword v82, v[4:5], off
	v_lshl_add_u64 v[4:5], v[2:3], 0, v[92:93]
	v_add_co_u32_e32 v6, vcc, s92, v4
	v_mul_f32_e32 v26, 0x3d372713, v25
	s_nop 0
	v_addc_co_u32_e32 v7, vcc, 0, v5, vcc
	global_load_dword v88, v[4:5], off
	global_load_dword v89, v[6:7], off
	v_lshl_add_u64 v[4:5], v[0:1], 0, v[94:95]
	global_load_dword v81, v[4:5], off
	v_lshl_add_u64 v[4:5], v[2:3], 0, v[96:97]
	v_add_co_u32_e32 v6, vcc, s92, v4
	v_mul_f32_e32 v26, v25, v26
	s_nop 0
	v_addc_co_u32_e32 v7, vcc, 0, v5, vcc
	global_load_dword v90, v[4:5], off
	global_load_dword v91, v[6:7], off
	v_lshl_add_u64 v[4:5], v[0:1], 0, v[98:99]
	global_load_dword v80, v[4:5], off
	v_lshl_add_u64 v[4:5], v[2:3], 0, v[100:101]
	v_add_co_u32_e32 v6, vcc, s92, v4
	v_fma_f32 v26, v25, v26, v25
	s_nop 0
	v_addc_co_u32_e32 v7, vcc, 0, v5, vcc
	global_load_dword v92, v[4:5], off
	global_load_dword v93, v[6:7], off
	v_lshl_add_u64 v[4:5], v[0:1], 0, v[102:103]
	global_load_dword v79, v[4:5], off
	v_lshl_add_u64 v[4:5], v[2:3], 0, v[104:105]
	v_add_co_u32_e32 v6, vcc, s92, v4
	v_lshl_add_u64 v[2:3], v[2:3], 0, v[110:111]
	s_nop 0
	v_addc_co_u32_e32 v7, vcc, 0, v5, vcc
	global_load_dword v94, v[4:5], off
	global_load_dword v95, v[6:7], off
	v_lshl_add_u64 v[4:5], v[0:1], 0, v[106:107]
	global_load_dword v78, v[4:5], off
	v_add_co_u32_e32 v4, vcc, s92, v2
	v_lshl_add_u64 v[0:1], v[0:1], 0, v[108:109]
	s_nop 0
	v_addc_co_u32_e32 v5, vcc, 0, v3, vcc
	global_load_dword v96, v[2:3], off
	global_load_dword v97, v[4:5], off
	ds_read_b64 v[2:3], v229 offset:63640
	global_load_dword v76, v[0:1], off
	v_add_u32_e32 v0, v112, v140
	v_ashrrev_i32_e32 v1, 31, v0
	v_mul_f32_e32 v26, 0xbfcc422a, v26
	s_waitcnt lgkmcnt(0)
	v_lshl_add_u64 v[0:1], v[0:1], 2, v[2:3]
	global_load_dword v77, v[0:1], off
	v_or_b32_e32 v0, v20, v139
	v_ashrrev_i32_e32 v1, 31, v0
	v_lshlrev_b64 v[0:1], 8, v[0:1]
	v_lshl_add_u64 v[0:1], v[72:73], 0, v[0:1]
	global_load_dwordx4 v[12:15], v[0:1], off
	global_load_dwordx4 v[8:11], v[0:1], off offset:64
	global_load_dwordx4 v[4:7], v[0:1], off offset:128
	s_nop 0
	global_load_dwordx4 v[0:3], v[0:1], off offset:192
	v_mul_f32_e32 v26, 0x3fb8aa3b, v26
	v_exp_f32_e32 v26, v26
	v_cvt_pk_bf16_f32 v21, v21, v21
	ds_write_b16 v28, v21 offset:35344
	v_add_f32_e32 v22, 1.0, v26
	v_rcp_f32_e32 v22, v22
	v_mul_f32_e32 v21, v24, v23
	v_add_f32_e32 v16, v133, v16
	v_cvt_pk_bf16_f32 v21, v21, v21
	v_fmac_f32_e32 v16, v124, v125
	ds_write_b16 v28, v21 offset:35872
	v_mul_f32_e32 v21, v25, v22
	v_mul_f32_e32 v22, 0x3d372713, v16
	v_mul_f32_e32 v22, v16, v22
	v_fma_f32 v22, v16, v22, v16
	v_mul_f32_e32 v22, 0xbfcc422a, v22
	v_mul_f32_e32 v22, 0x3fb8aa3b, v22
	v_exp_f32_e32 v22, v22
	v_add_f32_e32 v17, v145, v17
	v_cvt_pk_bf16_f32 v21, v21, v21
	v_fmac_f32_e32 v17, v123, v125
	ds_write_b16 v28, v21 offset:36400
	v_add_f32_e32 v21, 1.0, v22
	v_mul_f32_e32 v22, 0x3d372713, v17
	v_mul_f32_e32 v22, v17, v22
	v_fma_f32 v22, v17, v22, v17
	v_rcp_f32_e32 v21, v21
	v_mul_f32_e32 v22, 0xbfcc422a, v22
	v_mul_f32_e32 v22, 0x3fb8aa3b, v22
	v_exp_f32_e32 v22, v22
	v_mul_f32_e32 v16, v16, v21
	v_add_f32_e32 v18, v135, v18
	v_fmac_f32_e32 v18, v121, v125
	v_cvt_pk_bf16_f32 v16, v16, v16
	v_add_f32_e32 v21, 1.0, v22
	v_mul_f32_e32 v22, 0x3d372713, v18
	v_mul_f32_e32 v22, v18, v22
	v_fma_f32 v22, v18, v22, v18
	v_mul_f32_e32 v22, 0xbfcc422a, v22
	v_mul_f32_e32 v22, 0x3fb8aa3b, v22
	v_rcp_f32_e32 v21, v21
	v_exp_f32_e32 v22, v22
	v_add_f32_e32 v19, v146, v19
	v_fmac_f32_e32 v19, v122, v125
	ds_write_b16 v28, v16 offset:43264
	v_mul_f32_e32 v16, v17, v21
	v_add_f32_e32 v21, 1.0, v22
	v_mul_f32_e32 v22, 0x3d372713, v19
	v_mul_f32_e32 v22, v19, v22
	v_fma_f32 v22, v19, v22, v19
	v_mul_f32_e32 v22, 0xbfcc422a, v22
	v_mul_f32_e32 v22, 0x3fb8aa3b, v22
	v_exp_f32_e32 v22, v22
	v_rcp_f32_e32 v21, v21
	v_cvt_pk_bf16_f32 v16, v16, v16
	v_add_f32_e32 v17, 1.0, v22
	v_rcp_f32_e32 v17, v17
	ds_write_b16 v28, v16 offset:43792
	v_mul_f32_e32 v16, v18, v21
	v_cvt_pk_bf16_f32 v16, v16, v16
	ds_write_b16 v28, v16 offset:44320
	v_mul_f32_e32 v16, v19, v17
	v_cvt_pk_bf16_f32 v16, v16, v16
	ds_write_b16 v28, v16 offset:44848
	v_pk_mov_b32 v[16:17], v[70:71], v[70:71] op_sel:[1,0]
	v_mov_b32_e32 v18, v75

.LBB0_1489:
	v_pk_mul_f32 v[72:73], v[70:71], v[72:73] op_sel_hi:[1,0]
	v_add_u32_e32 v99, s0, v65
	v_pk_fma_f32 v[74:75], v[66:67], v[68:69], v[72:73] op_sel_hi:[1,0,1]
	v_pk_fma_f32 v[68:69], v[66:67], v[68:69], v[72:73] op_sel_hi:[1,0,1] neg_lo:[0,0,1] neg_hi:[0,0,1]
	v_cvt_pk_bf16_f32 v98, v68, v75
	v_pk_mul_f32 v[72:73], v[70:71], v[74:75] op_sel:[0,1]
	v_add_u32_e32 v100, 0x400, v99
	v_pk_fma_f32 v[74:75], v[66:67], v[68:69], v[72:73] op_sel_hi:[1,0,1]
	v_pk_fma_f32 v[68:69], v[66:67], v[68:69], v[72:73] op_sel_hi:[1,0,1] neg_lo:[0,0,1] neg_hi:[0,0,1]
	v_cvt_pk_bf16_f32 v72, v68, v75
	ds_write2_b32 v100, v72, v98 offset0:152 offset1:220
	v_pk_mul_f32 v[72:73], v[70:71], v[74:75] op_sel:[0,1]
	s_addk_i32 s0, 0xf780
	v_pk_fma_f32 v[74:75], v[66:67], v[68:69], v[72:73] op_sel_hi:[1,0,1]
	v_pk_fma_f32 v[68:69], v[66:67], v[68:69], v[72:73] op_sel_hi:[1,0,1] neg_lo:[0,0,1] neg_hi:[0,0,1]
	v_cvt_pk_bf16_f32 v98, v68, v75
	v_pk_mul_f32 v[72:73], v[70:71], v[74:75] op_sel:[0,1]
	s_cmpk_lg_i32 s0, 0xf780
	v_pk_fma_f32 v[74:75], v[66:67], v[68:69], v[72:73] op_sel_hi:[1,0,1]
	v_pk_fma_f32 v[68:69], v[66:67], v[68:69], v[72:73] op_sel_hi:[1,0,1] neg_lo:[0,0,1] neg_hi:[0,0,1]
	v_cvt_pk_bf16_f32 v72, v68, v75
	ds_write2_b32 v100, v72, v98 offset0:16 offset1:84
	v_pk_mul_f32 v[72:73], v[70:71], v[74:75] op_sel:[0,1]
	s_nop 0
	v_pk_fma_f32 v[74:75], v[66:67], v[68:69], v[72:73] op_sel_hi:[1,0,1]
	v_pk_fma_f32 v[68:69], v[66:67], v[68:69], v[72:73] op_sel_hi:[1,0,1] neg_lo:[0,0,1] neg_hi:[0,0,1]
	v_cvt_pk_bf16_f32 v98, v68, v75
	v_pk_mul_f32 v[72:73], v[70:71], v[74:75] op_sel:[0,1]
	s_nop 0
	v_pk_fma_f32 v[74:75], v[66:67], v[68:69], v[72:73] op_sel_hi:[1,0,1]
	v_pk_fma_f32 v[68:69], v[66:67], v[68:69], v[72:73] op_sel_hi:[1,0,1] neg_lo:[0,0,1] neg_hi:[0,0,1]
	v_cvt_pk_bf16_f32 v72, v68, v75
	ds_write2_b32 v99, v72, v98 offset0:136 offset1:204
	v_pk_mul_f32 v[72:73], v[70:71], v[74:75] op_sel:[0,1]
	s_nop 0
	v_pk_fma_f32 v[74:75], v[66:67], v[68:69], v[72:73] op_sel_hi:[1,0,1]
	v_pk_fma_f32 v[68:69], v[66:67], v[68:69], v[72:73] op_sel_hi:[1,0,1] neg_lo:[0,0,1] neg_hi:[0,0,1]
	v_bfe_u32 v73, v75, 16, 1
	v_bfe_u32 v72, v68, 16, 1
	v_add3_u32 v72, v68, v72, s89
	v_lshrrev_b32_e32 v72, 16, v72
	v_add3_u32 v73, v75, v73, s89
	v_pk_mul_f32 v[74:75], v[70:71], v[74:75] op_sel:[0,1]
	v_and_or_b32 v98, v73, s75, v72
	v_pk_fma_f32 v[72:73], v[66:67], v[68:69], v[74:75] op_sel_hi:[1,0,1]
	v_pk_fma_f32 v[68:69], v[66:67], v[68:69], v[74:75] op_sel_hi:[1,0,1] neg_lo:[0,0,1] neg_hi:[0,0,1]
	v_cvt_pk_bf16_f32 v69, v68, v73
	v_mov_b32_e32 v72, v73
	ds_write2_b32 v99, v69, v98 offset1:68
	s_cbranch_scc1 .LBB0_1489
	s_waitcnt vmcnt(7) lgkmcnt(11)
	v_mfma_f32_16x16x32_bf16 v[56:59], v[56:59], v[12:15], 0
	v_add_f32_e32 v65, v114, v115
	v_add_f32_e32 v69, v84, v85
	s_waitcnt lgkmcnt(9)
	v_mfma_f32_16x16x32_bf16 v[12:15], v[60:63], v[12:15], 0
	v_add_f32_e32 v67, v86, v87
	v_add_f32_e32 v70, v88, v89
	v_add_f32_e32 v66, v90, v91
	s_waitcnt vmcnt(6)
	v_mfma_f32_16x16x32_bf16 v[32:35], v[32:35], v[8:11], v[56:59]
	v_add_f32_e32 v71, v92, v93
	v_add_f32_e32 v68, v94, v95
	v_add_f32_e32 v72, v96, v97
	s_waitcnt lgkmcnt(8)
	v_mfma_f32_16x16x32_bf16 v[8:11], v[40:43], v[8:11], v[12:15]
	v_and_b32_e32 v40, 31, v137
	v_lshrrev_b32_e32 v41, 5, v138
	s_mov_b64 s[0:1], 0
	s_waitcnt vmcnt(5) lgkmcnt(7)
	v_mfma_f32_16x16x32_bf16 v[12:15], v[44:47], v[4:7], v[32:35]
	s_waitcnt lgkmcnt(5)
	v_mfma_f32_16x16x32_bf16 v[4:7], v[52:55], v[4:7], v[8:11]
	s_nop 0
	v_and_b32_e32 v34, 0xffffffdf, v137
	v_or_b32_e32 v32, 32, v137
	v_ashrrev_i32_e32 v35, 31, v34
	s_waitcnt vmcnt(4)
	v_mfma_f32_16x16x32_bf16 v[8:11], v[36:39], v[0:3], v[12:15]
	v_ashrrev_i32_e32 v33, 31, v32
	s_waitcnt lgkmcnt(4)
	v_mfma_f32_16x16x32_bf16 v[0:3], v[48:51], v[0:3], v[4:7]
	s_nop 2
	ds_read_b128 v[4:7], v131
	s_waitcnt vmcnt(3) lgkmcnt(0)
	v_mfma_f32_16x16x32_bf16 v[4:7], v[4:7], v[28:31], v[8:11]
	s_nop 2
	ds_read_b128 v[8:11], v131 offset:4352
	s_waitcnt lgkmcnt(0)
	v_mfma_f32_16x16x32_bf16 v[0:3], v[8:11], v[28:31], v[0:3]
	ds_read_b128 v[8:11], v131 offset:64
	s_waitcnt vmcnt(2) lgkmcnt(0)
	v_mfma_f32_16x16x32_bf16 v[4:7], v[8:11], v[24:27], v[4:7]
	ds_read_b128 v[8:11], v131 offset:4416
	s_waitcnt lgkmcnt(0)
	v_mfma_f32_16x16x32_bf16 v[0:3], v[8:11], v[24:27], v[0:3]
	ds_read_b128 v[8:11], v131 offset:128
	s_waitcnt vmcnt(1) lgkmcnt(0)
	v_mfma_f32_16x16x32_bf16 v[4:7], v[8:11], v[20:23], v[4:7]
	ds_read_b128 v[8:11], v131 offset:4480
	s_waitcnt lgkmcnt(0)
	v_mfma_f32_16x16x32_bf16 v[0:3], v[8:11], v[20:23], v[0:3]
	ds_read_b128 v[8:11], v131 offset:192
	s_waitcnt vmcnt(0) lgkmcnt(0)
	v_mfma_f32_16x16x32_bf16 v[4:7], v[8:11], v[16:19], v[4:7]
	ds_read_b128 v[8:11], v131 offset:4544
	s_nop 6
	v_add_f32_e32 v4, v65, v4
	v_fmac_f32_e32 v4, v113, v77
	s_waitcnt lgkmcnt(0)
	v_mfma_f32_16x16x32_bf16 v[0:3], v[8:11], v[16:19], v[0:3]
	v_mul_f32_e32 v9, 0x3d372713, v4
	v_mul_f32_e32 v9, v4, v9
	v_fma_f32 v9, v4, v9, v4
	v_mul_f32_e32 v9, 0xbfcc422a, v9
	v_mul_f32_e32 v9, 0x3fb8aa3b, v9
	v_exp_f32_e32 v9, v9
	v_lshlrev_b32_e32 v8, 1, v112
	v_add3_u32 v8, v130, v8, v132
	v_add_f32_e32 v0, v66, v0
	v_add_f32_e32 v9, 1.0, v9
	v_rcp_f32_e32 v9, v9
	v_fmac_f32_e32 v0, v80, v77
	v_mul_f32_e32 v4, v4, v9
	v_cvt_pk_bf16_f32 v4, v4, v4
	ds_write_b16 v8, v4 offset:34816
	v_add_f32_e32 v4, v69, v5
	v_fmac_f32_e32 v4, v83, v77
	v_mul_f32_e32 v5, 0x3d372713, v4
	v_mul_f32_e32 v5, v4, v5
	v_fma_f32 v5, v4, v5, v4
	v_mul_f32_e32 v5, 0xbfcc422a, v5
	v_mul_f32_e32 v5, 0x3fb8aa3b, v5
	v_exp_f32_e32 v5, v5
	s_nop 0
	v_add_f32_e32 v5, 1.0, v5
	v_rcp_f32_e32 v5, v5
	s_nop 0
	v_mul_f32_e32 v4, v4, v5
	v_cvt_pk_bf16_f32 v4, v4, v4
	ds_write_b16 v8, v4 offset:35344
	v_add_f32_e32 v4, v67, v6
	v_fmac_f32_e32 v4, v82, v77
	v_mul_f32_e32 v5, 0x3d372713, v4
	v_mul_f32_e32 v5, v4, v5
	v_fma_f32 v5, v4, v5, v4
	v_mul_f32_e32 v5, 0xbfcc422a, v5
	v_mul_f32_e32 v5, 0x3fb8aa3b, v5
	v_exp_f32_e32 v5, v5
	v_mul_u32_u24_e32 v6, 0x210, v40
	v_add_f32_e32 v5, 1.0, v5
	v_rcp_f32_e32 v5, v5
	s_nop 0
	v_mul_f32_e32 v4, v4, v5
	v_cvt_pk_bf16_f32 v4, v4, v4
	ds_write_b16 v8, v4 offset:35872
	v_add_f32_e32 v4, v70, v7
	v_fmac_f32_e32 v4, v81, v77
	v_mul_f32_e32 v5, 0x3d372713, v4
	v_mul_f32_e32 v5, v4, v5
	v_fma_f32 v5, v4, v5, v4
	v_mul_f32_e32 v5, 0xbfcc422a, v5
	v_mul_f32_e32 v5, 0x3fb8aa3b, v5
	v_exp_f32_e32 v5, v5
	v_lshlrev_b32_e32 v7, 4, v41
	v_add3_u32 v42, v6, v7, s26
	v_lshrrev_b32_e32 v6, 1, v137
	v_add_f32_e32 v5, 1.0, v5
	v_rcp_f32_e32 v5, v5
	v_and_b32_e32 v6, 16, v6
	v_mul_f32_e32 v4, v4, v5
	v_cvt_pk_bf16_f32 v4, v4, v4
	ds_write_b16 v8, v4 offset:36400
	v_mul_f32_e32 v4, 0x3d372713, v0
	v_mul_f32_e32 v4, v0, v4
	v_fma_f32 v4, v0, v4, v0
	v_mul_f32_e32 v4, 0xbfcc422a, v4
	v_mul_f32_e32 v4, 0x3fb8aa3b, v4
	v_exp_f32_e32 v4, v4
	s_nop 0
	v_add_f32_e32 v4, 1.0, v4
	v_rcp_f32_e32 v4, v4
	s_nop 0
	v_mul_f32_e32 v0, v0, v4
	v_cvt_pk_bf16_f32 v0, v0, v0
	ds_write_b16 v8, v0 offset:43264
	v_add_f32_e32 v0, v71, v1
	v_fmac_f32_e32 v0, v79, v77
	v_mul_f32_e32 v1, 0x3d372713, v0
	v_mul_f32_e32 v1, v0, v1
	v_fma_f32 v1, v0, v1, v0
	v_mul_f32_e32 v1, 0xbfcc422a, v1
	v_mul_f32_e32 v1, 0x3fb8aa3b, v1
	v_exp_f32_e32 v1, v1
	v_lshlrev_b64 v[4:5], 9, v[32:33]
	v_or_b32_e32 v4, v4, v6
	v_add_f32_e32 v1, 1.0, v1
	v_rcp_f32_e32 v1, v1
	s_nop 0
	v_mul_f32_e32 v0, v0, v1
	v_cvt_pk_bf16_f32 v0, v0, v0
	ds_write_b16 v8, v0 offset:43792
	v_add_f32_e32 v0, v68, v2
	v_fmac_f32_e32 v0, v78, v77
	v_mul_f32_e32 v1, 0x3d372713, v0
	v_mul_f32_e32 v1, v0, v1
	v_fma_f32 v1, v0, v1, v0
	v_mul_f32_e32 v1, 0xbfcc422a, v1
	v_mul_f32_e32 v1, 0x3fb8aa3b, v1
	v_exp_f32_e32 v1, v1
	s_nop 0
	v_add_f32_e32 v1, 1.0, v1
	v_rcp_f32_e32 v1, v1
	s_nop 0
	v_mul_f32_e32 v0, v0, v1
	v_cvt_pk_bf16_f32 v0, v0, v0
	ds_write_b16 v8, v0 offset:44320
	v_add_f32_e32 v0, v72, v3
	v_fmac_f32_e32 v0, v76, v77
	v_mul_f32_e32 v1, 0x3d372713, v0
	v_mul_f32_e32 v1, v0, v1
	v_fma_f32 v1, v0, v1, v0
	v_mul_f32_e32 v1, 0xbfcc422a, v1
	v_mul_f32_e32 v1, 0x3fb8aa3b, v1
	v_exp_f32_e32 v1, v1
	v_lshlrev_b64 v[2:3], 9, v[34:35]
	v_or_b32_e32 v2, v2, v6
	v_add_f32_e32 v1, 1.0, v1
	v_rcp_f32_e32 v1, v1
	s_nop 0
	v_mul_f32_e32 v0, v0, v1
	v_cvt_pk_bf16_f32 v0, v0, v0
	ds_write_b16 v8, v0 offset:44848
	s_waitcnt lgkmcnt(0)
	s_barrier
	ds_read_b64 v[0:1], v229 offset:63760
	s_waitcnt lgkmcnt(0)
	v_lshl_add_u64 v[36:37], v[0:1], 0, v[4:5]
	v_lshl_add_u64 v[38:39], v[0:1], 0, v[2:3]
	v_mov_b32_e32 v0, 0
	v_mov_b32_e32 v1, v0
	v_mov_b32_e32 v2, v0
	v_mov_b32_e32 v3, v0
	v_mov_b32_e32 v4, v0
	v_mov_b32_e32 v5, v0
	v_mov_b32_e32 v6, v0
	v_mov_b32_e32 v7, v0
	v_mov_b32_e32 v8, v0
	v_mov_b32_e32 v9, v0
	v_mov_b32_e32 v10, v0
	v_mov_b32_e32 v11, v0
	v_mov_b32_e32 v12, v0
	v_mov_b32_e32 v13, v0
	v_mov_b32_e32 v14, v0
	v_mov_b32_e32 v15, v0
	v_mov_b32_e32 v16, v0
	v_mov_b32_e32 v17, v0
	v_mov_b32_e32 v18, v0
	v_mov_b32_e32 v19, v0
	v_mov_b32_e32 v20, v0
	v_mov_b32_e32 v21, v0
	v_mov_b32_e32 v22, v0
	v_mov_b32_e32 v23, v0
	v_mov_b32_e32 v24, v0
	v_mov_b32_e32 v25, v0
	v_mov_b32_e32 v26, v0
	v_mov_b32_e32 v27, v0
	v_mov_b32_e32 v28, v0
	v_mov_b32_e32 v29, v0
	v_mov_b32_e32 v30, v0
	v_mov_b32_e32 v31, v0

.LBB0_2182:
	s_or_b64 exec, exec, s[0:1]
	v_add_u32_e32 v139, v168, v183
	s_mov_b64 s[0:1], 0xb2d4000
	ds_write_b32 v139, v186
	v_lshl_add_u32 v139, v254, 2, v167
	v_lshl_add_u64 v[128:129], v[232:233], 0, s[0:1]
	s_waitcnt lgkmcnt(0)
	s_barrier
	v_cmp_eq_u32_e64 s[0:1], 1, v166
	ds_read2st64_b32 v[166:167], v139 offset0:4 offset1:5
	s_cmp_lt_i32 s8, 16
	ds_read2_b32 v[186:187], v139 offset0:32 offset1:96
	s_movk_i32 s4, 0x80
	s_cselect_b64 s[2:3], -1, 0
	v_cmp_gt_u32_e64 s[4:5], s4, v252
	s_and_b64 s[4:5], s[2:3], s[4:5]
	s_and_b64 s[0:1], s[2:3], s[0:1]
	s_waitcnt lgkmcnt(1)
	v_cndmask_b32_e64 v139, 0, v167, s[4:5]
	v_and_b32_e32 v167, 64, v244
	v_xor_b32_e32 v147, 32, v244
	v_add_u32_e32 v167, 64, v167
	s_waitcnt lgkmcnt(0)
	v_cndmask_b32_e64 v217, 0, v186, s[0:1]
	v_cndmask_b32_e64 v218, 0, v187, s[0:1]
	v_cmp_lt_i32_e64 s[0:1], v147, v167
	s_waitcnt vmcnt(3)
	v_fma_f32 v223, v114, v153, v148
	v_fmac_f32_e32 v223, v115, v154
	v_cndmask_b32_e64 v147, v244, v147, s[0:1]
	v_lshlrev_b32_e32 v147, 2, v147
	ds_bpermute_b32 v219, v147, v80
	v_fma_f32 v224, v117, v153, v148
	v_fmac_f32_e32 v224, v118, v154
	v_fmac_f32_e32 v224, v119, v155
	ds_bpermute_b32 v220, v147, v64
	ds_bpermute_b32 v207, v147, v127
	v_and_b32_e32 v221, 0xffffff80, v252
	v_lshl_or_b32 v221, v253, 2, v221
	v_cndmask_b32_e64 v166, 0, v166, s[4:5]
	ds_bpermute_b32 v188, v147, v95
	ds_bpermute_b32 v168, v147, v63
	ds_bpermute_b32 v208, v147, v48
	ds_bpermute_b32 v187, v147, v16
	ds_bpermute_b32 v205, v147, v111
	ds_bpermute_b32 v186, v147, v79
	ds_bpermute_b32 v167, v147, v47
	ds_bpermute_b32 v206, v147, v32
	ds_bpermute_b32 v183, v147, v0
	s_nop 0
	s_nop 1
	s_nop 1
	s_nop 1
	s_nop 1
	s_nop 1
	ds_bpermute_b32 v146, v147, v146
	s_waitcnt lgkmcnt(0)
	v_cndmask_b32_e32 v146, v146, v217, vcc
	v_fma_f32 v146, v153, v146, v148
	v_fmac_f32_e32 v146, v154, v112
	v_fma_f32 v217, v153, v112, v148
	v_fmac_f32_e32 v146, v113, v155
	v_fmac_f32_e32 v217, v113, v154
	v_fmac_f32_e32 v217, v114, v155
	s_nop 1
	s_nop 1
	s_nop 1
	s_nop 1
	s_nop 1
	s_nop 1
	s_nop 1
	s_nop 1
	s_nop 1
	s_nop 1
	s_nop 1
	ds_bpermute_b32 v144, v147, v144
	s_waitcnt lgkmcnt(0)
	v_fmac_f32_e32 v223, v155, v144
	v_fma_f32 v144, v116, v153, v148
	v_fmac_f32_e32 v144, v117, v154
	v_fmac_f32_e32 v144, v118, v155
	s_nop 0
	s_nop 1
	s_nop 1
	s_nop 1
	s_nop 1
	s_nop 1
	s_nop 1
	s_nop 1
	s_nop 1
	s_nop 1
	s_nop 1
	s_nop 1
	s_nop 1
	ds_bpermute_b32 v142, v147, v142
	s_waitcnt lgkmcnt(0)
	v_fma_f32 v142, v153, v142, v148
	v_fmac_f32_e32 v142, v116, v154
	v_fmac_f32_e32 v142, v117, v155
	s_nop 1
	s_nop 1
	s_nop 1
	s_nop 1
	s_nop 1
	s_nop 1
	s_nop 1
	s_nop 1
	s_nop 1
	s_nop 1
	s_nop 1
	s_nop 1
	s_nop 1
	ds_bpermute_b32 v140, v147, v140
	s_nop 0
	s_nop 1
	s_nop 1
	s_nop 1
	s_nop 1
	s_nop 1
	s_nop 1
	s_nop 1
	s_nop 1
	s_nop 1
	s_nop 1
	s_nop 1
	s_nop 1
	s_nop 1
	s_nop 1
	ds_bpermute_b32 v136, v147, v136
	s_nop 0
	s_nop 1
	s_nop 1
	s_nop 1
	s_nop 1
	s_nop 1
	s_nop 1
	s_nop 1
	s_nop 1
	s_nop 1
	s_nop 1
	s_nop 1
	s_nop 1
	s_nop 1
	s_nop 1
	ds_bpermute_b32 v134, v147, v134
	s_nop 0
	s_nop 1
	s_nop 1
	s_nop 1
	s_nop 1
	s_nop 1
	s_nop 1
	s_nop 1
	s_nop 1
	s_nop 1
	s_nop 1
	s_nop 1
	s_nop 1
	s_nop 1
	s_nop 1
	ds_bpermute_b32 v138, v147, v138
	s_nop 0
	v_fma_f32 v112, v126, v153, v148
	v_fmac_f32_e32 v112, v127, v154
	s_nop 1
	s_nop 1
	v_fma_f32 v116, v122, v153, v148
	v_fmac_f32_e32 v116, v123, v154
	v_fma_f32 v117, v121, v153, v148
	s_waitcnt lgkmcnt(1)
	v_fmac_f32_e32 v116, v155, v134
	v_fma_f32 v118, v118, v153, v148
	v_fmac_f32_e32 v118, v119, v154
	v_fma_f32 v119, v153, v136, v148
	v_fmac_f32_e32 v119, v120, v154
	v_fma_f32 v120, v120, v153, v148
	v_fmac_f32_e32 v119, v121, v155
	v_fmac_f32_e32 v120, v121, v154
	s_waitcnt vmcnt(0)
	v_fma_f32 v134, v96, v150, v149
	v_fmac_f32_e32 v117, v122, v154
	v_fmac_f32_e32 v120, v122, v155
	v_fmac_f32_e32 v117, v123, v155
	ds_bpermute_b32 v122, v147, v215
	ds_bpermute_b32 v123, v147, v214
	v_fma_f32 v136, v97, v150, v149
	v_fmac_f32_e32 v136, v98, v151
	v_fmac_f32_e32 v136, v99, v152
	v_fmac_f32_e32 v134, v97, v151
	v_fmac_f32_e32 v118, v155, v140
	ds_bpermute_b32 v132, v147, v132
	v_fma_f32 v222, v113, v153, v148
	v_fmac_f32_e32 v222, v114, v154
	v_fmac_f32_e32 v222, v115, v155
	s_waitcnt lgkmcnt(3)
	v_fma_f32 v115, v153, v138, v148
	s_waitcnt lgkmcnt(0)
	v_cndmask_b32_e32 v121, v219, v132, vcc
	v_fmac_f32_e32 v112, v155, v121
	ds_bpermute_b32 v121, v147, v216
	v_fmac_f32_e32 v115, v124, v154
	v_fma_f32 v114, v124, v153, v148
	v_fmac_f32_e32 v115, v125, v155
	v_fmac_f32_e32 v114, v125, v154
	s_waitcnt lgkmcnt(0)
	v_cndmask_b32_e32 v121, v121, v218, vcc
	v_fma_f32 v121, v150, v121, v149
	v_fmac_f32_e32 v121, v96, v151
	v_mul_f32_e32 v96, 0x3d372713, v146
	v_mul_f32_e32 v96, v146, v96
	v_fma_f32 v96, v146, v96, v146
	v_mul_f32_e32 v96, 0xbfcc422a, v96
	v_mul_f32_e32 v96, 0x3fb8aa3b, v96
	v_exp_f32_e32 v96, v96
	v_fma_f32 v113, v125, v153, v148
	ds_bpermute_b32 v124, v147, v213
	ds_bpermute_b32 v125, v147, v212
	v_add_f32_e32 v96, 1.0, v96
	v_fmac_f32_e32 v113, v126, v154
	ds_bpermute_b32 v132, v147, v209
	v_fma_f32 v209, v102, v150, v149
	v_rcp_f32_e32 v96, v96
	v_fmac_f32_e32 v113, v127, v155
	ds_bpermute_b32 v127, v147, v210
	v_fmac_f32_e32 v209, v103, v151
	s_waitcnt lgkmcnt(3)
	v_fmac_f32_e32 v209, v152, v124
	s_waitcnt lgkmcnt(2)
	v_fma_f32 v124, v150, v125, v149
	v_fma_f32 v138, v98, v150, v149
	v_fmac_f32_e32 v124, v104, v151
	v_fma_f32 v104, v104, v150, v149
	v_fmac_f32_e32 v121, v97, v152
	v_fmac_f32_e32 v138, v99, v151
	v_fmac_f32_e32 v124, v105, v152
	v_fmac_f32_e32 v104, v105, v151
	v_fma_f32 v105, v105, v150, v149
	v_fma_f32 v99, v110, v150, v149
	v_mul_f32_e32 v96, v146, v96
	v_fmac_f32_e32 v138, v152, v122
	v_fma_f32 v122, v150, v123, v149
	v_fmac_f32_e32 v104, v106, v152
	v_fmac_f32_e32 v105, v106, v151
	v_fma_f32 v106, v106, v150, v149
	s_waitcnt lgkmcnt(1)
	v_cndmask_b32_e32 v97, v220, v132, vcc
	v_fmac_f32_e32 v99, v111, v151
	v_mul_f32_e32 v96, v121, v96
	v_fmac_f32_e32 v122, v100, v151
	v_fma_f32 v123, v100, v150, v149
	v_fmac_f32_e32 v105, v107, v152
	v_fmac_f32_e32 v106, v107, v151
	s_waitcnt lgkmcnt(0)
	v_fma_f32 v107, v150, v127, v149
	v_fmac_f32_e32 v99, v152, v97
	v_fmac_f32_e32 v122, v101, v152
	v_fmac_f32_e32 v123, v101, v151
	v_fma_f32 v140, v101, v150, v149
	v_fmac_f32_e32 v107, v108, v151
	v_fma_f32 v101, v108, v150, v149
	v_cvt_pk_bf16_f32 v108, v96, v96
	v_mul_f32_e32 v96, 0x3d372713, v217
	v_mul_f32_e32 v96, v217, v96
	v_fma_f32 v96, v217, v96, v217
	v_mul_f32_e32 v96, 0xbfcc422a, v96
	v_mul_f32_e32 v96, 0x3fb8aa3b, v96
	v_fmac_f32_e32 v107, v109, v152
	v_fmac_f32_e32 v101, v109, v151
	v_fma_f32 v100, v109, v150, v149
	v_exp_f32_e32 v109, v96
	v_fmac_f32_e32 v134, v98, v152
	v_fmac_f32_e32 v140, v102, v151
	v_mul_u32_u24_e32 v98, 0x1600, v221
	v_lshl_add_u32 v98, v130, 1, v98
	v_readfirstlane_b32 s18, v128
	v_readfirstlane_b32 s19, v129
	s_lshl_b32 s20, s8, 8
	s_mul_i32 s20, s20, 0x1600
	s_add_u32 s18, s18, s20
	s_addc_u32 s19, s19, 0
	v_add_f32_e32 v109, 1.0, v109
	v_rcp_f32_e32 v109, v109
	v_fmac_f32_e32 v123, v102, v152
	v_fmac_f32_e32 v140, v103, v152
	s_add_u32 s20, s18, 0x0
	s_addc_u32 s21, s19, 0
	global_store_short v98, v108, s[20:21]
	v_mul_f32_e32 v103, v217, v109
	v_mul_f32_e32 v109, 0x3d372713, v222
	v_mul_f32_e32 v109, v222, v109
	v_fma_f32 v109, v222, v109, v222
	v_mul_f32_e32 v109, 0xbfcc422a, v109
	v_mul_f32_e32 v109, 0x3fb8aa3b, v109
	v_exp_f32_e32 v109, v109
	v_mul_f32_e32 v103, v134, v103
	v_add_f32_e32 v109, 1.0, v109
	v_rcp_f32_e32 v109, v109
	v_cvt_pk_bf16_f32 v108, v103, v103
	s_add_u32 s20, s18, 0x1600
	s_addc_u32 s21, s19, 0
	global_store_short v98, v108, s[20:21]
	v_mul_f32_e32 v103, v222, v109
	v_mul_f32_e32 v109, 0x3d372713, v223
	v_mul_f32_e32 v109, v223, v109
	v_fma_f32 v109, v223, v109, v223
	v_mul_f32_e32 v109, 0xbfcc422a, v109
	v_mul_f32_e32 v109, 0x3fb8aa3b, v109
	v_exp_f32_e32 v109, v109
	v_mul_f32_e32 v103, v136, v103
	v_add_f32_e32 v109, 1.0, v109
	v_rcp_f32_e32 v109, v109
	v_cvt_pk_bf16_f32 v108, v103, v103
	v_fmac_f32_e32 v114, v126, v155
	ds_bpermute_b32 v126, v147, v211
	s_add_u32 s20, s18, 0x2c00
	s_addc_u32 s21, s19, 0
	global_store_short v98, v108, s[20:21]
	v_mul_f32_e32 v103, v223, v109
	v_mul_f32_e32 v103, v138, v103
	v_cvt_pk_bf16_f32 v108, v103, v103
	v_fmac_f32_e32 v100, v110, v151
	s_waitcnt lgkmcnt(0)
	v_fmac_f32_e32 v106, v152, v126
	v_fmac_f32_e32 v101, v110, v152
	v_fmac_f32_e32 v100, v111, v152
	s_add_u32 s20, s18, 0x4200
	s_addc_u32 s21, s19, 0
	global_store_short v98, v108, s[20:21]
	v_mul_f32_e32 v103, 0x3d372713, v142
	v_mul_f32_e32 v103, v142, v103
	v_fma_f32 v103, v142, v103, v142
	v_mul_f32_e32 v103, 0xbfcc422a, v103
	v_mul_f32_e32 v103, 0x3fb8aa3b, v103
	v_exp_f32_e32 v103, v103
	s_nop 0
	v_add_f32_e32 v103, 1.0, v103
	v_rcp_f32_e32 v103, v103
	s_nop 0
	v_mul_f32_e32 v103, v142, v103
	v_mul_f32_e32 v103, v122, v103
	v_cvt_pk_bf16_f32 v108, v103, v103
	s_add_u32 s20, s18, 0xb000
	s_addc_u32 s21, s19, 0
	global_store_short v98, v108, s[20:21]
	v_mul_f32_e32 v103, 0x3d372713, v144
	v_mul_f32_e32 v103, v144, v103
	v_fma_f32 v103, v144, v103, v144
	v_mul_f32_e32 v103, 0xbfcc422a, v103
	v_mul_f32_e32 v103, 0x3fb8aa3b, v103
	v_exp_f32_e32 v103, v103
	s_nop 0
	v_add_f32_e32 v103, 1.0, v103
	v_rcp_f32_e32 v103, v103
	s_nop 0
	v_mul_f32_e32 v103, v144, v103
	v_mul_f32_e32 v103, v123, v103
	v_cvt_pk_bf16_f32 v108, v103, v103
	s_add_u32 s20, s18, 0xc600
	s_addc_u32 s21, s19, 0
	global_store_short v98, v108, s[20:21]
	v_mul_f32_e32 v103, 0x3d372713, v224
	v_mul_f32_e32 v103, v224, v103
	v_fma_f32 v103, v224, v103, v224
	v_mul_f32_e32 v103, 0xbfcc422a, v103
	v_mul_f32_e32 v103, 0x3fb8aa3b, v103
	v_exp_f32_e32 v103, v103
	s_nop 0
	v_add_f32_e32 v103, 1.0, v103
	v_rcp_f32_e32 v103, v103
	s_nop 0
	v_mul_f32_e32 v103, v224, v103
	v_mul_f32_e32 v103, v140, v103
	v_cvt_pk_bf16_f32 v108, v103, v103
	s_add_u32 s20, s18, 0xdc00
	s_addc_u32 s21, s19, 0
	global_store_short v98, v108, s[20:21]
	v_mul_f32_e32 v103, 0x3d372713, v118
	v_mul_f32_e32 v103, v118, v103
	v_fma_f32 v103, v118, v103, v118
	v_mul_f32_e32 v103, 0xbfcc422a, v103
	v_mul_f32_e32 v103, 0x3fb8aa3b, v103
	v_exp_f32_e32 v103, v103
	s_nop 0
	v_add_f32_e32 v103, 1.0, v103
	v_rcp_f32_e32 v103, v103
	s_nop 0
	v_mul_f32_e32 v103, v118, v103
	v_mul_f32_e32 v103, v209, v103
	v_cvt_pk_bf16_f32 v108, v103, v103
	s_add_u32 s20, s18, 0xf200
	s_addc_u32 s21, s19, 0
	global_store_short v98, v108, s[20:21]
	v_mul_f32_e32 v103, 0x3d372713, v119
	v_mul_f32_e32 v103, v119, v103
	v_fma_f32 v103, v119, v103, v119
	v_mul_f32_e32 v103, 0xbfcc422a, v103
	v_mul_f32_e32 v103, 0x3fb8aa3b, v103
	v_exp_f32_e32 v103, v103
	s_nop 0
	v_add_f32_e32 v103, 1.0, v103
	v_rcp_f32_e32 v103, v103
	s_nop 0
	v_mul_f32_e32 v103, v119, v103
	v_mul_f32_e32 v103, v124, v103
	v_cvt_pk_bf16_f32 v108, v103, v103
	s_add_u32 s20, s18, 0x16000
	s_addc_u32 s21, s19, 0
	global_store_short v98, v108, s[20:21]
	v_mul_f32_e32 v103, 0x3d372713, v120
	v_mul_f32_e32 v103, v120, v103
	v_fma_f32 v103, v120, v103, v120
	v_mul_f32_e32 v103, 0xbfcc422a, v103
	v_mul_f32_e32 v103, 0x3fb8aa3b, v103
	v_exp_f32_e32 v103, v103
	s_nop 0
	v_add_f32_e32 v103, 1.0, v103
	v_rcp_f32_e32 v103, v103
	s_nop 0
	v_mul_f32_e32 v103, v120, v103
	v_mul_f32_e32 v103, v104, v103
	v_cvt_pk_bf16_f32 v104, v103, v103
	s_add_u32 s20, s18, 0x17600
	s_addc_u32 s21, s19, 0
	global_store_short v98, v104, s[20:21]
	v_mul_f32_e32 v103, 0x3d372713, v117
	v_mul_f32_e32 v103, v117, v103
	v_fma_f32 v103, v117, v103, v117
	v_mul_f32_e32 v103, 0xbfcc422a, v103
	v_mul_f32_e32 v103, 0x3fb8aa3b, v103
	v_exp_f32_e32 v103, v103
	s_nop 0
	v_add_f32_e32 v103, 1.0, v103
	v_rcp_f32_e32 v103, v103
	s_nop 0
	v_mul_f32_e32 v103, v117, v103
	v_mul_f32_e32 v103, v105, v103
	v_cvt_pk_bf16_f32 v104, v103, v103
	s_add_u32 s20, s18, 0x18c00
	s_addc_u32 s21, s19, 0
	global_store_short v98, v104, s[20:21]
	v_mul_f32_e32 v103, 0x3d372713, v116
	v_mul_f32_e32 v103, v116, v103
	v_fma_f32 v103, v116, v103, v116
	v_mul_f32_e32 v103, 0xbfcc422a, v103
	v_mul_f32_e32 v103, 0x3fb8aa3b, v103
	v_exp_f32_e32 v103, v103
	s_nop 0
	v_add_f32_e32 v103, 1.0, v103
	v_rcp_f32_e32 v103, v103
	s_nop 0
	v_mul_f32_e32 v103, v116, v103
	v_mul_f32_e32 v103, v106, v103
	v_cvt_pk_bf16_f32 v104, v103, v103
	s_add_u32 s20, s18, 0x1a200
	s_addc_u32 s21, s19, 0
	global_store_short v98, v104, s[20:21]
	v_mul_f32_e32 v103, 0x3d372713, v115
	v_mul_f32_e32 v103, v115, v103
	v_fma_f32 v103, v115, v103, v115
	v_mul_f32_e32 v103, 0xbfcc422a, v103
	v_mul_f32_e32 v103, 0x3fb8aa3b, v103
	v_exp_f32_e32 v103, v103
	s_nop 0
	v_add_f32_e32 v103, 1.0, v103
	v_rcp_f32_e32 v103, v103
	s_nop 0
	v_mul_f32_e32 v103, v115, v103
	v_mul_f32_e32 v103, v107, v103
	v_cvt_pk_bf16_f32 v104, v103, v103
	s_add_u32 s20, s18, 0x21000
	s_addc_u32 s21, s19, 0
	global_store_short v98, v104, s[20:21]
	v_mul_f32_e32 v103, 0x3d372713, v114
	v_mul_f32_e32 v103, v114, v103
	v_fma_f32 v103, v114, v103, v114
	v_mul_f32_e32 v103, 0xbfcc422a, v103
	v_mul_f32_e32 v103, 0x3fb8aa3b, v103
	v_exp_f32_e32 v103, v103
	s_nop 0
	v_add_f32_e32 v103, 1.0, v103
	v_rcp_f32_e32 v103, v103
	s_nop 0
	v_mul_f32_e32 v103, v114, v103
	v_mul_f32_e32 v101, v101, v103
	v_cvt_pk_bf16_f32 v101, v101, v101
	s_add_u32 s20, s18, 0x22600
	s_addc_u32 s21, s19, 0
	global_store_short v98, v101, s[20:21]
	v_mul_f32_e32 v102, 0x3d372713, v113
	v_mul_f32_e32 v102, v113, v102
	v_fma_f32 v102, v113, v102, v113
	v_mul_f32_e32 v102, 0xbfcc422a, v102
	v_mul_f32_e32 v102, 0x3fb8aa3b, v102
	v_exp_f32_e32 v102, v102
	s_nop 0
	v_add_f32_e32 v102, 1.0, v102
	v_rcp_f32_e32 v102, v102
	s_nop 0
	v_mul_f32_e32 v102, v113, v102
	v_mul_f32_e32 v100, v100, v102
	v_cvt_pk_bf16_f32 v102, v100, v100
	s_add_u32 s20, s18, 0x23c00
	s_addc_u32 s21, s19, 0
	global_store_short v98, v102, s[20:21]
	v_mul_f32_e32 v101, 0x3d372713, v112
	v_mul_f32_e32 v101, v112, v101
	v_fma_f32 v101, v112, v101, v112
	v_mul_f32_e32 v101, 0xbfcc422a, v101
	v_mul_f32_e32 v101, 0x3fb8aa3b, v101
	v_exp_f32_e32 v101, v101
	s_nop 0
	v_add_f32_e32 v101, 1.0, v101
	v_rcp_f32_e32 v101, v101
	s_nop 0
	v_mul_f32_e32 v101, v112, v101
	v_mul_f32_e32 v99, v99, v101
	v_cvt_pk_bf16_f32 v99, v99, v99
	s_add_u32 s20, s18, 0x25200
	s_addc_u32 s21, s19, 0
	global_store_short v98, v99, s[20:21]
	ds_bpermute_b32 v101, v147, v203
	ds_bpermute_b32 v102, v147, v202
	ds_bpermute_b32 v100, v147, v204
	ds_bpermute_b32 v104, v147, v200
	v_fma_f32 v110, v82, v153, v148
	ds_bpermute_b32 v106, v147, v198
	v_fmac_f32_e32 v110, v83, v154
	s_waitcnt lgkmcnt(4)
	v_fmac_f32_e32 v110, v155, v101
	s_waitcnt lgkmcnt(3)
	v_fma_f32 v101, v153, v102, v148
	v_fma_f32 v102, v84, v153, v148
	v_fmac_f32_e32 v101, v84, v154
	v_fmac_f32_e32 v102, v85, v154
	v_fma_f32 v111, v85, v153, v148
	v_fma_f32 v109, v81, v153, v148
	v_fmac_f32_e32 v101, v85, v155
	v_fmac_f32_e32 v102, v86, v155
	v_fmac_f32_e32 v111, v86, v154
	v_fma_f32 v86, v86, v153, v148
	v_fma_f32 v85, v89, v153, v148
	ds_bpermute_b32 v105, v147, v199
	s_waitcnt lgkmcnt(3)
	v_cndmask_b32_e32 v100, v100, v207, vcc
	v_fma_f32 v108, v80, v153, v148
	v_fmac_f32_e32 v109, v82, v154
	v_fmac_f32_e32 v111, v87, v155
	v_fmac_f32_e32 v86, v87, v154
	s_waitcnt lgkmcnt(2)
	v_fma_f32 v87, v153, v104, v148
	v_fmac_f32_e32 v85, v90, v154
	v_fma_f32 v84, v90, v153, v148
	v_fma_f32 v100, v153, v100, v148
	v_fmac_f32_e32 v108, v81, v154
	v_fmac_f32_e32 v109, v83, v155
	v_fmac_f32_e32 v87, v88, v154
	v_fma_f32 v88, v88, v153, v148
	v_fmac_f32_e32 v85, v91, v155
	v_fmac_f32_e32 v84, v91, v154
	s_waitcnt lgkmcnt(1)
	v_fma_f32 v83, v153, v106, v148
	ds_bpermute_b32 v91, v147, v195
	v_fmac_f32_e32 v100, v80, v154
	v_fmac_f32_e32 v108, v82, v155
	v_fmac_f32_e32 v88, v89, v154
	v_fmac_f32_e32 v83, v92, v154
	v_fma_f32 v82, v92, v153, v148
	ds_bpermute_b32 v92, v147, v194
	ds_bpermute_b32 v107, v147, v197
	v_fmac_f32_e32 v100, v81, v155
	v_fmac_f32_e32 v88, v90, v155
	v_fmac_f32_e32 v82, v93, v154
	v_fma_f32 v81, v93, v153, v148
	ds_bpermute_b32 v90, v147, v196
	v_fmac_f32_e32 v82, v94, v155
	v_fmac_f32_e32 v81, v94, v154
	v_fma_f32 v80, v94, v153, v148
	ds_bpermute_b32 v94, v147, v192
	v_fma_f32 v106, v66, v150, v149
	s_waitcnt lgkmcnt(5)
	v_fmac_f32_e32 v84, v155, v105
	v_fma_f32 v105, v65, v150, v149
	v_fmac_f32_e32 v106, v67, v151
	v_fmac_f32_e32 v105, v66, v151
	s_waitcnt lgkmcnt(4)
	v_fmac_f32_e32 v106, v152, v91
	v_fma_f32 v91, v68, v150, v149
	v_cndmask_b32_e64 v99, 0, v208, s[2:3]
	v_fmac_f32_e32 v105, v67, v152
	s_waitcnt lgkmcnt(3)
	v_fma_f32 v67, v150, v92, v149
	v_fmac_f32_e32 v91, v69, v151
	v_fma_f32 v92, v69, v150, v149
	v_fmac_f32_e32 v87, v89, v155
	s_waitcnt lgkmcnt(2)
	v_cndmask_b32_e32 v89, v99, v107, vcc
	ds_bpermute_b32 v99, v147, v190
	s_waitcnt lgkmcnt(2)
	v_cndmask_b32_e32 v90, v90, v205, vcc
	v_fmac_f32_e32 v91, v70, v152
	v_fmac_f32_e32 v92, v70, v151
	v_fma_f32 v70, v70, v150, v149
	v_fma_f32 v90, v150, v90, v149
	v_fmac_f32_e32 v92, v71, v152
	v_fmac_f32_e32 v70, v71, v151
	s_waitcnt lgkmcnt(1)
	v_fma_f32 v71, v150, v94, v149
	v_fmac_f32_e32 v90, v64, v151
	v_fma_f32 v104, v64, v150, v149
	v_fmac_f32_e32 v71, v72, v151
	v_fma_f32 v72, v72, v150, v149
	v_mul_f32_e32 v64, 0x3d372713, v100
	v_fmac_f32_e32 v71, v73, v152
	v_fmac_f32_e32 v72, v73, v151
	v_fma_f32 v73, v73, v150, v149
	v_mul_f32_e32 v64, v100, v64
	v_fmac_f32_e32 v72, v74, v152
	v_fmac_f32_e32 v73, v74, v151
	v_fma_f32 v74, v74, v150, v149
	v_fma_f32 v64, v100, v64, v100
	v_fmac_f32_e32 v104, v65, v151
	v_fmac_f32_e32 v73, v75, v152
	v_fmac_f32_e32 v74, v75, v151
	s_waitcnt lgkmcnt(0)
	v_fma_f32 v75, v150, v99, v149
	v_mul_f32_e32 v64, 0xbfcc422a, v64
	v_fmac_f32_e32 v104, v66, v152
	v_fmac_f32_e32 v75, v76, v151
	v_fma_f32 v66, v76, v150, v149
	v_mul_f32_e32 v64, 0x3fb8aa3b, v64
	ds_bpermute_b32 v103, v147, v201
	v_fmac_f32_e32 v90, v65, v152
	v_fmac_f32_e32 v67, v68, v151
	v_fmac_f32_e32 v75, v77, v152
	v_fmac_f32_e32 v66, v77, v151
	v_fma_f32 v65, v77, v150, v149
	v_exp_f32_e32 v68, v64
	v_mul_f32_e32 v77, 0x3d372713, v108
	v_mul_f32_e32 v77, v108, v77
	v_fma_f32 v77, v108, v77, v108
	v_mul_f32_e32 v77, 0xbfcc422a, v77
	v_add_f32_e32 v68, 1.0, v68
	v_mul_f32_e32 v77, 0x3fb8aa3b, v77
	s_waitcnt lgkmcnt(0)
	v_fmac_f32_e32 v86, v155, v103
	ds_bpermute_b32 v103, v147, v189
	v_rcp_f32_e32 v68, v68
	v_exp_f32_e32 v77, v77
	v_fmac_f32_e32 v80, v95, v154
	v_fmac_f32_e32 v80, v155, v89
	v_cndmask_b32_e64 v89, 0, v206, s[2:3]
	v_fma_f32 v64, v78, v150, v149
	v_mul_f32_e32 v68, v100, v68
	v_add_f32_e32 v77, 1.0, v77
	v_fmac_f32_e32 v67, v69, v152
	s_waitcnt lgkmcnt(0)
	v_cndmask_b32_e32 v69, v89, v103, vcc
	v_fmac_f32_e32 v64, v79, v151
	v_mul_f32_e32 v68, v90, v68
	v_rcp_f32_e32 v77, v77
	v_fmac_f32_e32 v64, v152, v69
	v_cvt_pk_bf16_f32 v76, v68, v68
	s_add_u32 s20, s18, 0x2c000
	s_addc_u32 s21, s19, 0
	global_store_short v98, v76, s[20:21]
	v_mul_f32_e32 v69, v108, v77
	v_mul_f32_e32 v77, 0x3d372713, v109
	v_mul_f32_e32 v77, v109, v77
	v_fma_f32 v77, v109, v77, v109
	v_mul_f32_e32 v77, 0xbfcc422a, v77
	v_mul_f32_e32 v77, 0x3fb8aa3b, v77
	v_exp_f32_e32 v77, v77
	v_mul_f32_e32 v69, v104, v69
	v_add_f32_e32 v77, 1.0, v77
	v_rcp_f32_e32 v77, v77
	v_cvt_pk_bf16_f32 v76, v69, v69
	s_add_u32 s20, s18, 0x2d600
	s_addc_u32 s21, s19, 0
	global_store_short v98, v76, s[20:21]
	v_mul_f32_e32 v69, v109, v77
	v_mul_f32_e32 v77, 0x3d372713, v110
	v_mul_f32_e32 v77, v110, v77
	v_fma_f32 v77, v110, v77, v110
	v_mul_f32_e32 v77, 0xbfcc422a, v77
	v_mul_f32_e32 v77, 0x3fb8aa3b, v77
	v_exp_f32_e32 v77, v77
	v_mul_f32_e32 v69, v105, v69
	v_add_f32_e32 v77, 1.0, v77
	v_rcp_f32_e32 v77, v77
	v_cvt_pk_bf16_f32 v76, v69, v69
	v_fmac_f32_e32 v83, v93, v155
	v_fmac_f32_e32 v81, v95, v155
	ds_bpermute_b32 v93, v147, v193
	ds_bpermute_b32 v95, v147, v191
	s_add_u32 s20, s18, 0x2ec00
	s_addc_u32 s21, s19, 0
	global_store_short v98, v76, s[20:21]
	v_mul_f32_e32 v69, v110, v77
	v_mul_f32_e32 v69, v106, v69
	v_cvt_pk_bf16_f32 v76, v69, v69
	v_fmac_f32_e32 v65, v78, v151
	s_waitcnt lgkmcnt(1)
	v_fmac_f32_e32 v70, v152, v93
	s_waitcnt lgkmcnt(0)
	v_fmac_f32_e32 v74, v152, v95
	v_fmac_f32_e32 v66, v78, v152
	v_fmac_f32_e32 v65, v79, v152
	s_add_u32 s20, s18, 0x30200
	s_addc_u32 s21, s19, 0
	global_store_short v98, v76, s[20:21]
	v_mul_f32_e32 v69, 0x3d372713, v101
	v_mul_f32_e32 v69, v101, v69
	v_fma_f32 v69, v101, v69, v101
	v_mul_f32_e32 v69, 0xbfcc422a, v69
	v_mul_f32_e32 v69, 0x3fb8aa3b, v69
	v_exp_f32_e32 v69, v69
	s_nop 0
	v_add_f32_e32 v69, 1.0, v69
	v_rcp_f32_e32 v69, v69
	s_nop 0
	v_mul_f32_e32 v69, v101, v69
	v_mul_f32_e32 v67, v67, v69
	v_cvt_pk_bf16_f32 v67, v67, v67
	s_add_u32 s20, s18, 0x37000
	s_addc_u32 s21, s19, 0
	global_store_short v98, v67, s[20:21]
	v_mul_f32_e32 v68, 0x3d372713, v102
	v_mul_f32_e32 v68, v102, v68
	v_fma_f32 v68, v102, v68, v102
	v_mul_f32_e32 v68, 0xbfcc422a, v68
	v_mul_f32_e32 v68, 0x3fb8aa3b, v68
	v_exp_f32_e32 v68, v68
	s_nop 0
	v_add_f32_e32 v68, 1.0, v68
	v_rcp_f32_e32 v68, v68
	s_nop 0
	v_mul_f32_e32 v68, v102, v68
	v_mul_f32_e32 v68, v91, v68
	v_cvt_pk_bf16_f32 v76, v68, v68
	s_add_u32 s20, s18, 0x38600
	s_addc_u32 s21, s19, 0
	global_store_short v98, v76, s[20:21]
	v_mul_f32_e32 v68, 0x3d372713, v111
	v_mul_f32_e32 v68, v111, v68
	v_fma_f32 v68, v111, v68, v111
	v_mul_f32_e32 v68, 0xbfcc422a, v68
	v_mul_f32_e32 v68, 0x3fb8aa3b, v68
	v_exp_f32_e32 v68, v68
	s_nop 0
	v_add_f32_e32 v68, 1.0, v68
	v_rcp_f32_e32 v68, v68
	s_nop 0
	v_mul_f32_e32 v68, v111, v68
	v_mul_f32_e32 v68, v92, v68
	v_cvt_pk_bf16_f32 v76, v68, v68
	s_add_u32 s20, s18, 0x39c00
	s_addc_u32 s21, s19, 0
	global_store_short v98, v76, s[20:21]
	v_mul_f32_e32 v68, 0x3d372713, v86
	v_mul_f32_e32 v68, v86, v68
	v_fma_f32 v68, v86, v68, v86
	v_mul_f32_e32 v68, 0xbfcc422a, v68
	v_mul_f32_e32 v68, 0x3fb8aa3b, v68
	v_exp_f32_e32 v68, v68
	s_nop 0
	v_add_f32_e32 v68, 1.0, v68
	v_rcp_f32_e32 v68, v68
	s_nop 0
	v_mul_f32_e32 v68, v86, v68
	v_mul_f32_e32 v68, v70, v68
	v_cvt_pk_bf16_f32 v70, v68, v68
	s_add_u32 s20, s18, 0x3b200
	s_addc_u32 s21, s19, 0
	global_store_short v98, v70, s[20:21]
	v_mul_f32_e32 v68, 0x3d372713, v87
	v_mul_f32_e32 v68, v87, v68
	v_fma_f32 v68, v87, v68, v87
	v_mul_f32_e32 v68, 0xbfcc422a, v68
	v_mul_f32_e32 v68, 0x3fb8aa3b, v68
	v_exp_f32_e32 v68, v68
	s_nop 0
	v_add_f32_e32 v68, 1.0, v68
	v_rcp_f32_e32 v68, v68
	s_nop 0
	v_mul_f32_e32 v68, v87, v68
	v_mul_f32_e32 v68, v71, v68
	v_cvt_pk_bf16_f32 v70, v68, v68
	s_add_u32 s20, s18, 0x42000
	s_addc_u32 s21, s19, 0
	global_store_short v98, v70, s[20:21]
	v_mul_f32_e32 v68, 0x3d372713, v88
	v_mul_f32_e32 v68, v88, v68
	v_fma_f32 v68, v88, v68, v88
	v_mul_f32_e32 v68, 0xbfcc422a, v68
	v_mul_f32_e32 v68, 0x3fb8aa3b, v68
	v_exp_f32_e32 v68, v68
	s_nop 0
	v_add_f32_e32 v68, 1.0, v68
	v_rcp_f32_e32 v68, v68
	s_nop 0
	v_mul_f32_e32 v68, v88, v68
	v_mul_f32_e32 v68, v72, v68
	v_cvt_pk_bf16_f32 v70, v68, v68
	s_add_u32 s20, s18, 0x43600
	s_addc_u32 s21, s19, 0
	global_store_short v98, v70, s[20:21]
	v_mul_f32_e32 v68, 0x3d372713, v85
	v_mul_f32_e32 v68, v85, v68
	v_fma_f32 v68, v85, v68, v85
	v_mul_f32_e32 v68, 0xbfcc422a, v68
	v_mul_f32_e32 v68, 0x3fb8aa3b, v68
	v_exp_f32_e32 v68, v68
	s_nop 0
	v_add_f32_e32 v68, 1.0, v68
	v_rcp_f32_e32 v68, v68
	s_nop 0
	v_mul_f32_e32 v68, v85, v68
	v_mul_f32_e32 v68, v73, v68
	v_cvt_pk_bf16_f32 v70, v68, v68
	s_add_u32 s20, s18, 0x44c00
	s_addc_u32 s21, s19, 0
	global_store_short v98, v70, s[20:21]
	v_mul_f32_e32 v68, 0x3d372713, v84
	v_mul_f32_e32 v68, v84, v68
	v_fma_f32 v68, v84, v68, v84
	v_mul_f32_e32 v68, 0xbfcc422a, v68
	v_mul_f32_e32 v68, 0x3fb8aa3b, v68
	v_exp_f32_e32 v68, v68
	s_nop 0
	v_add_f32_e32 v68, 1.0, v68
	v_rcp_f32_e32 v68, v68
	s_nop 0
	v_mul_f32_e32 v68, v84, v68
	v_mul_f32_e32 v68, v74, v68
	v_cvt_pk_bf16_f32 v70, v68, v68
	s_add_u32 s20, s18, 0x46200
	s_addc_u32 s21, s19, 0
	global_store_short v98, v70, s[20:21]
	v_mul_f32_e32 v68, 0x3d372713, v83
	v_mul_f32_e32 v68, v83, v68
	v_fma_f32 v68, v83, v68, v83
	v_mul_f32_e32 v68, 0xbfcc422a, v68
	v_mul_f32_e32 v68, 0x3fb8aa3b, v68
	v_exp_f32_e32 v68, v68
	s_nop 0
	v_add_f32_e32 v68, 1.0, v68
	v_rcp_f32_e32 v68, v68
	s_nop 0
	v_mul_f32_e32 v68, v83, v68
	v_mul_f32_e32 v68, v75, v68
	v_cvt_pk_bf16_f32 v70, v68, v68
	s_add_u32 s20, s18, 0x4d000
	s_addc_u32 s21, s19, 0
	global_store_short v98, v70, s[20:21]
	v_mul_f32_e32 v68, 0x3d372713, v82
	v_mul_f32_e32 v68, v82, v68
	v_fma_f32 v68, v82, v68, v82
	v_mul_f32_e32 v68, 0xbfcc422a, v68
	v_mul_f32_e32 v68, 0x3fb8aa3b, v68
	v_exp_f32_e32 v68, v68
	s_nop 0
	v_add_f32_e32 v68, 1.0, v68
	v_rcp_f32_e32 v68, v68
	s_nop 0
	v_mul_f32_e32 v68, v82, v68
	v_mul_f32_e32 v66, v66, v68
	v_cvt_pk_bf16_f32 v68, v66, v66
	s_add_u32 s20, s18, 0x4e600
	s_addc_u32 s21, s19, 0
	global_store_short v98, v68, s[20:21]
	v_mul_f32_e32 v67, 0x3d372713, v81
	v_mul_f32_e32 v67, v81, v67
	v_fma_f32 v67, v81, v67, v81
	v_mul_f32_e32 v67, 0xbfcc422a, v67
	v_mul_f32_e32 v67, 0x3fb8aa3b, v67
	v_exp_f32_e32 v67, v67
	s_nop 0
	v_add_f32_e32 v67, 1.0, v67
	v_rcp_f32_e32 v67, v67
	s_nop 0
	v_mul_f32_e32 v67, v81, v67
	v_mul_f32_e32 v65, v65, v67
	v_cvt_pk_bf16_f32 v65, v65, v65
	s_add_u32 s20, s18, 0x4fc00
	s_addc_u32 s21, s19, 0
	global_store_short v98, v65, s[20:21]
	v_mul_f32_e32 v66, 0x3d372713, v80
	v_mul_f32_e32 v66, v80, v66
	v_fma_f32 v66, v80, v66, v80
	v_mul_f32_e32 v66, 0xbfcc422a, v66
	v_mul_f32_e32 v66, 0x3fb8aa3b, v66
	v_exp_f32_e32 v66, v66
	s_nop 0
	v_add_f32_e32 v66, 1.0, v66
	v_rcp_f32_e32 v66, v66
	s_nop 0
	v_mul_f32_e32 v66, v80, v66
	v_mul_f32_e32 v64, v64, v66
	v_cvt_pk_bf16_f32 v66, v64, v64
	s_add_u32 s20, s18, 0x51200
	s_addc_u32 s21, s19, 0
	global_store_short v98, v66, s[20:21]
	ds_bpermute_b32 v66, v147, v184
	ds_bpermute_b32 v67, v147, v182
	ds_bpermute_b32 v65, v147, v185
	ds_bpermute_b32 v69, v147, v180
	v_fma_f32 v74, v50, v153, v148
	ds_bpermute_b32 v71, v147, v178
	v_fmac_f32_e32 v74, v51, v154
	s_waitcnt lgkmcnt(4)
	v_fmac_f32_e32 v74, v155, v66
	s_waitcnt lgkmcnt(3)
	v_fma_f32 v66, v153, v67, v148
	v_fma_f32 v67, v52, v153, v148
	v_fmac_f32_e32 v66, v52, v154
	v_fmac_f32_e32 v67, v53, v154
	v_fma_f32 v75, v53, v153, v148
	v_cndmask_b32_e64 v64, 0, v188, s[2:3]
	v_fma_f32 v73, v49, v153, v148
	v_fmac_f32_e32 v66, v53, v155
	v_fmac_f32_e32 v67, v54, v155
	v_fmac_f32_e32 v75, v54, v154
	v_fma_f32 v54, v54, v153, v148
	v_fma_f32 v53, v57, v153, v148
	ds_bpermute_b32 v70, v147, v179
	s_waitcnt lgkmcnt(3)
	v_cndmask_b32_e32 v64, v65, v64, vcc
	v_fma_f32 v65, v48, v153, v148
	v_fmac_f32_e32 v73, v50, v154
	v_fmac_f32_e32 v75, v55, v155
	v_fmac_f32_e32 v54, v55, v154
	s_waitcnt lgkmcnt(2)
	v_fma_f32 v55, v153, v69, v148
	v_fmac_f32_e32 v53, v58, v154
	v_fma_f32 v52, v58, v153, v148
	ds_bpermute_b32 v72, v147, v177
	v_fma_f32 v64, v153, v64, v148
	v_fmac_f32_e32 v65, v49, v154
	v_fmac_f32_e32 v73, v51, v155
	v_fmac_f32_e32 v55, v56, v154
	v_fma_f32 v56, v56, v153, v148
	v_fmac_f32_e32 v53, v59, v155
	v_fmac_f32_e32 v52, v59, v154
	s_waitcnt lgkmcnt(2)
	v_fma_f32 v51, v153, v71, v148
	ds_bpermute_b32 v59, v147, v175
	v_fmac_f32_e32 v64, v48, v154
	v_fmac_f32_e32 v65, v50, v155
	v_fmac_f32_e32 v56, v57, v154
	v_fmac_f32_e32 v51, v60, v154
	v_fma_f32 v50, v60, v153, v148
	ds_bpermute_b32 v60, v147, v174
	ds_bpermute_b32 v68, v147, v181
	v_fmac_f32_e32 v64, v49, v155
	v_fmac_f32_e32 v56, v58, v155
	v_fmac_f32_e32 v50, v61, v154
	v_fma_f32 v49, v61, v153, v148
	ds_bpermute_b32 v58, v147, v176
	v_fmac_f32_e32 v50, v62, v155
	v_fmac_f32_e32 v49, v62, v154
	v_fma_f32 v48, v62, v153, v148
	ds_bpermute_b32 v62, v147, v172
	v_fma_f32 v71, v34, v150, v149
	s_waitcnt lgkmcnt(6)
	v_fmac_f32_e32 v52, v155, v70
	v_fma_f32 v70, v33, v150, v149
	v_fmac_f32_e32 v71, v35, v151
	v_fmac_f32_e32 v55, v57, v155
	s_waitcnt lgkmcnt(5)
	v_cndmask_b32_e32 v57, v187, v72, vcc
	v_fmac_f32_e32 v48, v63, v154
	v_fmac_f32_e32 v70, v34, v151
	s_waitcnt lgkmcnt(4)
	v_fmac_f32_e32 v71, v152, v59
	v_fma_f32 v59, v36, v150, v149
	v_fmac_f32_e32 v48, v155, v57
	v_cndmask_b32_e64 v57, 0, v186, s[2:3]
	v_fmac_f32_e32 v70, v35, v152
	s_waitcnt lgkmcnt(3)
	v_fma_f32 v35, v150, v60, v149
	v_fmac_f32_e32 v59, v37, v151
	v_fma_f32 v60, v37, v150, v149
	s_waitcnt lgkmcnt(2)
	v_fmac_f32_e32 v54, v155, v68
	ds_bpermute_b32 v68, v147, v170
	s_waitcnt lgkmcnt(2)
	v_cndmask_b32_e32 v57, v58, v57, vcc
	v_fmac_f32_e32 v59, v38, v152
	v_fmac_f32_e32 v60, v38, v151
	v_fma_f32 v38, v38, v150, v149
	v_fma_f32 v57, v150, v57, v149
	v_fmac_f32_e32 v60, v39, v152
	v_fmac_f32_e32 v38, v39, v151
	s_waitcnt lgkmcnt(1)
	v_fma_f32 v39, v150, v62, v149
	v_fmac_f32_e32 v57, v32, v151
	v_fma_f32 v58, v32, v150, v149
	v_fmac_f32_e32 v39, v40, v151
	v_fma_f32 v40, v40, v150, v149
	v_mul_f32_e32 v32, 0x3d372713, v64
	v_fmac_f32_e32 v39, v41, v152
	v_fmac_f32_e32 v40, v41, v151
	v_fma_f32 v41, v41, v150, v149
	v_mul_f32_e32 v32, v64, v32
	v_fmac_f32_e32 v40, v42, v152
	v_fmac_f32_e32 v41, v42, v151
	v_fma_f32 v42, v42, v150, v149
	v_fma_f32 v32, v64, v32, v64
	v_fmac_f32_e32 v58, v33, v151
	v_fmac_f32_e32 v41, v43, v152
	v_fmac_f32_e32 v42, v43, v151
	s_waitcnt lgkmcnt(0)
	v_fma_f32 v43, v150, v68, v149
	v_mul_f32_e32 v32, 0xbfcc422a, v32
	v_fmac_f32_e32 v58, v34, v152
	v_fmac_f32_e32 v43, v44, v151
	v_fma_f32 v34, v44, v150, v149
	v_mul_f32_e32 v32, 0x3fb8aa3b, v32
	v_fmac_f32_e32 v57, v33, v152
	v_fmac_f32_e32 v35, v36, v151
	v_fmac_f32_e32 v43, v45, v152
	v_fmac_f32_e32 v34, v45, v151
	v_fma_f32 v33, v45, v150, v149
	v_exp_f32_e32 v36, v32
	v_mul_f32_e32 v45, 0x3d372713, v65
	v_mul_f32_e32 v45, v65, v45
	v_fma_f32 v45, v65, v45, v65
	v_mul_f32_e32 v45, 0xbfcc422a, v45
	v_add_f32_e32 v36, 1.0, v36
	v_mul_f32_e32 v45, 0x3fb8aa3b, v45
	ds_bpermute_b32 v69, v147, v169
	v_rcp_f32_e32 v36, v36
	v_exp_f32_e32 v45, v45
	v_fma_f32 v32, v46, v150, v149
	v_fmac_f32_e32 v35, v37, v152
	v_mul_f32_e32 v36, v64, v36
	v_add_f32_e32 v45, 1.0, v45
	s_waitcnt lgkmcnt(0)
	v_cndmask_b32_e32 v37, v183, v69, vcc
	v_fmac_f32_e32 v32, v47, v151
	v_mul_f32_e32 v36, v57, v36
	v_rcp_f32_e32 v45, v45
	v_fmac_f32_e32 v32, v152, v37
	v_cvt_pk_bf16_f32 v44, v36, v36
	s_add_u32 s20, s18, 0x58000
	s_addc_u32 s21, s19, 0
	global_store_short v98, v44, s[20:21]
	v_mul_f32_e32 v37, v65, v45
	v_mul_f32_e32 v45, 0x3d372713, v73
	v_mul_f32_e32 v45, v73, v45
	v_fma_f32 v45, v73, v45, v73
	v_mul_f32_e32 v45, 0xbfcc422a, v45
	v_mul_f32_e32 v45, 0x3fb8aa3b, v45
	v_exp_f32_e32 v45, v45
	v_mul_f32_e32 v37, v58, v37
	v_add_f32_e32 v45, 1.0, v45
	v_rcp_f32_e32 v45, v45
	v_cvt_pk_bf16_f32 v44, v37, v37
	s_add_u32 s20, s18, 0x59600
	s_addc_u32 s21, s19, 0
	global_store_short v98, v44, s[20:21]
	v_mul_f32_e32 v37, v73, v45
	v_mul_f32_e32 v45, 0x3d372713, v74
	v_mul_f32_e32 v45, v74, v45
	v_fma_f32 v45, v74, v45, v74
	v_mul_f32_e32 v45, 0xbfcc422a, v45
	v_mul_f32_e32 v45, 0x3fb8aa3b, v45
	v_exp_f32_e32 v45, v45
	v_mul_f32_e32 v37, v70, v37
	v_add_f32_e32 v45, 1.0, v45
	v_rcp_f32_e32 v45, v45
	v_cvt_pk_bf16_f32 v44, v37, v37
	v_fmac_f32_e32 v51, v61, v155
	v_fmac_f32_e32 v49, v63, v155
	ds_bpermute_b32 v61, v147, v173
	ds_bpermute_b32 v63, v147, v171
	s_add_u32 s20, s18, 0x5ac00
	s_addc_u32 s21, s19, 0
	global_store_short v98, v44, s[20:21]
	v_mul_f32_e32 v37, v74, v45
	v_mul_f32_e32 v37, v71, v37
	v_cvt_pk_bf16_f32 v44, v37, v37
	v_fmac_f32_e32 v33, v46, v151
	s_waitcnt lgkmcnt(1)
	v_fmac_f32_e32 v38, v152, v61
	s_waitcnt lgkmcnt(0)
	v_fmac_f32_e32 v42, v152, v63
	v_fmac_f32_e32 v34, v46, v152
	v_fmac_f32_e32 v33, v47, v152
	s_add_u32 s20, s18, 0x5c200
	s_addc_u32 s21, s19, 0
	global_store_short v98, v44, s[20:21]
	v_mul_f32_e32 v37, 0x3d372713, v66
	v_mul_f32_e32 v37, v66, v37
	v_fma_f32 v37, v66, v37, v66
	v_mul_f32_e32 v37, 0xbfcc422a, v37
	v_mul_f32_e32 v37, 0x3fb8aa3b, v37
	v_exp_f32_e32 v37, v37
	s_nop 0
	v_add_f32_e32 v37, 1.0, v37
	v_rcp_f32_e32 v37, v37
	s_nop 0
	v_mul_f32_e32 v37, v66, v37
	v_mul_f32_e32 v35, v35, v37
	v_cvt_pk_bf16_f32 v35, v35, v35
	s_add_u32 s20, s18, 0x63000
	s_addc_u32 s21, s19, 0
	global_store_short v98, v35, s[20:21]
	v_mul_f32_e32 v36, 0x3d372713, v67
	v_mul_f32_e32 v36, v67, v36
	v_fma_f32 v36, v67, v36, v67
	v_mul_f32_e32 v36, 0xbfcc422a, v36
	v_mul_f32_e32 v36, 0x3fb8aa3b, v36
	v_exp_f32_e32 v36, v36
	s_nop 0
	v_add_f32_e32 v36, 1.0, v36
	v_rcp_f32_e32 v36, v36
	s_nop 0
	v_mul_f32_e32 v36, v67, v36
	v_mul_f32_e32 v36, v59, v36
	v_cvt_pk_bf16_f32 v44, v36, v36
	s_add_u32 s20, s18, 0x64600
	s_addc_u32 s21, s19, 0
	global_store_short v98, v44, s[20:21]
	v_mul_f32_e32 v36, 0x3d372713, v75
	v_mul_f32_e32 v36, v75, v36
	v_fma_f32 v36, v75, v36, v75
	v_mul_f32_e32 v36, 0xbfcc422a, v36
	v_mul_f32_e32 v36, 0x3fb8aa3b, v36
	v_exp_f32_e32 v36, v36
	s_nop 0
	v_add_f32_e32 v36, 1.0, v36
	v_rcp_f32_e32 v36, v36
	s_nop 0
	v_mul_f32_e32 v36, v75, v36
	v_mul_f32_e32 v36, v60, v36
	v_cvt_pk_bf16_f32 v44, v36, v36
	s_add_u32 s20, s18, 0x65c00
	s_addc_u32 s21, s19, 0
	global_store_short v98, v44, s[20:21]
	v_mul_f32_e32 v36, 0x3d372713, v54
	v_mul_f32_e32 v36, v54, v36
	v_fma_f32 v36, v54, v36, v54
	v_mul_f32_e32 v36, 0xbfcc422a, v36
	v_mul_f32_e32 v36, 0x3fb8aa3b, v36
	v_exp_f32_e32 v36, v36
	s_nop 0
	v_add_f32_e32 v36, 1.0, v36
	v_rcp_f32_e32 v36, v36
	s_nop 0
	v_mul_f32_e32 v36, v54, v36
	v_mul_f32_e32 v36, v38, v36
	v_cvt_pk_bf16_f32 v38, v36, v36
	s_add_u32 s20, s18, 0x67200
	s_addc_u32 s21, s19, 0
	global_store_short v98, v38, s[20:21]
	v_mul_f32_e32 v36, 0x3d372713, v55
	v_mul_f32_e32 v36, v55, v36
	v_fma_f32 v36, v55, v36, v55
	v_mul_f32_e32 v36, 0xbfcc422a, v36
	v_mul_f32_e32 v36, 0x3fb8aa3b, v36
	v_exp_f32_e32 v36, v36
	s_nop 0
	v_add_f32_e32 v36, 1.0, v36
	v_rcp_f32_e32 v36, v36
	s_nop 0
	v_mul_f32_e32 v36, v55, v36
	v_mul_f32_e32 v36, v39, v36
	v_cvt_pk_bf16_f32 v38, v36, v36
	s_add_u32 s20, s18, 0x6e000
	s_addc_u32 s21, s19, 0
	global_store_short v98, v38, s[20:21]
	v_mul_f32_e32 v36, 0x3d372713, v56
	v_mul_f32_e32 v36, v56, v36
	v_fma_f32 v36, v56, v36, v56
	v_mul_f32_e32 v36, 0xbfcc422a, v36
	v_mul_f32_e32 v36, 0x3fb8aa3b, v36
	v_exp_f32_e32 v36, v36
	s_nop 0
	v_add_f32_e32 v36, 1.0, v36
	v_rcp_f32_e32 v36, v36
	s_nop 0
	v_mul_f32_e32 v36, v56, v36
	v_mul_f32_e32 v36, v40, v36
	v_cvt_pk_bf16_f32 v38, v36, v36
	s_add_u32 s20, s18, 0x6f600
	s_addc_u32 s21, s19, 0
	global_store_short v98, v38, s[20:21]
	v_mul_f32_e32 v36, 0x3d372713, v53
	v_mul_f32_e32 v36, v53, v36
	v_fma_f32 v36, v53, v36, v53
	v_mul_f32_e32 v36, 0xbfcc422a, v36
	v_mul_f32_e32 v36, 0x3fb8aa3b, v36
	v_exp_f32_e32 v36, v36
	s_nop 0
	v_add_f32_e32 v36, 1.0, v36
	v_rcp_f32_e32 v36, v36
	s_nop 0
	v_mul_f32_e32 v36, v53, v36
	v_mul_f32_e32 v36, v41, v36
	v_cvt_pk_bf16_f32 v38, v36, v36
	s_add_u32 s20, s18, 0x70c00
	s_addc_u32 s21, s19, 0
	global_store_short v98, v38, s[20:21]
	v_mul_f32_e32 v36, 0x3d372713, v52
	v_mul_f32_e32 v36, v52, v36
	v_fma_f32 v36, v52, v36, v52
	v_mul_f32_e32 v36, 0xbfcc422a, v36
	v_mul_f32_e32 v36, 0x3fb8aa3b, v36
	v_exp_f32_e32 v36, v36
	s_nop 0
	v_add_f32_e32 v36, 1.0, v36
	v_rcp_f32_e32 v36, v36
	s_nop 0
	v_mul_f32_e32 v36, v52, v36
	v_mul_f32_e32 v36, v42, v36
	v_cvt_pk_bf16_f32 v38, v36, v36
	s_add_u32 s20, s18, 0x72200
	s_addc_u32 s21, s19, 0
	global_store_short v98, v38, s[20:21]
	v_mul_f32_e32 v36, 0x3d372713, v51
	v_mul_f32_e32 v36, v51, v36
	v_fma_f32 v36, v51, v36, v51
	v_mul_f32_e32 v36, 0xbfcc422a, v36
	v_mul_f32_e32 v36, 0x3fb8aa3b, v36
	v_exp_f32_e32 v36, v36
	s_nop 0
	v_add_f32_e32 v36, 1.0, v36
	v_rcp_f32_e32 v36, v36
	s_nop 0
	v_mul_f32_e32 v36, v51, v36
	v_mul_f32_e32 v36, v43, v36
	v_cvt_pk_bf16_f32 v38, v36, v36
	s_add_u32 s20, s18, 0x79000
	s_addc_u32 s21, s19, 0
	global_store_short v98, v38, s[20:21]
	v_mul_f32_e32 v36, 0x3d372713, v50
	v_mul_f32_e32 v36, v50, v36
	v_fma_f32 v36, v50, v36, v50
	v_mul_f32_e32 v36, 0xbfcc422a, v36
	v_mul_f32_e32 v36, 0x3fb8aa3b, v36
	v_exp_f32_e32 v36, v36
	s_nop 0
	v_add_f32_e32 v36, 1.0, v36
	v_rcp_f32_e32 v36, v36
	s_nop 0
	v_mul_f32_e32 v36, v50, v36
	v_mul_f32_e32 v34, v34, v36
	v_cvt_pk_bf16_f32 v36, v34, v34
	s_add_u32 s20, s18, 0x7a600
	s_addc_u32 s21, s19, 0
	global_store_short v98, v36, s[20:21]
	v_mul_f32_e32 v35, 0x3d372713, v49
	v_mul_f32_e32 v35, v49, v35
	v_fma_f32 v35, v49, v35, v49
	v_mul_f32_e32 v35, 0xbfcc422a, v35
	v_mul_f32_e32 v35, 0x3fb8aa3b, v35
	v_exp_f32_e32 v35, v35
	s_nop 0
	v_add_f32_e32 v35, 1.0, v35
	v_rcp_f32_e32 v35, v35
	s_nop 0
	v_mul_f32_e32 v35, v49, v35
	v_mul_f32_e32 v33, v33, v35
	v_cvt_pk_bf16_f32 v33, v33, v33
	s_add_u32 s20, s18, 0x7bc00
	s_addc_u32 s21, s19, 0
	global_store_short v98, v33, s[20:21]
	v_mul_f32_e32 v34, 0x3d372713, v48
	v_mul_f32_e32 v34, v48, v34
	v_fma_f32 v34, v48, v34, v48
	v_mul_f32_e32 v34, 0xbfcc422a, v34
	v_mul_f32_e32 v34, 0x3fb8aa3b, v34
	v_exp_f32_e32 v34, v34
	s_nop 0
	v_add_f32_e32 v34, 1.0, v34
	v_rcp_f32_e32 v34, v34
	s_nop 0
	v_mul_f32_e32 v34, v48, v34
	v_mul_f32_e32 v32, v32, v34
	v_cvt_pk_bf16_f32 v34, v32, v32
	s_add_u32 s20, s18, 0x7d200
	s_addc_u32 s21, s19, 0
	global_store_short v98, v34, s[20:21]
	ds_bpermute_b32 v33, v147, v164
	ds_bpermute_b32 v34, v147, v163
	v_fma_f32 v42, v18, v153, v148
	ds_bpermute_b32 v36, v147, v161
	v_fmac_f32_e32 v42, v19, v154
	s_waitcnt lgkmcnt(2)
	v_fmac_f32_e32 v42, v155, v33
	s_waitcnt lgkmcnt(1)
	v_fma_f32 v33, v153, v34, v148
	v_fmac_f32_e32 v33, v20, v154
	v_fma_f32 v34, v20, v153, v148
	ds_bpermute_b32 v32, v147, v165
	v_fmac_f32_e32 v33, v21, v155
	v_fmac_f32_e32 v34, v21, v154
	v_fma_f32 v21, v21, v153, v148
	v_fmac_f32_e32 v34, v22, v155
	v_fmac_f32_e32 v21, v22, v154
	v_fma_f32 v22, v22, v153, v148
	ds_bpermute_b32 v38, v147, v159
	v_fma_f32 v41, v17, v153, v148
	v_fmac_f32_e32 v21, v23, v155
	v_fmac_f32_e32 v22, v23, v154
	s_waitcnt lgkmcnt(2)
	v_fma_f32 v23, v153, v36, v148
	v_fmac_f32_e32 v41, v18, v154
	v_fmac_f32_e32 v23, v24, v154
	v_fma_f32 v24, v24, v153, v148
	v_fma_f32 v20, v25, v153, v148
	v_fmac_f32_e32 v41, v19, v155
	v_fmac_f32_e32 v24, v25, v154
	v_fmac_f32_e32 v20, v26, v154
	v_fma_f32 v19, v26, v153, v148
	ds_bpermute_b32 v39, v147, v158
	s_waitcnt lgkmcnt(2)
	v_cndmask_b32_e32 v32, v32, v168, vcc
	v_fma_f32 v40, v16, v153, v148
	v_fmac_f32_e32 v24, v26, v155
	v_fmac_f32_e32 v20, v27, v155
	v_fmac_f32_e32 v19, v27, v154
	ds_bpermute_b32 v26, v147, v156
	ds_bpermute_b32 v27, v147, v145
	v_fma_f32 v32, v153, v32, v148
	v_fmac_f32_e32 v40, v17, v154
	v_fmac_f32_e32 v32, v16, v154
	v_fmac_f32_e32 v40, v18, v155
	s_waitcnt lgkmcnt(3)
	v_fma_f32 v18, v153, v38, v148
	v_fmac_f32_e32 v32, v17, v155
	v_fmac_f32_e32 v18, v28, v154
	v_fma_f32 v17, v28, v153, v148
	v_fma_f32 v38, v2, v150, v149
	ds_bpermute_b32 v37, v147, v160
	v_fmac_f32_e32 v18, v29, v155
	v_fmac_f32_e32 v17, v29, v154
	v_fma_f32 v16, v29, v153, v148
	v_fmac_f32_e32 v148, v30, v153
	ds_bpermute_b32 v29, v147, v141
	v_fmac_f32_e32 v38, v3, v151
	v_fmac_f32_e32 v23, v25, v155
	s_waitcnt lgkmcnt(4)
	v_cndmask_b32_e32 v25, v166, v39, vcc
	v_fmac_f32_e32 v148, v154, v31
	s_waitcnt lgkmcnt(3)
	v_fmac_f32_e32 v38, v152, v26
	s_waitcnt lgkmcnt(2)
	v_fma_f32 v26, v150, v27, v149
	v_fmac_f32_e32 v148, v155, v25
	ds_bpermute_b32 v25, v147, v157
	v_fmac_f32_e32 v26, v4, v151
	v_fma_f32 v4, v4, v150, v149
	v_fmac_f32_e32 v16, v30, v154
	v_fmac_f32_e32 v26, v5, v152
	v_fmac_f32_e32 v4, v5, v151
	v_fma_f32 v5, v5, v150, v149
	v_fmac_f32_e32 v16, v155, v31
	ds_bpermute_b32 v31, v147, v135
	v_fma_f32 v36, v0, v150, v149
	v_fmac_f32_e32 v4, v6, v152
	v_fmac_f32_e32 v5, v6, v151
	v_fma_f32 v6, v6, v150, v149
	s_waitcnt lgkmcnt(3)
	v_fmac_f32_e32 v19, v155, v37
	v_fmac_f32_e32 v36, v1, v151
	v_fma_f32 v37, v1, v150, v149
	v_fmac_f32_e32 v5, v7, v152
	v_fmac_f32_e32 v6, v7, v151
	s_waitcnt lgkmcnt(2)
	v_fma_f32 v7, v150, v29, v149
	v_fmac_f32_e32 v36, v2, v152
	v_fmac_f32_e32 v37, v2, v151
	v_fmac_f32_e32 v7, v8, v151
	v_fma_f32 v8, v8, v150, v149
	v_mul_f32_e32 v2, 0x3d372713, v32
	s_waitcnt lgkmcnt(1)
	v_cndmask_b32_e32 v25, v25, v167, vcc
	v_fmac_f32_e32 v7, v9, v152
	v_fmac_f32_e32 v8, v9, v151
	v_fma_f32 v9, v9, v150, v149
	v_mul_f32_e32 v2, v32, v2
	v_fma_f32 v25, v150, v25, v149
	v_fmac_f32_e32 v8, v10, v152
	v_fmac_f32_e32 v9, v10, v151
	v_fma_f32 v10, v10, v150, v149
	v_fma_f32 v2, v32, v2, v32
	v_fmac_f32_e32 v25, v0, v151
	v_fmac_f32_e32 v9, v11, v152
	v_fmac_f32_e32 v10, v11, v151
	s_waitcnt lgkmcnt(0)
	v_fma_f32 v11, v150, v31, v149
	v_mul_f32_e32 v2, 0xbfcc422a, v2
	v_fmac_f32_e32 v25, v1, v152
	v_fmac_f32_e32 v11, v12, v151
	v_fma_f32 v1, v12, v150, v149
	v_mul_f32_e32 v2, 0x3fb8aa3b, v2
	ds_bpermute_b32 v35, v147, v162
	v_fmac_f32_e32 v11, v13, v152
	v_fmac_f32_e32 v1, v13, v151
	v_fma_f32 v0, v13, v150, v149
	v_exp_f32_e32 v2, v2
	v_mul_f32_e32 v13, 0x3d372713, v40
	v_mul_f32_e32 v13, v40, v13
	v_fma_f32 v13, v40, v13, v40
	v_mul_f32_e32 v13, 0xbfcc422a, v13
	v_add_f32_e32 v2, 1.0, v2
	v_mul_f32_e32 v13, 0x3fb8aa3b, v13
	s_waitcnt lgkmcnt(0)
	v_fmac_f32_e32 v22, v155, v35
	ds_bpermute_b32 v35, v147, v133
	v_rcp_f32_e32 v2, v2
	v_exp_f32_e32 v13, v13
	v_fmac_f32_e32 v149, v14, v150
	v_fmac_f32_e32 v37, v3, v152
	v_mul_f32_e32 v2, v32, v2
	v_add_f32_e32 v13, 1.0, v13
	s_waitcnt lgkmcnt(0)
	v_cndmask_b32_e32 v3, v139, v35, vcc
	v_fmac_f32_e32 v149, v15, v151
	v_mul_f32_e32 v2, v25, v2
	v_rcp_f32_e32 v13, v13
	v_fmac_f32_e32 v149, v152, v3
	v_cvt_pk_bf16_f32 v12, v2, v2
	s_add_u32 s20, s18, 0x84000
	s_addc_u32 s21, s19, 0
	global_store_short v98, v12, s[20:21]
	v_mul_f32_e32 v3, v40, v13
	v_mul_f32_e32 v13, 0x3d372713, v41
	v_mul_f32_e32 v13, v41, v13
	v_fma_f32 v13, v41, v13, v41
	v_mul_f32_e32 v13, 0xbfcc422a, v13
	v_mul_f32_e32 v13, 0x3fb8aa3b, v13
	v_exp_f32_e32 v13, v13
	v_mul_f32_e32 v3, v36, v3
	v_add_f32_e32 v13, 1.0, v13
	v_rcp_f32_e32 v13, v13
	v_cvt_pk_bf16_f32 v12, v3, v3
	s_add_u32 s20, s18, 0x85600
	s_addc_u32 s21, s19, 0
	global_store_short v98, v12, s[20:21]
	v_mul_f32_e32 v3, v41, v13
	v_mul_f32_e32 v13, 0x3d372713, v42
	v_mul_f32_e32 v13, v42, v13
	v_fma_f32 v13, v42, v13, v42
	v_mul_f32_e32 v13, 0xbfcc422a, v13
	v_mul_f32_e32 v13, 0x3fb8aa3b, v13
	v_exp_f32_e32 v13, v13
	v_mul_f32_e32 v3, v37, v3
	v_add_f32_e32 v13, 1.0, v13
	v_rcp_f32_e32 v13, v13
	v_cvt_pk_bf16_f32 v12, v3, v3
	v_fmac_f32_e32 v17, v30, v155
	ds_bpermute_b32 v28, v147, v143
	ds_bpermute_b32 v30, v147, v137
	s_add_u32 s20, s18, 0x86c00
	s_addc_u32 s21, s19, 0
	global_store_short v98, v12, s[20:21]
	v_mul_f32_e32 v3, v42, v13
	v_mul_f32_e32 v3, v38, v3
	v_cvt_pk_bf16_f32 v12, v3, v3
	v_fmac_f32_e32 v0, v14, v151
	s_waitcnt lgkmcnt(1)
	v_fmac_f32_e32 v6, v152, v28
	s_waitcnt lgkmcnt(0)
	v_fmac_f32_e32 v10, v152, v30
	v_fmac_f32_e32 v1, v14, v152
	v_fmac_f32_e32 v0, v15, v152
	s_add_u32 s20, s18, 0x88200
	s_addc_u32 s21, s19, 0
	global_store_short v98, v12, s[20:21]
	v_mul_f32_e32 v3, 0x3d372713, v33
	v_mul_f32_e32 v3, v33, v3
	v_fma_f32 v3, v33, v3, v33
	v_mul_f32_e32 v3, 0xbfcc422a, v3
	v_mul_f32_e32 v3, 0x3fb8aa3b, v3
	v_exp_f32_e32 v3, v3
	s_nop 0
	v_add_f32_e32 v3, 1.0, v3
	v_rcp_f32_e32 v3, v3
	s_nop 0
	v_mul_f32_e32 v3, v33, v3
	v_mul_f32_e32 v3, v26, v3
	v_bfe_u32 v12, v3, 16, 1
	v_add3_u32 v12, v3, v12, s89
	s_add_u32 s20, s18, 0x8f000
	s_addc_u32 s21, s19, 0
	global_store_short_d16_hi v98, v12, s[20:21]
	v_mul_f32_e32 v3, 0x3d372713, v34
	v_mul_f32_e32 v3, v34, v3
	v_fma_f32 v3, v34, v3, v34
	v_mul_f32_e32 v3, 0xbfcc422a, v3
	v_mul_f32_e32 v3, 0x3fb8aa3b, v3
	v_exp_f32_e32 v3, v3
	s_nop 0
	v_add_f32_e32 v3, 1.0, v3
	v_rcp_f32_e32 v3, v3
	s_nop 0
	v_mul_f32_e32 v3, v34, v3
	v_mul_f32_e32 v3, v4, v3
	v_cvt_pk_bf16_f32 v4, v3, v3
	s_add_u32 s20, s18, 0x90600
	s_addc_u32 s21, s19, 0
	global_store_short v98, v4, s[20:21]
	v_mul_f32_e32 v3, 0x3d372713, v21
	v_mul_f32_e32 v3, v21, v3
	v_fma_f32 v3, v21, v3, v21
	v_mul_f32_e32 v3, 0xbfcc422a, v3
	v_mul_f32_e32 v3, 0x3fb8aa3b, v3
	v_exp_f32_e32 v3, v3
	s_nop 0
	v_add_f32_e32 v3, 1.0, v3
	v_rcp_f32_e32 v3, v3
	s_nop 0
	v_mul_f32_e32 v3, v21, v3
	v_mul_f32_e32 v3, v5, v3
	v_cvt_pk_bf16_f32 v4, v3, v3
	s_add_u32 s20, s18, 0x91c00
	s_addc_u32 s21, s19, 0
	global_store_short v98, v4, s[20:21]
	v_mul_f32_e32 v3, 0x3d372713, v22
	v_mul_f32_e32 v3, v22, v3
	v_fma_f32 v3, v22, v3, v22
	v_mul_f32_e32 v3, 0xbfcc422a, v3
	v_mul_f32_e32 v3, 0x3fb8aa3b, v3
	v_exp_f32_e32 v3, v3
	s_nop 0
	v_add_f32_e32 v3, 1.0, v3
	v_rcp_f32_e32 v3, v3
	s_nop 0
	v_mul_f32_e32 v3, v22, v3
	v_mul_f32_e32 v3, v6, v3
	v_cvt_pk_bf16_f32 v4, v3, v3
	s_add_u32 s20, s18, 0x93200
	s_addc_u32 s21, s19, 0
	global_store_short v98, v4, s[20:21]
	v_mul_f32_e32 v3, 0x3d372713, v23
	v_mul_f32_e32 v3, v23, v3
	v_fma_f32 v3, v23, v3, v23
	v_mul_f32_e32 v3, 0xbfcc422a, v3
	v_mul_f32_e32 v3, 0x3fb8aa3b, v3
	v_exp_f32_e32 v3, v3
	s_nop 0
	v_add_f32_e32 v3, 1.0, v3
	v_rcp_f32_e32 v3, v3
	s_nop 0
	v_mul_f32_e32 v3, v23, v3
	v_mul_f32_e32 v3, v7, v3
	v_cvt_pk_bf16_f32 v4, v3, v3
	s_add_u32 s20, s18, 0x9a000
	s_addc_u32 s21, s19, 0
	global_store_short v98, v4, s[20:21]
	v_mul_f32_e32 v3, 0x3d372713, v24
	v_mul_f32_e32 v3, v24, v3
	v_fma_f32 v3, v24, v3, v24
	v_mul_f32_e32 v3, 0xbfcc422a, v3
	v_mul_f32_e32 v3, 0x3fb8aa3b, v3
	v_exp_f32_e32 v3, v3
	s_nop 0
	v_add_f32_e32 v3, 1.0, v3
	v_rcp_f32_e32 v3, v3
	s_nop 0
	v_mul_f32_e32 v3, v24, v3
	v_mul_f32_e32 v3, v8, v3
	v_cvt_pk_bf16_f32 v4, v3, v3
	s_add_u32 s20, s18, 0x9b600
	s_addc_u32 s21, s19, 0
	global_store_short v98, v4, s[20:21]
	v_mul_f32_e32 v3, 0x3d372713, v20
	v_mul_f32_e32 v3, v20, v3
	v_fma_f32 v3, v20, v3, v20
	v_mul_f32_e32 v3, 0xbfcc422a, v3
	v_mul_f32_e32 v3, 0x3fb8aa3b, v3
	v_exp_f32_e32 v3, v3
	s_nop 0
	v_add_f32_e32 v3, 1.0, v3
	v_rcp_f32_e32 v3, v3
	s_nop 0
	v_mul_f32_e32 v3, v20, v3
	v_mul_f32_e32 v3, v9, v3
	v_cvt_pk_bf16_f32 v4, v3, v3
	s_add_u32 s20, s18, 0x9cc00
	s_addc_u32 s21, s19, 0
	global_store_short v98, v4, s[20:21]
	v_mul_f32_e32 v3, 0x3d372713, v19
	v_mul_f32_e32 v3, v19, v3
	v_fma_f32 v3, v19, v3, v19
	v_mul_f32_e32 v3, 0xbfcc422a, v3
	v_mul_f32_e32 v3, 0x3fb8aa3b, v3
	v_exp_f32_e32 v3, v3
	s_nop 0
	v_add_f32_e32 v3, 1.0, v3
	v_rcp_f32_e32 v3, v3
	s_nop 0
	v_mul_f32_e32 v3, v19, v3
	v_mul_f32_e32 v3, v10, v3
	v_cvt_pk_bf16_f32 v4, v3, v3
	s_add_u32 s20, s18, 0x9e200
	s_addc_u32 s21, s19, 0
	global_store_short v98, v4, s[20:21]
	v_mul_f32_e32 v3, 0x3d372713, v18
	v_mul_f32_e32 v3, v18, v3
	v_fma_f32 v3, v18, v3, v18
	v_mul_f32_e32 v3, 0xbfcc422a, v3
	v_mul_f32_e32 v3, 0x3fb8aa3b, v3
	v_exp_f32_e32 v3, v3
	s_nop 0
	v_add_f32_e32 v3, 1.0, v3
	v_rcp_f32_e32 v3, v3
	s_nop 0
	v_mul_f32_e32 v3, v18, v3
	v_mul_f32_e32 v3, v11, v3
	v_cvt_pk_bf16_f32 v4, v3, v3
	s_add_u32 s20, s18, 0xa5000
	s_addc_u32 s21, s19, 0
	global_store_short v98, v4, s[20:21]
	v_mul_f32_e32 v3, 0x3d372713, v17
	v_mul_f32_e32 v3, v17, v3
	v_fma_f32 v3, v17, v3, v17
	v_mul_f32_e32 v3, 0xbfcc422a, v3
	v_mul_f32_e32 v3, 0x3fb8aa3b, v3
	v_exp_f32_e32 v3, v3
	s_nop 0
	v_add_f32_e32 v3, 1.0, v3
	v_rcp_f32_e32 v3, v3
	s_nop 0
	v_mul_f32_e32 v3, v17, v3
	v_mul_f32_e32 v1, v1, v3
	v_bfe_u32 v3, v1, 16, 1
	v_add3_u32 v1, v1, v3, s89
	s_add_u32 s20, s18, 0xa6600
	s_addc_u32 s21, s19, 0
	global_store_short_d16_hi v98, v1, s[20:21]
	v_mul_f32_e32 v2, 0x3d372713, v16
	v_mul_f32_e32 v2, v16, v2
	v_fma_f32 v2, v16, v2, v16
	v_mul_f32_e32 v2, 0xbfcc422a, v2
	v_mul_f32_e32 v2, 0x3fb8aa3b, v2
	v_exp_f32_e32 v2, v2
	s_nop 0
	v_add_f32_e32 v2, 1.0, v2
	v_rcp_f32_e32 v2, v2
	s_nop 0
	v_mul_f32_e32 v2, v16, v2
	v_mul_f32_e32 v0, v0, v2
	v_cvt_pk_bf16_f32 v2, v0, v0
	s_add_u32 s20, s18, 0xa7c00
	s_addc_u32 s21, s19, 0
	global_store_short v98, v2, s[20:21]
	v_mul_f32_e32 v1, 0x3d372713, v148
	v_mul_f32_e32 v1, v148, v1
	v_fma_f32 v1, v148, v1, v148
	v_mul_f32_e32 v1, 0xbfcc422a, v1
	v_mul_f32_e32 v1, 0x3fb8aa3b, v1
	v_exp_f32_e32 v1, v1
	s_nop 0
	v_add_f32_e32 v1, 1.0, v1
	v_rcp_f32_e32 v1, v1
	s_nop 0
	v_mul_f32_e32 v1, v148, v1
	v_mul_f32_e32 v1, v149, v1
	v_cvt_pk_bf16_f32 v2, v1, v1
	s_add_u32 s20, s18, 0xa9200
	s_addc_u32 s21, s19, 0
	global_store_short v98, v2, s[20:21]
	s_add_i32 s10, s10, 1
	s_mov_b64 s[2:3], 0
	s_waitcnt vmcnt(63) expcnt(7) lgkmcnt(15)
	s_barrier
